# u-phase: last (slice, token) step peeled, no dummy row requests and no drain at its end
# speedup vs baseline: 1.0107x; 1.0007x over previous
; #define LAS __attribute__((address_space(3)))
; #define MFMA32(a, b, c) __builtin_amdgcn_mfma_f32_32x32x16_bf16((a), (b), (c), 0, 0, 0)
; __device__ __forceinline__ void route_task(int task, int tl0, const bf16* QP  , const LAS bf16* KHL, LAS unsigned short* EL, LAS float* GL, int lane) {
;     const int r = lane & 31, hi = lane >> 5, t = 4 * task + (r >> 3), head = r & 7;
;     int top[2][16]; bf16x8 qa[2][4];
;     { unsigned qo = (unsigned)t * (unsigned)D + (unsigned)(head * 128 + 8 * hi); asm volatile("" : "+v"(qo)); const bf16* qp = QP + qo;
; #pragma unroll
;       for (int hf = 0; hf < 2; ++hf)
; #pragma unroll
;         for (int ks = 0; ks < 4; ++ks) qa[hf][ks] = ldg8(qp + 64 * hf + 16 * ks); }
; #pragma unroll
;     for (int half = 0; half < 2; ++half) {
;         int cur[16];
; #pragma unroll
;         for (int kt = 0; kt < 4; ++kt) {
;             f32x16 X;
; #pragma unroll
;             for (int i = 0; i < 16; ++i) X[i] = 8.f;
;             const LAS bf16* khp = KHL + (half * 128 + 32 * kt + r) * 72 + 8 * hi;
; #pragma unroll
;             for (int ks = 0; ks < 4; ++ks) {
;                 const bf16x8 kh = lds8(khp + 16 * ks);
;                 X = MFMA32(kh, qa[half][ks], X);
;             }
;             int grp[16];
; #pragma unroll
;             for (int i = 0; i < 16; ++i) grp[i] = (int)((__float_as_uint(X[i]) | 127u) - (unsigned)(32 * kt + (i & 3) + 8 * (i >> 2)));
;             sort16_desc(grp);
;             if (kt == 0) {
; #pragma unroll
;                 for (int i = 0; i < 16; ++i) cur[i] = grp[i];
;             } else merge16_desc(cur, grp);
;         }
.LBB0_666:
	s_or_b64 exec, exec, s[10:11]
	s_lshl_b32 s10, s2, 4
	s_add_i32 s10, s10, s95
	s_lshl_b32 s10, s10, 12
	v_or_b32_e32 v82, s10, v88
	s_waitcnt lgkmcnt(0)
	s_barrier
	s_add_i32 s11, 0, 0x12000
	v_lshl_add_u64 v[70:71], v[82:83], 1, s[80:81]
	global_load_dwordx4 v[62:65], v[70:71], off
	global_load_dwordx4 v[54:57], v[70:71], off offset:32
	global_load_dwordx4 v[58:61], v[70:71], off offset:64
	global_load_dwordx4 v[50:53], v[70:71], off offset:96
	ds_read_b128 v[34:37], v94
	ds_read_b128 v[38:41], v94 offset:32
	s_add_i32 s10, s10, 0x8000
	s_mov_b32 s41, 0
	s_waitcnt vmcnt(3) lgkmcnt(1)
	v_mfma_f32_32x32x16_bf16 v[18:33], v[34:37], v[62:65], v[2:17]
	ds_read_b128 v[34:37], v94 offset:64
	ds_read_b128 v[66:69], v94 offset:96
	s_waitcnt vmcnt(2) lgkmcnt(2)
	v_mfma_f32_32x32x16_bf16 v[18:33], v[38:41], v[54:57], v[18:33]
	v_and_b32_e32 v38, 64, v112
	v_add_u32_e32 v122, 64, v38
	v_cmp_lt_i32_e32 vcc, v113, v122
	s_waitcnt vmcnt(1) lgkmcnt(1)
	v_mfma_f32_32x32x16_bf16 v[18:33], v[34:37], v[58:61], v[18:33]
	v_cndmask_b32_e32 v34, v112, v113, vcc
	v_lshlrev_b32_e32 v123, 2, v34
	global_load_dwordx4 v[46:49], v[70:71], off offset:128
	global_load_dwordx4 v[42:45], v[70:71], off offset:160
	global_load_dwordx4 v[38:41], v[70:71], off offset:192
	global_load_dwordx4 v[34:37], v[70:71], off offset:224
	s_waitcnt vmcnt(4) lgkmcnt(0)
	v_mfma_f32_32x32x16_bf16 v[18:33], v[66:69], v[50:53], v[18:33]
	s_nop 11
	s_movk_i32 s42, 0x7f
	s_movk_i32 s43, 0xff80
	v_bitop3_b32 v21, v21, s42, 3 bitop3:0x56
	v_bitop3_b32 v32, v32, s42, 26 bitop3:0x56
	v_bitop3_b32 v22, v22, s42, 8 bitop3:0x56
	v_bitop3_b32 v26, v26, s42, 16 bitop3:0x56
	v_bitop3_b32 v31, v31, s42, 25 bitop3:0x56
	v_bitop3_b32 v23, v23, s42, 9 bitop3:0x56
	v_bitop3_b32 v24, v24, s42, 10 bitop3:0x56
	v_bitop3_b32 v27, v27, s42, 17 bitop3:0x56
	v_bitop3_b32 v28, v28, s42, 18 bitop3:0x56
	v_bitop3_b32 v20, v20, s42, 2 bitop3:0x56
	v_bitop3_b32 v33, v33, s42, 27 bitop3:0x56
	v_bitop3_b32 v25, v25, s42, 11 bitop3:0x56
	v_bitop3_b32 v29, v29, s42, 19 bitop3:0x56
	v_bitop3_b32 v19, v19, s42, 1 bitop3:0x56
	v_bitop3_b32 v30, v30, s42, 24 bitop3:0x56
	v_or_b32_e32 v18, 0x7f, v18
	v_max_i32_e32 v66, v21, v32
	v_max_i32_e32 v67, v22, v26
	v_max_i32_e32 v68, v18, v31
	v_max_i32_e32 v69, v23, v24
	v_min_i32_e32 v70, v27, v28
	v_min_i32_e32 v71, v20, v33
	v_min_i32_e32 v72, v25, v29
	v_min_i32_e32 v73, v19, v30
	v_min_i32_e32 v23, v23, v24
	v_min_i32_e32 v18, v18, v31
	v_min_i32_e32 v22, v22, v26
	v_min_i32_e32 v21, v21, v32
	v_max_i32_e32 v19, v19, v30
	v_max_i32_e32 v24, v25, v29
	v_max_i32_e32 v20, v20, v33
	v_max_i32_e32 v25, v27, v28
	v_min_i32_e32 v26, v66, v67
	v_min_i32_e32 v27, v68, v69
	v_max_i32_e32 v28, v70, v71
	v_max_i32_e32 v29, v72, v73
	v_max_i32_e32 v30, v23, v18
	v_max_i32_e32 v31, v22, v21
	v_min_i32_e32 v32, v19, v24
	v_min_i32_e32 v33, v20, v25
	v_min_i32_e32 v18, v23, v18
	v_min_i32_e32 v21, v22, v21
	v_min_i32_e32 v22, v70, v71
	v_max_i32_e32 v23, v68, v69
	v_max_i32_e32 v19, v19, v24
	v_max_i32_e32 v20, v20, v25
	v_max_i32_e32 v24, v66, v67
	v_min_i32_e32 v25, v26, v27
	v_max_i32_e32 v67, v30, v31
	v_min_i32_e32 v30, v30, v31
	v_min_i32_e32 v31, v32, v33
	v_max_i32_e32 v26, v26, v27
	v_max_i32_e32 v27, v28, v29
	v_min_i32_e32 v66, v28, v29
	v_max_i32_e32 v68, v32, v33
	v_min_i32_e32 v75, v21, v22
	v_max_i32_e32 v21, v21, v22
	v_min_i32_e32 v22, v23, v19
	v_min_i32_e32 v28, v20, v24
	v_max_i32_e32 v33, v30, v31
	v_min_i32_e32 v69, v26, v27
	v_max_i32_e32 v29, v25, v66
	v_min_i32_e32 v32, v67, v68
	v_min_i32_e32 v77, v25, v66
	v_min_i32_e32 v25, v22, v28
	v_max_i32_e32 v80, v22, v28
	v_min_i32_e32 v22, v33, v69
	v_max_i32_e32 v125, v20, v24
	v_max_i32_e32 v129, v67, v68
	v_max_i32_e32 v24, v33, v69
	ds_read_b128 v[66:69], v95
	v_min_i32_e32 v72, v72, v73
	v_min_i32_e32 v74, v72, v18
	v_max_i32_e32 v18, v72, v18
	v_max_i32_e32 v124, v23, v19
	v_min_i32_e32 v76, v30, v31
	v_max_i32_e32 v78, v74, v75
	v_min_i32_e32 v79, v18, v21
	v_min_i32_e32 v126, v124, v125
	v_max_i32_e32 v128, v26, v27
	v_max_i32_e32 v18, v18, v21
	v_max_i32_e32 v81, v76, v77
	v_max_i32_e32 v82, v78, v79
	v_min_i32_e32 v127, v80, v126
	v_min_i32_e32 v130, v128, v129
	v_min_i32_e32 v21, v29, v32
	v_min_i32_e32 v28, v25, v18
	v_max_i32_e32 v18, v25, v18
	v_max_i32_e32 v30, v81, v82
	v_min_i32_e32 v19, v127, v130
	v_max_i32_e32 v23, v29, v32
	v_max_i32_e32 v25, v21, v22
	v_max_i32_e32 v31, v30, v28
	v_min_i32_e32 v20, v18, v19
	v_min_i32_e32 v26, v23, v24
	v_max_i32_e32 v70, v25, v31
	v_min_i32_e32 v27, v20, v26
	v_min_i32_e32 v131, v70, v27
	v_max_i32_e32 v143, v70, v27
	ds_read_b128 v[70:73], v95 offset:32
	v_min_i32_e32 v132, v25, v31
	v_min_i32_e32 v133, v21, v22
	v_min_i32_e32 v134, v30, v28
	v_max_i32_e32 v138, v18, v19
	v_max_i32_e32 v139, v23, v24
	v_max_i32_e32 v141, v20, v26
	s_waitcnt lgkmcnt(1)
	v_mfma_f32_32x32x16_bf16 v[18:33], v[66:69], v[62:65], v[2:17]
	ds_read_b128 v[66:69], v95 offset:64
	v_max_i32_e32 v135, v133, v134
	v_max_i32_e32 v136, v132, v135
	v_min_i32_e32 v76, v76, v77
	v_min_i32_e32 v77, v78, v79
	v_min_i32_e32 v132, v132, v135
	v_max_i32_e32 v127, v127, v130
	s_waitcnt lgkmcnt(1)
	v_mfma_f32_32x32x16_bf16 v[18:33], v[70:73], v[54:57], v[18:33]
	ds_read_b128 v[70:73], v95 offset:96
	v_max_i32_e32 v80, v80, v126
	v_min_i32_e32 v74, v74, v75
	v_min_i32_e32 v140, v138, v139
	v_max_i32_e32 v78, v76, v77
	v_min_i32_e32 v79, v81, v82
	v_min_i32_e32 v82, v133, v134
	s_waitcnt lgkmcnt(1)
	v_mfma_f32_32x32x16_bf16 v[18:33], v[66:69], v[58:61], v[18:33]
	v_max_i32_e32 v66, v128, v129
	v_max_i32_e32 v134, v138, v139
	v_min_i32_e32 v76, v76, v77
	v_max_i32_e32 v81, v78, v79
	v_min_i32_e32 v78, v78, v79
	v_min_i32_e32 v67, v80, v66
	v_min_i32_e32 v142, v140, v141
	s_waitcnt lgkmcnt(0)
; #define LAS __attribute__((address_space(3)))
; #define MFMA32(a, b, c) __builtin_amdgcn_mfma_f32_32x32x16_bf16((a), (b), (c), 0, 0, 0)
; __device__ __forceinline__ void route_task(int task, int tl0, const bf16* QP  , const LAS bf16* KHL, LAS unsigned short* EL, LAS float* GL, int lane) {
;     ...
; #pragma unroll
;         for (int kt = 0; kt < 4; ++kt) {
;             f32x16 X;
; #pragma unroll
;             for (int i = 0; i < 16; ++i) X[i] = 8.f;
;             const LAS bf16* khp = KHL + (half * 128 + 32 * kt + r) * 72 + 8 * hi;
; #pragma unroll
;             for (int ks = 0; ks < 4; ++ks) {
;                 const bf16x8 kh = lds8(khp + 16 * ks);
;                 X = MFMA32(kh, qa[half][ks], X);
;             }
;             int grp[16];
; #pragma unroll
;             for (int i = 0; i < 16; ++i) grp[i] = (int)((__float_as_uint(X[i]) | 127u) - (unsigned)(32 * kt + (i & 3) + 8 * (i >> 2)));
;             sort16_desc(grp);
;             if (kt == 0) {
; #pragma unroll
;                 for (int i = 0; i < 16; ++i) cur[i] = grp[i];
;             } else merge16_desc(cur, grp);
;         }
	v_mfma_f32_32x32x16_bf16 v[18:33], v[70:73], v[50:53], v[18:33]
	v_min_i32_e32 v68, v127, v67
	v_min_i32_e32 v137, v131, v136
	v_min_i32_e32 v144, v142, v143
	v_min_i32_e32 v133, v81, v82
	v_min_i32_e32 v69, v134, v68
	s_nop 6
	v_bitop3_b32 v21, v21, s42, 35 bitop3:0x56
	v_bitop3_b32 v32, v32, s42, 58 bitop3:0x56
	v_bitop3_b32 v22, v22, s42, 40 bitop3:0x56
	v_bitop3_b32 v26, v26, s42, 48 bitop3:0x56
	v_bitop3_b32 v18, v18, s42, 32 bitop3:0x56
	v_bitop3_b32 v31, v31, s42, 57 bitop3:0x56
	v_bitop3_b32 v23, v23, s42, 41 bitop3:0x56
	v_bitop3_b32 v24, v24, s42, 42 bitop3:0x56
	v_bitop3_b32 v27, v27, s42, 49 bitop3:0x56
	v_bitop3_b32 v28, v28, s42, 50 bitop3:0x56
	v_bitop3_b32 v20, v20, s42, 34 bitop3:0x56
	v_bitop3_b32 v33, v33, s42, 59 bitop3:0x56
	v_bitop3_b32 v25, v25, s42, 43 bitop3:0x56
	v_bitop3_b32 v29, v29, s42, 51 bitop3:0x56
	v_bitop3_b32 v19, v19, s42, 33 bitop3:0x56
	v_bitop3_b32 v30, v30, s42, 56 bitop3:0x56
	v_max_i32_e32 v70, v21, v32
	v_max_i32_e32 v71, v22, v26
	v_max_i32_e32 v73, v18, v31
	v_max_i32_e32 v75, v23, v24
	v_min_i32_e32 v126, v27, v28
	v_min_i32_e32 v128, v20, v33
	v_min_i32_e32 v130, v25, v29
	v_min_i32_e32 v135, v19, v30
	v_min_i32_e32 v23, v23, v24
	v_min_i32_e32 v18, v18, v31
	v_min_i32_e32 v22, v22, v26
	v_min_i32_e32 v21, v21, v32
	v_max_i32_e32 v19, v19, v30
	v_max_i32_e32 v25, v25, v29
	v_max_i32_e32 v20, v20, v33
	v_max_i32_e32 v27, v27, v28
	v_min_i32_e32 v72, v70, v71
	v_min_i32_e32 v77, v73, v75
	v_max_i32_e32 v129, v126, v128
	v_max_i32_e32 v138, v130, v135
	v_max_i32_e32 v24, v23, v18
	v_max_i32_e32 v26, v22, v21
	v_min_i32_e32 v29, v19, v25
	v_min_i32_e32 v28, v20, v27
	v_min_i32_e32 v130, v130, v135
	v_min_i32_e32 v18, v23, v18
	v_min_i32_e32 v21, v22, v21
	v_min_i32_e32 v22, v126, v128
	v_max_i32_e32 v73, v73, v75
	v_max_i32_e32 v19, v19, v25
	v_max_i32_e32 v20, v20, v27
	v_max_i32_e32 v27, v70, v71
	v_min_i32_e32 v79, v72, v77
	v_min_i32_e32 v139, v129, v138
	v_max_i32_e32 v31, v24, v26
	v_max_i32_e32 v30, v29, v28
	v_min_i32_e32 v24, v24, v26
	v_min_i32_e32 v26, v29, v28
	v_max_i32_e32 v29, v72, v77
	v_max_i32_e32 v72, v129, v138
	v_min_i32_e32 v23, v130, v18
	v_min_i32_e32 v126, v21, v22
	v_max_i32_e32 v18, v130, v18
	v_max_i32_e32 v21, v21, v22
	v_min_i32_e32 v25, v73, v19
	v_min_i32_e32 v70, v20, v27
	v_max_i32_e32 v19, v73, v19
	v_max_i32_e32 v20, v20, v27
	v_min_i32_e32 v32, v31, v30
	v_max_i32_e32 v28, v24, v26
	v_min_i32_e32 v77, v29, v72
	v_min_i32_e32 v24, v24, v26
	v_min_i32_e32 v26, v79, v139
	v_max_i32_e32 v128, v23, v126
	v_min_i32_e32 v22, v18, v21
	v_min_i32_e32 v71, v25, v70
	v_max_i32_e32 v25, v25, v70
	v_min_i32_e32 v27, v19, v20
	v_max_i32_e32 v29, v29, v72
	v_max_i32_e32 v30, v31, v30
	v_max_i32_e32 v145, v79, v139
	v_max_i32_e32 v79, v24, v26
	v_max_i32_e32 v130, v128, v22
	v_max_i32_e32 v18, v18, v21
	v_min_i32_e32 v70, v25, v27
	v_min_i32_e32 v31, v29, v30
	v_min_i32_e32 v33, v145, v32
	v_min_i32_e32 v129, v28, v77
	v_max_i32_e32 v135, v79, v130
	v_min_i32_e32 v21, v71, v18
	v_max_i32_e32 v18, v71, v18
	v_min_i32_e32 v71, v70, v31
	v_max_i32_e32 v32, v145, v32
	v_max_i32_e32 v28, v28, v77
	v_max_i32_e32 v138, v33, v129
	v_max_i32_e32 v75, v135, v21
	v_min_i32_e32 v72, v18, v71
	v_min_i32_e32 v73, v32, v28
	v_min_i32_e32 v33, v33, v129
	v_min_i32_e32 v21, v135, v21
	v_max_i32_e32 v18, v18, v71
	v_max_i32_e32 v28, v32, v28
	v_min_i32_e32 v24, v24, v26
	v_min_i32_e32 v22, v128, v22
	v_max_i32_e32 v25, v25, v27
	v_max_i32_e32 v27, v29, v30
	v_max_i32_e32 v139, v138, v75
	v_min_i32_e32 v77, v72, v73
	v_min_i32_e32 v75, v138, v75
	v_max_i32_e32 v129, v33, v21
	v_min_i32_e32 v32, v18, v28
	v_max_i32_e32 v71, v72, v73
	v_max_i32_e32 v26, v24, v22
	v_min_i32_e32 v79, v79, v130
	v_max_i32_e32 v18, v18, v28
	v_max_i32_e32 v28, v70, v31
	v_min_i32_e32 v29, v25, v27
	v_min_i32_e32 v145, v139, v77
	v_max_i32_e32 v135, v75, v129
	v_min_i32_e32 v72, v32, v71
	v_max_i32_e32 v73, v139, v77
	v_max_i32_e32 v128, v26, v79
	v_min_i32_e32 v21, v33, v21
	v_min_i32_e32 v30, v28, v29
	v_min_i32_e32 v138, v145, v135
	v_min_i32_e32 v77, v72, v73
	v_min_i32_e32 v33, v128, v21
	v_min_i32_e32 v75, v75, v129
	v_min_i32_e32 v31, v18, v30
	v_min_i32_e32 v26, v26, v79
	v_min_i32_e32 v22, v24, v22
	v_min_i32_e32 v23, v23, v126
	v_max3_i32 v23, v124, v125, v23
	v_max3_i32 v22, v80, v66, v22
	v_max3_i32 v24, v127, v67, v26
	v_max3_i32 v26, v134, v68, v33
	v_max3_i32 v21, v69, v128, v21
	v_max3_i32 v33, v140, v141, v75
	v_max3_i32 v66, v142, v143, v138
	v_max3_i32 v67, v144, v145, v135
	v_max3_i32 v68, v131, v136, v77
	v_max3_i32 v69, v137, v72, v73
	v_max3_i32 v32, v132, v32, v71
	v_max3_i32 v31, v81, v82, v31
	v_max3_i32 v18, v133, v18, v30
	v_max3_i32 v28, v78, v28, v29
	v_max3_i32 v25, v76, v25, v27
	v_max3_i32 v19, v74, v19, v20
	v_max_i32_e32 v20, v23, v68
	v_min_i32_e32 v23, v23, v68
	v_max_i32_e32 v27, v22, v69
	v_min_i32_e32 v22, v22, v69
	v_max_i32_e32 v29, v24, v32
	v_min_i32_e32 v24, v24, v32
	v_max_i32_e32 v30, v26, v31
	v_min_i32_e32 v26, v26, v31
	v_max_i32_e32 v31, v21, v18
	v_min_i32_e32 v18, v21, v18
	v_max_i32_e32 v21, v33, v28
	v_min_i32_e32 v28, v33, v28
	v_max_i32_e32 v32, v66, v25
	v_min_i32_e32 v25, v66, v25
	v_max_i32_e32 v33, v67, v19
	v_min_i32_e32 v19, v67, v19
	ds_read_b128 v[66:69], v94 offset:9216
	v_max_i32_e32 v70, v20, v31
	v_min_i32_e32 v74, v20, v31
	v_max_i32_e32 v20, v27, v21
	v_min_i32_e32 v75, v27, v21
	v_max_i32_e32 v21, v29, v32
	v_max_i32_e32 v27, v30, v33
	v_max_i32_e32 v127, v70, v21
	v_min_i32_e32 v128, v70, v21
	ds_read_b128 v[70:73], v94 offset:9248
	v_min_i32_e32 v76, v29, v32
	v_min_i32_e32 v77, v30, v33
	v_max_i32_e32 v78, v23, v18
	v_min_i32_e32 v79, v23, v18
	v_max_i32_e32 v80, v22, v28
	v_min_i32_e32 v81, v22, v28
	v_max_i32_e32 v82, v24, v25
	v_min_i32_e32 v124, v24, v25
	v_max_i32_e32 v125, v26, v19
	v_min_i32_e32 v126, v26, v19
	v_max_i32_e32 v129, v20, v27
	v_min_i32_e32 v130, v20, v27
	s_waitcnt lgkmcnt(1)
; #define LAS __attribute__((address_space(3)))
; #define MFMA32(a, b, c) __builtin_amdgcn_mfma_f32_32x32x16_bf16((a), (b), (c), 0, 0, 0)
; __device__ __forceinline__ void route_task(int task, int tl0, const bf16* QP  , const LAS bf16* KHL, LAS unsigned short* EL, LAS float* GL, int lane) {
;     ...
; #pragma unroll
;         for (int kt = 0; kt < 4; ++kt) {
;             f32x16 X;
; #pragma unroll
;             for (int i = 0; i < 16; ++i) X[i] = 8.f;
;             const LAS bf16* khp = KHL + (half * 128 + 32 * kt + r) * 72 + 8 * hi;
; #pragma unroll
;             for (int ks = 0; ks < 4; ++ks) {
;                 const bf16x8 kh = lds8(khp + 16 * ks);
;                 X = MFMA32(kh, qa[half][ks], X);
;             }
;             int grp[16];
; #pragma unroll
;             for (int i = 0; i < 16; ++i) grp[i] = (int)((__float_as_uint(X[i]) | 127u) - (unsigned)(32 * kt + (i & 3) + 8 * (i >> 2)));
;             sort16_desc(grp);
;             if (kt == 0) {
; #pragma unroll
;                 for (int i = 0; i < 16; ++i) cur[i] = grp[i];
;             } else merge16_desc(cur, grp);
;         }
	v_mfma_f32_32x32x16_bf16 v[18:33], v[66:69], v[62:65], v[2:17]
	ds_read_b128 v[66:69], v94 offset:9280
	v_max_i32_e32 v131, v74, v76
	v_min_i32_e32 v74, v74, v76
	v_max_i32_e32 v76, v75, v77
	v_min_i32_e32 v75, v75, v77
	v_max_i32_e32 v77, v78, v82
	v_min_i32_e32 v78, v78, v82
	s_waitcnt lgkmcnt(1)
	v_mfma_f32_32x32x16_bf16 v[18:33], v[70:73], v[54:57], v[18:33]
	ds_read_b128 v[70:73], v94 offset:9312
	v_max_i32_e32 v82, v80, v125
	v_min_i32_e32 v80, v80, v125
	v_max_i32_e32 v125, v79, v124
	v_min_i32_e32 v79, v79, v124
	v_max_i32_e32 v124, v81, v126
	v_min_i32_e32 v81, v81, v126
	s_waitcnt lgkmcnt(1)
	v_mfma_f32_32x32x16_bf16 v[18:33], v[66:69], v[58:61], v[18:33]
	v_min_i32_e32 v126, v127, v129
	v_min_i32_e32 v66, v128, v130
	v_min_i32_e32 v67, v131, v76
	v_min_i32_e32 v69, v77, v82
	v_min_i32_e32 v132, v78, v80
	v_min_i32_e32 v133, v125, v124
	v_min_i32_e32 v68, v74, v75
	s_waitcnt lgkmcnt(0)
	v_mfma_f32_32x32x16_bf16 v[18:33], v[70:73], v[50:53], v[18:33]
	v_min_i32_e32 v134, v79, v81
	s_nop 10
	v_and_or_b32 v21, v21, s43, 60
	v_and_or_b32 v32, v32, s43, 37
	v_and_or_b32 v22, v22, s43, 55
	v_and_or_b32 v26, v26, s43, 47
	v_bitop3_b32 v18, v18, s42, 64 bitop3:0x56
	v_and_or_b32 v31, v31, s43, 38
	v_and_or_b32 v23, v23, s43, 54
	v_and_or_b32 v24, v24, s43, 53
	v_and_or_b32 v27, v27, s43, 46
	v_and_or_b32 v28, v28, s43, 45
	v_and_or_b32 v20, v20, s43, 61
	v_and_or_b32 v33, v33, s43, 36
	v_and_or_b32 v25, v25, s43, 52
	v_and_or_b32 v29, v29, s43, 44
	v_and_or_b32 v19, v19, s43, 62
	v_and_or_b32 v30, v30, s43, 39
	v_max_i32_e32 v70, v21, v32
	v_max_i32_e32 v71, v22, v26
	v_max_i32_e32 v73, v18, v31
	v_max_i32_e32 v135, v23, v24
	v_min_i32_e32 v138, v27, v28
	v_min_i32_e32 v139, v20, v33
	v_min_i32_e32 v141, v25, v29
	v_min_i32_e32 v142, v19, v30
	v_min_i32_e32 v23, v23, v24
	v_min_i32_e32 v18, v18, v31
	v_min_i32_e32 v22, v22, v26
	v_min_i32_e32 v21, v21, v32
	v_max_i32_e32 v19, v19, v30
	v_max_i32_e32 v25, v25, v29
	v_max_i32_e32 v20, v20, v33
	v_max_i32_e32 v27, v27, v28
	v_min_i32_e32 v72, v70, v71
	v_min_i32_e32 v136, v73, v135
	v_max_i32_e32 v140, v138, v139
	v_max_i32_e32 v143, v141, v142
	v_max_i32_e32 v24, v23, v18
	v_max_i32_e32 v26, v22, v21
	v_min_i32_e32 v29, v19, v25
	v_min_i32_e32 v28, v20, v27
	v_min_i32_e32 v141, v141, v142
	v_min_i32_e32 v18, v23, v18
	v_min_i32_e32 v21, v22, v21
	v_min_i32_e32 v22, v138, v139
	v_max_i32_e32 v73, v73, v135
	v_max_i32_e32 v19, v19, v25
	v_max_i32_e32 v20, v20, v27
	v_max_i32_e32 v27, v70, v71
	v_min_i32_e32 v137, v72, v136
	v_min_i32_e32 v144, v140, v143
	v_max_i32_e32 v31, v24, v26
	v_max_i32_e32 v30, v29, v28
	v_min_i32_e32 v24, v24, v26
	v_min_i32_e32 v26, v29, v28
	v_max_i32_e32 v29, v72, v136
	v_max_i32_e32 v72, v140, v143
	v_min_i32_e32 v23, v141, v18
	v_min_i32_e32 v138, v21, v22
	v_max_i32_e32 v18, v141, v18
	v_max_i32_e32 v21, v21, v22
	v_min_i32_e32 v25, v73, v19
	v_min_i32_e32 v70, v20, v27
	v_max_i32_e32 v19, v73, v19
	v_max_i32_e32 v20, v20, v27
	v_min_i32_e32 v32, v31, v30
	v_max_i32_e32 v28, v24, v26
	v_min_i32_e32 v136, v29, v72
	v_min_i32_e32 v24, v24, v26
	v_min_i32_e32 v26, v137, v144
	v_max_i32_e32 v139, v23, v138
	v_min_i32_e32 v22, v18, v21
	v_min_i32_e32 v71, v25, v70
	v_max_i32_e32 v25, v25, v70
	v_min_i32_e32 v27, v19, v20
	v_max_i32_e32 v29, v29, v72
	v_max_i32_e32 v30, v31, v30
	v_max_i32_e32 v145, v137, v144
	v_max_i32_e32 v137, v24, v26
	v_max_i32_e32 v141, v139, v22
	v_max_i32_e32 v18, v18, v21
	v_min_i32_e32 v70, v25, v27
	v_min_i32_e32 v31, v29, v30
	v_min_i32_e32 v33, v145, v32
	v_min_i32_e32 v140, v28, v136
	v_max_i32_e32 v142, v137, v141
	v_min_i32_e32 v21, v71, v18
	v_max_i32_e32 v18, v71, v18
	v_min_i32_e32 v71, v70, v31
	v_max_i32_e32 v32, v145, v32
	v_max_i32_e32 v28, v28, v136
	v_max_i32_e32 v143, v33, v140
	v_max_i32_e32 v135, v142, v21
	v_min_i32_e32 v72, v18, v71
	v_min_i32_e32 v73, v32, v28
	v_min_i32_e32 v33, v33, v140
	v_min_i32_e32 v21, v142, v21
	v_max_i32_e32 v18, v18, v71
	v_max_i32_e32 v28, v32, v28
	v_min_i32_e32 v24, v24, v26
	v_min_i32_e32 v22, v139, v22
	v_max_i32_e32 v25, v25, v27
	v_max_i32_e32 v27, v29, v30
	v_max_i32_e32 v144, v143, v135
	v_min_i32_e32 v136, v72, v73
	v_min_i32_e32 v135, v143, v135
	v_max_i32_e32 v140, v33, v21
	v_min_i32_e32 v32, v18, v28
	v_max_i32_e32 v71, v72, v73
	v_max_i32_e32 v26, v24, v22
	v_min_i32_e32 v137, v137, v141
	v_max_i32_e32 v18, v18, v28
	v_max_i32_e32 v28, v70, v31
	v_min_i32_e32 v29, v25, v27
	v_min_i32_e32 v145, v144, v136
	v_max_i32_e32 v142, v135, v140
	v_min_i32_e32 v72, v32, v71
	v_max_i32_e32 v73, v144, v136
	v_max_i32_e32 v139, v26, v137
	v_min_i32_e32 v21, v33, v21
	v_min_i32_e32 v30, v28, v29
	v_min_i32_e32 v143, v145, v142
	v_min_i32_e32 v136, v72, v73
	v_min_i32_e32 v33, v139, v21
	v_max_i32_e32 v21, v139, v21
	v_min_i32_e32 v135, v135, v140
	v_max_i32_e32 v32, v32, v71
	v_min_i32_e32 v31, v18, v30
	v_max_i32_e32 v18, v18, v30
	v_min_i32_e32 v26, v26, v137
	v_min_i32_e32 v22, v24, v22
	v_max_i32_e32 v24, v25, v27
	v_min_i32_e32 v23, v23, v138
	v_max3_i32 v23, v127, v129, v23
	v_max_i32_e32 v22, v126, v22
	v_max3_i32 v25, v128, v130, v26
	v_max_i32_e32 v26, v66, v33
	v_max3_i32 v21, v131, v76, v21
	v_max_i32_e32 v27, v67, v135
	v_max3_i32 v30, v74, v75, v143
	v_max3_i32 v66, v77, v82, v136
	v_max3_i32 v67, v69, v72, v73
	v_max3_i32 v32, v78, v80, v32
	v_max_i32_e32 v31, v132, v31
	v_max3_i32 v18, v125, v124, v18
	v_max3_i32 v28, v133, v28, v29
	v_max3_i32 v24, v79, v81, v24
	v_max3_i32 v33, v68, v145, v142
	v_max3_i32 v19, v134, v19, v20
	v_max_i32_e32 v20, v23, v66
	v_min_i32_e32 v23, v23, v66
	v_max_i32_e32 v29, v22, v67
	v_max_i32_e32 v66, v25, v32
	v_min_i32_e32 v25, v25, v32
	v_max_i32_e32 v32, v26, v31
	v_min_i32_e32 v26, v26, v31
	v_max_i32_e32 v31, v21, v18
	v_min_i32_e32 v18, v21, v18
	v_max_i32_e32 v21, v27, v28
	v_min_i32_e32 v27, v27, v28
	v_max_i32_e32 v28, v30, v24
	v_min_i32_e32 v22, v22, v67
	v_min_i32_e32 v24, v30, v24
	v_max_i32_e32 v30, v33, v19
	v_min_i32_e32 v19, v33, v19
	v_max_i32_e32 v33, v20, v31
	v_min_i32_e32 v74, v20, v31
	v_max_i32_e32 v20, v29, v21
	v_min_i32_e32 v75, v29, v21
	v_max_i32_e32 v21, v66, v28
	v_min_i32_e32 v76, v66, v28
	ds_read_b128 v[66:69], v96
	ds_read_b128 v[70:73], v96 offset:32
	v_max_i32_e32 v28, v32, v30
	v_min_i32_e32 v77, v32, v30
	v_max_i32_e32 v78, v23, v18
	v_min_i32_e32 v79, v23, v18
	v_max_i32_e32 v80, v22, v27
	v_min_i32_e32 v81, v22, v27
	v_max_i32_e32 v82, v25, v24
	v_min_i32_e32 v124, v25, v24
	v_max_i32_e32 v125, v26, v19
	v_min_i32_e32 v126, v26, v19
	v_max_i32_e32 v127, v33, v21
	v_min_i32_e32 v128, v33, v21
	v_max_i32_e32 v129, v20, v28
	v_min_i32_e32 v130, v20, v28
	s_waitcnt lgkmcnt(1)
; #define LAS __attribute__((address_space(3)))
; #define MFMA32(a, b, c) __builtin_amdgcn_mfma_f32_32x32x16_bf16((a), (b), (c), 0, 0, 0)
; __device__ __forceinline__ void route_task(int task, int tl0, const bf16* QP  , const LAS bf16* KHL, LAS unsigned short* EL, LAS float* GL, int lane) {
;     ...
; #pragma unroll
;         for (int kt = 0; kt < 4; ++kt) {
;             f32x16 X;
; #pragma unroll
;             for (int i = 0; i < 16; ++i) X[i] = 8.f;
;             const LAS bf16* khp = KHL + (half * 128 + 32 * kt + r) * 72 + 8 * hi;
; #pragma unroll
;             for (int ks = 0; ks < 4; ++ks) {
;                 const bf16x8 kh = lds8(khp + 16 * ks);
;                 X = MFMA32(kh, qa[half][ks], X);
;             }
;             int grp[16];
; #pragma unroll
;             for (int i = 0; i < 16; ++i) grp[i] = (int)((__float_as_uint(X[i]) | 127u) - (unsigned)(32 * kt + (i & 3) + 8 * (i >> 2)));
;             sort16_desc(grp);
;             if (kt == 0) {
; #pragma unroll
;                 for (int i = 0; i < 16; ++i) cur[i] = grp[i];
;             } else merge16_desc(cur, grp);
;         }
	v_mfma_f32_32x32x16_bf16 v[18:33], v[66:69], v[62:65], v[2:17]
	ds_read_b128 v[62:65], v96 offset:64
	v_max_i32_e32 v67, v75, v77
	v_min_i32_e32 v68, v75, v77
	v_max_i32_e32 v75, v80, v125
	v_max_i32_e32 v131, v74, v76
	v_min_i32_e32 v66, v74, v76
	v_max_i32_e32 v69, v78, v82
	s_waitcnt lgkmcnt(1)
	v_mfma_f32_32x32x16_bf16 v[18:33], v[70:73], v[54:57], v[18:33]
	ds_read_b128 v[54:57], v96 offset:96
	v_min_i32_e32 v70, v80, v125
	v_max_i32_e32 v71, v79, v124
	v_min_i32_e32 v72, v79, v124
	v_min_i32_e32 v74, v78, v82
	v_max_i32_e32 v73, v81, v126
	v_min_i32_e32 v76, v81, v126
	s_waitcnt lgkmcnt(1)
	v_mfma_f32_32x32x16_bf16 v[18:33], v[62:65], v[58:61], v[18:33]
	v_min_i32_e32 v77, v127, v129
	v_min_i32_e32 v58, v128, v130
	v_min_i32_e32 v59, v131, v67
	v_min_i32_e32 v60, v66, v68
	v_min_i32_e32 v61, v69, v75
	v_min_i32_e32 v62, v74, v70
	v_min_i32_e32 v63, v71, v73
	s_waitcnt lgkmcnt(0)
	v_mfma_f32_32x32x16_bf16 v[18:33], v[54:57], v[50:53], v[18:33]
	v_min_i32_e32 v64, v72, v76
	s_nop 10
	v_and_or_b32 v25, v25, s43, 20
	v_and_or_b32 v29, v29, s43, 12
	v_and_or_b32 v19, v19, s43, 30
	v_and_or_b32 v30, v30, s43, 7
	v_and_or_b32 v23, v23, s43, 22
	v_and_or_b32 v24, v24, s43, 21
	v_and_or_b32 v18, v18, s43, 31
	v_and_or_b32 v31, v31, s43, 6
	v_and_or_b32 v22, v22, s43, 23
	v_and_or_b32 v26, v26, s43, 15
	v_and_or_b32 v21, v21, s43, 28
	v_and_or_b32 v32, v32, s43, 5
	v_and_or_b32 v27, v27, s43, 14
	v_and_or_b32 v28, v28, s43, 13
	v_and_or_b32 v20, v20, s43, 29
	v_and_or_b32 v33, v33, s43, 4
	v_min_i32_e32 v50, v25, v29
	v_min_i32_e32 v51, v19, v30
	v_min_i32_e32 v53, v23, v24
	v_min_i32_e32 v54, v18, v31
	v_min_i32_e32 v57, v22, v26
	v_min_i32_e32 v65, v21, v32
	v_min_i32_e32 v79, v27, v28
	v_min_i32_e32 v80, v20, v33
	v_max_i32_e32 v18, v18, v31
	v_max_i32_e32 v23, v23, v24
	v_max_i32_e32 v19, v19, v30
	v_max_i32_e32 v25, v25, v29
	v_max_i32_e32 v20, v20, v33
	v_max_i32_e32 v27, v27, v28
	v_max_i32_e32 v21, v21, v32
	v_max_i32_e32 v22, v22, v26
	v_max_i32_e32 v24, v18, v23
	v_max_i32_e32 v29, v19, v25
	v_max_i32_e32 v28, v20, v27
	v_max_i32_e32 v26, v21, v22
	v_min_i32_e32 v30, v24, v29
	v_min_i32_e32 v31, v28, v26
	v_min_i32_e32 v55, v53, v54
	v_min_i32_e32 v32, v30, v31
	v_max_i32_e32 v30, v30, v31
	v_min_i32_e32 v21, v21, v22
	v_min_i32_e32 v18, v18, v23
	v_max_i32_e32 v23, v79, v80
	v_max_i32_e32 v31, v50, v51
	v_max_i32_e32 v53, v53, v54
	v_max_i32_e32 v54, v57, v65
	v_min_i32_e32 v19, v19, v25
	v_min_i32_e32 v20, v20, v27
	v_min_i32_e32 v52, v50, v51
	v_min_i32_e32 v78, v57, v65
	v_min_i32_e32 v81, v79, v80
	v_max_i32_e32 v22, v21, v18
	v_max_i32_e32 v57, v53, v54
	v_max_i32_e32 v25, v19, v20
	v_min_i32_e32 v18, v21, v18
	v_min_i32_e32 v21, v23, v31
	v_min_i32_e32 v56, v52, v55
	v_min_i32_e32 v82, v78, v81
	v_max_i32_e32 v33, v52, v55
	v_max_i32_e32 v52, v78, v81
	v_max_i32_e32 v24, v24, v29
	v_max_i32_e32 v26, v28, v26
	v_max_i32_e32 v50, v23, v31
	v_max_i32_e32 v27, v57, v25
	v_max_i32_e32 v23, v18, v21
	v_min_i32_e32 v25, v57, v25
	v_min_i32_e32 v53, v53, v54
	v_min_i32_e32 v19, v19, v20
	v_max_i32_e32 v55, v33, v52
	v_min_i32_e32 v28, v24, v26
	v_max_i32_e32 v51, v22, v50
	v_max_i32_e32 v31, v23, v25
	v_max_i32_e32 v20, v53, v19
	v_min_i32_e32 v23, v23, v25
	v_min_i32_e32 v19, v53, v19
	v_min_i32_e32 v18, v18, v21
	v_max_i32_e32 v25, v56, v82
	v_min_i32_e32 v33, v33, v52
	v_min_i32_e32 v29, v30, v28
	v_min_i32_e32 v65, v51, v27
	v_min_i32_e32 v22, v22, v50
	v_max_i32_e32 v21, v19, v18
	v_max_i32_e32 v52, v25, v33
	v_max_i32_e32 v78, v32, v55
	v_min_i32_e32 v79, v29, v65
	v_max_i32_e32 v50, v20, v22
	v_min_i32_e32 v20, v20, v22
	v_max_i32_e32 v53, v21, v52
	v_min_i32_e32 v32, v32, v55
	v_max_i32_e32 v80, v78, v79
	v_max_i32_e32 v54, v31, v50
	v_min_i32_e32 v78, v78, v79
	v_min_i32_e32 v31, v31, v50
	v_max_i32_e32 v22, v23, v20
	v_max_i32_e32 v55, v53, v32
	v_min_i32_e32 v18, v19, v18
	v_min_i32_e32 v19, v25, v33
	v_min_i32_e32 v20, v23, v20
	v_min_i32_e32 v23, v53, v32
	v_max_i32_e32 v28, v30, v28
	v_max_i32_e32 v27, v51, v27
	v_min_i32_e32 v124, v56, v82
	v_min_i32_e32 v57, v80, v54
	v_max_i32_e32 v50, v78, v31
	v_max_i32_e32 v56, v22, v55
	v_min_i32_e32 v31, v78, v31
	v_max_i32_e32 v25, v18, v19
	v_min_i32_e32 v21, v21, v52
	v_min_i32_e32 v32, v20, v23
	v_max_i32_e32 v29, v29, v65
	v_min_i32_e32 v30, v28, v27
	v_min_i32_e32 v22, v22, v55
	v_max_i32_e32 v20, v20, v23
	v_min_i32_e32 v79, v57, v50
	v_max_i32_e32 v78, v56, v31
	v_max_i32_e32 v33, v25, v21
	v_max_i32_e32 v53, v80, v54
	v_min_i32_e32 v51, v29, v30
	v_min_i32_e32 v31, v56, v31
	v_max_i32_e32 v23, v22, v20
	v_min_i32_e32 v81, v79, v78
	v_max_i32_e32 v52, v33, v32
	v_max_i32_e32 v54, v53, v51
	v_min_i32_e32 v21, v25, v21
	v_max_i32_e32 v25, v57, v50
	v_min_i32_e32 v55, v31, v23
	v_max_i32_e32 v27, v28, v27
	v_min_i32_e32 v18, v18, v19
	v_min_i32_e32 v20, v22, v20
	v_min_i32_e32 v32, v33, v32
	v_min_i32_e32 v33, v53, v51
	v_max3_i32 v124, v127, v129, v124
	v_max3_i32 v69, v69, v75, v81
	v_max3_i32 v52, v131, v67, v52
	v_max3_i32 v54, v71, v73, v54
	v_max3_i32 v21, v128, v130, v21
	v_max3_i32 v25, v74, v70, v25
	v_max3_i32 v55, v66, v68, v55
	v_max3_i32 v27, v72, v76, v27
	v_max_i32_e32 v18, v77, v18
	v_max3_i32 v19, v61, v79, v78
	v_max_i32_e32 v20, v59, v20
	v_max3_i32 v22, v63, v29, v30
	v_max_i32_e32 v32, v58, v32
	v_max_i32_e32 v33, v62, v33
	v_max3_i32 v23, v60, v31, v23
	v_max3_i32 v24, v64, v24, v26
	v_min_i32_e32 v65, v52, v54
	v_min_i32_e32 v50, v21, v25
	v_min_i32_e32 v61, v18, v19
	v_min_i32_e32 v29, v20, v22
	v_min_i32_e32 v26, v23, v24
	v_max_i32_e32 v59, v124, v69
	v_max_i32_e32 v52, v52, v54
	v_max_i32_e32 v21, v21, v25
	v_max_i32_e32 v25, v55, v27
; #define LAS __attribute__((address_space(3)))
; #define MFMA32(a, b, c) __builtin_amdgcn_mfma_f32_32x32x16_bf16((a), (b), (c), 0, 0, 0)
; __device__ __forceinline__ void route_task(int task, int tl0, const bf16* QP  , const LAS bf16* KHL, LAS unsigned short* EL, LAS float* GL, int lane) {
;     ...
; #pragma unroll
;         for (int kt = 0; kt < 4; ++kt) {
;             f32x16 X;
; #pragma unroll
;             for (int i = 0; i < 16; ++i) X[i] = 8.f;
;             const LAS bf16* khp = KHL + (half * 128 + 32 * kt + r) * 72 + 8 * hi;
; #pragma unroll
;             for (int ks = 0; ks < 4; ++ks) {
;                 const bf16x8 kh = lds8(khp + 16 * ks);
;                 X = MFMA32(kh, qa[half][ks], X);
;             }
;     ...
;             } else merge16_desc(cur, grp);
;         }
;         { const unsigned h4 = 4u * (unsigned)hi;
; #pragma unroll
;           for (int i = 0; i < 16; ++i) cur[i] -= (int)h4; }
;         int oth[16];
; #pragma unroll
;         for (int i = 0; i < 16; ++i) oth[i] = __shfl_xor(cur[i], 32);
;         merge16_desc(cur, oth);
; #pragma unroll
;         for (int i = 0; i < 16; ++i) top[half][i] = cur[i];
	v_max_i32_e32 v18, v18, v19
	v_max_i32_e32 v19, v20, v22
	v_max_i32_e32 v22, v32, v33
	v_max_i32_e32 v23, v23, v24
	v_min_i32_e32 v28, v55, v27
	v_max_i32_e32 v54, v59, v52
	v_max_i32_e32 v27, v21, v25
	v_max_i32_e32 v20, v18, v19
	v_max_i32_e32 v24, v22, v23
	v_min_i32_e32 v51, v32, v33
	v_max_i32_e32 v55, v54, v27
	v_max_i32_e32 v32, v20, v24
	v_min_i32_e32 v27, v54, v27
	v_min_i32_e32 v20, v20, v24
	v_max_i32_e32 v24, v27, v20
	v_min_i32_e32 v20, v27, v20
	v_min_i32_e32 v27, v59, v52
	v_min_i32_e32 v21, v21, v25
	v_min_i32_e32 v18, v18, v19
	v_min_i32_e32 v19, v22, v23
	v_min_i32_e32 v75, v124, v69
	v_max_i32_e32 v25, v27, v21
	v_max_i32_e32 v22, v18, v19
	v_min_i32_e32 v21, v27, v21
	v_min_i32_e32 v18, v18, v19
	v_min_i32_e32 v56, v50, v28
	v_min_i32_e32 v31, v51, v26
	v_max_i32_e32 v23, v25, v22
	v_min_i32_e32 v22, v25, v22
	v_max_i32_e32 v19, v21, v18
	v_min_i32_e32 v18, v21, v18
	v_max_i32_e32 v21, v75, v65
	v_max_i32_e32 v25, v50, v28
	v_max_i32_e32 v28, v61, v29
	v_max_i32_e32 v26, v51, v26
	v_min_i32_e32 v67, v75, v65
	v_min_i32_e32 v30, v61, v29
	v_max_i32_e32 v27, v21, v25
	v_min_i32_e32 v21, v21, v25
	v_min_i32_e32 v25, v28, v26
	v_min_i32_e32 v57, v67, v56
	v_min_i32_e32 v53, v30, v31
	v_max_i32_e32 v29, v28, v26
	v_max_i32_e32 v26, v21, v25
	v_min_i32_e32 v21, v21, v25
	v_max_i32_e32 v25, v67, v56
	v_max_i32_e32 v28, v30, v31
	v_min_i32_e32 v58, v57, v53
	v_max_i32_e32 v33, v55, v32
	v_min_i32_e32 v32, v55, v32
	v_max_i32_e32 v50, v27, v29
	v_min_i32_e32 v27, v27, v29
	v_max_i32_e32 v29, v25, v28
	v_min_i32_e32 v25, v25, v28
	v_max_i32_e32 v28, v57, v53
	v_sub_u32_e32 v30, v33, v87
	v_sub_u32_e32 v31, v32, v87
	v_sub_u32_e32 v24, v24, v87
	v_sub_u32_e32 v20, v20, v87
	v_sub_u32_e32 v23, v23, v87
	v_sub_u32_e32 v22, v22, v87
	v_sub_u32_e32 v19, v19, v87
	v_sub_u32_e32 v18, v18, v87
	v_sub_u32_e32 v32, v50, v87
	v_sub_u32_e32 v27, v27, v87
	v_sub_u32_e32 v26, v26, v87
	v_sub_u32_e32 v21, v21, v87
	v_sub_u32_e32 v29, v29, v87
	v_sub_u32_e32 v25, v25, v87
	v_sub_u32_e32 v28, v28, v87
	v_sub_u32_e32 v33, v58, v87
	ds_bpermute_b32 v50, v123, v30
	ds_bpermute_b32 v51, v123, v31
	ds_bpermute_b32 v52, v123, v24
	ds_bpermute_b32 v53, v123, v20
	ds_bpermute_b32 v54, v123, v23
	ds_bpermute_b32 v55, v123, v22
	ds_bpermute_b32 v56, v123, v19
	ds_bpermute_b32 v57, v123, v18
	ds_bpermute_b32 v58, v123, v32
	ds_bpermute_b32 v59, v123, v27
	ds_bpermute_b32 v60, v123, v26
	ds_bpermute_b32 v61, v123, v33
	ds_bpermute_b32 v62, v123, v28
	ds_bpermute_b32 v63, v123, v25
	ds_bpermute_b32 v64, v123, v29
	ds_bpermute_b32 v65, v123, v21
	s_waitcnt lgkmcnt(4)
	v_max_i32_e32 v30, v30, v61
	s_waitcnt lgkmcnt(3)
	v_max_i32_e32 v31, v31, v62
	s_waitcnt lgkmcnt(2)
	v_max_i32_e32 v24, v24, v63
	s_waitcnt lgkmcnt(1)
	v_max_i32_e32 v20, v20, v64
	s_waitcnt lgkmcnt(0)
	v_max_i32_e32 v23, v23, v65
	v_max_i32_e32 v22, v22, v60
	v_max_i32_e32 v19, v19, v59
	v_max_i32_e32 v18, v18, v58
	v_max_i32_e32 v32, v32, v57
	v_max_i32_e32 v27, v27, v56
	v_max_i32_e32 v26, v26, v55
	v_max_i32_e32 v21, v21, v54
	v_max_i32_e32 v29, v29, v53
	v_max_i32_e32 v25, v25, v52
	v_max_i32_e32 v28, v28, v51
	v_max_i32_e32 v33, v33, v50
	v_max_i32_e32 v50, v30, v32
	v_min_i32_e32 v30, v30, v32
	v_max_i32_e32 v32, v31, v27
	v_min_i32_e32 v27, v31, v27
	v_max_i32_e32 v31, v24, v26
	v_min_i32_e32 v24, v24, v26
	v_max_i32_e32 v26, v20, v21
	v_min_i32_e32 v20, v20, v21
	v_max_i32_e32 v21, v23, v29
	v_min_i32_e32 v23, v23, v29
	v_max_i32_e32 v29, v22, v25
	v_min_i32_e32 v22, v22, v25
	v_max_i32_e32 v25, v19, v28
	v_min_i32_e32 v19, v19, v28
	v_max_i32_e32 v28, v18, v33
	v_min_i32_e32 v18, v18, v33
	v_max_i32_e32 v33, v50, v21
	v_min_i32_e32 v21, v50, v21
	v_max_i32_e32 v50, v32, v29
	v_min_i32_e32 v29, v32, v29
	v_max_i32_e32 v32, v31, v25
	v_min_i32_e32 v25, v31, v25
	v_max_i32_e32 v31, v26, v28
	v_max_i32_e32 v64, v50, v31
	v_min_i32_e32 v67, v50, v31
	ds_read_b128 v[50:53], v94 offset:18432
	ds_read_b128 v[54:57], v94 offset:18464
	v_min_i32_e32 v26, v26, v28
	v_max_i32_e32 v28, v30, v23
	v_min_i32_e32 v58, v30, v23
	v_max_i32_e32 v23, v27, v22
	v_min_i32_e32 v59, v27, v22
	v_max_i32_e32 v22, v24, v19
	v_min_i32_e32 v60, v24, v19
	v_max_i32_e32 v19, v20, v18
	v_min_i32_e32 v61, v20, v18
	v_max_i32_e32 v62, v33, v32
	v_min_i32_e32 v66, v33, v32
	v_max_i32_e32 v68, v21, v25
	v_min_i32_e32 v69, v21, v25
	v_max_i32_e32 v70, v29, v26
	v_min_i32_e32 v71, v29, v26
	v_max_i32_e32 v72, v28, v22
	v_min_i32_e32 v73, v28, v22
	v_max_i32_e32 v74, v23, v19
	v_min_i32_e32 v75, v23, v19
	s_waitcnt vmcnt(3) lgkmcnt(1)
	v_mfma_f32_32x32x16_bf16 v[18:33], v[50:53], v[46:49], v[2:17]
	ds_read_b128 v[50:53], v94 offset:18496
	v_max_i32_e32 v76, v58, v60
	v_min_i32_e32 v77, v58, v60
	v_max_i32_e32 v78, v59, v61
	v_min_i32_e32 v79, v59, v61
	v_max_i32_e32 v63, v62, v64
	v_min_i32_e32 v65, v62, v64
	s_waitcnt vmcnt(2) lgkmcnt(1)
	v_mfma_f32_32x32x16_bf16 v[18:33], v[54:57], v[42:45], v[18:33]
	v_max_i32_e32 v64, v66, v67
	v_min_i32_e32 v62, v66, v67
	v_max_i32_e32 v61, v68, v70
	v_min_i32_e32 v60, v68, v70
	v_max_i32_e32 v59, v69, v71
	v_min_i32_e32 v57, v69, v71
	ds_read_b128 v[66:69], v94 offset:18528
	s_waitcnt vmcnt(1) lgkmcnt(1)
	v_mfma_f32_32x32x16_bf16 v[18:33], v[50:53], v[38:41], v[18:33]
	v_max_i32_e32 v55, v72, v74
	v_min_i32_e32 v58, v72, v74
	v_max_i32_e32 v56, v73, v75
	v_min_i32_e32 v54, v73, v75
	v_max_i32_e32 v53, v76, v78
	v_min_i32_e32 v52, v76, v78
	v_max_i32_e32 v51, v77, v79
	s_waitcnt vmcnt(0) lgkmcnt(0)
; #define LAS __attribute__((address_space(3)))
; #define MFMA32(a, b, c) __builtin_amdgcn_mfma_f32_32x32x16_bf16((a), (b), (c), 0, 0, 0)
; __device__ __forceinline__ void route_task(int task, int tl0, const bf16* QP  , const LAS bf16* KHL, LAS unsigned short* EL, LAS float* GL, int lane) {
;     ...
; #pragma unroll
;         for (int kt = 0; kt < 4; ++kt) {
;             f32x16 X;
; #pragma unroll
;             for (int i = 0; i < 16; ++i) X[i] = 8.f;
;             const LAS bf16* khp = KHL + (half * 128 + 32 * kt + r) * 72 + 8 * hi;
; #pragma unroll
;             for (int ks = 0; ks < 4; ++ks) {
;                 const bf16x8 kh = lds8(khp + 16 * ks);
;                 X = MFMA32(kh, qa[half][ks], X);
;             }
;             int grp[16];
; #pragma unroll
;             for (int i = 0; i < 16; ++i) grp[i] = (int)((__float_as_uint(X[i]) | 127u) - (unsigned)(32 * kt + (i & 3) + 8 * (i >> 2)));
;             sort16_desc(grp);
;             if (kt == 0) {
; #pragma unroll
;                 for (int i = 0; i < 16; ++i) cur[i] = grp[i];
;             } else merge16_desc(cur, grp);
;         }
	v_mfma_f32_32x32x16_bf16 v[18:33], v[66:69], v[34:37], v[18:33]
	v_min_i32_e32 v50, v77, v79
	s_nop 10
	v_bitop3_b32 v21, v21, s42, 3 bitop3:0x56
	v_bitop3_b32 v32, v32, s42, 26 bitop3:0x56
	v_bitop3_b32 v22, v22, s42, 8 bitop3:0x56
	v_bitop3_b32 v26, v26, s42, 16 bitop3:0x56
	v_bitop3_b32 v31, v31, s42, 25 bitop3:0x56
	v_bitop3_b32 v23, v23, s42, 9 bitop3:0x56
	v_bitop3_b32 v24, v24, s42, 10 bitop3:0x56
	v_bitop3_b32 v27, v27, s42, 17 bitop3:0x56
	v_bitop3_b32 v28, v28, s42, 18 bitop3:0x56
	v_bitop3_b32 v20, v20, s42, 2 bitop3:0x56
	v_bitop3_b32 v33, v33, s42, 27 bitop3:0x56
	v_bitop3_b32 v25, v25, s42, 11 bitop3:0x56
	v_bitop3_b32 v29, v29, s42, 19 bitop3:0x56
	v_bitop3_b32 v19, v19, s42, 1 bitop3:0x56
	v_bitop3_b32 v30, v30, s42, 24 bitop3:0x56
	v_or_b32_e32 v18, 0x7f, v18
	v_max_i32_e32 v66, v21, v32
	v_max_i32_e32 v67, v22, v26
	v_max_i32_e32 v69, v18, v31
	v_max_i32_e32 v70, v23, v24
	v_min_i32_e32 v73, v27, v28
	v_min_i32_e32 v74, v20, v33
	v_min_i32_e32 v76, v25, v29
	v_min_i32_e32 v77, v19, v30
	v_min_i32_e32 v23, v23, v24
	v_min_i32_e32 v18, v18, v31
	v_min_i32_e32 v22, v22, v26
	v_min_i32_e32 v21, v21, v32
	v_max_i32_e32 v19, v19, v30
	v_max_i32_e32 v25, v25, v29
	v_max_i32_e32 v20, v20, v33
	v_max_i32_e32 v27, v27, v28
	v_max_i32_e32 v24, v23, v18
	v_max_i32_e32 v26, v22, v21
	v_min_i32_e32 v29, v19, v25
	v_min_i32_e32 v28, v20, v27
	v_max_i32_e32 v31, v24, v26
	v_min_i32_e32 v24, v24, v26
	v_min_i32_e32 v26, v29, v28
	v_min_i32_e32 v68, v66, v67
	v_min_i32_e32 v71, v69, v70
	v_max_i32_e32 v75, v73, v74
	v_max_i32_e32 v78, v76, v77
	v_max_i32_e32 v30, v29, v28
	v_max_i32_e32 v28, v24, v26
	v_min_i32_e32 v81, v24, v26
	v_min_i32_e32 v24, v76, v77
	v_min_i32_e32 v18, v23, v18
	v_min_i32_e32 v21, v22, v21
	v_min_i32_e32 v22, v73, v74
	v_min_i32_e32 v72, v68, v71
	v_min_i32_e32 v79, v75, v78
	v_min_i32_e32 v76, v24, v18
	v_min_i32_e32 v74, v21, v22
	v_max_i32_e32 v18, v24, v18
	v_max_i32_e32 v21, v21, v22
	v_max_i32_e32 v23, v69, v70
	v_max_i32_e32 v19, v19, v25
	v_max_i32_e32 v20, v20, v27
	v_max_i32_e32 v25, v66, v67
	v_max_i32_e32 v80, v72, v79
	v_max_i32_e32 v29, v68, v71
	v_max_i32_e32 v68, v75, v78
	v_min_i32_e32 v79, v72, v79
	v_max_i32_e32 v77, v76, v74
	v_min_i32_e32 v124, v18, v21
	v_min_i32_e32 v24, v23, v19
	v_min_i32_e32 v26, v20, v25
	v_min_i32_e32 v32, v31, v30
	v_min_i32_e32 v71, v29, v68
	v_max_i32_e32 v82, v81, v79
	v_max_i32_e32 v125, v77, v124
	v_min_i32_e32 v27, v24, v26
	v_max_i32_e32 v18, v18, v21
	v_min_i32_e32 v33, v80, v32
	v_min_i32_e32 v75, v28, v71
	v_max_i32_e32 v22, v82, v125
	v_min_i32_e32 v21, v27, v18
	v_max_i32_e32 v78, v33, v75
	v_max_i32_e32 v66, v22, v21
	v_max_i32_e32 v70, v78, v66
	v_max_i32_e32 v131, v29, v68
	v_min_i32_e32 v78, v78, v66
	ds_read_b128 v[66:69], v97
	v_max_i32_e32 v127, v23, v19
	v_max_i32_e32 v128, v20, v25
	v_max_i32_e32 v126, v24, v26
	v_min_i32_e32 v129, v127, v128
	v_max_i32_e32 v132, v31, v30
	v_min_i32_e32 v130, v126, v129
	v_min_i32_e32 v133, v131, v132
	v_max_i32_e32 v18, v27, v18
	v_min_i32_e32 v19, v130, v133
	v_max_i32_e32 v23, v80, v32
	v_max_i32_e32 v24, v28, v71
	v_min_i32_e32 v20, v18, v19
	v_min_i32_e32 v25, v23, v24
	v_min_i32_e32 v26, v20, v25
	v_min_i32_e32 v80, v70, v26
	v_max_i32_e32 v143, v70, v26
	ds_read_b128 v[70:73], v97 offset:32
	v_min_i32_e32 v75, v33, v75
	v_min_i32_e32 v134, v22, v21
	v_max_i32_e32 v138, v18, v19
	v_max_i32_e32 v139, v23, v24
	v_max_i32_e32 v141, v20, v25
	s_waitcnt lgkmcnt(1)
	v_mfma_f32_32x32x16_bf16 v[18:33], v[66:69], v[46:49], v[2:17]
	ds_read_b128 v[66:69], v97 offset:64
	v_max_i32_e32 v135, v75, v134
	v_max_i32_e32 v136, v78, v135
	v_min_i32_e32 v79, v81, v79
	v_min_i32_e32 v77, v77, v124
	v_min_i32_e32 v78, v78, v135
	v_max_i32_e32 v130, v130, v133
	s_waitcnt lgkmcnt(1)
	v_mfma_f32_32x32x16_bf16 v[18:33], v[70:73], v[42:45], v[18:33]
	ds_read_b128 v[70:73], v97 offset:96
	v_max_i32_e32 v126, v126, v129
	v_min_i32_e32 v74, v76, v74
	v_min_i32_e32 v140, v138, v139
	v_max_i32_e32 v81, v79, v77
	v_min_i32_e32 v82, v82, v125
	v_min_i32_e32 v75, v75, v134
	s_waitcnt lgkmcnt(1)
	v_mfma_f32_32x32x16_bf16 v[18:33], v[66:69], v[38:41], v[18:33]
	v_max_i32_e32 v66, v131, v132
	v_max_i32_e32 v134, v138, v139
	v_min_i32_e32 v77, v79, v77
	v_max_i32_e32 v124, v81, v82
	v_min_i32_e32 v81, v81, v82
	v_min_i32_e32 v67, v126, v66
	v_min_i32_e32 v142, v140, v141
	s_waitcnt lgkmcnt(0)
; #define LAS __attribute__((address_space(3)))
; #define MFMA32(a, b, c) __builtin_amdgcn_mfma_f32_32x32x16_bf16((a), (b), (c), 0, 0, 0)
; __device__ __forceinline__ void route_task(int task, int tl0, const bf16* QP  , const LAS bf16* KHL, LAS unsigned short* EL, LAS float* GL, int lane) {
;     ...
; #pragma unroll
;         for (int kt = 0; kt < 4; ++kt) {
;             f32x16 X;
; #pragma unroll
;             for (int i = 0; i < 16; ++i) X[i] = 8.f;
;             const LAS bf16* khp = KHL + (half * 128 + 32 * kt + r) * 72 + 8 * hi;
; #pragma unroll
;             for (int ks = 0; ks < 4; ++ks) {
;                 const bf16x8 kh = lds8(khp + 16 * ks);
;                 X = MFMA32(kh, qa[half][ks], X);
;             }
;             int grp[16];
; #pragma unroll
;             for (int i = 0; i < 16; ++i) grp[i] = (int)((__float_as_uint(X[i]) | 127u) - (unsigned)(32 * kt + (i & 3) + 8 * (i >> 2)));
;             sort16_desc(grp);
;             if (kt == 0) {
; #pragma unroll
;                 for (int i = 0; i < 16; ++i) cur[i] = grp[i];
;             } else merge16_desc(cur, grp);
;         }
	v_mfma_f32_32x32x16_bf16 v[18:33], v[70:73], v[34:37], v[18:33]
	v_min_i32_e32 v68, v130, v67
	v_min_i32_e32 v137, v80, v136
	v_min_i32_e32 v144, v142, v143
	v_min_i32_e32 v125, v124, v75
	v_min_i32_e32 v69, v134, v68
	s_nop 6
	v_bitop3_b32 v21, v21, s42, 35 bitop3:0x56
	v_bitop3_b32 v32, v32, s42, 58 bitop3:0x56
	v_bitop3_b32 v22, v22, s42, 40 bitop3:0x56
	v_bitop3_b32 v26, v26, s42, 48 bitop3:0x56
	v_bitop3_b32 v18, v18, s42, 32 bitop3:0x56
	v_bitop3_b32 v31, v31, s42, 57 bitop3:0x56
	v_bitop3_b32 v23, v23, s42, 41 bitop3:0x56
	v_bitop3_b32 v24, v24, s42, 42 bitop3:0x56
	v_bitop3_b32 v27, v27, s42, 49 bitop3:0x56
	v_bitop3_b32 v28, v28, s42, 50 bitop3:0x56
	v_bitop3_b32 v20, v20, s42, 34 bitop3:0x56
	v_bitop3_b32 v33, v33, s42, 59 bitop3:0x56
	v_bitop3_b32 v25, v25, s42, 43 bitop3:0x56
	v_bitop3_b32 v29, v29, s42, 51 bitop3:0x56
	v_bitop3_b32 v19, v19, s42, 33 bitop3:0x56
	v_bitop3_b32 v30, v30, s42, 56 bitop3:0x56
	v_max_i32_e32 v70, v21, v32
	v_max_i32_e32 v71, v22, v26
	v_max_i32_e32 v73, v18, v31
	v_max_i32_e32 v76, v23, v24
	v_min_i32_e32 v129, v27, v28
	v_min_i32_e32 v131, v20, v33
	v_min_i32_e32 v133, v25, v29
	v_min_i32_e32 v135, v19, v30
	v_min_i32_e32 v23, v23, v24
	v_min_i32_e32 v18, v18, v31
	v_min_i32_e32 v22, v22, v26
	v_min_i32_e32 v21, v21, v32
	v_max_i32_e32 v19, v19, v30
	v_max_i32_e32 v25, v25, v29
	v_max_i32_e32 v20, v20, v33
	v_max_i32_e32 v27, v27, v28
	v_min_i32_e32 v72, v70, v71
	v_min_i32_e32 v79, v73, v76
	v_max_i32_e32 v132, v129, v131
	v_max_i32_e32 v138, v133, v135
	v_max_i32_e32 v24, v23, v18
	v_max_i32_e32 v26, v22, v21
	v_min_i32_e32 v29, v19, v25
	v_min_i32_e32 v28, v20, v27
	v_min_i32_e32 v133, v133, v135
	v_min_i32_e32 v18, v23, v18
	v_min_i32_e32 v21, v22, v21
	v_min_i32_e32 v22, v129, v131
	v_max_i32_e32 v73, v73, v76
	v_max_i32_e32 v19, v19, v25
	v_max_i32_e32 v20, v20, v27
	v_max_i32_e32 v27, v70, v71
	v_min_i32_e32 v82, v72, v79
	v_min_i32_e32 v139, v132, v138
	v_max_i32_e32 v31, v24, v26
	v_max_i32_e32 v30, v29, v28
	v_min_i32_e32 v24, v24, v26
	v_min_i32_e32 v26, v29, v28
	v_max_i32_e32 v29, v72, v79
	v_max_i32_e32 v72, v132, v138
	v_min_i32_e32 v23, v133, v18
	v_min_i32_e32 v129, v21, v22
	v_max_i32_e32 v18, v133, v18
	v_max_i32_e32 v21, v21, v22
	v_min_i32_e32 v25, v73, v19
	v_min_i32_e32 v70, v20, v27
	v_max_i32_e32 v19, v73, v19
	v_max_i32_e32 v20, v20, v27
	v_min_i32_e32 v32, v31, v30
	v_max_i32_e32 v28, v24, v26
	v_min_i32_e32 v79, v29, v72
	v_min_i32_e32 v24, v24, v26
	v_min_i32_e32 v26, v82, v139
	v_max_i32_e32 v131, v23, v129
	v_min_i32_e32 v22, v18, v21
	v_min_i32_e32 v71, v25, v70
	v_max_i32_e32 v25, v25, v70
	v_min_i32_e32 v27, v19, v20
	v_max_i32_e32 v29, v29, v72
	v_max_i32_e32 v30, v31, v30
	v_max_i32_e32 v145, v82, v139
	v_max_i32_e32 v82, v24, v26
	v_max_i32_e32 v133, v131, v22
	v_max_i32_e32 v18, v18, v21
	v_min_i32_e32 v70, v25, v27
	v_min_i32_e32 v31, v29, v30
	v_min_i32_e32 v33, v145, v32
	v_min_i32_e32 v132, v28, v79
	v_max_i32_e32 v135, v82, v133
	v_min_i32_e32 v21, v71, v18
	v_max_i32_e32 v18, v71, v18
	v_min_i32_e32 v71, v70, v31
	v_max_i32_e32 v32, v145, v32
	v_max_i32_e32 v28, v28, v79
	v_max_i32_e32 v138, v33, v132
	v_max_i32_e32 v76, v135, v21
	v_min_i32_e32 v72, v18, v71
	v_min_i32_e32 v73, v32, v28
	v_min_i32_e32 v33, v33, v132
	v_min_i32_e32 v21, v135, v21
	v_max_i32_e32 v18, v18, v71
	v_max_i32_e32 v28, v32, v28
	v_min_i32_e32 v24, v24, v26
	v_min_i32_e32 v22, v131, v22
	v_max_i32_e32 v25, v25, v27
	v_max_i32_e32 v27, v29, v30
	v_max_i32_e32 v139, v138, v76
	v_min_i32_e32 v79, v72, v73
	v_min_i32_e32 v76, v138, v76
	v_max_i32_e32 v132, v33, v21
	v_min_i32_e32 v32, v18, v28
	v_max_i32_e32 v71, v72, v73
	v_max_i32_e32 v26, v24, v22
	v_min_i32_e32 v82, v82, v133
	v_max_i32_e32 v18, v18, v28
	v_max_i32_e32 v28, v70, v31
	v_min_i32_e32 v29, v25, v27
	v_min_i32_e32 v145, v139, v79
	v_max_i32_e32 v135, v76, v132
	v_min_i32_e32 v72, v32, v71
	v_max_i32_e32 v73, v139, v79
	v_max_i32_e32 v131, v26, v82
	v_min_i32_e32 v21, v33, v21
	v_min_i32_e32 v30, v28, v29
	v_min_i32_e32 v138, v145, v135
	v_min_i32_e32 v79, v72, v73
	v_min_i32_e32 v33, v131, v21
	v_min_i32_e32 v76, v76, v132
	v_min_i32_e32 v31, v18, v30
	v_min_i32_e32 v26, v26, v82
	v_min_i32_e32 v22, v24, v22
	v_min_i32_e32 v23, v23, v129
	v_max3_i32 v23, v127, v128, v23
	v_max3_i32 v22, v126, v66, v22
	v_max3_i32 v24, v130, v67, v26
	v_max3_i32 v26, v134, v68, v33
	v_max3_i32 v21, v69, v131, v21
	v_max3_i32 v33, v140, v141, v76
	v_max3_i32 v66, v142, v143, v138
	v_max3_i32 v67, v144, v145, v135
	v_max3_i32 v68, v80, v136, v79
	v_max3_i32 v69, v137, v72, v73
	v_max3_i32 v32, v78, v32, v71
	v_max3_i32 v31, v124, v75, v31
	v_max3_i32 v18, v125, v18, v30
	v_max3_i32 v28, v81, v28, v29
	v_max3_i32 v25, v77, v25, v27
	v_max3_i32 v19, v74, v19, v20
	v_max_i32_e32 v20, v23, v68
	v_min_i32_e32 v23, v23, v68
	v_max_i32_e32 v27, v22, v69
	v_min_i32_e32 v22, v22, v69
	v_max_i32_e32 v29, v24, v32
	v_min_i32_e32 v24, v24, v32
	v_max_i32_e32 v30, v26, v31
	v_min_i32_e32 v26, v26, v31
	v_max_i32_e32 v31, v21, v18
	v_min_i32_e32 v18, v21, v18
	v_max_i32_e32 v21, v33, v28
	v_min_i32_e32 v28, v33, v28
	v_max_i32_e32 v32, v66, v25
	v_min_i32_e32 v25, v66, v25
	v_max_i32_e32 v33, v67, v19
	v_min_i32_e32 v19, v67, v19
	ds_read_b128 v[66:69], v94 offset:27648
	v_max_i32_e32 v70, v20, v31
	v_min_i32_e32 v74, v20, v31
	v_max_i32_e32 v20, v27, v21
	v_min_i32_e32 v75, v27, v21
	v_max_i32_e32 v21, v29, v32
	v_max_i32_e32 v27, v30, v33
	v_max_i32_e32 v127, v70, v21
	v_min_i32_e32 v128, v70, v21
	ds_read_b128 v[70:73], v94 offset:27680
	v_min_i32_e32 v76, v29, v32
	v_min_i32_e32 v77, v30, v33
	v_max_i32_e32 v78, v23, v18
	v_min_i32_e32 v79, v23, v18
	v_max_i32_e32 v80, v22, v28
	v_min_i32_e32 v81, v22, v28
	v_max_i32_e32 v82, v24, v25
	v_min_i32_e32 v124, v24, v25
	v_max_i32_e32 v125, v26, v19
	v_min_i32_e32 v126, v26, v19
	v_max_i32_e32 v129, v20, v27
	v_min_i32_e32 v130, v20, v27
	s_waitcnt lgkmcnt(1)
; #define LAS __attribute__((address_space(3)))
; #define MFMA32(a, b, c) __builtin_amdgcn_mfma_f32_32x32x16_bf16((a), (b), (c), 0, 0, 0)
; __device__ __forceinline__ void route_task(int task, int tl0, const bf16* QP  , const LAS bf16* KHL, LAS unsigned short* EL, LAS float* GL, int lane) {
;     ...
; #pragma unroll
;         for (int kt = 0; kt < 4; ++kt) {
;             f32x16 X;
; #pragma unroll
;             for (int i = 0; i < 16; ++i) X[i] = 8.f;
;             const LAS bf16* khp = KHL + (half * 128 + 32 * kt + r) * 72 + 8 * hi;
; #pragma unroll
;             for (int ks = 0; ks < 4; ++ks) {
;                 const bf16x8 kh = lds8(khp + 16 * ks);
;                 X = MFMA32(kh, qa[half][ks], X);
;             }
;             int grp[16];
; #pragma unroll
;             for (int i = 0; i < 16; ++i) grp[i] = (int)((__float_as_uint(X[i]) | 127u) - (unsigned)(32 * kt + (i & 3) + 8 * (i >> 2)));
;             sort16_desc(grp);
;             if (kt == 0) {
; #pragma unroll
;                 for (int i = 0; i < 16; ++i) cur[i] = grp[i];
;             } else merge16_desc(cur, grp);
;         }
	v_mfma_f32_32x32x16_bf16 v[18:33], v[66:69], v[46:49], v[2:17]
	ds_read_b128 v[66:69], v94 offset:27712
	v_max_i32_e32 v131, v74, v76
	v_min_i32_e32 v74, v74, v76
	v_max_i32_e32 v76, v75, v77
	v_min_i32_e32 v75, v75, v77
	v_max_i32_e32 v77, v78, v82
	v_min_i32_e32 v78, v78, v82
	s_waitcnt lgkmcnt(1)
	v_mfma_f32_32x32x16_bf16 v[18:33], v[70:73], v[42:45], v[18:33]
	ds_read_b128 v[70:73], v94 offset:27744
	v_max_i32_e32 v82, v80, v125
	v_min_i32_e32 v80, v80, v125
	v_max_i32_e32 v125, v79, v124
	v_min_i32_e32 v79, v79, v124
	v_max_i32_e32 v124, v81, v126
	v_min_i32_e32 v81, v81, v126
	s_waitcnt lgkmcnt(1)
	v_mfma_f32_32x32x16_bf16 v[18:33], v[66:69], v[38:41], v[18:33]
	v_min_i32_e32 v126, v127, v129
	v_min_i32_e32 v66, v128, v130
	v_min_i32_e32 v67, v131, v76
	v_min_i32_e32 v69, v77, v82
	v_min_i32_e32 v132, v78, v80
	v_min_i32_e32 v133, v125, v124
	v_min_i32_e32 v68, v74, v75
	s_waitcnt lgkmcnt(0)
	v_mfma_f32_32x32x16_bf16 v[18:33], v[70:73], v[34:37], v[18:33]
	v_min_i32_e32 v134, v79, v81
	s_nop 10
	v_and_or_b32 v21, v21, s43, 60
	v_and_or_b32 v32, v32, s43, 37
	v_and_or_b32 v22, v22, s43, 55
	v_and_or_b32 v26, v26, s43, 47
	v_bitop3_b32 v18, v18, s42, 64 bitop3:0x56
	v_and_or_b32 v31, v31, s43, 38
	v_and_or_b32 v23, v23, s43, 54
	v_and_or_b32 v24, v24, s43, 53
	v_and_or_b32 v27, v27, s43, 46
	v_and_or_b32 v28, v28, s43, 45
	v_and_or_b32 v20, v20, s43, 61
	v_and_or_b32 v33, v33, s43, 36
	v_and_or_b32 v25, v25, s43, 52
	v_and_or_b32 v29, v29, s43, 44
	v_and_or_b32 v19, v19, s43, 62
	v_and_or_b32 v30, v30, s43, 39
	v_max_i32_e32 v70, v21, v32
	v_max_i32_e32 v71, v22, v26
	v_max_i32_e32 v73, v18, v31
	v_max_i32_e32 v135, v23, v24
	v_min_i32_e32 v138, v27, v28
	v_min_i32_e32 v139, v20, v33
	v_min_i32_e32 v141, v25, v29
	v_min_i32_e32 v142, v19, v30
	v_min_i32_e32 v23, v23, v24
	v_min_i32_e32 v18, v18, v31
	v_min_i32_e32 v22, v22, v26
	v_min_i32_e32 v21, v21, v32
	v_max_i32_e32 v19, v19, v30
	v_max_i32_e32 v25, v25, v29
	v_max_i32_e32 v20, v20, v33
	v_max_i32_e32 v27, v27, v28
	v_min_i32_e32 v72, v70, v71
	v_min_i32_e32 v136, v73, v135
	v_max_i32_e32 v140, v138, v139
	v_max_i32_e32 v143, v141, v142
	v_max_i32_e32 v24, v23, v18
	v_max_i32_e32 v26, v22, v21
	v_min_i32_e32 v29, v19, v25
	v_min_i32_e32 v28, v20, v27
	v_min_i32_e32 v141, v141, v142
	v_min_i32_e32 v18, v23, v18
	v_min_i32_e32 v21, v22, v21
	v_min_i32_e32 v22, v138, v139
	v_max_i32_e32 v73, v73, v135
	v_max_i32_e32 v19, v19, v25
	v_max_i32_e32 v20, v20, v27
	v_max_i32_e32 v27, v70, v71
	v_min_i32_e32 v137, v72, v136
	v_min_i32_e32 v144, v140, v143
	v_max_i32_e32 v31, v24, v26
	v_max_i32_e32 v30, v29, v28
	v_min_i32_e32 v24, v24, v26
	v_min_i32_e32 v26, v29, v28
	v_max_i32_e32 v29, v72, v136
	v_max_i32_e32 v72, v140, v143
	v_min_i32_e32 v23, v141, v18
	v_min_i32_e32 v138, v21, v22
	v_max_i32_e32 v18, v141, v18
	v_max_i32_e32 v21, v21, v22
	v_min_i32_e32 v25, v73, v19
	v_min_i32_e32 v70, v20, v27
	v_max_i32_e32 v19, v73, v19
	v_max_i32_e32 v20, v20, v27
	v_min_i32_e32 v32, v31, v30
	v_max_i32_e32 v28, v24, v26
	v_min_i32_e32 v136, v29, v72
	v_min_i32_e32 v24, v24, v26
	v_min_i32_e32 v26, v137, v144
	v_max_i32_e32 v139, v23, v138
	v_min_i32_e32 v22, v18, v21
	v_min_i32_e32 v71, v25, v70
	v_max_i32_e32 v25, v25, v70
	v_min_i32_e32 v27, v19, v20
	v_max_i32_e32 v29, v29, v72
	v_max_i32_e32 v30, v31, v30
	v_max_i32_e32 v145, v137, v144
	v_max_i32_e32 v137, v24, v26
	v_max_i32_e32 v141, v139, v22
	v_max_i32_e32 v18, v18, v21
	v_min_i32_e32 v70, v25, v27
	v_min_i32_e32 v31, v29, v30
	v_min_i32_e32 v33, v145, v32
	v_min_i32_e32 v140, v28, v136
	v_max_i32_e32 v142, v137, v141
	v_min_i32_e32 v21, v71, v18
	v_max_i32_e32 v18, v71, v18
	v_min_i32_e32 v71, v70, v31
	v_max_i32_e32 v32, v145, v32
	v_max_i32_e32 v28, v28, v136
	v_max_i32_e32 v143, v33, v140
	v_max_i32_e32 v135, v142, v21
	v_min_i32_e32 v72, v18, v71
	v_min_i32_e32 v73, v32, v28
	v_min_i32_e32 v33, v33, v140
	v_min_i32_e32 v21, v142, v21
	v_max_i32_e32 v18, v18, v71
	v_max_i32_e32 v28, v32, v28
	v_min_i32_e32 v24, v24, v26
	v_min_i32_e32 v22, v139, v22
	v_max_i32_e32 v25, v25, v27
	v_max_i32_e32 v27, v29, v30
	v_max_i32_e32 v144, v143, v135
	v_min_i32_e32 v136, v72, v73
	v_min_i32_e32 v135, v143, v135
	v_max_i32_e32 v140, v33, v21
	v_min_i32_e32 v32, v18, v28
	v_max_i32_e32 v71, v72, v73
	v_max_i32_e32 v26, v24, v22
	v_min_i32_e32 v137, v137, v141
	v_max_i32_e32 v18, v18, v28
	v_max_i32_e32 v28, v70, v31
	v_min_i32_e32 v29, v25, v27
	v_min_i32_e32 v145, v144, v136
	v_max_i32_e32 v142, v135, v140
	v_min_i32_e32 v72, v32, v71
	v_max_i32_e32 v73, v144, v136
	v_max_i32_e32 v139, v26, v137
	v_min_i32_e32 v21, v33, v21
	v_min_i32_e32 v30, v28, v29
	v_min_i32_e32 v143, v145, v142
	v_min_i32_e32 v136, v72, v73
	v_min_i32_e32 v33, v139, v21
	v_max_i32_e32 v21, v139, v21
	v_min_i32_e32 v135, v135, v140
	v_max_i32_e32 v32, v32, v71
	v_min_i32_e32 v31, v18, v30
	v_max_i32_e32 v18, v18, v30
	v_min_i32_e32 v26, v26, v137
	v_min_i32_e32 v22, v24, v22
	v_max_i32_e32 v24, v25, v27
	v_min_i32_e32 v23, v23, v138
	v_max3_i32 v23, v127, v129, v23
	v_max_i32_e32 v22, v126, v22
	v_max3_i32 v25, v128, v130, v26
	v_max_i32_e32 v26, v66, v33
	v_max3_i32 v21, v131, v76, v21
	v_max_i32_e32 v27, v67, v135
	v_max3_i32 v30, v74, v75, v143
	v_max3_i32 v66, v77, v82, v136
	v_max3_i32 v67, v69, v72, v73
	v_max3_i32 v32, v78, v80, v32
	v_max_i32_e32 v31, v132, v31
	v_max3_i32 v18, v125, v124, v18
	v_max3_i32 v28, v133, v28, v29
	v_max3_i32 v24, v79, v81, v24
	v_max3_i32 v33, v68, v145, v142
	v_max3_i32 v19, v134, v19, v20
	v_max_i32_e32 v20, v23, v66
	v_min_i32_e32 v23, v23, v66
	v_max_i32_e32 v29, v22, v67
	v_max_i32_e32 v66, v25, v32
	v_min_i32_e32 v25, v25, v32
	v_max_i32_e32 v32, v26, v31
	v_min_i32_e32 v26, v26, v31
	v_max_i32_e32 v31, v21, v18
	v_min_i32_e32 v18, v21, v18
	v_max_i32_e32 v21, v27, v28
	v_min_i32_e32 v27, v27, v28
	v_max_i32_e32 v28, v30, v24
	v_min_i32_e32 v22, v22, v67
	v_min_i32_e32 v24, v30, v24
	v_max_i32_e32 v30, v33, v19
	v_min_i32_e32 v19, v33, v19
	v_max_i32_e32 v33, v20, v31
	v_min_i32_e32 v74, v20, v31
	v_max_i32_e32 v20, v29, v21
	v_min_i32_e32 v75, v29, v21
	v_max_i32_e32 v21, v66, v28
	v_min_i32_e32 v76, v66, v28
	ds_read_b128 v[66:69], v98
	ds_read_b128 v[70:73], v98 offset:32
	v_max_i32_e32 v28, v32, v30
	v_min_i32_e32 v77, v32, v30
	v_max_i32_e32 v78, v23, v18
	v_min_i32_e32 v79, v23, v18
	v_max_i32_e32 v80, v22, v27
	v_min_i32_e32 v81, v22, v27
	v_max_i32_e32 v82, v25, v24
	v_min_i32_e32 v124, v25, v24
	v_max_i32_e32 v125, v26, v19
	v_min_i32_e32 v126, v26, v19
	v_max_i32_e32 v127, v33, v21
	v_min_i32_e32 v128, v33, v21
	v_max_i32_e32 v129, v20, v28
	v_min_i32_e32 v130, v20, v28
	s_waitcnt lgkmcnt(1)
; #define LAS __attribute__((address_space(3)))
; #define MFMA32(a, b, c) __builtin_amdgcn_mfma_f32_32x32x16_bf16((a), (b), (c), 0, 0, 0)
; __device__ __forceinline__ void route_task(int task, int tl0, const bf16* QP  , const LAS bf16* KHL, LAS unsigned short* EL, LAS float* GL, int lane) {
;     ...
; #pragma unroll
;         for (int kt = 0; kt < 4; ++kt) {
;             f32x16 X;
; #pragma unroll
;             for (int i = 0; i < 16; ++i) X[i] = 8.f;
;             const LAS bf16* khp = KHL + (half * 128 + 32 * kt + r) * 72 + 8 * hi;
; #pragma unroll
;             for (int ks = 0; ks < 4; ++ks) {
;                 const bf16x8 kh = lds8(khp + 16 * ks);
;                 X = MFMA32(kh, qa[half][ks], X);
;             }
;             int grp[16];
; #pragma unroll
;             for (int i = 0; i < 16; ++i) grp[i] = (int)((__float_as_uint(X[i]) | 127u) - (unsigned)(32 * kt + (i & 3) + 8 * (i >> 2)));
;             sort16_desc(grp);
;             if (kt == 0) {
; #pragma unroll
;                 for (int i = 0; i < 16; ++i) cur[i] = grp[i];
;             } else merge16_desc(cur, grp);
;         }
	v_mfma_f32_32x32x16_bf16 v[18:33], v[66:69], v[46:49], v[2:17]
	ds_read_b128 v[46:49], v98 offset:64
	v_max_i32_e32 v67, v75, v77
	v_min_i32_e32 v68, v75, v77
	v_max_i32_e32 v75, v80, v125
	v_max_i32_e32 v131, v74, v76
	v_min_i32_e32 v66, v74, v76
	v_max_i32_e32 v69, v78, v82
	s_waitcnt lgkmcnt(1)
	v_mfma_f32_32x32x16_bf16 v[18:33], v[70:73], v[42:45], v[18:33]
	ds_read_b128 v[42:45], v98 offset:96
	v_min_i32_e32 v70, v80, v125
	v_max_i32_e32 v71, v79, v124
	v_min_i32_e32 v72, v79, v124
	v_min_i32_e32 v74, v78, v82
	v_max_i32_e32 v73, v81, v126
	v_min_i32_e32 v76, v81, v126
	s_waitcnt lgkmcnt(1)
	v_mfma_f32_32x32x16_bf16 v[18:33], v[46:49], v[38:41], v[18:33]
	v_min_i32_e32 v77, v127, v129
	v_min_i32_e32 v38, v128, v130
	v_min_i32_e32 v39, v131, v67
	v_min_i32_e32 v40, v66, v68
	v_min_i32_e32 v41, v69, v75
	v_min_i32_e32 v46, v74, v70
	v_min_i32_e32 v47, v71, v73
	s_waitcnt lgkmcnt(0)
	v_mfma_f32_32x32x16_bf16 v[18:33], v[42:45], v[34:37], v[18:33]
	v_min_i32_e32 v48, v72, v76
	s_nop 10
	v_and_or_b32 v25, v25, s43, 20
	v_and_or_b32 v29, v29, s43, 12
	v_and_or_b32 v19, v19, s43, 30
	v_and_or_b32 v30, v30, s43, 7
	v_and_or_b32 v23, v23, s43, 22
	v_and_or_b32 v24, v24, s43, 21
	v_and_or_b32 v18, v18, s43, 31
	v_and_or_b32 v31, v31, s43, 6
	v_and_or_b32 v22, v22, s43, 23
	v_and_or_b32 v26, v26, s43, 15
	v_and_or_b32 v21, v21, s43, 28
	v_and_or_b32 v32, v32, s43, 5
	v_and_or_b32 v27, v27, s43, 14
	v_and_or_b32 v28, v28, s43, 13
	v_and_or_b32 v20, v20, s43, 29
	v_and_or_b32 v33, v33, s43, 4
	v_min_i32_e32 v34, v25, v29
	v_min_i32_e32 v35, v19, v30
	v_min_i32_e32 v37, v23, v24
	v_min_i32_e32 v42, v18, v31
	v_min_i32_e32 v45, v22, v26
	v_min_i32_e32 v49, v21, v32
	v_min_i32_e32 v79, v27, v28
	v_min_i32_e32 v80, v20, v33
	v_max_i32_e32 v18, v18, v31
	v_max_i32_e32 v23, v23, v24
	v_max_i32_e32 v19, v19, v30
	v_max_i32_e32 v25, v25, v29
	v_max_i32_e32 v20, v20, v33
	v_max_i32_e32 v27, v27, v28
	v_max_i32_e32 v21, v21, v32
	v_max_i32_e32 v22, v22, v26
	v_max_i32_e32 v24, v18, v23
	v_max_i32_e32 v29, v19, v25
	v_max_i32_e32 v28, v20, v27
	v_max_i32_e32 v26, v21, v22
	v_min_i32_e32 v30, v24, v29
	v_min_i32_e32 v31, v28, v26
	v_min_i32_e32 v43, v37, v42
	v_min_i32_e32 v32, v30, v31
	v_max_i32_e32 v30, v30, v31
	v_min_i32_e32 v21, v21, v22
	v_min_i32_e32 v18, v18, v23
	v_max_i32_e32 v23, v79, v80
	v_max_i32_e32 v31, v34, v35
	v_max_i32_e32 v37, v37, v42
	v_max_i32_e32 v42, v45, v49
	v_min_i32_e32 v19, v19, v25
	v_min_i32_e32 v20, v20, v27
	v_min_i32_e32 v36, v34, v35
	v_min_i32_e32 v78, v45, v49
	v_min_i32_e32 v81, v79, v80
	v_max_i32_e32 v22, v21, v18
	v_max_i32_e32 v45, v37, v42
	v_max_i32_e32 v25, v19, v20
	v_min_i32_e32 v18, v21, v18
	v_min_i32_e32 v21, v23, v31
	v_min_i32_e32 v44, v36, v43
	v_min_i32_e32 v82, v78, v81
	v_max_i32_e32 v33, v36, v43
	v_max_i32_e32 v36, v78, v81
	v_max_i32_e32 v24, v24, v29
	v_max_i32_e32 v26, v28, v26
	v_max_i32_e32 v34, v23, v31
	v_max_i32_e32 v27, v45, v25
	v_max_i32_e32 v23, v18, v21
	v_min_i32_e32 v25, v45, v25
	v_min_i32_e32 v37, v37, v42
	v_min_i32_e32 v19, v19, v20
	v_max_i32_e32 v43, v33, v36
	v_min_i32_e32 v28, v24, v26
	v_max_i32_e32 v35, v22, v34
	v_max_i32_e32 v31, v23, v25
	v_max_i32_e32 v20, v37, v19
	v_min_i32_e32 v23, v23, v25
	v_min_i32_e32 v19, v37, v19
	v_min_i32_e32 v18, v18, v21
	v_max_i32_e32 v25, v44, v82
	v_min_i32_e32 v33, v33, v36
	v_min_i32_e32 v29, v30, v28
	v_min_i32_e32 v49, v35, v27
	v_min_i32_e32 v22, v22, v34
	v_max_i32_e32 v21, v19, v18
	v_max_i32_e32 v36, v25, v33
	v_max_i32_e32 v78, v32, v43
	v_min_i32_e32 v79, v29, v49
	v_max_i32_e32 v34, v20, v22
	v_min_i32_e32 v20, v20, v22
	v_max_i32_e32 v37, v21, v36
	v_min_i32_e32 v32, v32, v43
	v_max_i32_e32 v80, v78, v79
	v_max_i32_e32 v42, v31, v34
	v_min_i32_e32 v78, v78, v79
	v_min_i32_e32 v31, v31, v34
	v_max_i32_e32 v22, v23, v20
	v_max_i32_e32 v43, v37, v32
	v_min_i32_e32 v18, v19, v18
	v_min_i32_e32 v19, v25, v33
	v_min_i32_e32 v20, v23, v20
	v_min_i32_e32 v23, v37, v32
	v_max_i32_e32 v28, v30, v28
	v_max_i32_e32 v27, v35, v27
	v_min_i32_e32 v124, v44, v82
	v_min_i32_e32 v45, v80, v42
	v_max_i32_e32 v34, v78, v31
	v_max_i32_e32 v44, v22, v43
	v_min_i32_e32 v31, v78, v31
	v_max_i32_e32 v25, v18, v19
	v_min_i32_e32 v21, v21, v36
	v_min_i32_e32 v32, v20, v23
	v_max_i32_e32 v29, v29, v49
	v_min_i32_e32 v30, v28, v27
	v_min_i32_e32 v22, v22, v43
	v_max_i32_e32 v20, v20, v23
	v_min_i32_e32 v79, v45, v34
	v_max_i32_e32 v78, v44, v31
	v_max_i32_e32 v33, v25, v21
	v_max_i32_e32 v37, v80, v42
	v_min_i32_e32 v35, v29, v30
	v_min_i32_e32 v31, v44, v31
	v_max_i32_e32 v23, v22, v20
	v_min_i32_e32 v81, v79, v78
	v_max_i32_e32 v36, v33, v32
	v_max_i32_e32 v42, v37, v35
	v_min_i32_e32 v21, v25, v21
	v_max_i32_e32 v25, v45, v34
	v_min_i32_e32 v43, v31, v23
	v_max_i32_e32 v27, v28, v27
	v_min_i32_e32 v18, v18, v19
	v_min_i32_e32 v20, v22, v20
	v_min_i32_e32 v32, v33, v32
	v_min_i32_e32 v33, v37, v35
	v_max3_i32 v124, v127, v129, v124
	v_max3_i32 v69, v69, v75, v81
	v_max3_i32 v36, v131, v67, v36
	v_max3_i32 v42, v71, v73, v42
	v_max3_i32 v21, v128, v130, v21
	v_max3_i32 v25, v74, v70, v25
	v_max3_i32 v43, v66, v68, v43
	v_max3_i32 v27, v72, v76, v27
	v_max_i32_e32 v18, v77, v18
	v_max3_i32 v19, v41, v79, v78
	v_max_i32_e32 v20, v39, v20
	v_max3_i32 v22, v47, v29, v30
	v_max_i32_e32 v32, v38, v32
	v_max_i32_e32 v33, v46, v33
	v_max3_i32 v23, v40, v31, v23
	v_max3_i32 v24, v48, v24, v26
	v_min_i32_e32 v49, v36, v42
	v_min_i32_e32 v34, v21, v25
	v_min_i32_e32 v41, v18, v19
	v_min_i32_e32 v29, v20, v22
	v_min_i32_e32 v26, v23, v24
	v_max_i32_e32 v39, v124, v69
	v_max_i32_e32 v36, v36, v42
	v_max_i32_e32 v21, v21, v25
	v_max_i32_e32 v25, v43, v27
; __device__ __forceinline__ void route_task(int task, int tl0, const bf16* QP  , const LAS bf16* KHL, LAS unsigned short* EL, LAS float* GL, int lane) {
;     ...
;             } else merge16_desc(cur, grp);
;         }
;         { const unsigned h4 = 4u * (unsigned)hi;
; #pragma unroll
;           for (int i = 0; i < 16; ++i) cur[i] -= (int)h4; }
;         int oth[16];
; #pragma unroll
;         for (int i = 0; i < 16; ++i) oth[i] = __shfl_xor(cur[i], 32);
;         merge16_desc(cur, oth);
; #pragma unroll
;         for (int i = 0; i < 16; ++i) top[half][i] = cur[i];
;     }
;     unsigned P1[4], P2[4];
; #pragma unroll
;     for (int q = 0; q < 4; ++q) { P1[q] = 0u; P2[q] = 0u;
; #pragma unroll
;         for (int s = 0; s < 4; ++s) { P1[q] |= (127u - ((unsigned)top[0][4 * q + s] & 127u)) << (8 * s); P2[q] |= (127u - ((unsigned)top[1][4 * q + s] & 127u)) << (8 * s); } }
	v_max_i32_e32 v18, v18, v19
	v_max_i32_e32 v19, v20, v22
	v_max_i32_e32 v22, v32, v33
	v_max_i32_e32 v23, v23, v24
	v_min_i32_e32 v28, v43, v27
	v_max_i32_e32 v40, v39, v36
	v_max_i32_e32 v27, v21, v25
	v_max_i32_e32 v20, v18, v19
	v_max_i32_e32 v24, v22, v23
	v_min_i32_e32 v35, v32, v33
	v_max_i32_e32 v42, v40, v27
	v_max_i32_e32 v32, v20, v24
	v_min_i32_e32 v27, v40, v27
	v_min_i32_e32 v20, v20, v24
	v_max_i32_e32 v24, v27, v20
	v_min_i32_e32 v20, v27, v20
	v_min_i32_e32 v27, v39, v36
	v_min_i32_e32 v21, v21, v25
	v_min_i32_e32 v18, v18, v19
	v_min_i32_e32 v19, v22, v23
	v_min_i32_e32 v75, v124, v69
	v_max_i32_e32 v25, v27, v21
	v_max_i32_e32 v22, v18, v19
	v_min_i32_e32 v21, v27, v21
	v_min_i32_e32 v18, v18, v19
	v_min_i32_e32 v44, v34, v28
	v_min_i32_e32 v31, v35, v26
	v_max_i32_e32 v23, v25, v22
	v_min_i32_e32 v22, v25, v22
	v_max_i32_e32 v19, v21, v18
	v_min_i32_e32 v18, v21, v18
	v_max_i32_e32 v21, v75, v49
	v_max_i32_e32 v25, v34, v28
	v_max_i32_e32 v28, v41, v29
	v_max_i32_e32 v26, v35, v26
	v_min_i32_e32 v67, v75, v49
	v_min_i32_e32 v30, v41, v29
	v_max_i32_e32 v27, v21, v25
	v_min_i32_e32 v21, v21, v25
	v_min_i32_e32 v25, v28, v26
	v_min_i32_e32 v45, v67, v44
	v_min_i32_e32 v37, v30, v31
	v_max_i32_e32 v29, v28, v26
	v_max_i32_e32 v26, v21, v25
	v_min_i32_e32 v21, v21, v25
	v_max_i32_e32 v25, v67, v44
	v_max_i32_e32 v28, v30, v31
	v_min_i32_e32 v38, v45, v37
	v_max_i32_e32 v33, v42, v32
	v_min_i32_e32 v32, v42, v32
	v_max_i32_e32 v34, v27, v29
	v_min_i32_e32 v27, v27, v29
	v_max_i32_e32 v29, v25, v28
	v_min_i32_e32 v25, v25, v28
	v_max_i32_e32 v28, v45, v37
	v_sub_u32_e32 v30, v33, v87
	v_sub_u32_e32 v31, v32, v87
	v_sub_u32_e32 v24, v24, v87
	v_sub_u32_e32 v20, v20, v87
	v_sub_u32_e32 v23, v23, v87
	v_sub_u32_e32 v22, v22, v87
	v_sub_u32_e32 v19, v19, v87
	v_sub_u32_e32 v18, v18, v87
	v_sub_u32_e32 v32, v34, v87
	v_sub_u32_e32 v27, v27, v87
	v_sub_u32_e32 v26, v26, v87
	v_sub_u32_e32 v21, v21, v87
	v_sub_u32_e32 v29, v29, v87
	v_sub_u32_e32 v25, v25, v87
	v_sub_u32_e32 v28, v28, v87
	v_sub_u32_e32 v33, v38, v87
	ds_bpermute_b32 v34, v123, v30
	ds_bpermute_b32 v35, v123, v31
	ds_bpermute_b32 v36, v123, v24
	ds_bpermute_b32 v37, v123, v20
	ds_bpermute_b32 v38, v123, v23
	ds_bpermute_b32 v39, v123, v22
	ds_bpermute_b32 v40, v123, v19
	ds_bpermute_b32 v41, v123, v18
	ds_bpermute_b32 v42, v123, v32
	ds_bpermute_b32 v43, v123, v27
	ds_bpermute_b32 v44, v123, v26
	ds_bpermute_b32 v45, v123, v33
	ds_bpermute_b32 v46, v123, v28
	ds_bpermute_b32 v47, v123, v25
	ds_bpermute_b32 v48, v123, v29
	ds_bpermute_b32 v49, v123, v21
	s_waitcnt lgkmcnt(4)
	v_max_i32_e32 v30, v30, v45
	s_waitcnt lgkmcnt(3)
	v_max_i32_e32 v31, v31, v46
	s_waitcnt lgkmcnt(2)
	v_max_i32_e32 v24, v24, v47
	s_waitcnt lgkmcnt(1)
	v_max_i32_e32 v20, v20, v48
	s_waitcnt lgkmcnt(0)
	v_max_i32_e32 v23, v23, v49
	v_max_i32_e32 v22, v22, v44
	v_max_i32_e32 v19, v19, v43
	v_max_i32_e32 v18, v18, v42
	v_max_i32_e32 v32, v32, v41
	v_max_i32_e32 v27, v27, v40
	v_max_i32_e32 v26, v26, v39
	v_max_i32_e32 v21, v21, v38
	v_max_i32_e32 v29, v29, v37
	v_max_i32_e32 v25, v25, v36
	v_max_i32_e32 v28, v28, v35
	v_max_i32_e32 v33, v33, v34
	v_max_i32_e32 v34, v30, v32
	v_min_i32_e32 v30, v30, v32
	v_max_i32_e32 v32, v31, v27
	v_min_i32_e32 v27, v31, v27
	v_max_i32_e32 v31, v24, v26
	v_min_i32_e32 v24, v24, v26
	v_max_i32_e32 v26, v20, v21
	v_min_i32_e32 v20, v20, v21
	v_max_i32_e32 v21, v23, v29
	v_min_i32_e32 v23, v23, v29
	v_max_i32_e32 v29, v22, v25
	v_min_i32_e32 v22, v22, v25
	v_max_i32_e32 v25, v19, v28
	v_min_i32_e32 v19, v19, v28
	v_max_i32_e32 v28, v18, v33
	v_min_i32_e32 v18, v18, v33
	v_max_i32_e32 v33, v34, v21
	v_min_i32_e32 v21, v34, v21
	v_max_i32_e32 v34, v32, v29
	v_min_i32_e32 v29, v32, v29
	v_max_i32_e32 v32, v31, v25
	v_min_i32_e32 v25, v31, v25
	v_max_i32_e32 v31, v26, v28
	v_min_i32_e32 v26, v26, v28
	v_max_i32_e32 v28, v30, v23
	v_min_i32_e32 v23, v30, v23
	v_max_i32_e32 v30, v27, v22
	v_min_i32_e32 v22, v27, v22
	v_max_i32_e32 v27, v24, v19
	v_min_i32_e32 v19, v24, v19
	v_max_i32_e32 v24, v20, v18
	v_min_i32_e32 v18, v20, v18
	v_max_i32_e32 v20, v33, v32
	v_min_i32_e32 v32, v33, v32
	v_max_i32_e32 v33, v34, v31
	v_min_i32_e32 v31, v34, v31
	v_max_i32_e32 v34, v21, v25
	v_min_i32_e32 v21, v21, v25
	v_max_i32_e32 v25, v29, v26
	v_min_i32_e32 v29, v29, v26
	v_max_i32_e32 v35, v28, v27
	v_min_i32_e32 v27, v28, v27
	v_max_i32_e32 v28, v30, v24
	v_min_i32_e32 v24, v30, v24
	v_max_i32_e32 v30, v23, v19
	v_min_i32_e32 v19, v23, v19
	v_max_i32_e32 v23, v22, v18
	v_min_i32_e32 v18, v22, v18
	v_max_i32_e32 v26, v20, v33
	v_min_i32_e32 v33, v20, v33
	v_lshlrev_b32_e32 v20, 8, v65
	v_lshlrev_b32_e32 v22, 16, v64
	v_max_i32_e32 v36, v32, v31
	v_max_i32_e32 v40, v19, v18
	v_min_i32_e32 v41, v19, v18
	v_and_b32_e32 v18, 0x7f, v63
	v_and_b32_e32 v20, 0x7f00, v20
	v_and_b32_e32 v22, 0x7f0000, v22
	v_max_i32_e32 v37, v21, v29
	v_min_i32_e32 v29, v21, v29
	v_lshlrev_b32_e32 v21, 8, v33
	v_or3_b32 v18, v20, v18, v22
	v_lshlrev_b32_e32 v20, 16, v36
	v_and_b32_e32 v19, 0x7f, v26
	v_and_b32_e32 v21, 0x7f00, v21
	v_and_b32_e32 v20, 0x7f0000, v20
	v_or3_b32 v20, v21, v19, v20
	v_lshlrev_b32_e32 v19, 24, v62
	v_min_i32_e32 v31, v32, v31
	v_and_b32_e32 v19, 0x7f000000, v19
	v_bitop3_b32 v19, v18, s68, v19 bitop3:0x36
	v_lshlrev_b32_e32 v18, 24, v31
	v_max_i32_e32 v38, v35, v28
	v_min_i32_e32 v28, v35, v28
	v_max_i32_e32 v35, v27, v24
	v_min_i32_e32 v27, v27, v24
	v_and_b32_e32 v18, 0x7f000000, v18
	v_lshlrev_b32_e32 v22, 8, v60
	v_lshlrev_b32_e32 v24, 16, v59
	v_max_i32_e32 v32, v34, v25
	v_min_i32_e32 v34, v34, v25
	v_bitop3_b32 v18, v20, s68, v18 bitop3:0x36
	v_and_b32_e32 v20, 0x7f, v61
; __device__ __forceinline__ void route_task(int task, int tl0, const bf16* QP  , const LAS bf16* KHL, LAS unsigned short* EL, LAS float* GL, int lane) {
;     ...
;     for (int q = 0; q < 4; ++q) { P1[q] = 0u; P2[q] = 0u;
; #pragma unroll
;         for (int s = 0; s < 4; ++s) { P1[q] |= (127u - ((unsigned)top[0][4 * q + s] & 127u)) << (8 * s); P2[q] |= (127u - ((unsigned)top[1][4 * q + s] & 127u)) << (8 * s); } }
;     int bk[16];
;     {
;         int hi2 = hi; asm volatile("" : "+v"(hi2));
;         const bool h1 = hi2 != 0;
;         constexpr int A1[16] = {1, 1, 1, 1, 1, 1, 1, 1, 2, 2, 2, 2, 2, 3, 3, 3}, B1[16] = {0, 1, 2, 3, 4, 5, 6, 7, 0, 1, 2, 3, 4, 0, 1, 2};
; #pragma unroll
;         for (int i = 0; i < 16; ++i) { const float ta = __int_as_float(h1 ? top[0][A1[i]] : top[0][0]), tb = __int_as_float(h1 ? top[1][B1[i]] : top[1][i]); const unsigned code = h1 ? (unsigned)(A1[i] * 16 + B1[i]) : (unsigned)i;
;             bk[i] = (int)((__float_as_uint(ta + tb) | 255u) - code); }
;         sort16_desc(bk);
	v_and_b32_e32 v22, 0x7f00, v22
	v_and_b32_e32 v24, 0x7f0000, v24
	v_max_i32_e32 v39, v30, v23
	v_min_i32_e32 v30, v30, v23
	v_lshlrev_b32_e32 v23, 8, v34
	v_or3_b32 v20, v22, v20, v24
	v_lshlrev_b32_e32 v22, 16, v37
	v_and_b32_e32 v21, 0x7f, v32
	v_and_b32_e32 v23, 0x7f00, v23
	v_and_b32_e32 v22, 0x7f0000, v22
	v_or3_b32 v22, v23, v21, v22
	v_lshlrev_b32_e32 v21, 24, v57
	v_and_b32_e32 v21, 0x7f000000, v21
	v_bitop3_b32 v21, v20, s68, v21 bitop3:0x36
	v_lshlrev_b32_e32 v20, 24, v29
	v_and_b32_e32 v20, 0x7f000000, v20
	v_lshlrev_b32_e32 v24, 8, v58
	v_lshlrev_b32_e32 v42, 16, v56
	v_bitop3_b32 v20, v22, s68, v20 bitop3:0x36
	v_and_b32_e32 v22, 0x7f, v55
	v_and_b32_e32 v24, 0x7f00, v24
	v_and_b32_e32 v42, 0x7f0000, v42
	v_lshlrev_b32_e32 v25, 8, v28
	v_or3_b32 v22, v24, v22, v42
	v_lshlrev_b32_e32 v24, 16, v35
	v_and_b32_e32 v23, 0x7f, v38
	v_and_b32_e32 v25, 0x7f00, v25
	v_and_b32_e32 v24, 0x7f0000, v24
	v_or3_b32 v24, v25, v23, v24
	v_lshlrev_b32_e32 v23, 24, v54
	v_and_b32_e32 v23, 0x7f000000, v23
	v_bitop3_b32 v23, v22, s68, v23 bitop3:0x36
	v_lshlrev_b32_e32 v22, 24, v27
	v_and_b32_e32 v22, 0x7f000000, v22
	v_lshlrev_b32_e32 v42, 8, v52
	v_lshlrev_b32_e32 v44, 16, v51
	v_bitop3_b32 v22, v24, s68, v22 bitop3:0x36
	v_and_b32_e32 v24, 0x7f, v53
	v_and_b32_e32 v42, 0x7f00, v42
	v_and_b32_e32 v44, 0x7f0000, v44
	v_lshlrev_b32_e32 v43, 8, v30
	v_or3_b32 v24, v42, v24, v44
	v_lshlrev_b32_e32 v42, 16, v40
	v_and_b32_e32 v25, 0x7f, v39
	v_and_b32_e32 v43, 0x7f00, v43
	v_and_b32_e32 v42, 0x7f0000, v42
	v_or3_b32 v42, v43, v25, v42
	v_lshlrev_b32_e32 v25, 24, v50
	v_and_b32_e32 v25, 0x7f000000, v25
	v_bitop3_b32 v25, v24, s68, v25 bitop3:0x36
	v_lshlrev_b32_e32 v24, 24, v41
	v_and_b32_e32 v24, 0x7f000000, v24
	v_bitop3_b32 v24, v42, s68, v24 bitop3:0x36
	v_mov_b32_e32 v42, v86
	v_add_f32_e32 v55, v55, v26
	v_cmp_eq_u32_e32 vcc, 0, v42
	v_add_f32_e32 v56, v56, v26
	v_add_f32_e32 v54, v54, v26
	v_cndmask_b32_e32 v42, v65, v63, vcc
	v_add_f32_e32 v44, v42, v26
	v_cndmask_b32_e64 v43, -16, 0, vcc
	v_or_b32_e32 v44, 0xff, v44
	v_add_f32_e32 v45, v42, v33
	v_add_u32_e32 v43, v44, v43
	v_cndmask_b32_e64 v44, v99, -1, vcc
	v_or_b32_e32 v45, 0xff, v45
	v_add_f32_e32 v46, v42, v36
	v_add_u32_e32 v44, v45, v44
	v_cndmask_b32_e64 v45, v100, -2, vcc
	v_or_b32_e32 v46, 0xff, v46
	v_add_f32_e32 v47, v42, v31
	v_add_u32_e32 v45, v46, v45
	v_cndmask_b32_e64 v46, v101, -3, vcc
	v_or_b32_e32 v47, 0xff, v47
	v_add_f32_e32 v48, v42, v32
	v_add_u32_e32 v46, v47, v46
	v_cndmask_b32_e64 v47, v102, -4, vcc
	v_or_b32_e32 v48, 0xff, v48
	v_add_f32_e32 v34, v42, v34
	v_add_f32_e32 v37, v42, v37
	v_add_f32_e32 v29, v42, v29
	v_cndmask_b32_e32 v42, v64, v63, vcc
	v_cndmask_b32_e32 v32, v32, v39, vcc
	v_add_u32_e32 v47, v48, v47
	v_cndmask_b32_e64 v48, v103, -5, vcc
	v_or_b32_e32 v34, 0xff, v34
	v_add_f32_e32 v32, v42, v32
	v_add_u32_e32 v34, v34, v48
	v_cndmask_b32_e64 v48, v104, -6, vcc
	v_or_b32_e32 v37, 0xff, v37
	v_cndmask_b32_e32 v38, v26, v38, vcc
	v_cndmask_b32_e64 v39, v116, -12, vcc
	v_or_b32_e32 v32, 0xff, v32
	v_add_u32_e32 v37, v37, v48
	v_cndmask_b32_e64 v48, v105, -7, vcc
	v_or_b32_e32 v29, 0xff, v29
	v_add_f32_e32 v38, v42, v38
	v_cndmask_b32_e32 v28, v33, v28, vcc
	v_add_u32_e32 v32, v32, v39
	v_cndmask_b32_e32 v39, v62, v63, vcc
	v_cndmask_b32_e32 v30, v26, v30, vcc
	v_add_u32_e32 v29, v29, v48
	v_cndmask_b32_e64 v48, v106, -8, vcc
	v_or_b32_e32 v38, 0xff, v38
	v_add_f32_e32 v28, v42, v28
	v_cndmask_b32_e32 v35, v36, v35, vcc
	v_cndmask_b32_e32 v27, v31, v27, vcc
	v_add_f32_e32 v30, v39, v30
	v_cndmask_b32_e32 v40, v33, v40, vcc
	v_add_u32_e32 v38, v38, v48
	v_cndmask_b32_e64 v48, v107, -9, vcc
	v_or_b32_e32 v28, 0xff, v28
	v_add_f32_e32 v35, v42, v35
	v_add_f32_e32 v27, v42, v27
	v_cndmask_b32_e64 v42, v117, -13, vcc
	v_or_b32_e32 v30, 0xff, v30
	v_add_f32_e32 v40, v39, v40
	v_cndmask_b32_e32 v41, v36, v41, vcc
	v_add_u32_e32 v28, v28, v48
	v_cndmask_b32_e64 v48, v114, -10, vcc
	v_or_b32_e32 v35, 0xff, v35
	v_add_u32_e32 v30, v30, v42
	v_cndmask_b32_e64 v42, v118, -14, vcc
	v_or_b32_e32 v40, 0xff, v40
	v_add_f32_e32 v39, v39, v41
	v_add_u32_e32 v35, v35, v48
	v_cndmask_b32_e64 v48, v115, -11, vcc
	v_or_b32_e32 v27, 0xff, v27
	v_add_u32_e32 v40, v40, v42
	v_cndmask_b32_e64 v42, v119, -15, vcc
	v_or_b32_e32 v39, 0xff, v39
	v_add_u32_e32 v27, v27, v48
	v_add_u32_e32 v39, v39, v42
	v_max_i32_e32 v41, v43, v30
	v_min_i32_e32 v30, v43, v30
	v_max_i32_e32 v42, v44, v32
	v_min_i32_e32 v32, v44, v32
	v_max_i32_e32 v43, v45, v39
	v_min_i32_e32 v39, v45, v39
	v_max_i32_e32 v44, v46, v40
	v_min_i32_e32 v40, v46, v40
	v_max_i32_e32 v45, v47, v38
	v_min_i32_e32 v38, v47, v38
	v_max_i32_e32 v46, v34, v37
	v_min_i32_e32 v34, v34, v37
	v_max_i32_e32 v37, v29, v27
	v_min_i32_e32 v27, v29, v27
	v_max_i32_e32 v29, v28, v35
	v_min_i32_e32 v28, v28, v35
	v_max_i32_e32 v35, v41, v46
	v_min_i32_e32 v41, v41, v46
	v_max_i32_e32 v46, v42, v37
	v_min_i32_e32 v37, v42, v37
	v_max_i32_e32 v42, v43, v29
	v_min_i32_e32 v29, v43, v29
	v_max_i32_e32 v43, v44, v45
	v_min_i32_e32 v44, v44, v45
	v_max_i32_e32 v45, v34, v30
	v_min_i32_e32 v30, v34, v30
	v_max_i32_e32 v34, v38, v40
	v_min_i32_e32 v38, v38, v40
	v_max_i32_e32 v40, v28, v39
	v_min_i32_e32 v28, v28, v39
	v_max_i32_e32 v39, v27, v32
	v_min_i32_e32 v27, v27, v32
	v_max_i32_e32 v32, v35, v46
	v_min_i32_e32 v35, v35, v46
	v_max_i32_e32 v46, v42, v43
	v_min_i32_e32 v42, v42, v43
	v_max_i32_e32 v43, v44, v41
	v_min_i32_e32 v41, v44, v41
	v_max_i32_e32 v44, v45, v34
	v_min_i32_e32 v34, v45, v34
	v_max_i32_e32 v45, v37, v29
	v_min_i32_e32 v29, v37, v29
	v_max_i32_e32 v37, v40, v39
	v_min_i32_e32 v39, v40, v39
	v_max_i32_e32 v40, v27, v30
; #define CAND(a, b) (int)((__float_as_uint(__int_as_float(top[0][a]) + __int_as_float(top[1][b])) | 255u) - (unsigned)((a) * 16 + (b)))
; __device__ __forceinline__ void route_task(int task, int tl0, const bf16* QP  , const LAS bf16* KHL, LAS unsigned short* EL, LAS float* GL, int lane) {
;     ...
;         sort16_desc(bk);
;         int oth[16];
; #pragma unroll
;         for (int i = 0; i < 16; ++i) oth[i] = __shfl_xor(bk[i], 32);
;         merge16_desc(bk, oth);
;     }
;     ...
;     {
;         int gk[16];
;         gk[0] = CAND(3, 3); gk[1] = CAND(4, 0); gk[2] = CAND(4, 1); gk[3] = CAND(4, 2); gk[4] = CAND(5, 0); gk[5] = CAND(5, 1); gk[6] = CAND(6, 0); gk[7] = CAND(6, 1);
;         gk[8] = CAND(7, 0); gk[9] = CAND(7, 1); gk[10] = CAND(8, 0); gk[11] = CAND(9, 0); gk[12] = CAND(10, 0); gk[13] = CAND(11, 0); gk[14] = CAND(12, 0); gk[15] = CAND(13, 0);
;         sort16_desc(gk);
	v_min_i32_e32 v27, v27, v30
	v_max_i32_e32 v30, v38, v28
	v_min_i32_e32 v28, v38, v28
	v_max_i32_e32 v38, v32, v46
	v_min_i32_e32 v32, v32, v46
	v_max_i32_e32 v46, v35, v42
	v_min_i32_e32 v35, v35, v42
	v_max_i32_e32 v42, v43, v37
	v_min_i32_e32 v37, v43, v37
	v_max_i32_e32 v43, v41, v39
	v_min_i32_e32 v39, v41, v39
	v_max_i32_e32 v41, v44, v45
	v_min_i32_e32 v44, v44, v45
	v_max_i32_e32 v45, v34, v29
	v_min_i32_e32 v29, v34, v29
	v_max_i32_e32 v34, v40, v30
	v_min_i32_e32 v30, v40, v30
	v_max_i32_e32 v40, v27, v28
	v_min_i32_e32 v27, v27, v28
	v_max_i32_e32 v28, v46, v32
	v_min_i32_e32 v32, v46, v32
	v_max_i32_e32 v46, v35, v34
	v_min_i32_e32 v34, v35, v34
	v_max_i32_e32 v35, v42, v41
	v_min_i32_e32 v41, v42, v41
	v_max_i32_e32 v42, v43, v44
	v_min_i32_e32 v43, v43, v44
	v_max_i32_e32 v44, v45, v37
	v_min_i32_e32 v37, v45, v37
	v_max_i32_e32 v45, v29, v39
	v_min_i32_e32 v29, v29, v39
	v_max_i32_e32 v39, v40, v30
	v_min_i32_e32 v30, v40, v30
	v_max_i32_e32 v40, v28, v35
	v_min_i32_e32 v28, v28, v35
	v_max_i32_e32 v35, v32, v41
	v_min_i32_e32 v32, v32, v41
	v_max_i32_e32 v41, v42, v44
	v_min_i32_e32 v42, v42, v44
	v_max_i32_e32 v44, v43, v37
	v_min_i32_e32 v37, v43, v37
	v_max_i32_e32 v43, v45, v39
	v_min_i32_e32 v39, v45, v39
	v_max_i32_e32 v45, v29, v30
	v_min_i32_e32 v29, v29, v30
	v_max_i32_e32 v30, v35, v28
	v_min_i32_e32 v28, v35, v28
	v_max_i32_e32 v35, v46, v32
	v_min_i32_e32 v32, v46, v32
	v_max_i32_e32 v46, v43, v34
	v_min_i32_e32 v34, v43, v34
	v_max_i32_e32 v43, v45, v39
	v_min_i32_e32 v39, v45, v39
	v_max_i32_e32 v45, v35, v41
	v_min_i32_e32 v35, v35, v41
	v_max_i32_e32 v41, v32, v42
	v_min_i32_e32 v32, v32, v42
	v_max_i32_e32 v42, v44, v46
	v_min_i32_e32 v44, v44, v46
	v_max_i32_e32 v46, v37, v34
	v_min_i32_e32 v34, v37, v34
	v_max_i32_e32 v37, v45, v28
	v_min_i32_e32 v28, v45, v28
	v_max_i32_e32 v45, v35, v41
	v_min_i32_e32 v35, v35, v41
	v_max_i32_e32 v41, v42, v32
	v_min_i32_e32 v32, v42, v32
	v_max_i32_e32 v42, v44, v46
	v_min_i32_e32 v44, v44, v46
	v_max_i32_e32 v46, v43, v34
	v_min_i32_e32 v34, v43, v34
	v_max_i32_e32 v43, v35, v41
	v_min_i32_e32 v35, v35, v41
	v_max_i32_e32 v41, v32, v42
	v_min_i32_e32 v32, v32, v42
	ds_bpermute_b32 v67, v123, v41
	ds_bpermute_b32 v68, v123, v32
	ds_bpermute_b32 v69, v123, v44
	ds_bpermute_b32 v64, v123, v45
	ds_bpermute_b32 v65, v123, v43
	ds_bpermute_b32 v66, v123, v35
	s_waitcnt lgkmcnt(4)
	v_max_i32_e32 v43, v43, v68
	s_waitcnt lgkmcnt(3)
	v_max_i32_e32 v45, v45, v69
	v_max_i32_e32 v35, v35, v67
	v_add_f32_e32 v31, v62, v31
	v_add_f32_e32 v62, v61, v26
	v_add_f32_e32 v67, v61, v33
	v_add_f32_e32 v36, v61, v36
	v_add_f32_e32 v61, v60, v26
	v_add_f32_e32 v60, v60, v33
	v_add_f32_e32 v68, v59, v26
	v_add_f32_e32 v59, v59, v33
	v_add_f32_e32 v69, v57, v26
	v_add_f32_e32 v33, v57, v33
	v_add_f32_e32 v57, v58, v26
	v_add_f32_e32 v53, v53, v26
	v_add_f32_e32 v52, v52, v26
	ds_bpermute_b32 v70, v123, v27
	v_or_b32_e32 v31, 0xff, v31
	v_or_b32_e32 v62, 0xff, v62
	v_or_b32_e32 v67, 0xff, v67
	v_or_b32_e32 v36, 0xff, v36
	v_or_b32_e32 v61, 0xff, v61
	v_or_b32_e32 v60, 0xff, v60
	v_or_b32_e32 v68, 0xff, v68
	v_or_b32_e32 v59, 0xff, v59
	v_or_b32_e32 v69, 0xff, v69
	v_or_b32_e32 v33, 0xff, v33
	v_or_b32_e32 v55, 0xff, v55
	v_or_b32_e32 v57, 0xff, v57
	v_or_b32_e32 v56, 0xff, v56
	v_or_b32_e32 v54, 0xff, v54
	v_or_b32_e32 v53, 0xff, v53
	v_or_b32_e32 v52, 0xff, v52
	v_subrev_u32_e32 v31, 51, v31
	v_subrev_u32_e32 v62, 64, v62
	v_add_u32_e32 v67, 0xffffffbf, v67
	v_add_u32_e32 v36, 0xffffffbe, v36
	v_add_u32_e32 v61, 0xffffffb0, v61
	v_add_u32_e32 v60, 0xffffffaf, v60
	v_add_u32_e32 v68, 0xffffffa0, v68
	v_add_u32_e32 v59, 0xffffff9f, v59
	v_add_u32_e32 v69, 0xffffff90, v69
	v_add_u32_e32 v33, 0xffffff8f, v33
	v_add_u32_e32 v55, 0xffffff80, v55
	v_add_u32_e32 v57, 0xffffff70, v57
	v_add_u32_e32 v56, 0xffffff60, v56
	v_add_u32_e32 v54, 0xffffff50, v54
	v_add_u32_e32 v53, 0xffffff40, v53
	v_add_u32_e32 v52, 0xffffff30, v52
	ds_bpermute_b32 v42, v123, v38
	ds_bpermute_b32 v47, v123, v40
	ds_bpermute_b32 v48, v123, v30
	ds_bpermute_b32 v49, v123, v37
	ds_bpermute_b32 v63, v123, v28
	ds_bpermute_b32 v71, v123, v29
	ds_bpermute_b32 v72, v123, v39
	ds_bpermute_b32 v73, v123, v34
	ds_bpermute_b32 v74, v123, v46
	v_max_i32_e32 v58, v31, v54
	v_min_i32_e32 v31, v31, v54
	v_max_i32_e32 v54, v62, v56
	v_min_i32_e32 v56, v62, v56
	v_max_i32_e32 v62, v67, v52
	v_min_i32_e32 v52, v67, v52
	v_max_i32_e32 v67, v36, v53
	v_min_i32_e32 v36, v36, v53
	v_max_i32_e32 v53, v61, v69
	v_min_i32_e32 v61, v61, v69
	v_max_i32_e32 v69, v60, v68
	v_min_i32_e32 v60, v60, v68
	v_max_i32_e32 v68, v59, v57
	v_min_i32_e32 v57, v59, v57
	v_max_i32_e32 v59, v33, v55
	v_min_i32_e32 v33, v33, v55
	v_max_i32_e32 v55, v58, v69
	v_min_i32_e32 v58, v58, v69
	v_max_i32_e32 v69, v54, v68
	v_min_i32_e32 v54, v54, v68
	v_max_i32_e32 v68, v62, v59
	v_min_i32_e32 v59, v62, v59
	v_max_i32_e32 v62, v67, v53
	v_min_i32_e32 v53, v67, v53
	v_max_i32_e32 v67, v60, v31
	v_min_i32_e32 v31, v60, v31
	v_max_i32_e32 v60, v61, v36
	v_min_i32_e32 v36, v61, v36
	v_max_i32_e32 v61, v33, v52
	v_min_i32_e32 v33, v33, v52
	v_max_i32_e32 v52, v57, v56
	v_min_i32_e32 v56, v57, v56
	v_max_i32_e32 v57, v55, v69
	v_min_i32_e32 v55, v55, v69
	v_max_i32_e32 v69, v68, v62
	v_min_i32_e32 v62, v68, v62
	v_max_i32_e32 v68, v53, v58
	v_min_i32_e32 v53, v53, v58
	v_max_i32_e32 v58, v67, v60
	v_min_i32_e32 v60, v67, v60
	v_max_i32_e32 v67, v54, v59
	v_min_i32_e32 v54, v54, v59
	v_max_i32_e32 v59, v61, v52
	v_min_i32_e32 v52, v61, v52
	v_max_i32_e32 v61, v56, v31
	v_min_i32_e32 v31, v56, v31
	v_max_i32_e32 v56, v36, v33
	v_min_i32_e32 v33, v36, v33
	s_waitcnt lgkmcnt(9)
; #define CAND(a, b) (int)((__float_as_uint(__int_as_float(top[0][a]) + __int_as_float(top[1][b])) | 255u) - (unsigned)((a) * 16 + (b)))
; __device__ __forceinline__ void route_task(int task, int tl0, const bf16* QP  , const LAS bf16* KHL, LAS unsigned short* EL, LAS float* GL, int lane) {
;     ...
;         int oth[16];
; #pragma unroll
;         for (int i = 0; i < 16; ++i) oth[i] = __shfl_xor(bk[i], 32);
;         merge16_desc(bk, oth);
;     }
;     ...
;     {
;         int gk[16];
;         gk[0] = CAND(3, 3); gk[1] = CAND(4, 0); gk[2] = CAND(4, 1); gk[3] = CAND(4, 2); gk[4] = CAND(5, 0); gk[5] = CAND(5, 1); gk[6] = CAND(6, 0); gk[7] = CAND(6, 1);
;         gk[8] = CAND(7, 0); gk[9] = CAND(7, 1); gk[10] = CAND(8, 0); gk[11] = CAND(9, 0); gk[12] = CAND(10, 0); gk[13] = CAND(11, 0); gk[14] = CAND(12, 0); gk[15] = CAND(13, 0);
;         sort16_desc(gk);
;         merge16_desc(bk, gk);
;     }
	v_max_i32_e32 v38, v38, v70
	v_min_i32_e32 v36, v57, v69
	v_max_i32_e32 v70, v55, v62
	v_min_i32_e32 v55, v55, v62
	v_max_i32_e32 v62, v68, v59
	v_min_i32_e32 v59, v68, v59
	v_max_i32_e32 v68, v53, v52
	v_min_i32_e32 v52, v53, v52
	v_max_i32_e32 v53, v58, v67
	v_min_i32_e32 v58, v58, v67
	v_max_i32_e32 v67, v60, v54
	v_min_i32_e32 v54, v60, v54
	v_max_i32_e32 v60, v61, v56
	v_min_i32_e32 v56, v61, v56
	v_max_i32_e32 v61, v31, v33
	v_min_i32_e32 v31, v31, v33
	v_max_i32_e32 v33, v70, v36
	v_min_i32_e32 v36, v70, v36
	v_max_i32_e32 v70, v55, v60
	v_min_i32_e32 v55, v55, v60
	v_max_i32_e32 v60, v62, v53
	v_min_i32_e32 v53, v62, v53
	v_max_i32_e32 v62, v68, v58
	v_min_i32_e32 v58, v68, v58
	v_max_i32_e32 v68, v67, v59
	v_min_i32_e32 v59, v67, v59
	v_max_i32_e32 v67, v54, v52
	v_min_i32_e32 v52, v54, v52
	v_max_i32_e32 v54, v61, v56
	s_waitcnt lgkmcnt(3)
	v_max_i32_e32 v40, v40, v71
	s_waitcnt lgkmcnt(2)
	v_max_i32_e32 v30, v30, v72
	s_waitcnt lgkmcnt(1)
	v_max_i32_e32 v37, v37, v73
	s_waitcnt lgkmcnt(0)
	v_max_i32_e32 v28, v28, v74
	v_max_i32_e32 v41, v41, v66
	v_max_i32_e32 v32, v32, v65
	v_max_i32_e32 v44, v44, v64
	v_max_i32_e32 v46, v46, v63
	v_max_i32_e32 v34, v34, v49
	v_max_i32_e32 v39, v39, v48
	v_max_i32_e32 v29, v29, v47
	v_max_i32_e32 v27, v27, v42
	v_min_i32_e32 v56, v61, v56
	v_max_i32_e32 v61, v33, v60
	v_min_i32_e32 v33, v33, v60
	v_max_i32_e32 v60, v36, v53
	v_min_i32_e32 v36, v36, v53
	v_max_i32_e32 v53, v62, v68
	v_min_i32_e32 v62, v62, v68
	v_max_i32_e32 v68, v58, v59
	v_min_i32_e32 v58, v58, v59
	v_max_i32_e32 v59, v67, v54
	v_max_i32_e32 v42, v38, v41
	v_min_i32_e32 v38, v38, v41
	v_max_i32_e32 v41, v40, v32
	v_min_i32_e32 v32, v40, v32
	v_max_i32_e32 v40, v30, v44
	v_min_i32_e32 v30, v30, v44
	v_max_i32_e32 v44, v37, v46
	v_min_i32_e32 v37, v37, v46
	v_max_i32_e32 v46, v28, v34
	v_min_i32_e32 v28, v28, v34
	v_max_i32_e32 v34, v45, v39
	v_min_i32_e32 v39, v45, v39
	v_max_i32_e32 v45, v43, v29
	v_min_i32_e32 v29, v43, v29
	v_max_i32_e32 v43, v35, v27
	v_min_i32_e32 v27, v35, v27
	v_min_i32_e32 v54, v67, v54
	v_max_i32_e32 v67, v52, v56
	v_max_i32_e32 v71, v70, v36
	v_min_i32_e32 v36, v70, v36
	v_max_i32_e32 v70, v59, v55
	v_min_i32_e32 v55, v59, v55
	v_max_i32_e32 v35, v42, v46
	v_min_i32_e32 v42, v42, v46
	v_max_i32_e32 v46, v41, v34
	v_min_i32_e32 v34, v41, v34
	v_max_i32_e32 v41, v40, v45
	v_min_i32_e32 v40, v40, v45
	v_max_i32_e32 v45, v44, v43
	v_min_i32_e32 v43, v44, v43
	v_max_i32_e32 v44, v38, v28
	v_min_i32_e32 v28, v38, v28
	v_max_i32_e32 v38, v32, v39
	v_min_i32_e32 v32, v32, v39
	v_max_i32_e32 v39, v30, v29
	v_min_i32_e32 v29, v30, v29
	v_max_i32_e32 v30, v37, v27
	v_min_i32_e32 v27, v37, v27
	v_min_i32_e32 v52, v52, v56
	v_min_i32_e32 v56, v60, v33
	v_max_i32_e32 v59, v67, v54
	v_min_i32_e32 v54, v67, v54
	v_max_i32_e32 v67, v71, v53
	v_min_i32_e32 v53, v71, v53
	v_max_i32_e32 v71, v36, v62
	v_min_i32_e32 v36, v36, v62
	v_max_i32_e32 v62, v68, v70
	v_min_i32_e32 v68, v68, v70
	v_max_i32_e32 v70, v58, v55
	v_max_i32_e32 v37, v35, v41
	v_min_i32_e32 v35, v35, v41
	v_max_i32_e32 v41, v46, v45
	v_min_i32_e32 v45, v46, v45
	v_max_i32_e32 v46, v42, v40
	v_min_i32_e32 v40, v42, v40
	v_max_i32_e32 v42, v34, v43
	v_min_i32_e32 v34, v34, v43
	v_max_i32_e32 v43, v44, v39
	v_min_i32_e32 v39, v44, v39
	v_max_i32_e32 v44, v38, v30
	v_min_i32_e32 v30, v38, v30
	v_max_i32_e32 v38, v28, v29
	v_min_i32_e32 v28, v28, v29
	v_max_i32_e32 v29, v32, v27
	v_min_i32_e32 v27, v32, v27
	v_min_i32_e32 v55, v58, v55
	v_max_i32_e32 v58, v67, v56
	v_min_i32_e32 v56, v67, v56
	v_max_i32_e32 v67, v53, v71
	v_min_i32_e32 v53, v53, v71
	v_max_i32_e32 v71, v62, v36
	v_min_i32_e32 v36, v62, v36
	v_max_i32_e32 v62, v68, v70
	v_min_i32_e32 v32, v37, v41
	v_min_i32_e32 v47, v35, v45
	v_min_i32_e32 v48, v46, v42
	v_min_i32_e32 v49, v40, v34
	v_min_i32_e32 v63, v43, v44
	v_min_i32_e32 v64, v39, v30
	v_min_i32_e32 v65, v38, v29
	v_min_i32_e32 v66, v28, v27
	v_min_i32_e32 v68, v68, v70
	v_max_i32_e32 v70, v59, v55
	v_min_i32_e32 v55, v59, v55
	v_min_i32_e32 v59, v53, v71
	v_min_i32_e32 v72, v36, v62
	v_max3_i32 v31, v37, v41, v31
	v_max_i32_e32 v32, v32, v52
	v_max3_i32 v35, v35, v45, v54
	v_max_i32_e32 v37, v47, v55
	v_max3_i32 v41, v46, v42, v70
	v_max_i32_e32 v42, v48, v68
	v_max3_i32 v34, v40, v34, v72
	v_max3_i32 v36, v49, v36, v62
	v_max3_i32 v40, v43, v44, v59
	v_max3_i32 v43, v63, v53, v71
	v_max3_i32 v30, v39, v30, v67
	v_max_i32_e32 v39, v64, v56
	v_max3_i32 v29, v38, v29, v58
	v_max3_i32 v33, v65, v60, v33
	v_max3_i32 v27, v28, v27, v61
	v_max3_i32 v28, v66, v57, v69
	v_max_i32_e32 v38, v31, v40
	v_min_i32_e32 v31, v31, v40
	v_max_i32_e32 v40, v32, v43
	v_min_i32_e32 v32, v32, v43
	v_max_i32_e32 v43, v35, v30
	v_min_i32_e32 v30, v35, v30
	v_max_i32_e32 v35, v37, v39
	v_min_i32_e32 v37, v37, v39
	v_max_i32_e32 v39, v41, v29
	v_min_i32_e32 v29, v41, v29
	v_max_i32_e32 v41, v42, v33
	v_min_i32_e32 v33, v42, v33
	v_max_i32_e32 v42, v34, v27
	v_min_i32_e32 v27, v34, v27
	v_max_i32_e32 v34, v36, v28
	v_min_i32_e32 v28, v36, v28
	v_max_i32_e32 v36, v38, v39
	v_min_i32_e32 v38, v38, v39
	v_max_i32_e32 v39, v40, v41
	v_min_i32_e32 v40, v40, v41
	v_max_i32_e32 v41, v43, v42
	v_min_i32_e32 v42, v43, v42
	v_max_i32_e32 v43, v35, v34
	v_min_i32_e32 v34, v35, v34
	v_max_i32_e32 v35, v31, v29
	v_min_i32_e32 v29, v31, v29
	v_max_i32_e32 v31, v32, v33
	v_min_i32_e32 v32, v32, v33
	v_max_i32_e32 v33, v30, v27
	v_min_i32_e32 v27, v30, v27
	v_max_i32_e32 v30, v37, v28
	v_min_i32_e32 v28, v37, v28
	v_max_i32_e32 v37, v36, v41
	v_min_i32_e32 v36, v36, v41
	v_max_i32_e32 v41, v39, v43
	v_min_i32_e32 v39, v39, v43
	v_max_i32_e32 v43, v38, v42
	v_min_i32_e32 v38, v38, v42
; #define CAND(a, b) (int)((__float_as_uint(__int_as_float(top[0][a]) + __int_as_float(top[1][b])) | 255u) - (unsigned)((a) * 16 + (b)))
; __device__ __forceinline__ void route_task(int task, int tl0, const bf16* QP  , const LAS bf16* KHL, LAS unsigned short* EL, LAS float* GL, int lane) {
;     ...
;         merge16_desc(bk, gk);
;     }
;     {
;         const int c14 = CAND(14, 0), c15 = CAND(15, 0);
;         const int n14 = max(bk[14], c14), n15 = max(min(bk[14], c14), max(bk[15], c15));
;         bk[14] = n14; bk[15] = n15;
;     }
;     ...
;     int my[8];
; #pragma unroll
;     for (int i = 0; i < 8; ++i) { int lo_ = bk[i], hi_ = bk[8 + i]; asm volatile("" : "+v"(lo_), "+v"(hi_)); my[i] = hi ? hi_ : lo_; }
;     int bv[8];
; #pragma unroll
;     for (int i = 0; i < 8; ++i) {
;         const unsigned cd = 255u - ((unsigned)my[i] & 255u), ca = cd >> 4, cb = cd & 15u;
;         const unsigned wa = (ca >> 2) == 0u ? P1[0] : (ca >> 2) == 1u ? P1[1] : (ca >> 2) == 2u ? P1[2] : P1[3];
;         const unsigned wb = (cb >> 2) == 0u ? P2[0] : (cb >> 2) == 1u ? P2[1] : (cb >> 2) == 2u ? P2[2] : P2[3];
;         bv[i] = (int)((((wa >> (8u * (ca & 3u))) & 255u) << 7) | ((wb >> (8u * (cb & 3u))) & 255u));
;     }
	v_max_i32_e32 v42, v40, v34
	v_min_i32_e32 v34, v40, v34
	v_max_i32_e32 v40, v35, v33
	v_min_i32_e32 v33, v35, v33
	v_max_i32_e32 v35, v31, v30
	v_min_i32_e32 v30, v31, v30
	v_max_i32_e32 v31, v29, v27
	v_min_i32_e32 v27, v29, v27
	v_max_i32_e32 v29, v32, v28
	v_min_i32_e32 v28, v32, v28
	v_max_i32_e32 v32, v37, v41
	v_min_i32_e32 v37, v37, v41
	v_max_i32_e32 v41, v36, v39
	v_min_i32_e32 v36, v36, v39
	v_max_i32_e32 v39, v43, v42
	v_min_i32_e32 v42, v43, v42
	v_max_i32_e32 v43, v38, v34
	v_min_i32_e32 v34, v38, v34
	v_max_i32_e32 v38, v40, v35
	v_min_i32_e32 v35, v40, v35
	v_max_i32_e32 v40, v33, v30
	v_min_i32_e32 v30, v33, v30
	v_max_i32_e32 v33, v31, v29
	v_min_i32_e32 v29, v31, v29
	v_max_i32_e32 v31, v27, v28
	v_min_i32_e32 v27, v27, v28
	v_add_f32_e32 v28, v51, v26
	v_or_b32_e32 v28, 0xff, v28
	v_add_f32_e32 v26, v50, v26
	v_add_u32_e32 v28, 0xffffff20, v28
	v_or_b32_e32 v26, 0xff, v26
	v_add_u32_e32 v26, 0xffffff10, v26
	v_max_i32_e32 v44, v31, v28
	v_min_i32_e32 v28, v31, v28
	v_max3_i32 v26, v28, v27, v26
	v_mov_b32_e32 v27, v32
	s_nop 0
	v_cndmask_b32_e64 v27, v38, v27, s[6:7]
	v_not_b32_e32 v28, v27
	v_bfe_u32 v45, v28, 6, 2
	v_cmp_eq_u32_e32 vcc, 2, v45
	v_cndmask_b32_e64 v34, v26, v34, s[6:7]
	v_bitop3_b32 v26, v27, s3, v27 bitop3:0xc
	v_cndmask_b32_e32 v46, v25, v23, vcc
	v_cmp_eq_u32_e32 vcc, 1, v45
	v_cndmask_b32_e64 v31, v35, v37, s[6:7]
	v_not_b32_e32 v35, v31
	v_cndmask_b32_e32 v45, v46, v21, vcc
	v_cmp_gt_u32_e32 vcc, 64, v26
	v_cndmask_b32_e64 v37, v40, v41, s[6:7]
	v_cndmask_b32_e64 v41, v44, v43, s[6:7]
	v_cndmask_b32_e32 v26, v45, v19, vcc
	v_bfe_u32 v45, v28, 2, 2
	v_cmp_eq_u32_e32 vcc, 2, v45
	v_bitop3_b32 v44, v27, 15, v27 bitop3:0xc
	v_bfe_u32 v47, v35, 6, 2
	v_cndmask_b32_e32 v46, v24, v22, vcc
	v_cmp_eq_u32_e32 vcc, 1, v45
	v_not_b32_e32 v38, v37
	v_bfe_u32 v49, v38, 6, 2
	v_cndmask_b32_e32 v45, v46, v20, vcc
	v_cmp_gt_u32_e32 vcc, 4, v44
	v_bitop3_b32 v46, v31, 15, v31 bitop3:0xc
	v_cndmask_b32_e64 v30, v30, v36, s[6:7]
	v_cndmask_b32_e32 v44, v45, v18, vcc
	v_cmp_eq_u32_e32 vcc, 2, v47
	v_bitop3_b32 v45, v31, s3, v31 bitop3:0xc
	v_not_b32_e32 v36, v30
	v_cndmask_b32_e32 v48, v25, v23, vcc
	v_cmp_eq_u32_e32 vcc, 1, v47
	v_bfe_u32 v51, v36, 6, 2
	v_cndmask_b32_e64 v33, v33, v39, s[6:7]
	v_cndmask_b32_e32 v47, v48, v21, vcc
	v_cmp_gt_u32_e32 vcc, 64, v45
	v_not_b32_e32 v39, v33
	v_bfe_u32 v53, v39, 6, 2
	v_cndmask_b32_e32 v45, v47, v19, vcc
	v_bfe_u32 v47, v35, 2, 2
	v_cmp_eq_u32_e32 vcc, 2, v47
	v_cndmask_b32_e64 v29, v29, v42, s[6:7]
	v_not_b32_e32 v40, v29
	v_cndmask_b32_e32 v48, v24, v22, vcc
	v_cmp_eq_u32_e32 vcc, 1, v47
	v_bfe_u32 v55, v40, 6, 2
	v_not_b32_e32 v42, v41
	v_cndmask_b32_e32 v47, v48, v20, vcc
	v_cmp_gt_u32_e32 vcc, 4, v46
	v_bitop3_b32 v48, v37, 15, v37 bitop3:0xc
	v_bfe_u32 v57, v42, 6, 2
	v_cndmask_b32_e32 v46, v47, v18, vcc
	v_cmp_eq_u32_e32 vcc, 2, v49
	v_bitop3_b32 v47, v37, s3, v37 bitop3:0xc
	v_not_b32_e32 v43, v34
	v_cndmask_b32_e32 v50, v25, v23, vcc
	v_cmp_eq_u32_e32 vcc, 1, v49
	v_bfe_u32 v59, v43, 6, 2
	v_or_b32_e32 v82, s10, v88
	v_cndmask_b32_e32 v49, v50, v21, vcc
	v_cmp_gt_u32_e32 vcc, 64, v47
	s_nop 1
	v_cndmask_b32_e32 v47, v49, v19, vcc
	v_bfe_u32 v49, v38, 2, 2
	v_cmp_eq_u32_e32 vcc, 2, v49
	s_nop 1
	v_cndmask_b32_e32 v50, v24, v22, vcc
	v_cmp_eq_u32_e32 vcc, 1, v49
	s_nop 1
	v_cndmask_b32_e32 v49, v50, v20, vcc
	v_cmp_gt_u32_e32 vcc, 4, v48
	v_bitop3_b32 v50, v30, 15, v30 bitop3:0xc
	s_nop 0
	v_cndmask_b32_e32 v48, v49, v18, vcc
	v_cmp_eq_u32_e32 vcc, 2, v51
	v_bitop3_b32 v49, v30, s3, v30 bitop3:0xc
	s_nop 0
	v_cndmask_b32_e32 v52, v25, v23, vcc
	v_cmp_eq_u32_e32 vcc, 1, v51
	s_nop 1
	v_cndmask_b32_e32 v51, v52, v21, vcc
	v_cmp_gt_u32_e32 vcc, 64, v49
	s_nop 1
	v_cndmask_b32_e32 v49, v51, v19, vcc
	v_bfe_u32 v51, v36, 2, 2
	v_cmp_eq_u32_e32 vcc, 2, v51
	s_nop 1
	v_cndmask_b32_e32 v52, v24, v22, vcc
	v_cmp_eq_u32_e32 vcc, 1, v51
	s_nop 1
	v_cndmask_b32_e32 v51, v52, v20, vcc
	v_cmp_gt_u32_e32 vcc, 4, v50
	v_bitop3_b32 v52, v33, 15, v33 bitop3:0xc
	s_nop 0
	v_cndmask_b32_e32 v50, v51, v18, vcc
	v_cmp_eq_u32_e32 vcc, 2, v53
	v_bitop3_b32 v51, v33, s3, v33 bitop3:0xc
	s_nop 0
	v_cndmask_b32_e32 v54, v25, v23, vcc
	v_cmp_eq_u32_e32 vcc, 1, v53
	s_nop 1
	v_cndmask_b32_e32 v53, v54, v21, vcc
	v_cmp_gt_u32_e32 vcc, 64, v51
	s_nop 1
	v_cndmask_b32_e32 v51, v53, v19, vcc
	v_bfe_u32 v53, v39, 2, 2
	v_cmp_eq_u32_e32 vcc, 2, v53
	s_nop 1
	v_cndmask_b32_e32 v54, v24, v22, vcc
	v_cmp_eq_u32_e32 vcc, 1, v53
	s_nop 1
	v_cndmask_b32_e32 v53, v54, v20, vcc
	v_cmp_gt_u32_e32 vcc, 4, v52
	v_bitop3_b32 v54, v29, 15, v29 bitop3:0xc
	s_nop 0
	v_cndmask_b32_e32 v52, v53, v18, vcc
	v_cmp_eq_u32_e32 vcc, 2, v55
	v_bitop3_b32 v53, v29, s3, v29 bitop3:0xc
	s_nop 0
	v_cndmask_b32_e32 v56, v25, v23, vcc
	v_cmp_eq_u32_e32 vcc, 1, v55
	s_nop 1
	v_cndmask_b32_e32 v55, v56, v21, vcc
	v_cmp_gt_u32_e32 vcc, 64, v53
	s_nop 1
	v_cndmask_b32_e32 v53, v55, v19, vcc
	v_bfe_u32 v55, v40, 2, 2
	v_cmp_eq_u32_e32 vcc, 2, v55
	s_nop 1
	v_cndmask_b32_e32 v56, v24, v22, vcc
	v_cmp_eq_u32_e32 vcc, 1, v55
	s_nop 1
	v_cndmask_b32_e32 v55, v56, v20, vcc
	v_cmp_gt_u32_e32 vcc, 4, v54
	v_bitop3_b32 v56, v41, 15, v41 bitop3:0xc
	s_nop 0
	v_cndmask_b32_e32 v54, v55, v18, vcc
	v_cmp_eq_u32_e32 vcc, 2, v57
	v_bitop3_b32 v55, v41, s3, v41 bitop3:0xc
	s_nop 0
	v_cndmask_b32_e32 v58, v25, v23, vcc
	v_cmp_eq_u32_e32 vcc, 1, v57
	s_nop 1
	v_cndmask_b32_e32 v57, v58, v21, vcc
	v_cmp_gt_u32_e32 vcc, 64, v55
	s_nop 1
	v_cndmask_b32_e32 v55, v57, v19, vcc
	v_bfe_u32 v57, v42, 2, 2
	v_cmp_eq_u32_e32 vcc, 2, v57
	s_nop 1
	v_cndmask_b32_e32 v58, v24, v22, vcc
	v_cmp_eq_u32_e32 vcc, 1, v57
	s_nop 1
	v_cndmask_b32_e32 v57, v58, v20, vcc
; #define LAS __attribute__((address_space(3)))
; #define MFMA32(a, b, c) __builtin_amdgcn_mfma_f32_32x32x16_bf16((a), (b), (c), 0, 0, 0)
; __device__ __forceinline__ void route_task(int task, int tl0, const bf16* QP  , const LAS bf16* KHL, LAS unsigned short* EL, LAS float* GL, int lane) {
;     ...
;     { unsigned qo = (unsigned)t * (unsigned)D + (unsigned)(head * 128 + 8 * hi); asm volatile("" : "+v"(qo)); const bf16* qp = QP + qo;
; #pragma unroll
;       for (int hf = 0; hf < 2; ++hf)
; #pragma unroll
;         for (int ks = 0; ks < 4; ++ks) qa[hf][ks] = ldg8(qp + 64 * hf + 16 * ks); }
; #pragma unroll
;     for (int half = 0; half < 2; ++half) {
;         int cur[16];
; #pragma unroll
;         for (int kt = 0; kt < 4; ++kt) {
;             f32x16 X;
; #pragma unroll
;             for (int i = 0; i < 16; ++i) X[i] = 8.f;
;             const LAS bf16* khp = KHL + (half * 128 + 32 * kt + r) * 72 + 8 * hi;
; #pragma unroll
;             for (int ks = 0; ks < 4; ++ks) {
;                 const bf16x8 kh = lds8(khp + 16 * ks);
;                 X = MFMA32(kh, qa[half][ks], X);
;     ...
;         const unsigned cd = 255u - ((unsigned)my[i] & 255u), ca = cd >> 4, cb = cd & 15u;
;         const unsigned wa = (ca >> 2) == 0u ? P1[0] : (ca >> 2) == 1u ? P1[1] : (ca >> 2) == 2u ? P1[2] : P1[3];
;         const unsigned wb = (cb >> 2) == 0u ? P2[0] : (cb >> 2) == 1u ? P2[1] : (cb >> 2) == 2u ? P2[2] : P2[3];
;         bv[i] = (int)((((wa >> (8u * (ca & 3u))) & 255u) << 7) | ((wb >> (8u * (cb & 3u))) & 255u));
;     }
;     float e[8], se = 0.f;
; #pragma unroll
;     for (int i = 0; i < 8; ++i) { e[i] = __expf(__int_as_float(my[i]) - __int_as_float(bk[0])); se += e[i]; }
;     se += __shfl_xor(se, 32);
;     const float inv = 1.f / se;
;     {
;         int l2 = lane; asm volatile("" : "+v"(l2));
;         const int o2 = (tl0 + ((l2 & 31) >> 3)) * 128 + (l2 & 7) * 16 + 8 * (l2 >> 5);
;         LAS v4u* ip = (LAS v4u*)(EL + o2); typedef float f4v __attribute__((ext_vector_type(4))); LAS f4v* gp = (LAS f4v*)(GL + o2);
;         ip[0] = (v4u){(unsigned)bv[0] | ((unsigned)bv[1] << 16), (unsigned)bv[2] | ((unsigned)bv[3] << 16), (unsigned)bv[4] | ((unsigned)bv[5] << 16), (unsigned)bv[6] | ((unsigned)bv[7] << 16)};
;         gp[0] = (f4v){e[0] * inv, e[1] * inv, e[2] * inv, e[3] * inv}; gp[1] = (f4v){e[4] * inv, e[5] * inv, e[6] * inv, e[7] * inv};
;     }
	v_cmp_gt_u32_e32 vcc, 4, v56
	v_bitop3_b32 v58, v34, 15, v34 bitop3:0xc
	s_nop 0
	v_cndmask_b32_e32 v56, v57, v18, vcc
	v_cmp_eq_u32_e32 vcc, 2, v59
	v_bitop3_b32 v57, v34, s3, v34 bitop3:0xc
	s_nop 0
	v_cndmask_b32_e32 v23, v25, v23, vcc
	v_cmp_eq_u32_e32 vcc, 1, v59
	v_sub_f32_e32 v25, v30, v32
	v_mul_f32_e32 v25, 0x3fb8aa3b, v25
	v_cndmask_b32_e32 v21, v23, v21, vcc
	v_cmp_gt_u32_e32 vcc, 64, v57
	v_lshrrev_b32_e32 v23, 1, v39
	v_and_b32_e32 v23, 24, v23
	v_cndmask_b32_e32 v19, v21, v19, vcc
	v_bfe_u32 v21, v43, 2, 2
	v_cmp_eq_u32_e32 vcc, 2, v21
	v_lshrrev_b32_e32 v23, v23, v51
	v_lshlrev_b32_e32 v23, 7, v23
	v_cndmask_b32_e32 v22, v24, v22, vcc
	v_cmp_eq_u32_e32 vcc, 1, v21
	v_lshrrev_b32_e32 v21, 1, v42
	v_and_b32_e32 v21, 24, v21
	v_cndmask_b32_e32 v20, v22, v20, vcc
	v_cmp_gt_u32_e32 vcc, 4, v58
	v_lshrrev_b32_e32 v21, v21, v55
	v_lshrrev_b32_e32 v22, 1, v40
	v_cndmask_b32_e32 v18, v20, v18, vcc
	v_lshlrev_b32_e32 v20, 3, v42
	v_lshlrev_b32_e32 v21, 7, v21
	v_and_b32_e32 v22, 24, v22
	v_lshrrev_b32_e32 v20, v20, v56
	v_and_b32_e32 v21, 0x7f80, v21
	v_lshrrev_b32_e32 v22, v22, v53
	v_and_or_b32 v21, v20, s3, v21
	v_lshlrev_b32_e32 v20, 3, v40
	v_lshlrev_b32_e32 v22, 7, v22
	v_lshrrev_b32_e32 v20, v20, v54
	v_and_b32_e32 v22, 0x7f80, v22
	v_and_or_b32 v20, v20, s3, v22
	v_lshlrev_b32_e32 v22, 3, v39
	v_lshrrev_b32_e32 v22, v22, v52
	v_and_b32_e32 v23, 0x7f80, v23
	v_and_or_b32 v39, v22, s3, v23
	v_lshrrev_b32_e32 v23, 1, v36
	v_and_b32_e32 v23, 24, v23
	v_lshrrev_b32_e32 v23, v23, v49
	v_lshlrev_b32_e32 v22, 3, v36
	v_lshlrev_b32_e32 v23, 7, v23
	v_lshrrev_b32_e32 v22, v22, v50
	v_and_b32_e32 v23, 0x7f80, v23
	v_and_or_b32 v36, v22, s3, v23
	v_lshrrev_b32_e32 v23, 1, v38
	v_and_b32_e32 v23, 24, v23
	v_lshrrev_b32_e32 v23, v23, v47
	v_lshlrev_b32_e32 v22, 3, v38
	v_lshlrev_b32_e32 v23, 7, v23
	v_lshrrev_b32_e32 v22, v22, v48
	v_and_b32_e32 v23, 0x7f80, v23
	v_and_or_b32 v38, v22, s3, v23
	v_lshrrev_b32_e32 v23, 1, v35
	v_and_b32_e32 v23, 24, v23
	v_lshrrev_b32_e32 v23, v23, v45
	v_lshlrev_b32_e32 v22, 3, v35
	v_lshlrev_b32_e32 v23, 7, v23
	v_lshrrev_b32_e32 v22, v22, v46
	v_and_b32_e32 v23, 0x7f80, v23
	v_and_or_b32 v35, v22, s3, v23
	v_lshrrev_b32_e32 v23, 1, v28
	v_and_b32_e32 v23, 24, v23
	v_lshrrev_b32_e32 v23, v23, v26
	v_lshlrev_b32_e32 v22, 3, v28
	v_lshlrev_b32_e32 v23, 7, v23
	v_lshrrev_b32_e32 v22, v22, v44
	v_and_b32_e32 v23, 0x7f80, v23
	v_and_or_b32 v40, v22, s3, v23
	v_sub_f32_e32 v22, v27, v32
	v_mul_f32_e32 v22, 0x3fb8aa3b, v22
	v_sub_f32_e32 v23, v31, v32
	v_exp_f32_e32 v22, v22
	v_mul_f32_e32 v23, 0x3fb8aa3b, v23
	v_sub_f32_e32 v24, v37, v32
	v_exp_f32_e32 v23, v23
	v_mul_f32_e32 v24, 0x3fb8aa3b, v24
	v_exp_f32_e32 v24, v24
	v_exp_f32_e32 v25, v25
	v_add_f32_e32 v26, 0, v22
	v_add_f32_e32 v26, v23, v26
	v_add_f32_e32 v26, v24, v26
	v_add_f32_e32 v30, v25, v26
	v_sub_f32_e32 v26, v33, v32
	v_mul_f32_e32 v26, 0x3fb8aa3b, v26
	v_sub_f32_e32 v27, v29, v32
	v_exp_f32_e32 v26, v26
	v_mul_f32_e32 v27, 0x3fb8aa3b, v27
	v_sub_f32_e32 v28, v41, v32
	v_exp_f32_e32 v27, v27
	v_mul_f32_e32 v28, 0x3fb8aa3b, v28
	v_sub_f32_e32 v29, v34, v32
	v_exp_f32_e32 v28, v28
	v_mul_f32_e32 v29, 0x3fb8aa3b, v29
	v_exp_f32_e32 v29, v29
	v_add_f32_e32 v30, v26, v30
	v_add_f32_e32 v30, v27, v30
	v_add_f32_e32 v30, v28, v30
	v_add_f32_e32 v30, v29, v30
	ds_bpermute_b32 v31, v123, v30
	v_lshrrev_b32_e32 v42, 1, v43
	v_and_b32_e32 v32, 24, v42
	v_lshrrev_b32_e32 v19, v32, v19
	v_lshlrev_b32_e32 v19, 7, v19
	s_waitcnt lgkmcnt(0)
	v_add_f32_e32 v30, v30, v31
	v_div_scale_f32 v31, s[12:13], v30, v30, 1.0
	v_rcp_f32_e32 v32, v31
	v_lshlrev_b32_e32 v33, 3, v43
	v_and_b32_e32 v19, 0x7f80, v19
	v_lshrrev_b32_e32 v18, v33, v18
	v_and_or_b32 v33, v18, s3, v19
	v_fma_f32 v18, -v31, v32, 1.0
	v_fmac_f32_e32 v32, v18, v32
	v_div_scale_f32 v18, vcc, 1.0, v30, 1.0
	v_mul_f32_e32 v19, v18, v32
	v_fma_f32 v34, -v31, v19, v18
	v_fmac_f32_e32 v19, v34, v32
	v_fma_f32 v18, -v31, v19, v18
	v_div_fmas_f32 v18, v18, v32, v19
	v_div_fixup_f32 v30, v18, v30, 1.0
	v_mov_b32_e32 v18, v1
	v_lshl_or_b32 v20, v20, 16, v39
	v_lshrrev_b32_e32 v19, 3, v18
	v_and_or_b32 v19, v19, 3, s55
	v_lshlrev_b32_e32 v31, 4, v18
	v_ashrrev_i32_e32 v18, 2, v18
	v_lshlrev_b32_e32 v19, 7, v19
	v_and_b32_e32 v31, 0x70, v31
	v_and_b32_e32 v18, -8, v18
	v_add3_u32 v18, v18, v31, v19
	v_lshl_add_u32 v31, v18, 1, s11
	v_lshl_add_u32 v32, v18, 2, s69
	v_lshl_or_b32 v18, v35, 16, v40
	v_lshl_or_b32 v19, v36, 16, v38
	v_lshl_or_b32 v21, v33, 16, v21
	ds_write_b128 v31, v[18:21]
	v_pk_mul_f32 v[20:21], v[24:25], v[30:31] op_sel_hi:[1,0]
	v_pk_mul_f32 v[18:19], v[22:23], v[30:31] op_sel_hi:[1,0]
	ds_write_b128 v32, v[18:21]
	v_pk_mul_f32 v[20:21], v[28:29], v[30:31] op_sel_hi:[1,0]
	v_pk_mul_f32 v[18:19], v[26:27], v[30:31] op_sel_hi:[1,0]
	ds_write_b128 v32, v[18:21] offset:16
	v_mov_b64_e32 v[32:33], s[30:31]
	v_lshl_add_u64 v[128:129], v[82:83], 1, s[80:81]
	global_load_dwordx4 v[78:81], v[128:129], off
	global_load_dwordx4 v[74:77], v[128:129], off offset:32
	global_load_dwordx4 v[70:73], v[128:129], off offset:64
	global_load_dwordx4 v[66:69], v[128:129], off offset:96
	ds_read_b128 v[50:53], v94
	ds_read_b128 v[54:57], v94 offset:32
	v_mov_b64_e32 v[30:31], s[28:29]
	v_mov_b64_e32 v[28:29], s[26:27]
	v_mov_b64_e32 v[26:27], s[24:25]
	v_mov_b64_e32 v[24:25], s[22:23]
	v_mov_b64_e32 v[22:23], s[20:21]
	v_mov_b64_e32 v[20:21], s[18:19]
	v_mov_b64_e32 v[18:19], s[16:17]
	s_waitcnt vmcnt(3) lgkmcnt(1)
	s_nop 0
	v_mfma_f32_32x32x16_bf16 v[34:49], v[50:53], v[78:81], v[18:33]
	ds_read_b128 v[50:53], v94 offset:64
	ds_read_b128 v[124:127], v94 offset:96
	s_waitcnt vmcnt(2) lgkmcnt(2)
; #define LAS __attribute__((address_space(3)))
; #define MFMA32(a, b, c) __builtin_amdgcn_mfma_f32_32x32x16_bf16((a), (b), (c), 0, 0, 0)
; #define CE_(a, b) ce_desc(v[a], v[b])
; __device__ __forceinline__ void sort16_desc(int (&v)[16]) {
;     ...
;     CE_(0,13); CE_(1,12); CE_(2,15); CE_(3,14); CE_(4,8); CE_(5,6); CE_(7,11); CE_(9,10);
;     CE_(0,5); CE_(1,7); CE_(2,9); CE_(3,4); CE_(6,13); CE_(8,14); CE_(10,15); CE_(11,12);
;     CE_(0,1); CE_(2,3); CE_(4,5); CE_(6,8); CE_(7,9); CE_(10,11); CE_(12,13); CE_(14,15);
;     CE_(0,2); CE_(1,3); CE_(4,10); CE_(5,11); CE_(6,7); CE_(8,9); CE_(12,14); CE_(13,15);
;     CE_(1,2); CE_(3,12); CE_(4,6); CE_(5,7); CE_(8,10); CE_(9,11); CE_(13,14);
;     CE_(1,4); CE_(2,6); CE_(5,8); CE_(7,10); CE_(9,13); CE_(11,14);
;     CE_(2,4); CE_(3,6); CE_(9,12); CE_(11,13);
;     CE_(3,5); CE_(6,8); CE_(7,9); CE_(10,12);
;     CE_(3,4); CE_(5,6); CE_(7,8); CE_(9,10); CE_(11,12);
;     CE_(6,7); CE_(8,9);
;     ...
; }
; __device__ __forceinline__ void route_task(int task, int tl0, const bf16* QP  , const LAS bf16* KHL, LAS unsigned short* EL, LAS float* GL, int lane) {
;     ...
;         for (int kt = 0; kt < 4; ++kt) {
;             f32x16 X;
; #pragma unroll
;             for (int i = 0; i < 16; ++i) X[i] = 8.f;
;             const LAS bf16* khp = KHL + (half * 128 + 32 * kt + r) * 72 + 8 * hi;
; #pragma unroll
;             for (int ks = 0; ks < 4; ++ks) {
;                 const bf16x8 kh = lds8(khp + 16 * ks);
;                 X = MFMA32(kh, qa[half][ks], X);
;             }
;             int grp[16];
; #pragma unroll
;             for (int i = 0; i < 16; ++i) grp[i] = (int)((__float_as_uint(X[i]) | 127u) - (unsigned)(32 * kt + (i & 3) + 8 * (i >> 2)));
;             sort16_desc(grp);
;             if (kt == 0) {
; #pragma unroll
;                 for (int i = 0; i < 16; ++i) cur[i] = grp[i];
;             } else merge16_desc(cur, grp);
	v_mfma_f32_32x32x16_bf16 v[34:49], v[54:57], v[74:77], v[34:49]
	s_waitcnt vmcnt(1) lgkmcnt(1)
	v_mfma_f32_32x32x16_bf16 v[34:49], v[50:53], v[70:73], v[34:49]
	global_load_dwordx4 v[62:65], v[128:129], off offset:128
	global_load_dwordx4 v[58:61], v[128:129], off offset:160
	global_load_dwordx4 v[54:57], v[128:129], off offset:192
	global_load_dwordx4 v[50:53], v[128:129], off offset:224
	s_waitcnt vmcnt(4) lgkmcnt(0)
	v_mfma_f32_32x32x16_bf16 v[34:49], v[124:127], v[66:69], v[34:49]
	s_nop 11
	v_bitop3_b32 v37, v37, s42, 3 bitop3:0x56
	v_bitop3_b32 v48, v48, s42, 26 bitop3:0x56
	v_bitop3_b32 v38, v38, s42, 8 bitop3:0x56
	v_bitop3_b32 v42, v42, s42, 16 bitop3:0x56
	v_bitop3_b32 v47, v47, s42, 25 bitop3:0x56
	v_bitop3_b32 v39, v39, s42, 9 bitop3:0x56
	v_bitop3_b32 v40, v40, s42, 10 bitop3:0x56
	v_bitop3_b32 v43, v43, s42, 17 bitop3:0x56
	v_bitop3_b32 v44, v44, s42, 18 bitop3:0x56
	v_bitop3_b32 v36, v36, s42, 2 bitop3:0x56
	v_bitop3_b32 v49, v49, s42, 27 bitop3:0x56
	v_bitop3_b32 v41, v41, s42, 11 bitop3:0x56
	v_bitop3_b32 v45, v45, s42, 19 bitop3:0x56
	v_bitop3_b32 v35, v35, s42, 1 bitop3:0x56
	v_bitop3_b32 v46, v46, s42, 24 bitop3:0x56
	v_or_b32_e32 v34, 0x7f, v34
	v_max_i32_e32 v82, v37, v48
	v_max_i32_e32 v124, v38, v42
	v_max_i32_e32 v126, v34, v47
	v_max_i32_e32 v127, v39, v40
	v_min_i32_e32 v130, v43, v44
	v_min_i32_e32 v131, v36, v49
	v_min_i32_e32 v133, v41, v45
	v_min_i32_e32 v134, v35, v46
	v_min_i32_e32 v39, v39, v40
	v_min_i32_e32 v34, v34, v47
	v_min_i32_e32 v38, v38, v42
	v_min_i32_e32 v37, v37, v48
	v_max_i32_e32 v35, v35, v46
	v_max_i32_e32 v41, v41, v45
	v_max_i32_e32 v36, v36, v49
	v_max_i32_e32 v43, v43, v44
	v_min_i32_e32 v125, v82, v124
	v_min_i32_e32 v128, v126, v127
	v_max_i32_e32 v132, v130, v131
	v_max_i32_e32 v135, v133, v134
	v_max_i32_e32 v40, v39, v34
	v_max_i32_e32 v42, v38, v37
	v_min_i32_e32 v45, v35, v41
	v_min_i32_e32 v44, v36, v43
	v_min_i32_e32 v129, v125, v128
	v_max_i32_e32 v47, v40, v42
	v_max_i32_e32 v46, v45, v44
	v_min_i32_e32 v40, v40, v42
	v_min_i32_e32 v42, v45, v44
	v_max_i32_e32 v45, v125, v128
	v_max_i32_e32 v125, v132, v135
	v_min_i32_e32 v128, v45, v125
	v_min_i32_e32 v34, v39, v34
	v_max_i32_e32 v39, v126, v127
	v_max_i32_e32 v35, v35, v41
	v_max_i32_e32 v41, v82, v124
	v_max_i32_e32 v148, v45, v125
	ds_read_b128 v[124:127], v95
	v_max_i32_e32 v44, v40, v42
	v_min_i32_e32 v138, v40, v42
	v_min_i32_e32 v40, v133, v134
	v_min_i32_e32 v37, v38, v37
	v_min_i32_e32 v38, v130, v131
	v_max_i32_e32 v36, v36, v43
	v_min_i32_e32 v136, v132, v135
	v_min_i32_e32 v133, v40, v34
	v_min_i32_e32 v134, v37, v38
	v_max_i32_e32 v34, v40, v34
	v_max_i32_e32 v37, v37, v38
	v_min_i32_e32 v40, v39, v35
	v_min_i32_e32 v42, v36, v41
	v_max_i32_e32 v144, v39, v35
	v_max_i32_e32 v145, v36, v41
	v_max_i32_e32 v137, v129, v136
	v_min_i32_e32 v136, v129, v136
	v_max_i32_e32 v140, v133, v134
	v_min_i32_e32 v141, v34, v37
	v_max_i32_e32 v143, v40, v42
	v_min_i32_e32 v146, v144, v145
	v_max_i32_e32 v149, v47, v46
	v_min_i32_e32 v48, v47, v46
	v_max_i32_e32 v139, v138, v136
	v_max_i32_e32 v142, v140, v141
	v_min_i32_e32 v43, v40, v42
	v_max_i32_e32 v34, v34, v37
	v_min_i32_e32 v147, v143, v146
	v_min_i32_e32 v150, v148, v149
	v_min_i32_e32 v49, v137, v48
	v_min_i32_e32 v132, v44, v128
	v_max_i32_e32 v38, v139, v142
	v_min_i32_e32 v37, v43, v34
	v_max_i32_e32 v34, v43, v34
	v_min_i32_e32 v35, v147, v150
	v_max_i32_e32 v39, v137, v48
	v_max_i32_e32 v40, v44, v128
	v_max_i32_e32 v135, v49, v132
	v_max_i32_e32 v82, v38, v37
	v_min_i32_e32 v36, v34, v35
	v_min_i32_e32 v41, v39, v40
	v_max_i32_e32 v129, v135, v82
	v_min_i32_e32 v42, v36, v41
	v_min_i32_e32 v137, v129, v42
	v_max_i32_e32 v159, v129, v42
	ds_read_b128 v[128:131], v95 offset:32
	v_min_i32_e32 v82, v135, v82
	v_min_i32_e32 v132, v49, v132
	v_min_i32_e32 v135, v38, v37
	v_max_i32_e32 v154, v34, v35
	v_max_i32_e32 v155, v39, v40
	v_max_i32_e32 v157, v36, v41
	s_waitcnt lgkmcnt(1)
	v_mfma_f32_32x32x16_bf16 v[34:49], v[124:127], v[78:81], v[18:33]
	ds_read_b128 v[124:127], v95 offset:64
	v_max_i32_e32 v151, v132, v135
	v_max_i32_e32 v152, v82, v151
	v_min_i32_e32 v136, v138, v136
	v_min_i32_e32 v138, v140, v141
	v_min_i32_e32 v82, v82, v151
	v_max_i32_e32 v147, v147, v150
	s_waitcnt lgkmcnt(1)
	v_mfma_f32_32x32x16_bf16 v[34:49], v[128:131], v[74:77], v[34:49]
	ds_read_b128 v[128:131], v95 offset:96
	v_max_i32_e32 v143, v143, v146
	v_min_i32_e32 v133, v133, v134
	v_min_i32_e32 v156, v154, v155
	v_max_i32_e32 v140, v136, v138
	v_min_i32_e32 v139, v139, v142
	v_max_i32_e32 v142, v154, v155
	s_waitcnt lgkmcnt(1)
	v_mfma_f32_32x32x16_bf16 v[34:49], v[124:127], v[70:73], v[34:49]
	v_max_i32_e32 v124, v148, v149
	v_min_i32_e32 v136, v136, v138
	v_max_i32_e32 v141, v140, v139
	v_min_i32_e32 v139, v140, v139
	v_min_i32_e32 v125, v143, v124
	v_min_i32_e32 v158, v156, v157
	v_min_i32_e32 v132, v132, v135
	s_waitcnt lgkmcnt(0)
; #define LAS __attribute__((address_space(3)))
; #define MFMA32(a, b, c) __builtin_amdgcn_mfma_f32_32x32x16_bf16((a), (b), (c), 0, 0, 0)
; #define CE_(a, b) ce_desc(v[a], v[b])
; __device__ __forceinline__ void sort16_desc(int (&v)[16]) {
;     ...
;     CE_(0,13); CE_(1,12); CE_(2,15); CE_(3,14); CE_(4,8); CE_(5,6); CE_(7,11); CE_(9,10);
;     CE_(0,5); CE_(1,7); CE_(2,9); CE_(3,4); CE_(6,13); CE_(8,14); CE_(10,15); CE_(11,12);
;     CE_(0,1); CE_(2,3); CE_(4,5); CE_(6,8); CE_(7,9); CE_(10,11); CE_(12,13); CE_(14,15);
;     CE_(0,2); CE_(1,3); CE_(4,10); CE_(5,11); CE_(6,7); CE_(8,9); CE_(12,14); CE_(13,15);
;     CE_(1,2); CE_(3,12); CE_(4,6); CE_(5,7); CE_(8,10); CE_(9,11); CE_(13,14);
;     CE_(1,4); CE_(2,6); CE_(5,8); CE_(7,10); CE_(9,13); CE_(11,14);
;     CE_(2,4); CE_(3,6); CE_(9,12); CE_(11,13);
;     CE_(3,5); CE_(6,8); CE_(7,9); CE_(10,12);
;     CE_(3,4); CE_(5,6); CE_(7,8); CE_(9,10); CE_(11,12);
;     CE_(6,7); CE_(8,9);
;     ...
; }
; __device__ __forceinline__ void merge16_desc(int (&a)[16], const int (&b)[16]) {
; #pragma unroll
;     for (int i = 0; i < 16; ++i) a[i] = a[i] > b[15 - i] ? a[i] : b[15 - i];
; #pragma unroll
;     for (int j = 8; j > 0; j >>= 1)
; #pragma unroll
;         for (int i = 0; i < 16; ++i) { const int l = i ^ j; if (l > i) ce_desc(a[i], a[l]); }
; }
; __device__ __forceinline__ void route_task(int task, int tl0, const bf16* QP  , const LAS bf16* KHL, LAS unsigned short* EL, LAS float* GL, int lane) {
;     ...
;         for (int kt = 0; kt < 4; ++kt) {
;             f32x16 X;
; #pragma unroll
;             for (int i = 0; i < 16; ++i) X[i] = 8.f;
;             const LAS bf16* khp = KHL + (half * 128 + 32 * kt + r) * 72 + 8 * hi;
; #pragma unroll
;             for (int ks = 0; ks < 4; ++ks) {
;                 const bf16x8 kh = lds8(khp + 16 * ks);
;                 X = MFMA32(kh, qa[half][ks], X);
;             }
;             int grp[16];
; #pragma unroll
;             for (int i = 0; i < 16; ++i) grp[i] = (int)((__float_as_uint(X[i]) | 127u) - (unsigned)(32 * kt + (i & 3) + 8 * (i >> 2)));
;             sort16_desc(grp);
;             if (kt == 0) {
; #pragma unroll
;                 for (int i = 0; i < 16; ++i) cur[i] = grp[i];
;             } else merge16_desc(cur, grp);
	v_mfma_f32_32x32x16_bf16 v[34:49], v[128:131], v[66:69], v[34:49]
	v_min_i32_e32 v126, v147, v125
	v_min_i32_e32 v153, v137, v152
	v_min_i32_e32 v160, v158, v159
	v_min_i32_e32 v135, v141, v132
	v_min_i32_e32 v127, v142, v126
	s_nop 6
	v_bitop3_b32 v37, v37, s42, 35 bitop3:0x56
	v_bitop3_b32 v48, v48, s42, 58 bitop3:0x56
	v_bitop3_b32 v38, v38, s42, 40 bitop3:0x56
	v_bitop3_b32 v42, v42, s42, 48 bitop3:0x56
	v_bitop3_b32 v34, v34, s42, 32 bitop3:0x56
	v_bitop3_b32 v47, v47, s42, 57 bitop3:0x56
	v_bitop3_b32 v39, v39, s42, 41 bitop3:0x56
	v_bitop3_b32 v40, v40, s42, 42 bitop3:0x56
	v_bitop3_b32 v43, v43, s42, 49 bitop3:0x56
	v_bitop3_b32 v44, v44, s42, 50 bitop3:0x56
	v_bitop3_b32 v36, v36, s42, 34 bitop3:0x56
	v_bitop3_b32 v49, v49, s42, 59 bitop3:0x56
	v_bitop3_b32 v41, v41, s42, 43 bitop3:0x56
	v_bitop3_b32 v45, v45, s42, 51 bitop3:0x56
	v_bitop3_b32 v35, v35, s42, 33 bitop3:0x56
	v_bitop3_b32 v46, v46, s42, 56 bitop3:0x56
	v_max_i32_e32 v128, v37, v48
	v_max_i32_e32 v129, v38, v42
	v_max_i32_e32 v131, v34, v47
	v_max_i32_e32 v134, v39, v40
	v_min_i32_e32 v146, v43, v44
	v_min_i32_e32 v148, v36, v49
	v_min_i32_e32 v150, v41, v45
	v_min_i32_e32 v151, v35, v46
	v_min_i32_e32 v39, v39, v40
	v_min_i32_e32 v34, v34, v47
	v_min_i32_e32 v38, v38, v42
	v_min_i32_e32 v37, v37, v48
	v_max_i32_e32 v35, v35, v46
	v_max_i32_e32 v41, v41, v45
	v_max_i32_e32 v36, v36, v49
	v_max_i32_e32 v43, v43, v44
	v_min_i32_e32 v130, v128, v129
	v_min_i32_e32 v138, v131, v134
	v_max_i32_e32 v149, v146, v148
	v_max_i32_e32 v154, v150, v151
	v_max_i32_e32 v40, v39, v34
	v_max_i32_e32 v42, v38, v37
	v_min_i32_e32 v45, v35, v41
	v_min_i32_e32 v44, v36, v43
	v_min_i32_e32 v150, v150, v151
	v_min_i32_e32 v34, v39, v34
	v_min_i32_e32 v37, v38, v37
	v_min_i32_e32 v38, v146, v148
	v_max_i32_e32 v131, v131, v134
	v_max_i32_e32 v35, v35, v41
	v_max_i32_e32 v36, v36, v43
	v_max_i32_e32 v43, v128, v129
	v_min_i32_e32 v140, v130, v138
	v_min_i32_e32 v155, v149, v154
	v_max_i32_e32 v47, v40, v42
	v_max_i32_e32 v46, v45, v44
	v_min_i32_e32 v40, v40, v42
	v_min_i32_e32 v42, v45, v44
	v_max_i32_e32 v45, v130, v138
	v_max_i32_e32 v130, v149, v154
	v_min_i32_e32 v39, v150, v34
	v_min_i32_e32 v146, v37, v38
	v_max_i32_e32 v34, v150, v34
	v_max_i32_e32 v37, v37, v38
	v_min_i32_e32 v41, v131, v35
	v_min_i32_e32 v128, v36, v43
	v_max_i32_e32 v35, v131, v35
	v_max_i32_e32 v36, v36, v43
	v_min_i32_e32 v48, v47, v46
	v_max_i32_e32 v44, v40, v42
	v_min_i32_e32 v138, v45, v130
	v_min_i32_e32 v40, v40, v42
	v_min_i32_e32 v42, v140, v155
	v_max_i32_e32 v148, v39, v146
	v_min_i32_e32 v38, v34, v37
	v_min_i32_e32 v129, v41, v128
	v_max_i32_e32 v41, v41, v128
	v_min_i32_e32 v43, v35, v36
	v_max_i32_e32 v45, v45, v130
	v_max_i32_e32 v46, v47, v46
	v_max_i32_e32 v161, v140, v155
	v_max_i32_e32 v140, v40, v42
	v_max_i32_e32 v150, v148, v38
	v_max_i32_e32 v34, v34, v37
	v_min_i32_e32 v128, v41, v43
	v_min_i32_e32 v47, v45, v46
	v_min_i32_e32 v49, v161, v48
	v_min_i32_e32 v149, v44, v138
	v_max_i32_e32 v151, v140, v150
	v_min_i32_e32 v37, v129, v34
	v_max_i32_e32 v34, v129, v34
	v_min_i32_e32 v129, v128, v47
	v_max_i32_e32 v48, v161, v48
	v_max_i32_e32 v44, v44, v138
	v_max_i32_e32 v154, v49, v149
	v_max_i32_e32 v134, v151, v37
	v_min_i32_e32 v130, v34, v129
	v_min_i32_e32 v131, v48, v44
	v_min_i32_e32 v49, v49, v149
	v_min_i32_e32 v37, v151, v37
	v_max_i32_e32 v34, v34, v129
	v_max_i32_e32 v44, v48, v44
	v_min_i32_e32 v40, v40, v42
	v_min_i32_e32 v38, v148, v38
	v_max_i32_e32 v41, v41, v43
	v_max_i32_e32 v43, v45, v46
	v_max_i32_e32 v155, v154, v134
	v_min_i32_e32 v138, v130, v131
	v_min_i32_e32 v134, v154, v134
	v_max_i32_e32 v149, v49, v37
	v_min_i32_e32 v48, v34, v44
	v_max_i32_e32 v129, v130, v131
	v_max_i32_e32 v42, v40, v38
	v_min_i32_e32 v140, v140, v150
	v_max_i32_e32 v34, v34, v44
	v_max_i32_e32 v44, v128, v47
	v_min_i32_e32 v45, v41, v43
	v_min_i32_e32 v161, v155, v138
	v_max_i32_e32 v151, v134, v149
	v_min_i32_e32 v130, v48, v129
	v_max_i32_e32 v131, v155, v138
	v_max_i32_e32 v148, v42, v140
	v_min_i32_e32 v37, v49, v37
	v_min_i32_e32 v46, v44, v45
	v_min_i32_e32 v154, v161, v151
	v_min_i32_e32 v138, v130, v131
	v_min_i32_e32 v49, v148, v37
	v_min_i32_e32 v134, v134, v149
	v_min_i32_e32 v47, v34, v46
	v_min_i32_e32 v42, v42, v140
	v_min_i32_e32 v38, v40, v38
	v_min_i32_e32 v39, v39, v146
	v_max3_i32 v39, v144, v145, v39
	v_max3_i32 v38, v143, v124, v38
	v_max3_i32 v40, v147, v125, v42
	v_max3_i32 v42, v142, v126, v49
	v_max3_i32 v37, v127, v148, v37
	v_max3_i32 v49, v156, v157, v134
	v_max3_i32 v124, v158, v159, v154
	v_max3_i32 v125, v160, v161, v151
	v_max3_i32 v126, v137, v152, v138
	v_max3_i32 v127, v153, v130, v131
	v_max3_i32 v48, v82, v48, v129
	v_max3_i32 v47, v141, v132, v47
	v_max3_i32 v34, v135, v34, v46
	v_max3_i32 v44, v139, v44, v45
	v_max3_i32 v41, v136, v41, v43
	v_max3_i32 v35, v133, v35, v36
	v_max_i32_e32 v36, v39, v126
	v_min_i32_e32 v39, v39, v126
	v_max_i32_e32 v43, v38, v127
	v_min_i32_e32 v38, v38, v127
	v_max_i32_e32 v45, v40, v48
	v_min_i32_e32 v40, v40, v48
	v_max_i32_e32 v46, v42, v47
	v_min_i32_e32 v42, v42, v47
	v_max_i32_e32 v47, v37, v34
	v_min_i32_e32 v34, v37, v34
	v_max_i32_e32 v37, v49, v44
	v_min_i32_e32 v44, v49, v44
	v_max_i32_e32 v48, v124, v41
	v_min_i32_e32 v41, v124, v41
	v_max_i32_e32 v49, v125, v35
	v_min_i32_e32 v35, v125, v35
	ds_read_b128 v[124:127], v94 offset:9216
	ds_read_b128 v[128:131], v94 offset:9248
	v_max_i32_e32 v82, v36, v47
	v_min_i32_e32 v132, v36, v47
	v_max_i32_e32 v36, v43, v37
	v_min_i32_e32 v133, v43, v37
	v_max_i32_e32 v37, v45, v48
	v_max_i32_e32 v43, v46, v49
	v_min_i32_e32 v134, v45, v48
	v_min_i32_e32 v135, v46, v49
	v_max_i32_e32 v136, v39, v34
	v_min_i32_e32 v137, v39, v34
	v_max_i32_e32 v138, v38, v44
	v_min_i32_e32 v139, v38, v44
	v_max_i32_e32 v140, v40, v41
	v_min_i32_e32 v141, v40, v41
	v_max_i32_e32 v142, v42, v35
	v_min_i32_e32 v143, v42, v35
	v_max_i32_e32 v144, v82, v37
	v_min_i32_e32 v82, v82, v37
	v_max_i32_e32 v145, v36, v43
	v_min_i32_e32 v146, v36, v43
	s_waitcnt lgkmcnt(1)
; #define LAS __attribute__((address_space(3)))
; #define MFMA32(a, b, c) __builtin_amdgcn_mfma_f32_32x32x16_bf16((a), (b), (c), 0, 0, 0)
; #define CE_(a, b) ce_desc(v[a], v[b])
; __device__ __forceinline__ void sort16_desc(int (&v)[16]) {
;     ...
;     CE_(0,13); CE_(1,12); CE_(2,15); CE_(3,14); CE_(4,8); CE_(5,6); CE_(7,11); CE_(9,10);
;     CE_(0,5); CE_(1,7); CE_(2,9); CE_(3,4); CE_(6,13); CE_(8,14); CE_(10,15); CE_(11,12);
;     CE_(0,1); CE_(2,3); CE_(4,5); CE_(6,8); CE_(7,9); CE_(10,11); CE_(12,13); CE_(14,15);
;     CE_(0,2); CE_(1,3); CE_(4,10); CE_(5,11); CE_(6,7); CE_(8,9); CE_(12,14); CE_(13,15);
;     CE_(1,2); CE_(3,12); CE_(4,6); CE_(5,7); CE_(8,10); CE_(9,11); CE_(13,14);
;     CE_(1,4); CE_(2,6); CE_(5,8); CE_(7,10); CE_(9,13); CE_(11,14);
;     CE_(2,4); CE_(3,6); CE_(9,12); CE_(11,13);
;     CE_(3,5); CE_(6,8); CE_(7,9); CE_(10,12);
;     CE_(3,4); CE_(5,6); CE_(7,8); CE_(9,10); CE_(11,12);
;     CE_(6,7); CE_(8,9);
;     ...
; }
; __device__ __forceinline__ void merge16_desc(int (&a)[16], const int (&b)[16]) {
; #pragma unroll
;     for (int i = 0; i < 16; ++i) a[i] = a[i] > b[15 - i] ? a[i] : b[15 - i];
; #pragma unroll
;     for (int j = 8; j > 0; j >>= 1)
; #pragma unroll
;         for (int i = 0; i < 16; ++i) { const int l = i ^ j; if (l > i) ce_desc(a[i], a[l]); }
; }
; __device__ __forceinline__ void route_task(int task, int tl0, const bf16* QP  , const LAS bf16* KHL, LAS unsigned short* EL, LAS float* GL, int lane) {
;     ...
;         for (int kt = 0; kt < 4; ++kt) {
;             f32x16 X;
; #pragma unroll
;             for (int i = 0; i < 16; ++i) X[i] = 8.f;
;             const LAS bf16* khp = KHL + (half * 128 + 32 * kt + r) * 72 + 8 * hi;
; #pragma unroll
;             for (int ks = 0; ks < 4; ++ks) {
;                 const bf16x8 kh = lds8(khp + 16 * ks);
;                 X = MFMA32(kh, qa[half][ks], X);
;             }
;             int grp[16];
; #pragma unroll
;             for (int i = 0; i < 16; ++i) grp[i] = (int)((__float_as_uint(X[i]) | 127u) - (unsigned)(32 * kt + (i & 3) + 8 * (i >> 2)));
;             sort16_desc(grp);
;             if (kt == 0) {
; #pragma unroll
;                 for (int i = 0; i < 16; ++i) cur[i] = grp[i];
;             } else merge16_desc(cur, grp);
	v_mfma_f32_32x32x16_bf16 v[34:49], v[124:127], v[78:81], v[18:33]
	ds_read_b128 v[124:127], v94 offset:9280
	v_max_i32_e32 v147, v132, v134
	v_min_i32_e32 v132, v132, v134
	v_max_i32_e32 v134, v133, v135
	v_min_i32_e32 v133, v133, v135
	v_max_i32_e32 v135, v136, v140
	v_min_i32_e32 v136, v136, v140
	s_waitcnt lgkmcnt(1)
	v_mfma_f32_32x32x16_bf16 v[34:49], v[128:131], v[74:77], v[34:49]
	ds_read_b128 v[128:131], v94 offset:9312
	v_max_i32_e32 v140, v138, v142
	v_min_i32_e32 v138, v138, v142
	v_max_i32_e32 v142, v137, v141
	v_min_i32_e32 v137, v137, v141
	v_max_i32_e32 v141, v139, v143
	v_min_i32_e32 v139, v139, v143
	s_waitcnt lgkmcnt(1)
	v_mfma_f32_32x32x16_bf16 v[34:49], v[124:127], v[70:73], v[34:49]
	v_min_i32_e32 v143, v144, v145
	v_min_i32_e32 v124, v82, v146
	v_min_i32_e32 v127, v135, v140
	v_min_i32_e32 v125, v147, v134
	v_min_i32_e32 v126, v132, v133
	v_min_i32_e32 v149, v142, v141
	v_min_i32_e32 v148, v136, v138
	s_waitcnt lgkmcnt(0)
	v_mfma_f32_32x32x16_bf16 v[34:49], v[128:131], v[66:69], v[34:49]
	v_min_i32_e32 v150, v137, v139
	s_nop 10
	v_and_or_b32 v37, v37, s43, 60
	v_and_or_b32 v48, v48, s43, 37
	v_and_or_b32 v38, v38, s43, 55
	v_and_or_b32 v42, v42, s43, 47
	v_bitop3_b32 v34, v34, s42, 64 bitop3:0x56
	v_and_or_b32 v47, v47, s43, 38
	v_and_or_b32 v39, v39, s43, 54
	v_and_or_b32 v40, v40, s43, 53
	v_and_or_b32 v43, v43, s43, 46
	v_and_or_b32 v44, v44, s43, 45
	v_and_or_b32 v36, v36, s43, 61
	v_and_or_b32 v49, v49, s43, 36
	v_and_or_b32 v41, v41, s43, 52
	v_and_or_b32 v45, v45, s43, 44
	v_and_or_b32 v35, v35, s43, 62
	v_and_or_b32 v46, v46, s43, 39
	v_max_i32_e32 v128, v37, v48
	v_max_i32_e32 v129, v38, v42
	v_max_i32_e32 v131, v34, v47
	v_max_i32_e32 v151, v39, v40
	v_min_i32_e32 v154, v43, v44
	v_min_i32_e32 v155, v36, v49
	v_min_i32_e32 v157, v41, v45
	v_min_i32_e32 v158, v35, v46
	v_min_i32_e32 v39, v39, v40
	v_min_i32_e32 v34, v34, v47
	v_min_i32_e32 v38, v38, v42
	v_min_i32_e32 v37, v37, v48
	v_max_i32_e32 v35, v35, v46
	v_max_i32_e32 v41, v41, v45
	v_max_i32_e32 v36, v36, v49
	v_max_i32_e32 v43, v43, v44
	v_min_i32_e32 v130, v128, v129
	v_min_i32_e32 v152, v131, v151
	v_max_i32_e32 v156, v154, v155
	v_max_i32_e32 v159, v157, v158
	v_max_i32_e32 v40, v39, v34
	v_max_i32_e32 v42, v38, v37
	v_min_i32_e32 v45, v35, v41
	v_min_i32_e32 v44, v36, v43
	v_min_i32_e32 v157, v157, v158
	v_min_i32_e32 v34, v39, v34
	v_min_i32_e32 v37, v38, v37
	v_min_i32_e32 v38, v154, v155
	v_max_i32_e32 v131, v131, v151
	v_max_i32_e32 v35, v35, v41
	v_max_i32_e32 v36, v36, v43
	v_max_i32_e32 v43, v128, v129
	v_min_i32_e32 v153, v130, v152
	v_min_i32_e32 v160, v156, v159
	v_max_i32_e32 v47, v40, v42
	v_max_i32_e32 v46, v45, v44
	v_min_i32_e32 v40, v40, v42
	v_min_i32_e32 v42, v45, v44
	v_max_i32_e32 v45, v130, v152
	v_max_i32_e32 v130, v156, v159
	v_min_i32_e32 v39, v157, v34
	v_min_i32_e32 v154, v37, v38
	v_max_i32_e32 v34, v157, v34
	v_max_i32_e32 v37, v37, v38
	v_min_i32_e32 v41, v131, v35
	v_min_i32_e32 v128, v36, v43
	v_max_i32_e32 v35, v131, v35
	v_max_i32_e32 v36, v36, v43
	v_min_i32_e32 v48, v47, v46
	v_max_i32_e32 v44, v40, v42
	v_min_i32_e32 v152, v45, v130
	v_min_i32_e32 v40, v40, v42
	v_min_i32_e32 v42, v153, v160
	v_max_i32_e32 v155, v39, v154
	v_min_i32_e32 v38, v34, v37
	v_min_i32_e32 v129, v41, v128
	v_max_i32_e32 v41, v41, v128
	v_min_i32_e32 v43, v35, v36
	v_max_i32_e32 v45, v45, v130
	v_max_i32_e32 v46, v47, v46
	v_max_i32_e32 v161, v153, v160
	v_max_i32_e32 v153, v40, v42
	v_max_i32_e32 v157, v155, v38
	v_max_i32_e32 v34, v34, v37
	v_min_i32_e32 v128, v41, v43
	v_min_i32_e32 v47, v45, v46
	v_min_i32_e32 v49, v161, v48
	v_min_i32_e32 v156, v44, v152
	v_max_i32_e32 v158, v153, v157
	v_min_i32_e32 v37, v129, v34
	v_max_i32_e32 v34, v129, v34
	v_min_i32_e32 v129, v128, v47
	v_max_i32_e32 v48, v161, v48
	v_max_i32_e32 v44, v44, v152
	v_min_i32_e32 v40, v40, v42
	v_min_i32_e32 v38, v155, v38
	v_max_i32_e32 v159, v49, v156
	v_max_i32_e32 v151, v158, v37
	v_min_i32_e32 v130, v34, v129
	v_min_i32_e32 v131, v48, v44
	v_min_i32_e32 v49, v49, v156
	v_min_i32_e32 v37, v158, v37
	v_max_i32_e32 v34, v34, v129
	v_max_i32_e32 v44, v48, v44
	v_max_i32_e32 v42, v40, v38
	v_min_i32_e32 v153, v153, v157
	v_max_i32_e32 v160, v159, v151
	v_min_i32_e32 v152, v130, v131
	v_max_i32_e32 v156, v49, v37
	v_min_i32_e32 v48, v34, v44
	v_max_i32_e32 v129, v130, v131
	v_max_i32_e32 v155, v42, v153
	v_min_i32_e32 v37, v49, v37
	v_min_i32_e32 v151, v159, v151
	v_min_i32_e32 v130, v48, v129
	v_max_i32_e32 v131, v160, v152
	v_min_i32_e32 v49, v155, v37
	v_max_i32_e32 v41, v41, v43
	v_max_i32_e32 v43, v45, v46
	v_min_i32_e32 v42, v42, v153
	v_min_i32_e32 v38, v40, v38
	v_min_i32_e32 v161, v160, v152
	v_max_i32_e32 v158, v151, v156
	v_min_i32_e32 v151, v151, v156
	v_max_i32_e32 v34, v34, v44
	v_max_i32_e32 v44, v128, v47
	v_min_i32_e32 v45, v41, v43
	v_max_i32_e32 v40, v41, v43
	v_max_i32_e32 v38, v143, v38
	v_max3_i32 v41, v82, v146, v42
	v_max_i32_e32 v42, v124, v49
	v_max3_i32 v124, v127, v130, v131
	v_min_i32_e32 v46, v44, v45
	v_max_i32_e32 v43, v125, v151
	v_max3_i32 v49, v126, v161, v158
	v_max3_i32 v44, v149, v44, v45
	v_max_i32_e32 v45, v38, v124
	v_min_i32_e32 v38, v38, v124
	ds_read_b128 v[124:127], v96
	v_min_i32_e32 v159, v161, v158
	v_min_i32_e32 v152, v130, v131
	v_max_i32_e32 v37, v155, v37
	v_max_i32_e32 v48, v48, v129
	v_min_i32_e32 v47, v34, v46
	v_max_i32_e32 v34, v34, v46
	v_min_i32_e32 v39, v39, v154
	v_max3_i32 v39, v144, v145, v39
	v_max3_i32 v37, v147, v134, v37
	v_max3_i32 v46, v132, v133, v159
	v_max3_i32 v82, v135, v140, v152
	v_max3_i32 v48, v136, v138, v48
	v_max_i32_e32 v47, v148, v47
	v_max3_i32 v34, v142, v141, v34
	v_max3_i32 v40, v137, v139, v40
	v_max3_i32 v35, v150, v35, v36
	v_max_i32_e32 v36, v39, v82
	v_min_i32_e32 v39, v39, v82
	v_max_i32_e32 v82, v41, v48
	v_min_i32_e32 v41, v41, v48
	v_max_i32_e32 v48, v42, v47
	v_min_i32_e32 v42, v42, v47
	v_max_i32_e32 v47, v37, v34
	v_min_i32_e32 v34, v37, v34
	v_max_i32_e32 v37, v43, v44
	v_min_i32_e32 v43, v43, v44
	v_max_i32_e32 v44, v46, v40
	v_min_i32_e32 v40, v46, v40
	v_max_i32_e32 v46, v49, v35
	v_min_i32_e32 v35, v49, v35
	v_max_i32_e32 v49, v36, v47
	v_min_i32_e32 v132, v36, v47
	v_max_i32_e32 v36, v45, v37
	v_min_i32_e32 v133, v45, v37
	v_max_i32_e32 v37, v82, v44
	v_min_i32_e32 v82, v82, v44
	v_max_i32_e32 v44, v48, v46
	ds_read_b128 v[128:131], v96 offset:32
	v_min_i32_e32 v134, v48, v46
	v_max_i32_e32 v135, v39, v34
	v_min_i32_e32 v136, v39, v34
	v_max_i32_e32 v137, v38, v43
	v_min_i32_e32 v138, v38, v43
	v_max_i32_e32 v139, v41, v40
	v_min_i32_e32 v140, v41, v40
	v_max_i32_e32 v141, v42, v35
	v_min_i32_e32 v142, v42, v35
	v_max_i32_e32 v143, v49, v37
	v_min_i32_e32 v144, v49, v37
	v_max_i32_e32 v145, v36, v44
	v_min_i32_e32 v146, v36, v44
	s_waitcnt lgkmcnt(1)
; #define LAS __attribute__((address_space(3)))
; #define MFMA32(a, b, c) __builtin_amdgcn_mfma_f32_32x32x16_bf16((a), (b), (c), 0, 0, 0)
; #define CE_(a, b) ce_desc(v[a], v[b])
; __device__ __forceinline__ void sort16_desc(int (&v)[16]) {
;     ...
;     CE_(0,13); CE_(1,12); CE_(2,15); CE_(3,14); CE_(4,8); CE_(5,6); CE_(7,11); CE_(9,10);
;     CE_(0,5); CE_(1,7); CE_(2,9); CE_(3,4); CE_(6,13); CE_(8,14); CE_(10,15); CE_(11,12);
;     CE_(0,1); CE_(2,3); CE_(4,5); CE_(6,8); CE_(7,9); CE_(10,11); CE_(12,13); CE_(14,15);
;     CE_(0,2); CE_(1,3); CE_(4,10); CE_(5,11); CE_(6,7); CE_(8,9); CE_(12,14); CE_(13,15);
;     CE_(1,2); CE_(3,12); CE_(4,6); CE_(5,7); CE_(8,10); CE_(9,11); CE_(13,14);
;     CE_(1,4); CE_(2,6); CE_(5,8); CE_(7,10); CE_(9,13); CE_(11,14);
;     CE_(2,4); CE_(3,6); CE_(9,12); CE_(11,13);
;     CE_(3,5); CE_(6,8); CE_(7,9); CE_(10,12);
;     CE_(3,4); CE_(5,6); CE_(7,8); CE_(9,10); CE_(11,12);
;     CE_(6,7); CE_(8,9);
;     ...
; }
; __device__ __forceinline__ void merge16_desc(int (&a)[16], const int (&b)[16]) {
; #pragma unroll
;     for (int i = 0; i < 16; ++i) a[i] = a[i] > b[15 - i] ? a[i] : b[15 - i];
; #pragma unroll
;     for (int j = 8; j > 0; j >>= 1)
; #pragma unroll
;         for (int i = 0; i < 16; ++i) { const int l = i ^ j; if (l > i) ce_desc(a[i], a[l]); }
; }
; __device__ __forceinline__ void route_task(int task, int tl0, const bf16* QP  , const LAS bf16* KHL, LAS unsigned short* EL, LAS float* GL, int lane) {
;     ...
;         for (int kt = 0; kt < 4; ++kt) {
;             f32x16 X;
; #pragma unroll
;             for (int i = 0; i < 16; ++i) X[i] = 8.f;
;             const LAS bf16* khp = KHL + (half * 128 + 32 * kt + r) * 72 + 8 * hi;
; #pragma unroll
;             for (int ks = 0; ks < 4; ++ks) {
;                 const bf16x8 kh = lds8(khp + 16 * ks);
;                 X = MFMA32(kh, qa[half][ks], X);
;             }
;             int grp[16];
; #pragma unroll
;             for (int i = 0; i < 16; ++i) grp[i] = (int)((__float_as_uint(X[i]) | 127u) - (unsigned)(32 * kt + (i & 3) + 8 * (i >> 2)));
;             sort16_desc(grp);
;             if (kt == 0) {
; #pragma unroll
;                 for (int i = 0; i < 16; ++i) cur[i] = grp[i];
;             } else merge16_desc(cur, grp);
	v_mfma_f32_32x32x16_bf16 v[34:49], v[124:127], v[78:81], v[18:33]
	ds_read_b128 v[78:81], v96 offset:64
	v_max_i32_e32 v147, v132, v82
	v_min_i32_e32 v82, v132, v82
	v_max_i32_e32 v132, v137, v141
	v_max_i32_e32 v124, v133, v134
	v_min_i32_e32 v125, v133, v134
	v_max_i32_e32 v126, v135, v139
	s_waitcnt lgkmcnt(1)
	v_mfma_f32_32x32x16_bf16 v[34:49], v[128:131], v[74:77], v[34:49]
	ds_read_b128 v[74:77], v96 offset:96
	v_min_i32_e32 v128, v137, v141
	v_max_i32_e32 v129, v136, v140
	v_min_i32_e32 v130, v136, v140
	v_min_i32_e32 v127, v135, v139
	v_max_i32_e32 v131, v138, v142
	v_min_i32_e32 v133, v138, v142
	s_waitcnt lgkmcnt(1)
	v_mfma_f32_32x32x16_bf16 v[34:49], v[78:81], v[70:73], v[34:49]
	v_min_i32_e32 v134, v143, v145
	v_min_i32_e32 v70, v144, v146
	v_min_i32_e32 v71, v147, v124
	v_min_i32_e32 v72, v82, v125
	v_min_i32_e32 v73, v126, v132
	v_min_i32_e32 v78, v127, v128
	v_min_i32_e32 v79, v129, v131
	s_waitcnt lgkmcnt(0)
	v_mfma_f32_32x32x16_bf16 v[34:49], v[74:77], v[66:69], v[34:49]
	v_min_i32_e32 v80, v130, v133
	s_nop 10
	v_and_or_b32 v41, v41, s43, 20
	v_and_or_b32 v45, v45, s43, 12
	v_and_or_b32 v35, v35, s43, 30
	v_and_or_b32 v46, v46, s43, 7
	v_and_or_b32 v39, v39, s43, 22
	v_and_or_b32 v40, v40, s43, 21
	v_and_or_b32 v34, v34, s43, 31
	v_and_or_b32 v47, v47, s43, 6
	v_and_or_b32 v38, v38, s43, 23
	v_and_or_b32 v42, v42, s43, 15
	v_and_or_b32 v37, v37, s43, 28
	v_and_or_b32 v48, v48, s43, 5
	v_and_or_b32 v43, v43, s43, 14
	v_and_or_b32 v44, v44, s43, 13
	v_and_or_b32 v36, v36, s43, 29
	v_and_or_b32 v49, v49, s43, 4
	v_min_i32_e32 v66, v41, v45
	v_min_i32_e32 v67, v35, v46
	v_min_i32_e32 v69, v39, v40
	v_min_i32_e32 v74, v34, v47
	v_min_i32_e32 v77, v38, v42
	v_min_i32_e32 v81, v37, v48
	v_min_i32_e32 v136, v43, v44
	v_min_i32_e32 v137, v36, v49
	v_max_i32_e32 v34, v34, v47
	v_max_i32_e32 v39, v39, v40
	v_max_i32_e32 v35, v35, v46
	v_max_i32_e32 v41, v41, v45
	v_max_i32_e32 v36, v36, v49
	v_max_i32_e32 v43, v43, v44
	v_max_i32_e32 v37, v37, v48
	v_max_i32_e32 v38, v38, v42
	v_max_i32_e32 v40, v34, v39
	v_max_i32_e32 v45, v35, v41
	v_max_i32_e32 v44, v36, v43
	v_max_i32_e32 v42, v37, v38
	v_min_i32_e32 v46, v40, v45
	v_min_i32_e32 v47, v44, v42
	v_min_i32_e32 v75, v69, v74
	v_min_i32_e32 v48, v46, v47
	v_max_i32_e32 v46, v46, v47
	v_min_i32_e32 v37, v37, v38
	v_min_i32_e32 v34, v34, v39
	v_max_i32_e32 v39, v136, v137
	v_max_i32_e32 v47, v66, v67
	v_max_i32_e32 v69, v69, v74
	v_max_i32_e32 v74, v77, v81
	v_min_i32_e32 v35, v35, v41
	v_min_i32_e32 v36, v36, v43
	v_min_i32_e32 v68, v66, v67
	v_min_i32_e32 v135, v77, v81
	v_min_i32_e32 v138, v136, v137
	v_max_i32_e32 v38, v37, v34
	v_max_i32_e32 v77, v69, v74
	v_max_i32_e32 v41, v35, v36
	v_min_i32_e32 v34, v37, v34
	v_min_i32_e32 v37, v39, v47
	v_min_i32_e32 v76, v68, v75
	v_min_i32_e32 v139, v135, v138
	v_max_i32_e32 v49, v68, v75
	v_max_i32_e32 v68, v135, v138
	v_max_i32_e32 v40, v40, v45
	v_max_i32_e32 v42, v44, v42
	v_max_i32_e32 v66, v39, v47
	v_max_i32_e32 v43, v77, v41
	v_max_i32_e32 v39, v34, v37
	v_min_i32_e32 v41, v77, v41
	v_min_i32_e32 v69, v69, v74
	v_min_i32_e32 v35, v35, v36
	v_max_i32_e32 v75, v49, v68
	v_min_i32_e32 v44, v40, v42
	v_max_i32_e32 v67, v38, v66
	v_max_i32_e32 v47, v39, v41
	v_max_i32_e32 v36, v69, v35
	v_min_i32_e32 v39, v39, v41
	v_min_i32_e32 v35, v69, v35
	v_min_i32_e32 v34, v34, v37
	v_max_i32_e32 v41, v76, v139
	v_min_i32_e32 v49, v49, v68
	v_min_i32_e32 v45, v46, v44
	v_min_i32_e32 v81, v67, v43
	v_min_i32_e32 v38, v38, v66
	v_max_i32_e32 v37, v35, v34
	v_max_i32_e32 v68, v41, v49
	v_max_i32_e32 v135, v48, v75
	v_min_i32_e32 v136, v45, v81
	v_max_i32_e32 v66, v36, v38
	v_min_i32_e32 v36, v36, v38
	v_max_i32_e32 v69, v37, v68
	v_min_i32_e32 v48, v48, v75
	v_max_i32_e32 v137, v135, v136
	v_max_i32_e32 v74, v47, v66
	v_min_i32_e32 v135, v135, v136
	v_min_i32_e32 v47, v47, v66
	v_max_i32_e32 v38, v39, v36
	v_max_i32_e32 v75, v69, v48
	v_min_i32_e32 v34, v35, v34
	v_min_i32_e32 v35, v41, v49
	v_min_i32_e32 v36, v39, v36
	v_min_i32_e32 v39, v69, v48
	v_max_i32_e32 v44, v46, v44
	v_max_i32_e32 v43, v67, v43
	v_min_i32_e32 v140, v76, v139
	v_min_i32_e32 v77, v137, v74
	v_max_i32_e32 v66, v135, v47
	v_max_i32_e32 v76, v38, v75
	v_min_i32_e32 v47, v135, v47
	v_max_i32_e32 v41, v34, v35
	v_min_i32_e32 v37, v37, v68
	v_min_i32_e32 v48, v36, v39
	v_max_i32_e32 v45, v45, v81
	v_min_i32_e32 v46, v44, v43
	v_min_i32_e32 v38, v38, v75
	v_max_i32_e32 v36, v36, v39
	v_min_i32_e32 v136, v77, v66
	v_max_i32_e32 v135, v76, v47
	v_max_i32_e32 v49, v41, v37
	v_max_i32_e32 v69, v137, v74
	v_min_i32_e32 v67, v45, v46
	v_min_i32_e32 v47, v76, v47
	v_max_i32_e32 v39, v38, v36
	v_min_i32_e32 v138, v136, v135
	v_max_i32_e32 v68, v49, v48
	v_max_i32_e32 v74, v69, v67
	v_min_i32_e32 v37, v41, v37
	v_max_i32_e32 v41, v77, v66
	v_min_i32_e32 v75, v47, v39
	v_max_i32_e32 v43, v44, v43
	v_min_i32_e32 v34, v34, v35
	v_min_i32_e32 v36, v38, v36
	v_min_i32_e32 v48, v49, v48
	v_min_i32_e32 v49, v69, v67
	v_max3_i32 v140, v143, v145, v140
	v_max3_i32 v126, v126, v132, v138
	v_max3_i32 v68, v147, v124, v68
	v_max3_i32 v74, v129, v131, v74
	v_max3_i32 v37, v144, v146, v37
	v_max3_i32 v41, v127, v128, v41
	v_max3_i32 v75, v82, v125, v75
	v_max3_i32 v43, v130, v133, v43
	v_max_i32_e32 v34, v134, v34
	v_max3_i32 v35, v73, v136, v135
	v_max_i32_e32 v36, v71, v36
	v_max3_i32 v38, v79, v45, v46
	v_max_i32_e32 v48, v70, v48
	v_max_i32_e32 v49, v78, v49
	v_max3_i32 v39, v72, v47, v39
	v_max3_i32 v40, v80, v40, v42
	v_min_i32_e32 v81, v68, v74
	v_min_i32_e32 v66, v37, v41
	v_min_i32_e32 v73, v34, v35
	v_min_i32_e32 v45, v36, v38
	v_min_i32_e32 v42, v39, v40
	v_max_i32_e32 v71, v140, v126
; #define CE_(a, b) ce_desc(v[a], v[b])
; __device__ __forceinline__ void sort16_desc(int (&v)[16]) {
;     ...
;     CE_(0,13); CE_(1,12); CE_(2,15); CE_(3,14); CE_(4,8); CE_(5,6); CE_(7,11); CE_(9,10);
;     CE_(0,5); CE_(1,7); CE_(2,9); CE_(3,4); CE_(6,13); CE_(8,14); CE_(10,15); CE_(11,12);
;     CE_(0,1); CE_(2,3); CE_(4,5); CE_(6,8); CE_(7,9); CE_(10,11); CE_(12,13); CE_(14,15);
;     CE_(0,2); CE_(1,3); CE_(4,10); CE_(5,11); CE_(6,7); CE_(8,9); CE_(12,14); CE_(13,15);
;     CE_(1,2); CE_(3,12); CE_(4,6); CE_(5,7); CE_(8,10); CE_(9,11); CE_(13,14);
;     CE_(1,4); CE_(2,6); CE_(5,8); CE_(7,10); CE_(9,13); CE_(11,14);
;     CE_(2,4); CE_(3,6); CE_(9,12); CE_(11,13);
;     CE_(3,5); CE_(6,8); CE_(7,9); CE_(10,12);
;     CE_(3,4); CE_(5,6); CE_(7,8); CE_(9,10); CE_(11,12);
;     CE_(6,7); CE_(8,9);
;     ...
; }
; __device__ __forceinline__ void merge16_desc(int (&a)[16], const int (&b)[16]) {
; #pragma unroll
;     for (int i = 0; i < 16; ++i) a[i] = a[i] > b[15 - i] ? a[i] : b[15 - i];
; #pragma unroll
;     for (int j = 8; j > 0; j >>= 1)
; #pragma unroll
;         for (int i = 0; i < 16; ++i) { const int l = i ^ j; if (l > i) ce_desc(a[i], a[l]); }
; }
; __device__ __forceinline__ void route_task(int task, int tl0, const bf16* QP  , const LAS bf16* KHL, LAS unsigned short* EL, LAS float* GL, int lane) {
;     ...
;         { const unsigned h4 = 4u * (unsigned)hi;
; #pragma unroll
;           for (int i = 0; i < 16; ++i) cur[i] -= (int)h4; }
;         int oth[16];
; #pragma unroll
;         for (int i = 0; i < 16; ++i) oth[i] = __shfl_xor(cur[i], 32);
;         merge16_desc(cur, oth);
; #pragma unroll
;         for (int i = 0; i < 16; ++i) top[half][i] = cur[i];
	v_max_i32_e32 v68, v68, v74
	v_max_i32_e32 v37, v37, v41
	v_max_i32_e32 v41, v75, v43
	v_max_i32_e32 v34, v34, v35
	v_max_i32_e32 v35, v36, v38
	v_max_i32_e32 v38, v48, v49
	v_max_i32_e32 v39, v39, v40
	v_min_i32_e32 v44, v75, v43
	v_max_i32_e32 v72, v71, v68
	v_max_i32_e32 v43, v37, v41
	v_max_i32_e32 v36, v34, v35
	v_max_i32_e32 v40, v38, v39
	v_min_i32_e32 v67, v48, v49
	v_max_i32_e32 v74, v72, v43
	v_max_i32_e32 v48, v36, v40
	v_min_i32_e32 v43, v72, v43
	v_min_i32_e32 v36, v36, v40
	v_max_i32_e32 v40, v43, v36
	v_min_i32_e32 v36, v43, v36
	v_min_i32_e32 v43, v71, v68
	v_min_i32_e32 v37, v37, v41
	v_min_i32_e32 v34, v34, v35
	v_min_i32_e32 v35, v38, v39
	v_min_i32_e32 v132, v140, v126
	v_max_i32_e32 v41, v43, v37
	v_max_i32_e32 v38, v34, v35
	v_min_i32_e32 v37, v43, v37
	v_min_i32_e32 v34, v34, v35
	v_min_i32_e32 v76, v66, v44
	v_min_i32_e32 v47, v67, v42
	v_max_i32_e32 v39, v41, v38
	v_min_i32_e32 v38, v41, v38
	v_max_i32_e32 v35, v37, v34
	v_min_i32_e32 v34, v37, v34
	v_max_i32_e32 v37, v132, v81
	v_max_i32_e32 v41, v66, v44
	v_max_i32_e32 v44, v73, v45
	v_max_i32_e32 v42, v67, v42
	v_min_i32_e32 v124, v132, v81
	v_min_i32_e32 v46, v73, v45
	v_max_i32_e32 v43, v37, v41
	v_min_i32_e32 v37, v37, v41
	v_min_i32_e32 v41, v44, v42
	v_min_i32_e32 v77, v124, v76
	v_min_i32_e32 v69, v46, v47
	v_max_i32_e32 v45, v44, v42
	v_max_i32_e32 v42, v37, v41
	v_min_i32_e32 v37, v37, v41
	v_max_i32_e32 v41, v124, v76
	v_max_i32_e32 v44, v46, v47
	v_min_i32_e32 v70, v77, v69
	v_max_i32_e32 v49, v74, v48
	v_min_i32_e32 v48, v74, v48
	v_max_i32_e32 v66, v43, v45
	v_min_i32_e32 v43, v43, v45
	v_max_i32_e32 v45, v41, v44
	v_min_i32_e32 v41, v41, v44
	v_max_i32_e32 v44, v77, v69
	v_sub_u32_e32 v46, v49, v87
	v_sub_u32_e32 v47, v48, v87
	v_sub_u32_e32 v40, v40, v87
	v_sub_u32_e32 v36, v36, v87
	v_sub_u32_e32 v39, v39, v87
	v_sub_u32_e32 v38, v38, v87
	v_sub_u32_e32 v35, v35, v87
	v_sub_u32_e32 v34, v34, v87
	v_sub_u32_e32 v48, v66, v87
	v_sub_u32_e32 v43, v43, v87
	v_sub_u32_e32 v42, v42, v87
	v_sub_u32_e32 v37, v37, v87
	v_sub_u32_e32 v45, v45, v87
	v_sub_u32_e32 v41, v41, v87
	v_sub_u32_e32 v44, v44, v87
	v_sub_u32_e32 v49, v70, v87
	ds_bpermute_b32 v66, v123, v46
	ds_bpermute_b32 v67, v123, v47
	ds_bpermute_b32 v68, v123, v40
	ds_bpermute_b32 v69, v123, v36
	ds_bpermute_b32 v70, v123, v39
	ds_bpermute_b32 v71, v123, v38
	ds_bpermute_b32 v72, v123, v35
	ds_bpermute_b32 v73, v123, v34
	ds_bpermute_b32 v74, v123, v48
	ds_bpermute_b32 v75, v123, v43
	ds_bpermute_b32 v76, v123, v42
	ds_bpermute_b32 v77, v123, v49
	ds_bpermute_b32 v78, v123, v44
	ds_bpermute_b32 v79, v123, v41
	ds_bpermute_b32 v80, v123, v45
	ds_bpermute_b32 v81, v123, v37
	s_waitcnt lgkmcnt(4)
	v_max_i32_e32 v46, v46, v77
	s_waitcnt lgkmcnt(3)
	v_max_i32_e32 v47, v47, v78
	s_waitcnt lgkmcnt(2)
	v_max_i32_e32 v40, v40, v79
	s_waitcnt lgkmcnt(1)
	v_max_i32_e32 v36, v36, v80
	s_waitcnt lgkmcnt(0)
	v_max_i32_e32 v39, v39, v81
	v_max_i32_e32 v38, v38, v76
	v_max_i32_e32 v35, v35, v75
	v_max_i32_e32 v34, v34, v74
	v_max_i32_e32 v48, v48, v73
	v_max_i32_e32 v43, v43, v72
	v_max_i32_e32 v42, v42, v71
	v_max_i32_e32 v37, v37, v70
	v_max_i32_e32 v45, v45, v69
	v_max_i32_e32 v41, v41, v68
	v_max_i32_e32 v44, v44, v67
	v_max_i32_e32 v49, v49, v66
	v_max_i32_e32 v66, v46, v48
	v_min_i32_e32 v46, v46, v48
	v_max_i32_e32 v48, v47, v43
	v_min_i32_e32 v43, v47, v43
	v_max_i32_e32 v47, v40, v42
	v_min_i32_e32 v40, v40, v42
	v_max_i32_e32 v42, v36, v37
	v_min_i32_e32 v36, v36, v37
	v_max_i32_e32 v37, v39, v45
	v_min_i32_e32 v39, v39, v45
	v_max_i32_e32 v45, v38, v41
	v_min_i32_e32 v38, v38, v41
	v_max_i32_e32 v41, v35, v44
	v_min_i32_e32 v35, v35, v44
	v_max_i32_e32 v44, v34, v49
	v_min_i32_e32 v34, v34, v49
	v_max_i32_e32 v49, v66, v37
	v_min_i32_e32 v37, v66, v37
	v_max_i32_e32 v66, v48, v45
	v_min_i32_e32 v45, v48, v45
	v_max_i32_e32 v48, v47, v41
	v_min_i32_e32 v41, v47, v41
	v_max_i32_e32 v47, v42, v44
	v_max_i32_e32 v80, v66, v47
	v_min_i32_e32 v124, v66, v47
	ds_read_b128 v[66:69], v94 offset:18432
	ds_read_b128 v[70:73], v94 offset:18464
	v_min_i32_e32 v42, v42, v44
	v_max_i32_e32 v44, v46, v39
	v_min_i32_e32 v74, v46, v39
	v_max_i32_e32 v39, v43, v38
	v_min_i32_e32 v75, v43, v38
	v_max_i32_e32 v38, v40, v35
	v_min_i32_e32 v76, v40, v35
	v_max_i32_e32 v35, v36, v34
	v_min_i32_e32 v77, v36, v34
	v_max_i32_e32 v78, v49, v48
	v_min_i32_e32 v82, v49, v48
	v_max_i32_e32 v125, v37, v41
	v_min_i32_e32 v126, v37, v41
	v_max_i32_e32 v127, v45, v42
	v_min_i32_e32 v128, v45, v42
	v_max_i32_e32 v129, v44, v38
	v_min_i32_e32 v130, v44, v38
	v_max_i32_e32 v131, v39, v35
	v_min_i32_e32 v132, v39, v35
	s_waitcnt vmcnt(3) lgkmcnt(1)
	v_mfma_f32_32x32x16_bf16 v[34:49], v[66:69], v[62:65], v[18:33]
	ds_read_b128 v[66:69], v94 offset:18496
	v_max_i32_e32 v133, v74, v76
	v_min_i32_e32 v134, v74, v76
	v_max_i32_e32 v135, v75, v77
	v_min_i32_e32 v136, v75, v77
	v_max_i32_e32 v79, v78, v80
	v_min_i32_e32 v81, v78, v80
	s_waitcnt vmcnt(2) lgkmcnt(1)
	v_mfma_f32_32x32x16_bf16 v[34:49], v[70:73], v[58:61], v[34:49]
	v_max_i32_e32 v80, v82, v124
	v_min_i32_e32 v78, v82, v124
	v_max_i32_e32 v77, v125, v127
	v_min_i32_e32 v76, v125, v127
	v_max_i32_e32 v75, v126, v128
	v_min_i32_e32 v73, v126, v128
	ds_read_b128 v[124:127], v94 offset:18528
	s_waitcnt vmcnt(1) lgkmcnt(1)
	v_mfma_f32_32x32x16_bf16 v[34:49], v[66:69], v[54:57], v[34:49]
	v_max_i32_e32 v71, v129, v131
	v_min_i32_e32 v74, v129, v131
	v_max_i32_e32 v72, v130, v132
	v_min_i32_e32 v70, v130, v132
	v_max_i32_e32 v69, v133, v135
	v_min_i32_e32 v68, v133, v135
	v_max_i32_e32 v67, v134, v136
	s_waitcnt vmcnt(0) lgkmcnt(0)
; #define LAS __attribute__((address_space(3)))
; #define MFMA32(a, b, c) __builtin_amdgcn_mfma_f32_32x32x16_bf16((a), (b), (c), 0, 0, 0)
; #define CE_(a, b) ce_desc(v[a], v[b])
; __device__ __forceinline__ void sort16_desc(int (&v)[16]) {
;     ...
;     CE_(0,13); CE_(1,12); CE_(2,15); CE_(3,14); CE_(4,8); CE_(5,6); CE_(7,11); CE_(9,10);
;     CE_(0,5); CE_(1,7); CE_(2,9); CE_(3,4); CE_(6,13); CE_(8,14); CE_(10,15); CE_(11,12);
;     CE_(0,1); CE_(2,3); CE_(4,5); CE_(6,8); CE_(7,9); CE_(10,11); CE_(12,13); CE_(14,15);
;     CE_(0,2); CE_(1,3); CE_(4,10); CE_(5,11); CE_(6,7); CE_(8,9); CE_(12,14); CE_(13,15);
;     CE_(1,2); CE_(3,12); CE_(4,6); CE_(5,7); CE_(8,10); CE_(9,11); CE_(13,14);
;     CE_(1,4); CE_(2,6); CE_(5,8); CE_(7,10); CE_(9,13); CE_(11,14);
;     CE_(2,4); CE_(3,6); CE_(9,12); CE_(11,13);
;     CE_(3,5); CE_(6,8); CE_(7,9); CE_(10,12);
;     CE_(3,4); CE_(5,6); CE_(7,8); CE_(9,10); CE_(11,12);
;     CE_(6,7); CE_(8,9);
;     ...
; }
; __device__ __forceinline__ void merge16_desc(int (&a)[16], const int (&b)[16]) {
; #pragma unroll
;     for (int i = 0; i < 16; ++i) a[i] = a[i] > b[15 - i] ? a[i] : b[15 - i];
; #pragma unroll
;     for (int j = 8; j > 0; j >>= 1)
; #pragma unroll
;         for (int i = 0; i < 16; ++i) { const int l = i ^ j; if (l > i) ce_desc(a[i], a[l]); }
; }
; __device__ __forceinline__ void route_task(int task, int tl0, const bf16* QP  , const LAS bf16* KHL, LAS unsigned short* EL, LAS float* GL, int lane) {
;     ...
;         for (int kt = 0; kt < 4; ++kt) {
;             f32x16 X;
; #pragma unroll
;             for (int i = 0; i < 16; ++i) X[i] = 8.f;
;             const LAS bf16* khp = KHL + (half * 128 + 32 * kt + r) * 72 + 8 * hi;
; #pragma unroll
;             for (int ks = 0; ks < 4; ++ks) {
;                 const bf16x8 kh = lds8(khp + 16 * ks);
;                 X = MFMA32(kh, qa[half][ks], X);
;             }
;             int grp[16];
; #pragma unroll
;             for (int i = 0; i < 16; ++i) grp[i] = (int)((__float_as_uint(X[i]) | 127u) - (unsigned)(32 * kt + (i & 3) + 8 * (i >> 2)));
;             sort16_desc(grp);
;             if (kt == 0) {
; #pragma unroll
;                 for (int i = 0; i < 16; ++i) cur[i] = grp[i];
;             } else merge16_desc(cur, grp);
	v_mfma_f32_32x32x16_bf16 v[34:49], v[124:127], v[50:53], v[34:49]
	v_min_i32_e32 v66, v134, v136
	s_nop 10
	v_bitop3_b32 v37, v37, s42, 3 bitop3:0x56
	v_bitop3_b32 v48, v48, s42, 26 bitop3:0x56
	v_bitop3_b32 v38, v38, s42, 8 bitop3:0x56
	v_bitop3_b32 v42, v42, s42, 16 bitop3:0x56
	v_bitop3_b32 v47, v47, s42, 25 bitop3:0x56
	v_bitop3_b32 v39, v39, s42, 9 bitop3:0x56
	v_bitop3_b32 v40, v40, s42, 10 bitop3:0x56
	v_bitop3_b32 v43, v43, s42, 17 bitop3:0x56
	v_bitop3_b32 v44, v44, s42, 18 bitop3:0x56
	v_bitop3_b32 v36, v36, s42, 2 bitop3:0x56
	v_bitop3_b32 v49, v49, s42, 27 bitop3:0x56
	v_bitop3_b32 v41, v41, s42, 11 bitop3:0x56
	v_bitop3_b32 v45, v45, s42, 19 bitop3:0x56
	v_bitop3_b32 v35, v35, s42, 1 bitop3:0x56
	v_bitop3_b32 v46, v46, s42, 24 bitop3:0x56
	v_or_b32_e32 v34, 0x7f, v34
	v_max_i32_e32 v82, v37, v48
	v_max_i32_e32 v124, v38, v42
	v_max_i32_e32 v126, v34, v47
	v_max_i32_e32 v127, v39, v40
	v_min_i32_e32 v130, v43, v44
	v_min_i32_e32 v131, v36, v49
	v_min_i32_e32 v133, v41, v45
	v_min_i32_e32 v134, v35, v46
	v_min_i32_e32 v39, v39, v40
	v_min_i32_e32 v34, v34, v47
	v_min_i32_e32 v38, v38, v42
	v_min_i32_e32 v37, v37, v48
	v_max_i32_e32 v35, v35, v46
	v_max_i32_e32 v41, v41, v45
	v_max_i32_e32 v36, v36, v49
	v_max_i32_e32 v43, v43, v44
	v_min_i32_e32 v125, v82, v124
	v_min_i32_e32 v128, v126, v127
	v_max_i32_e32 v132, v130, v131
	v_max_i32_e32 v135, v133, v134
	v_max_i32_e32 v40, v39, v34
	v_max_i32_e32 v42, v38, v37
	v_min_i32_e32 v45, v35, v41
	v_min_i32_e32 v44, v36, v43
	v_min_i32_e32 v129, v125, v128
	v_max_i32_e32 v47, v40, v42
	v_max_i32_e32 v46, v45, v44
	v_min_i32_e32 v40, v40, v42
	v_min_i32_e32 v42, v45, v44
	v_max_i32_e32 v45, v125, v128
	v_max_i32_e32 v125, v132, v135
	v_min_i32_e32 v128, v45, v125
	v_min_i32_e32 v34, v39, v34
	v_max_i32_e32 v39, v126, v127
	v_max_i32_e32 v35, v35, v41
	v_max_i32_e32 v41, v82, v124
	v_max_i32_e32 v148, v45, v125
	ds_read_b128 v[124:127], v97
	v_max_i32_e32 v44, v40, v42
	v_min_i32_e32 v138, v40, v42
	v_min_i32_e32 v40, v133, v134
	v_min_i32_e32 v37, v38, v37
	v_min_i32_e32 v38, v130, v131
	v_max_i32_e32 v36, v36, v43
	v_min_i32_e32 v136, v132, v135
	v_min_i32_e32 v133, v40, v34
	v_min_i32_e32 v134, v37, v38
	v_max_i32_e32 v34, v40, v34
	v_max_i32_e32 v37, v37, v38
	v_min_i32_e32 v40, v39, v35
	v_min_i32_e32 v42, v36, v41
	v_max_i32_e32 v144, v39, v35
	v_max_i32_e32 v145, v36, v41
	v_max_i32_e32 v137, v129, v136
	v_min_i32_e32 v136, v129, v136
	v_max_i32_e32 v140, v133, v134
	v_min_i32_e32 v141, v34, v37
	v_max_i32_e32 v143, v40, v42
	v_min_i32_e32 v146, v144, v145
	v_max_i32_e32 v149, v47, v46
	v_min_i32_e32 v48, v47, v46
	v_max_i32_e32 v139, v138, v136
	v_max_i32_e32 v142, v140, v141
	v_min_i32_e32 v43, v40, v42
	v_max_i32_e32 v34, v34, v37
	v_min_i32_e32 v147, v143, v146
	v_min_i32_e32 v150, v148, v149
	v_min_i32_e32 v49, v137, v48
	v_min_i32_e32 v132, v44, v128
	v_max_i32_e32 v38, v139, v142
	v_min_i32_e32 v37, v43, v34
	v_max_i32_e32 v34, v43, v34
	v_min_i32_e32 v35, v147, v150
	v_max_i32_e32 v39, v137, v48
	v_max_i32_e32 v40, v44, v128
	v_max_i32_e32 v135, v49, v132
	v_max_i32_e32 v82, v38, v37
	v_min_i32_e32 v36, v34, v35
	v_min_i32_e32 v41, v39, v40
	v_max_i32_e32 v129, v135, v82
	v_min_i32_e32 v42, v36, v41
	v_min_i32_e32 v137, v129, v42
	v_max_i32_e32 v159, v129, v42
	ds_read_b128 v[128:131], v97 offset:32
	v_min_i32_e32 v82, v135, v82
	v_min_i32_e32 v132, v49, v132
	v_min_i32_e32 v135, v38, v37
	v_max_i32_e32 v154, v34, v35
	v_max_i32_e32 v155, v39, v40
	v_max_i32_e32 v157, v36, v41
	s_waitcnt lgkmcnt(1)
	v_mfma_f32_32x32x16_bf16 v[34:49], v[124:127], v[62:65], v[18:33]
	ds_read_b128 v[124:127], v97 offset:64
	v_max_i32_e32 v151, v132, v135
	v_max_i32_e32 v152, v82, v151
	v_min_i32_e32 v136, v138, v136
	v_min_i32_e32 v138, v140, v141
	v_min_i32_e32 v82, v82, v151
	v_max_i32_e32 v147, v147, v150
	s_waitcnt lgkmcnt(1)
	v_mfma_f32_32x32x16_bf16 v[34:49], v[128:131], v[58:61], v[34:49]
	ds_read_b128 v[128:131], v97 offset:96
	v_max_i32_e32 v143, v143, v146
	v_min_i32_e32 v133, v133, v134
	v_min_i32_e32 v156, v154, v155
	v_max_i32_e32 v140, v136, v138
	v_min_i32_e32 v139, v139, v142
	v_max_i32_e32 v142, v154, v155
	s_waitcnt lgkmcnt(1)
	v_mfma_f32_32x32x16_bf16 v[34:49], v[124:127], v[54:57], v[34:49]
	v_max_i32_e32 v124, v148, v149
	v_min_i32_e32 v136, v136, v138
	v_max_i32_e32 v141, v140, v139
	v_min_i32_e32 v139, v140, v139
	v_min_i32_e32 v125, v143, v124
	v_min_i32_e32 v158, v156, v157
	v_min_i32_e32 v132, v132, v135
	s_waitcnt lgkmcnt(0)
; #define LAS __attribute__((address_space(3)))
; #define MFMA32(a, b, c) __builtin_amdgcn_mfma_f32_32x32x16_bf16((a), (b), (c), 0, 0, 0)
; #define CE_(a, b) ce_desc(v[a], v[b])
; __device__ __forceinline__ void sort16_desc(int (&v)[16]) {
;     ...
;     CE_(0,13); CE_(1,12); CE_(2,15); CE_(3,14); CE_(4,8); CE_(5,6); CE_(7,11); CE_(9,10);
;     CE_(0,5); CE_(1,7); CE_(2,9); CE_(3,4); CE_(6,13); CE_(8,14); CE_(10,15); CE_(11,12);
;     CE_(0,1); CE_(2,3); CE_(4,5); CE_(6,8); CE_(7,9); CE_(10,11); CE_(12,13); CE_(14,15);
;     CE_(0,2); CE_(1,3); CE_(4,10); CE_(5,11); CE_(6,7); CE_(8,9); CE_(12,14); CE_(13,15);
;     CE_(1,2); CE_(3,12); CE_(4,6); CE_(5,7); CE_(8,10); CE_(9,11); CE_(13,14);
;     CE_(1,4); CE_(2,6); CE_(5,8); CE_(7,10); CE_(9,13); CE_(11,14);
;     CE_(2,4); CE_(3,6); CE_(9,12); CE_(11,13);
;     CE_(3,5); CE_(6,8); CE_(7,9); CE_(10,12);
;     CE_(3,4); CE_(5,6); CE_(7,8); CE_(9,10); CE_(11,12);
;     CE_(6,7); CE_(8,9);
;     ...
; }
; __device__ __forceinline__ void merge16_desc(int (&a)[16], const int (&b)[16]) {
; #pragma unroll
;     for (int i = 0; i < 16; ++i) a[i] = a[i] > b[15 - i] ? a[i] : b[15 - i];
; #pragma unroll
;     for (int j = 8; j > 0; j >>= 1)
; #pragma unroll
;         for (int i = 0; i < 16; ++i) { const int l = i ^ j; if (l > i) ce_desc(a[i], a[l]); }
; }
; __device__ __forceinline__ void route_task(int task, int tl0, const bf16* QP  , const LAS bf16* KHL, LAS unsigned short* EL, LAS float* GL, int lane) {
;     ...
;         for (int kt = 0; kt < 4; ++kt) {
;             f32x16 X;
; #pragma unroll
;             for (int i = 0; i < 16; ++i) X[i] = 8.f;
;             const LAS bf16* khp = KHL + (half * 128 + 32 * kt + r) * 72 + 8 * hi;
; #pragma unroll
;             for (int ks = 0; ks < 4; ++ks) {
;                 const bf16x8 kh = lds8(khp + 16 * ks);
;                 X = MFMA32(kh, qa[half][ks], X);
;             }
;             int grp[16];
; #pragma unroll
;             for (int i = 0; i < 16; ++i) grp[i] = (int)((__float_as_uint(X[i]) | 127u) - (unsigned)(32 * kt + (i & 3) + 8 * (i >> 2)));
;             sort16_desc(grp);
;             if (kt == 0) {
; #pragma unroll
;                 for (int i = 0; i < 16; ++i) cur[i] = grp[i];
;             } else merge16_desc(cur, grp);
	v_mfma_f32_32x32x16_bf16 v[34:49], v[128:131], v[50:53], v[34:49]
	v_min_i32_e32 v126, v147, v125
	v_min_i32_e32 v153, v137, v152
	v_min_i32_e32 v160, v158, v159
	v_min_i32_e32 v135, v141, v132
	v_min_i32_e32 v127, v142, v126
	s_nop 6
	v_bitop3_b32 v37, v37, s42, 35 bitop3:0x56
	v_bitop3_b32 v48, v48, s42, 58 bitop3:0x56
	v_bitop3_b32 v38, v38, s42, 40 bitop3:0x56
	v_bitop3_b32 v42, v42, s42, 48 bitop3:0x56
	v_bitop3_b32 v34, v34, s42, 32 bitop3:0x56
	v_bitop3_b32 v47, v47, s42, 57 bitop3:0x56
	v_bitop3_b32 v39, v39, s42, 41 bitop3:0x56
	v_bitop3_b32 v40, v40, s42, 42 bitop3:0x56
	v_bitop3_b32 v43, v43, s42, 49 bitop3:0x56
	v_bitop3_b32 v44, v44, s42, 50 bitop3:0x56
	v_bitop3_b32 v36, v36, s42, 34 bitop3:0x56
	v_bitop3_b32 v49, v49, s42, 59 bitop3:0x56
	v_bitop3_b32 v41, v41, s42, 43 bitop3:0x56
	v_bitop3_b32 v45, v45, s42, 51 bitop3:0x56
	v_bitop3_b32 v35, v35, s42, 33 bitop3:0x56
	v_bitop3_b32 v46, v46, s42, 56 bitop3:0x56
	v_max_i32_e32 v128, v37, v48
	v_max_i32_e32 v129, v38, v42
	v_max_i32_e32 v131, v34, v47
	v_max_i32_e32 v134, v39, v40
	v_min_i32_e32 v146, v43, v44
	v_min_i32_e32 v148, v36, v49
	v_min_i32_e32 v150, v41, v45
	v_min_i32_e32 v151, v35, v46
	v_min_i32_e32 v39, v39, v40
	v_min_i32_e32 v34, v34, v47
	v_min_i32_e32 v38, v38, v42
	v_min_i32_e32 v37, v37, v48
	v_max_i32_e32 v35, v35, v46
	v_max_i32_e32 v41, v41, v45
	v_max_i32_e32 v36, v36, v49
	v_max_i32_e32 v43, v43, v44
	v_min_i32_e32 v130, v128, v129
	v_min_i32_e32 v138, v131, v134
	v_max_i32_e32 v149, v146, v148
	v_max_i32_e32 v154, v150, v151
	v_max_i32_e32 v40, v39, v34
	v_max_i32_e32 v42, v38, v37
	v_min_i32_e32 v45, v35, v41
	v_min_i32_e32 v44, v36, v43
	v_min_i32_e32 v150, v150, v151
	v_min_i32_e32 v34, v39, v34
	v_min_i32_e32 v37, v38, v37
	v_min_i32_e32 v38, v146, v148
	v_max_i32_e32 v131, v131, v134
	v_max_i32_e32 v35, v35, v41
	v_max_i32_e32 v36, v36, v43
	v_max_i32_e32 v43, v128, v129
	v_min_i32_e32 v140, v130, v138
	v_min_i32_e32 v155, v149, v154
	v_max_i32_e32 v47, v40, v42
	v_max_i32_e32 v46, v45, v44
	v_min_i32_e32 v40, v40, v42
	v_min_i32_e32 v42, v45, v44
	v_max_i32_e32 v45, v130, v138
	v_max_i32_e32 v130, v149, v154
	v_min_i32_e32 v39, v150, v34
	v_min_i32_e32 v146, v37, v38
	v_max_i32_e32 v34, v150, v34
	v_max_i32_e32 v37, v37, v38
	v_min_i32_e32 v41, v131, v35
	v_min_i32_e32 v128, v36, v43
	v_max_i32_e32 v35, v131, v35
	v_max_i32_e32 v36, v36, v43
	v_min_i32_e32 v48, v47, v46
	v_max_i32_e32 v44, v40, v42
	v_min_i32_e32 v138, v45, v130
	v_min_i32_e32 v40, v40, v42
	v_min_i32_e32 v42, v140, v155
	v_max_i32_e32 v148, v39, v146
	v_min_i32_e32 v38, v34, v37
	v_min_i32_e32 v129, v41, v128
	v_max_i32_e32 v41, v41, v128
	v_min_i32_e32 v43, v35, v36
	v_max_i32_e32 v45, v45, v130
	v_max_i32_e32 v46, v47, v46
	v_max_i32_e32 v161, v140, v155
	v_max_i32_e32 v140, v40, v42
	v_max_i32_e32 v150, v148, v38
	v_max_i32_e32 v34, v34, v37
	v_min_i32_e32 v128, v41, v43
	v_min_i32_e32 v47, v45, v46
	v_min_i32_e32 v49, v161, v48
	v_min_i32_e32 v149, v44, v138
	v_max_i32_e32 v151, v140, v150
	v_min_i32_e32 v37, v129, v34
	v_max_i32_e32 v34, v129, v34
	v_min_i32_e32 v129, v128, v47
	v_max_i32_e32 v48, v161, v48
	v_max_i32_e32 v44, v44, v138
	v_max_i32_e32 v154, v49, v149
	v_max_i32_e32 v134, v151, v37
	v_min_i32_e32 v130, v34, v129
	v_min_i32_e32 v131, v48, v44
	v_min_i32_e32 v49, v49, v149
	v_min_i32_e32 v37, v151, v37
	v_max_i32_e32 v34, v34, v129
	v_max_i32_e32 v44, v48, v44
	v_min_i32_e32 v40, v40, v42
	v_min_i32_e32 v38, v148, v38
	v_max_i32_e32 v41, v41, v43
	v_max_i32_e32 v43, v45, v46
	v_max_i32_e32 v155, v154, v134
	v_min_i32_e32 v138, v130, v131
	v_min_i32_e32 v134, v154, v134
	v_max_i32_e32 v149, v49, v37
	v_min_i32_e32 v48, v34, v44
	v_max_i32_e32 v129, v130, v131
	v_max_i32_e32 v42, v40, v38
	v_min_i32_e32 v140, v140, v150
	v_max_i32_e32 v34, v34, v44
	v_max_i32_e32 v44, v128, v47
	v_min_i32_e32 v45, v41, v43
	v_min_i32_e32 v161, v155, v138
	v_max_i32_e32 v151, v134, v149
	v_min_i32_e32 v130, v48, v129
	v_max_i32_e32 v131, v155, v138
	v_max_i32_e32 v148, v42, v140
	v_min_i32_e32 v37, v49, v37
	v_min_i32_e32 v46, v44, v45
	v_min_i32_e32 v154, v161, v151
	v_min_i32_e32 v138, v130, v131
	v_min_i32_e32 v49, v148, v37
	v_min_i32_e32 v134, v134, v149
	v_min_i32_e32 v47, v34, v46
	v_min_i32_e32 v42, v42, v140
	v_min_i32_e32 v38, v40, v38
	v_min_i32_e32 v39, v39, v146
	v_max3_i32 v39, v144, v145, v39
	v_max3_i32 v38, v143, v124, v38
	v_max3_i32 v40, v147, v125, v42
	v_max3_i32 v42, v142, v126, v49
	v_max3_i32 v37, v127, v148, v37
	v_max3_i32 v49, v156, v157, v134
	v_max3_i32 v124, v158, v159, v154
	v_max3_i32 v125, v160, v161, v151
	v_max3_i32 v126, v137, v152, v138
	v_max3_i32 v127, v153, v130, v131
	v_max3_i32 v48, v82, v48, v129
	v_max3_i32 v47, v141, v132, v47
	v_max3_i32 v34, v135, v34, v46
	v_max3_i32 v44, v139, v44, v45
	v_max3_i32 v41, v136, v41, v43
	v_max3_i32 v35, v133, v35, v36
	v_max_i32_e32 v36, v39, v126
	v_min_i32_e32 v39, v39, v126
	v_max_i32_e32 v43, v38, v127
	v_min_i32_e32 v38, v38, v127
	v_max_i32_e32 v45, v40, v48
	v_min_i32_e32 v40, v40, v48
	v_max_i32_e32 v46, v42, v47
	v_min_i32_e32 v42, v42, v47
	v_max_i32_e32 v47, v37, v34
	v_min_i32_e32 v34, v37, v34
	v_max_i32_e32 v37, v49, v44
	v_min_i32_e32 v44, v49, v44
	v_max_i32_e32 v48, v124, v41
	v_min_i32_e32 v41, v124, v41
	v_max_i32_e32 v49, v125, v35
	v_min_i32_e32 v35, v125, v35
	ds_read_b128 v[124:127], v94 offset:27648
	ds_read_b128 v[128:131], v94 offset:27680
	v_max_i32_e32 v82, v36, v47
	v_min_i32_e32 v132, v36, v47
	v_max_i32_e32 v36, v43, v37
	v_min_i32_e32 v133, v43, v37
	v_max_i32_e32 v37, v45, v48
	v_max_i32_e32 v43, v46, v49
	v_min_i32_e32 v134, v45, v48
	v_min_i32_e32 v135, v46, v49
	v_max_i32_e32 v136, v39, v34
	v_min_i32_e32 v137, v39, v34
	v_max_i32_e32 v138, v38, v44
	v_min_i32_e32 v139, v38, v44
	v_max_i32_e32 v140, v40, v41
	v_min_i32_e32 v141, v40, v41
	v_max_i32_e32 v142, v42, v35
	v_min_i32_e32 v143, v42, v35
	v_max_i32_e32 v144, v82, v37
	v_min_i32_e32 v82, v82, v37
	v_max_i32_e32 v145, v36, v43
	v_min_i32_e32 v146, v36, v43
	s_waitcnt lgkmcnt(1)
; #define LAS __attribute__((address_space(3)))
; #define MFMA32(a, b, c) __builtin_amdgcn_mfma_f32_32x32x16_bf16((a), (b), (c), 0, 0, 0)
; #define CE_(a, b) ce_desc(v[a], v[b])
; __device__ __forceinline__ void sort16_desc(int (&v)[16]) {
;     ...
;     CE_(0,13); CE_(1,12); CE_(2,15); CE_(3,14); CE_(4,8); CE_(5,6); CE_(7,11); CE_(9,10);
;     CE_(0,5); CE_(1,7); CE_(2,9); CE_(3,4); CE_(6,13); CE_(8,14); CE_(10,15); CE_(11,12);
;     CE_(0,1); CE_(2,3); CE_(4,5); CE_(6,8); CE_(7,9); CE_(10,11); CE_(12,13); CE_(14,15);
;     CE_(0,2); CE_(1,3); CE_(4,10); CE_(5,11); CE_(6,7); CE_(8,9); CE_(12,14); CE_(13,15);
;     CE_(1,2); CE_(3,12); CE_(4,6); CE_(5,7); CE_(8,10); CE_(9,11); CE_(13,14);
;     CE_(1,4); CE_(2,6); CE_(5,8); CE_(7,10); CE_(9,13); CE_(11,14);
;     CE_(2,4); CE_(3,6); CE_(9,12); CE_(11,13);
;     CE_(3,5); CE_(6,8); CE_(7,9); CE_(10,12);
;     CE_(3,4); CE_(5,6); CE_(7,8); CE_(9,10); CE_(11,12);
;     CE_(6,7); CE_(8,9);
;     ...
; }
; __device__ __forceinline__ void merge16_desc(int (&a)[16], const int (&b)[16]) {
; #pragma unroll
;     for (int i = 0; i < 16; ++i) a[i] = a[i] > b[15 - i] ? a[i] : b[15 - i];
; #pragma unroll
;     for (int j = 8; j > 0; j >>= 1)
; #pragma unroll
;         for (int i = 0; i < 16; ++i) { const int l = i ^ j; if (l > i) ce_desc(a[i], a[l]); }
; }
; __device__ __forceinline__ void route_task(int task, int tl0, const bf16* QP  , const LAS bf16* KHL, LAS unsigned short* EL, LAS float* GL, int lane) {
;     ...
;         for (int kt = 0; kt < 4; ++kt) {
;             f32x16 X;
; #pragma unroll
;             for (int i = 0; i < 16; ++i) X[i] = 8.f;
;             const LAS bf16* khp = KHL + (half * 128 + 32 * kt + r) * 72 + 8 * hi;
; #pragma unroll
;             for (int ks = 0; ks < 4; ++ks) {
;                 const bf16x8 kh = lds8(khp + 16 * ks);
;                 X = MFMA32(kh, qa[half][ks], X);
;             }
;             int grp[16];
; #pragma unroll
;             for (int i = 0; i < 16; ++i) grp[i] = (int)((__float_as_uint(X[i]) | 127u) - (unsigned)(32 * kt + (i & 3) + 8 * (i >> 2)));
;             sort16_desc(grp);
;             if (kt == 0) {
; #pragma unroll
;                 for (int i = 0; i < 16; ++i) cur[i] = grp[i];
;             } else merge16_desc(cur, grp);
	v_mfma_f32_32x32x16_bf16 v[34:49], v[124:127], v[62:65], v[18:33]
	ds_read_b128 v[124:127], v94 offset:27712
	v_max_i32_e32 v147, v132, v134
	v_min_i32_e32 v132, v132, v134
	v_max_i32_e32 v134, v133, v135
	v_min_i32_e32 v133, v133, v135
	v_max_i32_e32 v135, v136, v140
	v_min_i32_e32 v136, v136, v140
	s_waitcnt lgkmcnt(1)
	v_mfma_f32_32x32x16_bf16 v[34:49], v[128:131], v[58:61], v[34:49]
	ds_read_b128 v[128:131], v94 offset:27744
	v_max_i32_e32 v140, v138, v142
	v_min_i32_e32 v138, v138, v142
	v_max_i32_e32 v142, v137, v141
	v_min_i32_e32 v137, v137, v141
	v_max_i32_e32 v141, v139, v143
	v_min_i32_e32 v139, v139, v143
	s_waitcnt lgkmcnt(1)
	v_mfma_f32_32x32x16_bf16 v[34:49], v[124:127], v[54:57], v[34:49]
	v_min_i32_e32 v143, v144, v145
	v_min_i32_e32 v124, v82, v146
	v_min_i32_e32 v127, v135, v140
	v_min_i32_e32 v125, v147, v134
	v_min_i32_e32 v126, v132, v133
	v_min_i32_e32 v149, v142, v141
	v_min_i32_e32 v148, v136, v138
	s_waitcnt lgkmcnt(0)
	v_mfma_f32_32x32x16_bf16 v[34:49], v[128:131], v[50:53], v[34:49]
	v_min_i32_e32 v150, v137, v139
	s_nop 10
	v_and_or_b32 v37, v37, s43, 60
	v_and_or_b32 v48, v48, s43, 37
	v_and_or_b32 v38, v38, s43, 55
	v_and_or_b32 v42, v42, s43, 47
	v_bitop3_b32 v34, v34, s42, 64 bitop3:0x56
	v_and_or_b32 v47, v47, s43, 38
	v_and_or_b32 v39, v39, s43, 54
	v_and_or_b32 v40, v40, s43, 53
	v_and_or_b32 v43, v43, s43, 46
	v_and_or_b32 v44, v44, s43, 45
	v_and_or_b32 v36, v36, s43, 61
	v_and_or_b32 v49, v49, s43, 36
	v_and_or_b32 v41, v41, s43, 52
	v_and_or_b32 v45, v45, s43, 44
	v_and_or_b32 v35, v35, s43, 62
	v_and_or_b32 v46, v46, s43, 39
	v_max_i32_e32 v128, v37, v48
	v_max_i32_e32 v129, v38, v42
	v_max_i32_e32 v131, v34, v47
	v_max_i32_e32 v151, v39, v40
	v_min_i32_e32 v154, v43, v44
	v_min_i32_e32 v155, v36, v49
	v_min_i32_e32 v157, v41, v45
	v_min_i32_e32 v158, v35, v46
	v_min_i32_e32 v39, v39, v40
	v_min_i32_e32 v34, v34, v47
	v_min_i32_e32 v38, v38, v42
	v_min_i32_e32 v37, v37, v48
	v_max_i32_e32 v35, v35, v46
	v_max_i32_e32 v41, v41, v45
	v_max_i32_e32 v36, v36, v49
	v_max_i32_e32 v43, v43, v44
	v_min_i32_e32 v130, v128, v129
	v_min_i32_e32 v152, v131, v151
	v_max_i32_e32 v156, v154, v155
	v_max_i32_e32 v159, v157, v158
	v_max_i32_e32 v40, v39, v34
	v_max_i32_e32 v42, v38, v37
	v_min_i32_e32 v45, v35, v41
	v_min_i32_e32 v44, v36, v43
	v_min_i32_e32 v157, v157, v158
	v_min_i32_e32 v34, v39, v34
	v_min_i32_e32 v37, v38, v37
	v_min_i32_e32 v38, v154, v155
	v_max_i32_e32 v131, v131, v151
	v_max_i32_e32 v35, v35, v41
	v_max_i32_e32 v36, v36, v43
	v_max_i32_e32 v43, v128, v129
	v_min_i32_e32 v153, v130, v152
	v_min_i32_e32 v160, v156, v159
	v_max_i32_e32 v47, v40, v42
	v_max_i32_e32 v46, v45, v44
	v_min_i32_e32 v40, v40, v42
	v_min_i32_e32 v42, v45, v44
	v_max_i32_e32 v45, v130, v152
	v_max_i32_e32 v130, v156, v159
	v_min_i32_e32 v39, v157, v34
	v_min_i32_e32 v154, v37, v38
	v_max_i32_e32 v34, v157, v34
	v_max_i32_e32 v37, v37, v38
	v_min_i32_e32 v41, v131, v35
	v_min_i32_e32 v128, v36, v43
	v_max_i32_e32 v35, v131, v35
	v_max_i32_e32 v36, v36, v43
	v_min_i32_e32 v48, v47, v46
	v_max_i32_e32 v44, v40, v42
	v_min_i32_e32 v152, v45, v130
	v_min_i32_e32 v40, v40, v42
	v_min_i32_e32 v42, v153, v160
	v_max_i32_e32 v155, v39, v154
	v_min_i32_e32 v38, v34, v37
	v_min_i32_e32 v129, v41, v128
	v_max_i32_e32 v41, v41, v128
	v_min_i32_e32 v43, v35, v36
	v_max_i32_e32 v45, v45, v130
	v_max_i32_e32 v46, v47, v46
	v_max_i32_e32 v161, v153, v160
	v_max_i32_e32 v153, v40, v42
	v_max_i32_e32 v157, v155, v38
	v_max_i32_e32 v34, v34, v37
	v_min_i32_e32 v128, v41, v43
	v_min_i32_e32 v47, v45, v46
	v_min_i32_e32 v49, v161, v48
	v_min_i32_e32 v156, v44, v152
	v_max_i32_e32 v158, v153, v157
	v_min_i32_e32 v37, v129, v34
	v_max_i32_e32 v34, v129, v34
	v_min_i32_e32 v129, v128, v47
	v_max_i32_e32 v48, v161, v48
	v_max_i32_e32 v44, v44, v152
	v_min_i32_e32 v40, v40, v42
	v_min_i32_e32 v38, v155, v38
	v_max_i32_e32 v159, v49, v156
	v_max_i32_e32 v151, v158, v37
	v_min_i32_e32 v130, v34, v129
	v_min_i32_e32 v131, v48, v44
	v_min_i32_e32 v49, v49, v156
	v_min_i32_e32 v37, v158, v37
	v_max_i32_e32 v34, v34, v129
	v_max_i32_e32 v44, v48, v44
	v_max_i32_e32 v42, v40, v38
	v_min_i32_e32 v153, v153, v157
	v_max_i32_e32 v160, v159, v151
	v_min_i32_e32 v152, v130, v131
	v_max_i32_e32 v156, v49, v37
	v_min_i32_e32 v48, v34, v44
	v_max_i32_e32 v129, v130, v131
	v_max_i32_e32 v155, v42, v153
	v_min_i32_e32 v37, v49, v37
	v_min_i32_e32 v151, v159, v151
	v_min_i32_e32 v130, v48, v129
	v_max_i32_e32 v131, v160, v152
	v_min_i32_e32 v49, v155, v37
	v_max_i32_e32 v41, v41, v43
	v_max_i32_e32 v43, v45, v46
	v_min_i32_e32 v42, v42, v153
	v_min_i32_e32 v38, v40, v38
	v_min_i32_e32 v161, v160, v152
	v_max_i32_e32 v158, v151, v156
	v_min_i32_e32 v151, v151, v156
	v_max_i32_e32 v34, v34, v44
	v_max_i32_e32 v44, v128, v47
	v_min_i32_e32 v45, v41, v43
	v_max_i32_e32 v40, v41, v43
	v_max_i32_e32 v38, v143, v38
	v_max3_i32 v41, v82, v146, v42
	v_max_i32_e32 v42, v124, v49
	v_max3_i32 v124, v127, v130, v131
	v_min_i32_e32 v46, v44, v45
	v_max_i32_e32 v43, v125, v151
	v_max3_i32 v49, v126, v161, v158
	v_max3_i32 v44, v149, v44, v45
	v_max_i32_e32 v45, v38, v124
	v_min_i32_e32 v38, v38, v124
	ds_read_b128 v[124:127], v98
	v_min_i32_e32 v159, v161, v158
	v_min_i32_e32 v152, v130, v131
	v_max_i32_e32 v37, v155, v37
	v_max_i32_e32 v48, v48, v129
	v_min_i32_e32 v47, v34, v46
	v_max_i32_e32 v34, v34, v46
	v_min_i32_e32 v39, v39, v154
	v_max3_i32 v39, v144, v145, v39
	v_max3_i32 v37, v147, v134, v37
	v_max3_i32 v46, v132, v133, v159
	v_max3_i32 v82, v135, v140, v152
	v_max3_i32 v48, v136, v138, v48
	v_max_i32_e32 v47, v148, v47
	v_max3_i32 v34, v142, v141, v34
	v_max3_i32 v40, v137, v139, v40
	v_max3_i32 v35, v150, v35, v36
	v_max_i32_e32 v36, v39, v82
	v_min_i32_e32 v39, v39, v82
	v_max_i32_e32 v82, v41, v48
	v_min_i32_e32 v41, v41, v48
	v_max_i32_e32 v48, v42, v47
	v_min_i32_e32 v42, v42, v47
	v_max_i32_e32 v47, v37, v34
	v_min_i32_e32 v34, v37, v34
	v_max_i32_e32 v37, v43, v44
	v_min_i32_e32 v43, v43, v44
	v_max_i32_e32 v44, v46, v40
	v_min_i32_e32 v40, v46, v40
	v_max_i32_e32 v46, v49, v35
	v_min_i32_e32 v35, v49, v35
	v_max_i32_e32 v49, v36, v47
	v_min_i32_e32 v132, v36, v47
	v_max_i32_e32 v36, v45, v37
	v_min_i32_e32 v133, v45, v37
	v_max_i32_e32 v37, v82, v44
	v_min_i32_e32 v82, v82, v44
	v_max_i32_e32 v44, v48, v46
	ds_read_b128 v[128:131], v98 offset:32
	v_min_i32_e32 v134, v48, v46
	v_max_i32_e32 v135, v39, v34
	v_min_i32_e32 v136, v39, v34
	v_max_i32_e32 v137, v38, v43
	v_min_i32_e32 v138, v38, v43
	v_max_i32_e32 v139, v41, v40
	v_min_i32_e32 v140, v41, v40
	v_max_i32_e32 v141, v42, v35
	v_min_i32_e32 v142, v42, v35
	v_max_i32_e32 v143, v49, v37
	v_min_i32_e32 v144, v49, v37
	v_max_i32_e32 v145, v36, v44
	v_min_i32_e32 v146, v36, v44
	s_waitcnt lgkmcnt(1)
; #define LAS __attribute__((address_space(3)))
; #define MFMA32(a, b, c) __builtin_amdgcn_mfma_f32_32x32x16_bf16((a), (b), (c), 0, 0, 0)
; #define CE_(a, b) ce_desc(v[a], v[b])
; __device__ __forceinline__ void sort16_desc(int (&v)[16]) {
;     ...
;     CE_(0,13); CE_(1,12); CE_(2,15); CE_(3,14); CE_(4,8); CE_(5,6); CE_(7,11); CE_(9,10);
;     CE_(0,5); CE_(1,7); CE_(2,9); CE_(3,4); CE_(6,13); CE_(8,14); CE_(10,15); CE_(11,12);
;     CE_(0,1); CE_(2,3); CE_(4,5); CE_(6,8); CE_(7,9); CE_(10,11); CE_(12,13); CE_(14,15);
;     CE_(0,2); CE_(1,3); CE_(4,10); CE_(5,11); CE_(6,7); CE_(8,9); CE_(12,14); CE_(13,15);
;     CE_(1,2); CE_(3,12); CE_(4,6); CE_(5,7); CE_(8,10); CE_(9,11); CE_(13,14);
;     CE_(1,4); CE_(2,6); CE_(5,8); CE_(7,10); CE_(9,13); CE_(11,14);
;     CE_(2,4); CE_(3,6); CE_(9,12); CE_(11,13);
;     CE_(3,5); CE_(6,8); CE_(7,9); CE_(10,12);
;     CE_(3,4); CE_(5,6); CE_(7,8); CE_(9,10); CE_(11,12);
;     CE_(6,7); CE_(8,9);
;     ...
; }
; __device__ __forceinline__ void merge16_desc(int (&a)[16], const int (&b)[16]) {
; #pragma unroll
;     for (int i = 0; i < 16; ++i) a[i] = a[i] > b[15 - i] ? a[i] : b[15 - i];
; #pragma unroll
;     for (int j = 8; j > 0; j >>= 1)
; #pragma unroll
;         for (int i = 0; i < 16; ++i) { const int l = i ^ j; if (l > i) ce_desc(a[i], a[l]); }
; }
; __device__ __forceinline__ void route_task(int task, int tl0, const bf16* QP  , const LAS bf16* KHL, LAS unsigned short* EL, LAS float* GL, int lane) {
;     ...
;         for (int kt = 0; kt < 4; ++kt) {
;             f32x16 X;
; #pragma unroll
;             for (int i = 0; i < 16; ++i) X[i] = 8.f;
;             const LAS bf16* khp = KHL + (half * 128 + 32 * kt + r) * 72 + 8 * hi;
; #pragma unroll
;             for (int ks = 0; ks < 4; ++ks) {
;                 const bf16x8 kh = lds8(khp + 16 * ks);
;                 X = MFMA32(kh, qa[half][ks], X);
;             }
;             int grp[16];
; #pragma unroll
;             for (int i = 0; i < 16; ++i) grp[i] = (int)((__float_as_uint(X[i]) | 127u) - (unsigned)(32 * kt + (i & 3) + 8 * (i >> 2)));
;             sort16_desc(grp);
;             if (kt == 0) {
; #pragma unroll
;                 for (int i = 0; i < 16; ++i) cur[i] = grp[i];
;             } else merge16_desc(cur, grp);
	v_mfma_f32_32x32x16_bf16 v[34:49], v[124:127], v[62:65], v[18:33]
	v_max_i32_e32 v147, v132, v82
	s_nop 5
	ds_read_b128 v[18:21], v98 offset:64
	ds_read_b128 v[22:25], v98 offset:96
	s_waitcnt lgkmcnt(2)
	v_mfma_f32_32x32x16_bf16 v[34:49], v[128:131], v[58:61], v[34:49]
	v_min_i32_e32 v26, v132, v82
	v_max_i32_e32 v27, v133, v134
	v_min_i32_e32 v30, v135, v139
	v_min_i32_e32 v32, v137, v141
	v_max_i32_e32 v33, v136, v140
	v_max_i32_e32 v59, v138, v142
	v_min_i32_e32 v28, v133, v134
	s_waitcnt lgkmcnt(1)
	v_mfma_f32_32x32x16_bf16 v[34:49], v[18:21], v[54:57], v[34:49]
	v_min_i32_e32 v19, v147, v27
	v_min_i32_e32 v54, v30, v32
	v_min_i32_e32 v55, v33, v59
	v_max_i32_e32 v29, v135, v139
	v_max_i32_e32 v31, v137, v141
	v_min_i32_e32 v58, v136, v140
	v_min_i32_e32 v60, v138, v142
	s_waitcnt lgkmcnt(0)
	v_mfma_f32_32x32x16_bf16 v[34:49], v[22:25], v[50:53], v[34:49]
	v_min_i32_e32 v18, v144, v146
	v_min_i32_e32 v61, v143, v145
	v_min_i32_e32 v20, v26, v28
	v_min_i32_e32 v21, v29, v31
	v_min_i32_e32 v56, v58, v60
	s_nop 6
	v_or_b32_e32 v22, 0x7f, v41
	v_or_b32_e32 v23, 0x7f, v45
	v_or_b32_e32 v25, 0x7f, v35
	v_or_b32_e32 v35, 0x7f, v46
	v_and_or_b32 v39, v39, s43, 22
	v_and_or_b32 v40, v40, s43, 21
	v_and_or_b32 v34, v34, s43, 31
	v_and_or_b32 v47, v47, s43, 6
	v_and_or_b32 v38, v38, s43, 23
	v_and_or_b32 v42, v42, s43, 15
	v_and_or_b32 v37, v37, s43, 28
	v_and_or_b32 v48, v48, s43, 5
	v_and_or_b32 v43, v43, s43, 14
	v_and_or_b32 v44, v44, s43, 13
	v_and_or_b32 v36, v36, s43, 29
	v_and_or_b32 v49, v49, s43, 4
	v_add_u32_e32 v22, 0xffffff95, v22
	v_add_u32_e32 v23, 0xffffff8d, v23
	v_add_u32_e32 v25, 0xffffff9f, v25
	v_add_u32_e32 v35, 0xffffff88, v35
	v_min_i32_e32 v24, v22, v23
	v_min_i32_e32 v41, v25, v35
	v_min_i32_e32 v46, v39, v40
	v_min_i32_e32 v50, v34, v47
	v_min_i32_e32 v53, v38, v42
	v_min_i32_e32 v57, v37, v48
	v_min_i32_e32 v63, v43, v44
	v_min_i32_e32 v64, v36, v49
	v_max_i32_e32 v34, v34, v47
	v_max_i32_e32 v39, v39, v40
	v_max_i32_e32 v25, v25, v35
	v_max_i32_e32 v22, v22, v23
	v_max_i32_e32 v36, v36, v49
	v_max_i32_e32 v43, v43, v44
	v_max_i32_e32 v37, v37, v48
	v_max_i32_e32 v38, v38, v42
	v_min_i32_e32 v45, v24, v41
	v_min_i32_e32 v51, v46, v50
	v_max_i32_e32 v40, v34, v39
	v_max_i32_e32 v23, v25, v22
	v_max_i32_e32 v44, v36, v43
	v_max_i32_e32 v42, v37, v38
	v_min_i32_e32 v37, v37, v38
	v_min_i32_e32 v34, v34, v39
	v_max_i32_e32 v39, v63, v64
	v_max_i32_e32 v24, v24, v41
	v_max_i32_e32 v46, v46, v50
	v_max_i32_e32 v50, v53, v57
	v_min_i32_e32 v22, v25, v22
	v_min_i32_e32 v25, v36, v43
	v_min_i32_e32 v62, v53, v57
	v_min_i32_e32 v65, v63, v64
	v_min_i32_e32 v35, v40, v23
	v_min_i32_e32 v47, v44, v42
	v_max_i32_e32 v23, v40, v23
	v_max_i32_e32 v40, v44, v42
	v_max_i32_e32 v38, v37, v34
	v_max_i32_e32 v41, v39, v24
	v_max_i32_e32 v53, v46, v50
	v_max_i32_e32 v36, v22, v25
	v_min_i32_e32 v46, v46, v50
	v_min_i32_e32 v22, v22, v25
	v_min_i32_e32 v52, v45, v51
	v_min_i32_e32 v82, v62, v65
	v_min_i32_e32 v48, v35, v47
	v_max_i32_e32 v45, v45, v51
	v_max_i32_e32 v49, v62, v65
	v_max_i32_e32 v35, v35, v47
	v_min_i32_e32 v42, v23, v40
	v_max_i32_e32 v47, v38, v41
	v_max_i32_e32 v43, v53, v36
	v_min_i32_e32 v34, v37, v34
	v_min_i32_e32 v24, v39, v24
	v_max_i32_e32 v25, v46, v22
	v_min_i32_e32 v38, v38, v41
	v_max_i32_e32 v51, v45, v49
	v_min_i32_e32 v44, v35, v42
	v_min_i32_e32 v57, v47, v43
	v_max_i32_e32 v37, v34, v24
	v_min_i32_e32 v36, v53, v36
	v_max_i32_e32 v41, v25, v38
	v_min_i32_e32 v25, v25, v38
	v_min_i32_e32 v22, v46, v22
	v_min_i32_e32 v24, v34, v24
	v_max_i32_e32 v38, v52, v82
	v_min_i32_e32 v45, v45, v49
	v_max_i32_e32 v62, v48, v51
	v_min_i32_e32 v63, v44, v57
	v_max_i32_e32 v39, v37, v36
	v_max_i32_e32 v34, v22, v24
	v_max_i32_e32 v46, v38, v45
	v_max_i32_e32 v64, v62, v63
	v_max_i32_e32 v50, v39, v41
	v_min_i32_e32 v62, v62, v63
	v_min_i32_e32 v39, v39, v41
	v_min_i32_e32 v36, v37, v36
	v_max_i32_e32 v49, v34, v46
	v_min_i32_e32 v48, v48, v51
	v_min_i32_e32 v22, v22, v24
	v_min_i32_e32 v24, v38, v45
	v_min_i32_e32 v53, v64, v50
	v_max_i32_e32 v41, v62, v39
	v_max_i32_e32 v37, v36, v25
	v_max_i32_e32 v51, v49, v48
	v_max_i32_e32 v38, v22, v24
	v_min_i32_e32 v34, v34, v46
	v_min_i32_e32 v25, v36, v25
	v_min_i32_e32 v36, v49, v48
	v_min_i32_e32 v124, v52, v82
	v_max_i32_e32 v52, v37, v51
	v_min_i32_e32 v39, v62, v39
	v_max_i32_e32 v45, v38, v34
	v_min_i32_e32 v46, v25, v36
	v_max_i32_e32 v35, v35, v42
	v_max_i32_e32 v42, v47, v43
	v_min_i32_e32 v34, v38, v34
	v_max_i32_e32 v38, v53, v41
	v_min_i32_e32 v37, v37, v51
	v_max_i32_e32 v25, v25, v36
	v_max_i32_e32 v48, v45, v46
	v_max_i32_e32 v44, v44, v57
	v_min_i32_e32 v43, v35, v42
	v_max3_i32 v30, v30, v32, v38
	v_min_i32_e32 v38, v52, v39
	v_max_i32_e32 v36, v37, v25
	v_min_i32_e32 v25, v37, v25
	v_min_i32_e32 v63, v53, v41
	v_max_i32_e32 v62, v52, v39
	v_max3_i32 v27, v147, v27, v48
	v_max_i32_e32 v48, v64, v50
	v_min_i32_e32 v47, v44, v43
	v_min_i32_e32 v39, v38, v36
	v_max_i32_e32 v19, v19, v25
	v_max3_i32 v25, v55, v44, v43
	v_min_i32_e32 v43, v45, v46
	v_min_i32_e32 v65, v63, v62
	v_max_i32_e32 v49, v48, v47
	v_max3_i32 v26, v26, v28, v39
	v_max_i32_e32 v28, v35, v42
	v_min_i32_e32 v22, v22, v24
	v_max_i32_e32 v18, v18, v43
	v_min_i32_e32 v43, v48, v47
	v_max3_i32 v124, v143, v145, v124
	v_max3_i32 v29, v29, v31, v65
	v_max3_i32 v33, v33, v59, v49
	v_max3_i32 v34, v144, v146, v34
	v_max3_i32 v28, v58, v60, v28
	v_max_i32_e32 v22, v61, v22
	v_max3_i32 v21, v21, v63, v62
	v_max_i32_e32 v43, v54, v43
	v_max3_i32 v20, v20, v38, v36
	v_max3_i32 v23, v56, v23, v40
	v_min_i32_e32 v31, v124, v29
	v_min_i32_e32 v49, v27, v33
	v_min_i32_e32 v32, v34, v30
	v_min_i32_e32 v35, v26, v28
; __device__ __forceinline__ void merge16_desc(int (&a)[16], const int (&b)[16]) {
; #pragma unroll
;     for (int i = 0; i < 16; ++i) a[i] = a[i] > b[15 - i] ? a[i] : b[15 - i];
; #pragma unroll
;     for (int j = 8; j > 0; j >>= 1)
; #pragma unroll
;         for (int i = 0; i < 16; ++i) { const int l = i ^ j; if (l > i) ce_desc(a[i], a[l]); }
; }
; __device__ __forceinline__ void route_task(int task, int tl0, const bf16* QP  , const LAS bf16* KHL, LAS unsigned short* EL, LAS float* GL, int lane) {
;     ...
;         { const unsigned h4 = 4u * (unsigned)hi;
; #pragma unroll
;           for (int i = 0; i < 16; ++i) cur[i] -= (int)h4; }
;         int oth[16];
; #pragma unroll
;         for (int i = 0; i < 16; ++i) oth[i] = __shfl_xor(cur[i], 32);
;         merge16_desc(cur, oth);
; #pragma unroll
;         for (int i = 0; i < 16; ++i) top[half][i] = cur[i];
;     }
;     unsigned P1[4], P2[4];
; #pragma unroll
;     for (int q = 0; q < 4; ++q) { P1[q] = 0u; P2[q] = 0u;
; #pragma unroll
;         for (int s = 0; s < 4; ++s) { P1[q] |= (127u - ((unsigned)top[0][4 * q + s] & 127u)) << (8 * s); P2[q] |= (127u - ((unsigned)top[1][4 * q + s] & 127u)) << (8 * s); } }
	v_min_i32_e32 v24, v22, v21
	v_min_i32_e32 v37, v19, v25
	v_min_i32_e32 v44, v18, v43
	v_min_i32_e32 v36, v20, v23
	v_max_i32_e32 v29, v124, v29
	v_max_i32_e32 v27, v27, v33
	v_max_i32_e32 v30, v34, v30
	v_max_i32_e32 v26, v26, v28
	v_max_i32_e32 v21, v22, v21
	v_max_i32_e32 v19, v19, v25
	v_max_i32_e32 v18, v18, v43
	v_max_i32_e32 v20, v20, v23
	v_max_i32_e32 v33, v29, v27
	v_max_i32_e32 v28, v30, v26
	v_max_i32_e32 v22, v21, v19
	v_max_i32_e32 v23, v18, v20
	v_max_i32_e32 v34, v33, v28
	v_max_i32_e32 v25, v22, v23
	v_min_i32_e32 v28, v33, v28
	v_min_i32_e32 v22, v22, v23
	v_min_i32_e32 v27, v29, v27
	v_min_i32_e32 v26, v30, v26
	v_min_i32_e32 v19, v21, v19
	v_min_i32_e32 v18, v18, v20
	v_max_i32_e32 v23, v28, v22
	v_min_i32_e32 v22, v28, v22
	v_max_i32_e32 v28, v27, v26
	v_max_i32_e32 v20, v19, v18
	v_min_i32_e32 v26, v27, v26
	v_min_i32_e32 v18, v19, v18
	v_min_i32_e32 v42, v24, v37
	v_max_i32_e32 v19, v26, v18
	v_min_i32_e32 v18, v26, v18
	v_max_i32_e32 v26, v31, v49
	v_max_i32_e32 v27, v32, v35
	v_max_i32_e32 v24, v24, v37
	v_max_i32_e32 v29, v44, v36
	v_min_i32_e32 v50, v31, v49
	v_min_i32_e32 v39, v32, v35
	v_min_i32_e32 v38, v44, v36
	v_max_i32_e32 v21, v28, v20
	v_min_i32_e32 v20, v28, v20
	v_max_i32_e32 v28, v26, v27
	v_max_i32_e32 v30, v24, v29
	v_min_i32_e32 v26, v26, v27
	v_min_i32_e32 v24, v24, v29
	v_min_i32_e32 v41, v50, v39
	v_min_i32_e32 v40, v42, v38
	v_max_i32_e32 v27, v26, v24
	v_min_i32_e32 v24, v26, v24
	v_max_i32_e32 v26, v50, v39
	v_max_i32_e32 v29, v42, v38
	v_min_i32_e32 v45, v41, v40
	v_max_i32_e32 v43, v34, v25
	v_min_i32_e32 v25, v34, v25
	v_max_i32_e32 v31, v28, v30
	v_min_i32_e32 v28, v28, v30
	v_max_i32_e32 v30, v26, v29
	v_min_i32_e32 v26, v26, v29
	v_max_i32_e32 v29, v41, v40
	v_sub_u32_e32 v32, v43, v87
	v_sub_u32_e32 v25, v25, v87
	v_sub_u32_e32 v23, v23, v87
	v_sub_u32_e32 v22, v22, v87
	v_sub_u32_e32 v21, v21, v87
	v_sub_u32_e32 v20, v20, v87
	v_sub_u32_e32 v19, v19, v87
	v_sub_u32_e32 v18, v18, v87
	v_sub_u32_e32 v31, v31, v87
	v_sub_u32_e32 v28, v28, v87
	v_sub_u32_e32 v27, v27, v87
	v_sub_u32_e32 v24, v24, v87
	v_sub_u32_e32 v30, v30, v87
	v_sub_u32_e32 v26, v26, v87
	v_sub_u32_e32 v29, v29, v87
	v_sub_u32_e32 v33, v45, v87
	ds_bpermute_b32 v34, v123, v32
	ds_bpermute_b32 v35, v123, v25
	ds_bpermute_b32 v36, v123, v23
	ds_bpermute_b32 v37, v123, v22
	ds_bpermute_b32 v38, v123, v21
	ds_bpermute_b32 v39, v123, v20
	ds_bpermute_b32 v40, v123, v19
	ds_bpermute_b32 v41, v123, v18
	ds_bpermute_b32 v42, v123, v31
	ds_bpermute_b32 v43, v123, v28
	ds_bpermute_b32 v44, v123, v27
	ds_bpermute_b32 v45, v123, v33
	ds_bpermute_b32 v46, v123, v29
	ds_bpermute_b32 v47, v123, v26
	ds_bpermute_b32 v48, v123, v30
	ds_bpermute_b32 v49, v123, v24
	s_waitcnt lgkmcnt(4)
	v_max_i32_e32 v32, v32, v45
	s_waitcnt lgkmcnt(3)
	v_max_i32_e32 v25, v25, v46
	s_waitcnt lgkmcnt(2)
	v_max_i32_e32 v23, v23, v47
	s_waitcnt lgkmcnt(1)
	v_max_i32_e32 v22, v22, v48
	s_waitcnt lgkmcnt(0)
	v_max_i32_e32 v21, v21, v49
	v_max_i32_e32 v20, v20, v44
	v_max_i32_e32 v19, v19, v43
	v_max_i32_e32 v18, v18, v42
	v_max_i32_e32 v31, v31, v41
	v_max_i32_e32 v28, v28, v40
	v_max_i32_e32 v27, v27, v39
	v_max_i32_e32 v24, v24, v38
	v_max_i32_e32 v30, v30, v37
	v_max_i32_e32 v26, v26, v36
	v_max_i32_e32 v29, v29, v35
	v_max_i32_e32 v33, v33, v34
	v_max_i32_e32 v34, v32, v31
	v_min_i32_e32 v31, v32, v31
	v_max_i32_e32 v32, v25, v28
	v_min_i32_e32 v25, v25, v28
	v_max_i32_e32 v28, v23, v27
	v_min_i32_e32 v23, v23, v27
	v_max_i32_e32 v27, v22, v24
	v_min_i32_e32 v22, v22, v24
	v_max_i32_e32 v24, v21, v30
	v_min_i32_e32 v21, v21, v30
	v_max_i32_e32 v30, v20, v26
	v_min_i32_e32 v20, v20, v26
	v_max_i32_e32 v26, v19, v29
	v_min_i32_e32 v19, v19, v29
	v_max_i32_e32 v29, v18, v33
	v_min_i32_e32 v18, v18, v33
	v_max_i32_e32 v33, v34, v24
	v_min_i32_e32 v24, v34, v24
	v_max_i32_e32 v34, v32, v30
	v_min_i32_e32 v30, v32, v30
	v_max_i32_e32 v32, v28, v26
	v_min_i32_e32 v26, v28, v26
	v_max_i32_e32 v28, v27, v29
	v_min_i32_e32 v27, v27, v29
	v_max_i32_e32 v29, v31, v21
	v_min_i32_e32 v21, v31, v21
	v_max_i32_e32 v31, v25, v20
	v_min_i32_e32 v20, v25, v20
	v_max_i32_e32 v25, v23, v19
	v_min_i32_e32 v19, v23, v19
	v_max_i32_e32 v23, v22, v18
	v_min_i32_e32 v18, v22, v18
	v_max_i32_e32 v22, v33, v32
	v_min_i32_e32 v32, v33, v32
	v_max_i32_e32 v33, v34, v28
	v_min_i32_e32 v28, v34, v28
	v_max_i32_e32 v34, v24, v26
	v_min_i32_e32 v24, v24, v26
	v_max_i32_e32 v35, v30, v27
	v_min_i32_e32 v27, v30, v27
	v_max_i32_e32 v30, v29, v25
	v_min_i32_e32 v25, v29, v25
	v_max_i32_e32 v29, v31, v23
	v_min_i32_e32 v23, v31, v23
	v_max_i32_e32 v31, v21, v19
	v_min_i32_e32 v19, v21, v19
	v_max_i32_e32 v21, v20, v18
	v_min_i32_e32 v18, v20, v18
	v_max_i32_e32 v26, v22, v33
	v_min_i32_e32 v33, v22, v33
	v_lshlrev_b32_e32 v20, 8, v81
	v_lshlrev_b32_e32 v22, 16, v80
	v_max_i32_e32 v36, v32, v28
	v_max_i32_e32 v40, v19, v18
	v_min_i32_e32 v41, v19, v18
	v_and_b32_e32 v18, 0x7f, v79
	v_and_b32_e32 v20, 0x7f00, v20
	v_and_b32_e32 v22, 0x7f0000, v22
	v_max_i32_e32 v39, v31, v21
	v_min_i32_e32 v31, v31, v21
	v_lshlrev_b32_e32 v21, 8, v33
	v_or3_b32 v18, v20, v18, v22
	v_lshlrev_b32_e32 v20, 16, v36
	v_and_b32_e32 v19, 0x7f, v26
	v_and_b32_e32 v21, 0x7f00, v21
	v_and_b32_e32 v20, 0x7f0000, v20
	v_or3_b32 v20, v21, v19, v20
	v_lshlrev_b32_e32 v19, 24, v78
	v_min_i32_e32 v28, v32, v28
	v_and_b32_e32 v19, 0x7f000000, v19
	v_bitop3_b32 v19, v18, s68, v19 bitop3:0x36
	v_lshlrev_b32_e32 v18, 24, v28
	v_max_i32_e32 v32, v34, v35
	v_min_i32_e32 v34, v34, v35
	v_max_i32_e32 v35, v24, v27
	v_min_i32_e32 v27, v24, v27
	v_and_b32_e32 v18, 0x7f000000, v18
	v_lshlrev_b32_e32 v22, 8, v76
	v_lshlrev_b32_e32 v24, 16, v75
; #define CE_(a, b) ce_desc(v[a], v[b])
; __device__ __forceinline__ void sort16_desc(int (&v)[16]) {
;     ...
;     CE_(0,13); CE_(1,12); CE_(2,15); CE_(3,14); CE_(4,8); CE_(5,6); CE_(7,11); CE_(9,10);
;     CE_(0,5); CE_(1,7); CE_(2,9); CE_(3,4); CE_(6,13); CE_(8,14); CE_(10,15); CE_(11,12);
;     CE_(0,1); CE_(2,3); CE_(4,5); CE_(6,8); CE_(7,9); CE_(10,11); CE_(12,13); CE_(14,15);
;     CE_(0,2); CE_(1,3); CE_(4,10); CE_(5,11); CE_(6,7); CE_(8,9); CE_(12,14); CE_(13,15);
;     CE_(1,2); CE_(3,12); CE_(4,6); CE_(5,7); CE_(8,10); CE_(9,11); CE_(13,14);
;     CE_(1,4); CE_(2,6); CE_(5,8); CE_(7,10); CE_(9,13); CE_(11,14);
;     CE_(2,4); CE_(3,6); CE_(9,12); CE_(11,13);
;     CE_(3,5); CE_(6,8); CE_(7,9); CE_(10,12);
;     CE_(3,4); CE_(5,6); CE_(7,8); CE_(9,10); CE_(11,12);
;     CE_(6,7); CE_(8,9);
;     ...
; }
; __device__ __forceinline__ void route_task(int task, int tl0, const bf16* QP  , const LAS bf16* KHL, LAS unsigned short* EL, LAS float* GL, int lane) {
;     ...
;     for (int q = 0; q < 4; ++q) { P1[q] = 0u; P2[q] = 0u;
; #pragma unroll
;         for (int s = 0; s < 4; ++s) { P1[q] |= (127u - ((unsigned)top[0][4 * q + s] & 127u)) << (8 * s); P2[q] |= (127u - ((unsigned)top[1][4 * q + s] & 127u)) << (8 * s); } }
;     int bk[16];
;     {
;         int hi2 = hi; asm volatile("" : "+v"(hi2));
;         const bool h1 = hi2 != 0;
;         constexpr int A1[16] = {1, 1, 1, 1, 1, 1, 1, 1, 2, 2, 2, 2, 2, 3, 3, 3}, B1[16] = {0, 1, 2, 3, 4, 5, 6, 7, 0, 1, 2, 3, 4, 0, 1, 2};
; #pragma unroll
;         for (int i = 0; i < 16; ++i) { const float ta = __int_as_float(h1 ? top[0][A1[i]] : top[0][0]), tb = __int_as_float(h1 ? top[1][B1[i]] : top[1][i]); const unsigned code = h1 ? (unsigned)(A1[i] * 16 + B1[i]) : (unsigned)i;
;             bk[i] = (int)((__float_as_uint(ta + tb) | 255u) - code); }
;         sort16_desc(bk);
	v_bitop3_b32 v18, v20, s68, v18 bitop3:0x36
	v_and_b32_e32 v20, 0x7f, v77
	v_and_b32_e32 v22, 0x7f00, v22
	v_and_b32_e32 v24, 0x7f0000, v24
	v_max_i32_e32 v37, v30, v29
	v_min_i32_e32 v29, v30, v29
	v_max_i32_e32 v30, v25, v23
	v_min_i32_e32 v38, v25, v23
	v_lshlrev_b32_e32 v23, 8, v34
	v_or3_b32 v20, v22, v20, v24
	v_lshlrev_b32_e32 v22, 16, v35
	v_and_b32_e32 v21, 0x7f, v32
	v_and_b32_e32 v23, 0x7f00, v23
	v_and_b32_e32 v22, 0x7f0000, v22
	v_or3_b32 v22, v23, v21, v22
	v_lshlrev_b32_e32 v21, 24, v73
	v_and_b32_e32 v21, 0x7f000000, v21
	v_bitop3_b32 v21, v20, s68, v21 bitop3:0x36
	v_lshlrev_b32_e32 v20, 24, v27
	v_and_b32_e32 v20, 0x7f000000, v20
	v_lshlrev_b32_e32 v24, 8, v74
	v_lshlrev_b32_e32 v42, 16, v72
	v_bitop3_b32 v20, v22, s68, v20 bitop3:0x36
	v_and_b32_e32 v22, 0x7f, v71
	v_and_b32_e32 v24, 0x7f00, v24
	v_and_b32_e32 v42, 0x7f0000, v42
	v_lshlrev_b32_e32 v25, 8, v29
	v_or3_b32 v22, v24, v22, v42
	v_lshlrev_b32_e32 v24, 16, v30
	v_and_b32_e32 v23, 0x7f, v37
	v_and_b32_e32 v25, 0x7f00, v25
	v_and_b32_e32 v24, 0x7f0000, v24
	v_or3_b32 v24, v25, v23, v24
	v_lshlrev_b32_e32 v23, 24, v70
	v_and_b32_e32 v23, 0x7f000000, v23
	v_bitop3_b32 v23, v22, s68, v23 bitop3:0x36
	v_lshlrev_b32_e32 v22, 24, v38
	v_and_b32_e32 v22, 0x7f000000, v22
	v_lshlrev_b32_e32 v42, 8, v68
	v_lshlrev_b32_e32 v44, 16, v67
	v_bitop3_b32 v22, v24, s68, v22 bitop3:0x36
	v_and_b32_e32 v24, 0x7f, v69
	v_and_b32_e32 v42, 0x7f00, v42
	v_and_b32_e32 v44, 0x7f0000, v44
	v_lshlrev_b32_e32 v43, 8, v31
	v_or3_b32 v24, v42, v24, v44
	v_lshlrev_b32_e32 v42, 16, v40
	v_and_b32_e32 v25, 0x7f, v39
	v_and_b32_e32 v43, 0x7f00, v43
	v_and_b32_e32 v42, 0x7f0000, v42
	v_or3_b32 v42, v43, v25, v42
	v_lshlrev_b32_e32 v25, 24, v66
	v_and_b32_e32 v25, 0x7f000000, v25
	v_bitop3_b32 v25, v24, s68, v25 bitop3:0x36
	v_lshlrev_b32_e32 v24, 24, v41
	v_and_b32_e32 v24, 0x7f000000, v24
	v_bitop3_b32 v24, v42, s68, v24 bitop3:0x36
	v_mov_b32_e32 v42, v86
	v_add_f32_e32 v62, v74, v26
	v_cmp_eq_u32_e32 vcc, 0, v42
	v_add_f32_e32 v63, v72, v26
	v_add_f32_e32 v64, v70, v26
	v_cndmask_b32_e32 v42, v81, v79, vcc
	v_add_f32_e32 v44, v42, v26
	v_cndmask_b32_e64 v43, -16, 0, vcc
	v_or_b32_e32 v44, 0xff, v44
	v_add_f32_e32 v45, v42, v33
	v_add_u32_e32 v43, v44, v43
	v_cndmask_b32_e64 v44, v99, -1, vcc
	v_or_b32_e32 v45, 0xff, v45
	v_add_f32_e32 v46, v42, v36
	v_add_u32_e32 v44, v45, v44
	v_cndmask_b32_e64 v45, v100, -2, vcc
	v_or_b32_e32 v46, 0xff, v46
	v_add_f32_e32 v47, v42, v28
	v_add_u32_e32 v45, v46, v45
	v_cndmask_b32_e64 v46, v101, -3, vcc
	v_or_b32_e32 v47, 0xff, v47
	v_add_f32_e32 v48, v42, v32
	v_add_u32_e32 v46, v47, v46
	v_cndmask_b32_e64 v47, v102, -4, vcc
	v_or_b32_e32 v48, 0xff, v48
	v_add_f32_e32 v34, v42, v34
	v_add_f32_e32 v35, v42, v35
	v_add_f32_e32 v27, v42, v27
	v_cndmask_b32_e32 v42, v80, v79, vcc
	v_cndmask_b32_e32 v32, v32, v39, vcc
	v_add_u32_e32 v47, v48, v47
	v_cndmask_b32_e64 v48, v103, -5, vcc
	v_or_b32_e32 v34, 0xff, v34
	v_add_f32_e32 v32, v42, v32
	v_add_u32_e32 v34, v34, v48
	v_cndmask_b32_e64 v48, v104, -6, vcc
	v_or_b32_e32 v35, 0xff, v35
	v_cndmask_b32_e32 v37, v26, v37, vcc
	v_cndmask_b32_e64 v39, v116, -12, vcc
	v_or_b32_e32 v32, 0xff, v32
	v_add_u32_e32 v35, v35, v48
	v_cndmask_b32_e64 v48, v105, -7, vcc
	v_or_b32_e32 v27, 0xff, v27
	v_add_f32_e32 v37, v42, v37
	v_cndmask_b32_e32 v29, v33, v29, vcc
	v_add_u32_e32 v32, v32, v39
	v_cndmask_b32_e32 v39, v78, v79, vcc
	v_cndmask_b32_e32 v31, v26, v31, vcc
	v_add_u32_e32 v27, v27, v48
	v_cndmask_b32_e64 v48, v106, -8, vcc
	v_or_b32_e32 v37, 0xff, v37
	v_add_f32_e32 v29, v42, v29
	v_cndmask_b32_e32 v30, v36, v30, vcc
	v_cndmask_b32_e32 v38, v28, v38, vcc
	v_add_f32_e32 v31, v39, v31
	v_cndmask_b32_e32 v40, v33, v40, vcc
	v_add_u32_e32 v37, v37, v48
	v_cndmask_b32_e64 v48, v107, -9, vcc
	v_or_b32_e32 v29, 0xff, v29
	v_add_f32_e32 v30, v42, v30
	v_add_f32_e32 v38, v42, v38
	v_cndmask_b32_e64 v42, v117, -13, vcc
	v_or_b32_e32 v31, 0xff, v31
	v_add_f32_e32 v40, v39, v40
	v_cndmask_b32_e32 v41, v36, v41, vcc
	v_add_u32_e32 v29, v29, v48
	v_cndmask_b32_e64 v48, v114, -10, vcc
	v_or_b32_e32 v30, 0xff, v30
	v_add_u32_e32 v31, v31, v42
	v_cndmask_b32_e64 v42, v118, -14, vcc
	v_or_b32_e32 v40, 0xff, v40
	v_add_f32_e32 v39, v39, v41
	v_add_u32_e32 v30, v30, v48
	v_cndmask_b32_e64 v48, v115, -11, vcc
	v_or_b32_e32 v38, 0xff, v38
	v_add_u32_e32 v40, v40, v42
	v_cndmask_b32_e64 v42, v119, -15, vcc
	v_or_b32_e32 v39, 0xff, v39
	v_add_u32_e32 v38, v38, v48
	v_add_u32_e32 v39, v39, v42
	v_max_i32_e32 v41, v43, v31
	v_min_i32_e32 v31, v43, v31
	v_max_i32_e32 v42, v44, v32
	v_min_i32_e32 v32, v44, v32
	v_max_i32_e32 v43, v45, v39
	v_min_i32_e32 v39, v45, v39
	v_max_i32_e32 v44, v46, v40
	v_min_i32_e32 v40, v46, v40
	v_max_i32_e32 v45, v47, v37
	v_min_i32_e32 v37, v47, v37
	v_max_i32_e32 v46, v34, v35
	v_min_i32_e32 v34, v34, v35
	v_max_i32_e32 v35, v27, v38
	v_min_i32_e32 v27, v27, v38
	v_max_i32_e32 v38, v29, v30
	v_min_i32_e32 v29, v29, v30
	v_max_i32_e32 v30, v41, v46
	v_min_i32_e32 v41, v41, v46
	v_max_i32_e32 v46, v42, v35
	v_min_i32_e32 v35, v42, v35
	v_max_i32_e32 v42, v43, v38
	v_min_i32_e32 v38, v43, v38
	v_max_i32_e32 v43, v44, v45
	v_min_i32_e32 v44, v44, v45
	v_max_i32_e32 v45, v34, v31
	v_min_i32_e32 v31, v34, v31
	v_max_i32_e32 v34, v37, v40
	v_min_i32_e32 v37, v37, v40
	v_max_i32_e32 v40, v29, v39
	v_min_i32_e32 v29, v29, v39
	v_max_i32_e32 v39, v27, v32
	v_min_i32_e32 v27, v27, v32
	v_max_i32_e32 v32, v30, v46
	v_min_i32_e32 v30, v30, v46
	v_max_i32_e32 v46, v42, v43
	v_min_i32_e32 v42, v42, v43
	v_max_i32_e32 v43, v44, v41
	v_min_i32_e32 v41, v44, v41
	v_max_i32_e32 v44, v45, v34
	v_min_i32_e32 v34, v45, v34
; #define CAND(a, b) (int)((__float_as_uint(__int_as_float(top[0][a]) + __int_as_float(top[1][b])) | 255u) - (unsigned)((a) * 16 + (b)))
; __device__ __forceinline__ void route_task(int task, int tl0, const bf16* QP  , const LAS bf16* KHL, LAS unsigned short* EL, LAS float* GL, int lane) {
;     ...
;         sort16_desc(bk);
;         int oth[16];
; #pragma unroll
;         for (int i = 0; i < 16; ++i) oth[i] = __shfl_xor(bk[i], 32);
;         merge16_desc(bk, oth);
;     }
;     ...
;     {
;         int gk[16];
;         gk[0] = CAND(3, 3); gk[1] = CAND(4, 0); gk[2] = CAND(4, 1); gk[3] = CAND(4, 2); gk[4] = CAND(5, 0); gk[5] = CAND(5, 1); gk[6] = CAND(6, 0); gk[7] = CAND(6, 1);
;         gk[8] = CAND(7, 0); gk[9] = CAND(7, 1); gk[10] = CAND(8, 0); gk[11] = CAND(9, 0); gk[12] = CAND(10, 0); gk[13] = CAND(11, 0); gk[14] = CAND(12, 0); gk[15] = CAND(13, 0);
;         sort16_desc(gk);
;         merge16_desc(bk, gk);
	v_max_i32_e32 v45, v35, v38
	v_min_i32_e32 v35, v35, v38
	v_max_i32_e32 v38, v40, v39
	v_min_i32_e32 v39, v40, v39
	v_max_i32_e32 v40, v27, v31
	v_min_i32_e32 v27, v27, v31
	v_max_i32_e32 v31, v37, v29
	v_min_i32_e32 v29, v37, v29
	v_max_i32_e32 v37, v32, v46
	v_min_i32_e32 v32, v32, v46
	v_max_i32_e32 v46, v30, v42
	v_min_i32_e32 v30, v30, v42
	v_max_i32_e32 v42, v43, v38
	v_min_i32_e32 v38, v43, v38
	v_max_i32_e32 v43, v41, v39
	v_min_i32_e32 v39, v41, v39
	v_max_i32_e32 v41, v44, v45
	v_min_i32_e32 v44, v44, v45
	v_max_i32_e32 v45, v34, v35
	v_min_i32_e32 v34, v34, v35
	v_max_i32_e32 v35, v40, v31
	v_min_i32_e32 v31, v40, v31
	v_max_i32_e32 v40, v27, v29
	v_min_i32_e32 v27, v27, v29
	v_max_i32_e32 v29, v46, v32
	v_min_i32_e32 v32, v46, v32
	v_max_i32_e32 v46, v30, v35
	v_min_i32_e32 v30, v30, v35
	v_max_i32_e32 v35, v42, v41
	v_min_i32_e32 v41, v42, v41
	v_max_i32_e32 v42, v43, v44
	v_min_i32_e32 v43, v43, v44
	v_max_i32_e32 v44, v45, v38
	v_min_i32_e32 v38, v45, v38
	v_max_i32_e32 v45, v34, v39
	v_min_i32_e32 v34, v34, v39
	v_max_i32_e32 v39, v40, v31
	v_min_i32_e32 v31, v40, v31
	v_max_i32_e32 v40, v29, v35
	v_min_i32_e32 v29, v29, v35
	v_max_i32_e32 v35, v32, v41
	v_min_i32_e32 v32, v32, v41
	v_max_i32_e32 v41, v42, v44
	v_min_i32_e32 v42, v42, v44
	v_max_i32_e32 v44, v43, v38
	v_min_i32_e32 v38, v43, v38
	v_max_i32_e32 v43, v45, v39
	v_min_i32_e32 v39, v45, v39
	v_max_i32_e32 v45, v34, v31
	v_min_i32_e32 v31, v34, v31
	v_max_i32_e32 v34, v35, v29
	v_min_i32_e32 v29, v35, v29
	v_max_i32_e32 v35, v46, v32
	v_min_i32_e32 v32, v46, v32
	v_max_i32_e32 v46, v43, v30
	v_min_i32_e32 v30, v43, v30
	v_max_i32_e32 v43, v45, v39
	v_min_i32_e32 v39, v45, v39
	v_max_i32_e32 v45, v35, v41
	v_min_i32_e32 v35, v35, v41
	v_max_i32_e32 v41, v32, v42
	v_min_i32_e32 v32, v32, v42
	v_max_i32_e32 v42, v44, v46
	v_min_i32_e32 v44, v44, v46
	v_max_i32_e32 v46, v38, v30
	v_min_i32_e32 v30, v38, v30
	v_max_i32_e32 v38, v45, v29
	v_min_i32_e32 v29, v45, v29
	v_max_i32_e32 v45, v35, v41
	v_min_i32_e32 v35, v35, v41
	v_max_i32_e32 v41, v42, v32
	v_min_i32_e32 v32, v42, v32
	v_max_i32_e32 v42, v44, v46
	v_min_i32_e32 v44, v44, v46
	v_max_i32_e32 v46, v43, v30
	v_min_i32_e32 v30, v43, v30
	v_max_i32_e32 v43, v35, v41
	v_min_i32_e32 v35, v35, v41
	v_max_i32_e32 v41, v32, v42
	v_min_i32_e32 v32, v32, v42
	ds_bpermute_b32 v54, v123, v41
	ds_bpermute_b32 v55, v123, v32
	ds_bpermute_b32 v56, v123, v44
	ds_bpermute_b32 v57, v123, v27
	ds_bpermute_b32 v58, v123, v31
	ds_bpermute_b32 v59, v123, v39
	ds_bpermute_b32 v60, v123, v30
	ds_bpermute_b32 v61, v123, v46
	ds_bpermute_b32 v42, v123, v37
	ds_bpermute_b32 v47, v123, v40
	ds_bpermute_b32 v48, v123, v34
	ds_bpermute_b32 v49, v123, v38
	ds_bpermute_b32 v50, v123, v29
	ds_bpermute_b32 v51, v123, v45
	ds_bpermute_b32 v52, v123, v43
	ds_bpermute_b32 v53, v123, v35
	s_waitcnt lgkmcnt(12)
	v_max_i32_e32 v37, v37, v57
	s_waitcnt lgkmcnt(11)
	v_max_i32_e32 v40, v40, v58
	s_waitcnt lgkmcnt(10)
	v_max_i32_e32 v34, v34, v59
	s_waitcnt lgkmcnt(9)
	v_max_i32_e32 v38, v38, v60
	s_waitcnt lgkmcnt(8)
	v_max_i32_e32 v29, v29, v61
	v_max_i32_e32 v45, v45, v56
	v_max_i32_e32 v43, v43, v55
	v_max_i32_e32 v35, v35, v54
	v_add_f32_e32 v28, v78, v28
	v_add_f32_e32 v54, v77, v26
	v_add_f32_e32 v55, v77, v33
	v_add_f32_e32 v36, v77, v36
	v_add_f32_e32 v56, v76, v26
	v_add_f32_e32 v57, v76, v33
	v_add_f32_e32 v58, v75, v26
	v_add_f32_e32 v59, v75, v33
	v_add_f32_e32 v60, v73, v26
	v_add_f32_e32 v33, v73, v33
	v_add_f32_e32 v61, v71, v26
	v_add_f32_e32 v65, v69, v26
	v_add_f32_e32 v68, v68, v26
	v_or_b32_e32 v28, 0xff, v28
	v_or_b32_e32 v54, 0xff, v54
	v_or_b32_e32 v55, 0xff, v55
	v_or_b32_e32 v36, 0xff, v36
	v_or_b32_e32 v56, 0xff, v56
	v_or_b32_e32 v57, 0xff, v57
	v_or_b32_e32 v58, 0xff, v58
	v_or_b32_e32 v59, 0xff, v59
	v_or_b32_e32 v60, 0xff, v60
	v_or_b32_e32 v33, 0xff, v33
	v_or_b32_e32 v61, 0xff, v61
	v_or_b32_e32 v62, 0xff, v62
	v_or_b32_e32 v63, 0xff, v63
	v_or_b32_e32 v64, 0xff, v64
	v_or_b32_e32 v65, 0xff, v65
	v_or_b32_e32 v68, 0xff, v68
	v_subrev_u32_e32 v28, 51, v28
	v_subrev_u32_e32 v54, 64, v54
	v_add_u32_e32 v55, 0xffffffbf, v55
	v_add_u32_e32 v36, 0xffffffbe, v36
	v_add_u32_e32 v56, 0xffffffb0, v56
	v_add_u32_e32 v57, 0xffffffaf, v57
	v_add_u32_e32 v58, 0xffffffa0, v58
	v_add_u32_e32 v59, 0xffffff9f, v59
	v_add_u32_e32 v60, 0xffffff90, v60
	v_add_u32_e32 v33, 0xffffff8f, v33
	v_add_u32_e32 v61, 0xffffff80, v61
	v_add_u32_e32 v62, 0xffffff70, v62
	v_add_u32_e32 v63, 0xffffff60, v63
	v_add_u32_e32 v64, 0xffffff50, v64
	v_add_u32_e32 v65, 0xffffff40, v65
	v_add_u32_e32 v68, 0xffffff30, v68
	v_max_i32_e32 v69, v28, v64
	v_min_i32_e32 v28, v28, v64
	v_max_i32_e32 v64, v54, v63
	v_min_i32_e32 v54, v54, v63
	v_max_i32_e32 v63, v55, v68
	v_min_i32_e32 v55, v55, v68
	v_max_i32_e32 v68, v36, v65
	v_min_i32_e32 v36, v36, v65
	v_max_i32_e32 v65, v56, v60
	v_min_i32_e32 v56, v56, v60
	v_max_i32_e32 v60, v57, v58
	v_min_i32_e32 v57, v57, v58
	v_max_i32_e32 v58, v59, v62
	v_min_i32_e32 v59, v59, v62
	v_max_i32_e32 v62, v33, v61
	v_min_i32_e32 v33, v33, v61
	v_max_i32_e32 v61, v69, v60
	v_min_i32_e32 v60, v69, v60
	v_max_i32_e32 v69, v64, v58
	v_min_i32_e32 v58, v64, v58
	v_max_i32_e32 v64, v63, v62
	v_min_i32_e32 v62, v63, v62
	v_max_i32_e32 v63, v68, v65
	v_min_i32_e32 v65, v68, v65
	v_max_i32_e32 v68, v57, v28
	v_min_i32_e32 v28, v57, v28
	v_max_i32_e32 v57, v56, v36
	v_min_i32_e32 v36, v56, v36
	v_max_i32_e32 v56, v33, v55
	v_min_i32_e32 v33, v33, v55
	v_max_i32_e32 v55, v59, v54
	v_min_i32_e32 v54, v59, v54
	v_max_i32_e32 v59, v61, v69
	v_min_i32_e32 v61, v61, v69
	v_max_i32_e32 v69, v64, v63
	v_min_i32_e32 v63, v64, v63
	v_max_i32_e32 v64, v65, v60
	v_min_i32_e32 v60, v65, v60
	v_max_i32_e32 v65, v68, v57
	v_min_i32_e32 v57, v68, v57
	v_max_i32_e32 v68, v58, v62
	v_min_i32_e32 v58, v58, v62
	v_max_i32_e32 v62, v56, v55
	v_min_i32_e32 v55, v56, v55
	v_max_i32_e32 v56, v54, v28
	v_min_i32_e32 v28, v54, v28
	v_max_i32_e32 v54, v36, v33
	v_min_i32_e32 v33, v36, v33
	v_min_i32_e32 v36, v59, v69
	v_max_i32_e32 v70, v61, v63
	v_min_i32_e32 v61, v61, v63
	v_max_i32_e32 v63, v64, v62
	v_min_i32_e32 v62, v64, v62
	v_max_i32_e32 v64, v60, v55
	v_min_i32_e32 v55, v60, v55
	v_max_i32_e32 v60, v65, v68
	v_min_i32_e32 v65, v65, v68
	v_max_i32_e32 v68, v57, v58
	v_min_i32_e32 v57, v57, v58
	v_max_i32_e32 v58, v56, v54
	v_min_i32_e32 v54, v56, v54
	v_max_i32_e32 v56, v28, v33
	v_min_i32_e32 v28, v28, v33
	v_max_i32_e32 v33, v70, v36
	v_min_i32_e32 v36, v70, v36
	v_max_i32_e32 v70, v61, v58
	v_min_i32_e32 v58, v61, v58
	v_max_i32_e32 v61, v63, v60
	v_min_i32_e32 v60, v63, v60
	v_max_i32_e32 v63, v64, v65
	v_min_i32_e32 v64, v64, v65
	v_max_i32_e32 v65, v68, v62
	v_min_i32_e32 v62, v68, v62
	v_max_i32_e32 v68, v57, v55
	v_min_i32_e32 v55, v57, v55
	v_max_i32_e32 v57, v56, v54
	s_waitcnt lgkmcnt(0)
; #define CAND(a, b) (int)((__float_as_uint(__int_as_float(top[0][a]) + __int_as_float(top[1][b])) | 255u) - (unsigned)((a) * 16 + (b)))
; __device__ __forceinline__ void merge16_desc(int (&a)[16], const int (&b)[16]) {
; #pragma unroll
;     for (int i = 0; i < 16; ++i) a[i] = a[i] > b[15 - i] ? a[i] : b[15 - i];
; #pragma unroll
;     for (int j = 8; j > 0; j >>= 1)
; #pragma unroll
;         for (int i = 0; i < 16; ++i) { const int l = i ^ j; if (l > i) ce_desc(a[i], a[l]); }
; }
; __device__ __forceinline__ void route_task(int task, int tl0, const bf16* QP  , const LAS bf16* KHL, LAS unsigned short* EL, LAS float* GL, int lane) {
;     ...
;         gk[0] = CAND(3, 3); gk[1] = CAND(4, 0); gk[2] = CAND(4, 1); gk[3] = CAND(4, 2); gk[4] = CAND(5, 0); gk[5] = CAND(5, 1); gk[6] = CAND(6, 0); gk[7] = CAND(6, 1);
;         gk[8] = CAND(7, 0); gk[9] = CAND(7, 1); gk[10] = CAND(8, 0); gk[11] = CAND(9, 0); gk[12] = CAND(10, 0); gk[13] = CAND(11, 0); gk[14] = CAND(12, 0); gk[15] = CAND(13, 0);
;         sort16_desc(gk);
;         merge16_desc(bk, gk);
;     }
;     {
;         const int c14 = CAND(14, 0), c15 = CAND(15, 0);
;         const int n14 = max(bk[14], c14), n15 = max(min(bk[14], c14), max(bk[15], c15));
;         bk[14] = n14; bk[15] = n15;
;     }
	v_max_i32_e32 v41, v41, v53
	v_max_i32_e32 v32, v32, v52
	v_max_i32_e32 v44, v44, v51
	v_max_i32_e32 v46, v46, v50
	v_max_i32_e32 v30, v30, v49
	v_max_i32_e32 v39, v39, v48
	v_max_i32_e32 v31, v31, v47
	v_max_i32_e32 v27, v27, v42
	v_min_i32_e32 v54, v56, v54
	v_max_i32_e32 v56, v33, v61
	v_min_i32_e32 v33, v33, v61
	v_max_i32_e32 v61, v36, v60
	v_min_i32_e32 v36, v36, v60
	v_max_i32_e32 v60, v63, v65
	v_min_i32_e32 v63, v63, v65
	v_max_i32_e32 v65, v64, v62
	v_min_i32_e32 v62, v64, v62
	v_max_i32_e32 v64, v68, v57
	v_max_i32_e32 v42, v37, v41
	v_min_i32_e32 v37, v37, v41
	v_max_i32_e32 v41, v40, v32
	v_min_i32_e32 v32, v40, v32
	v_max_i32_e32 v40, v34, v44
	v_min_i32_e32 v34, v34, v44
	v_max_i32_e32 v44, v38, v46
	v_min_i32_e32 v38, v38, v46
	v_max_i32_e32 v46, v29, v30
	v_min_i32_e32 v29, v29, v30
	v_max_i32_e32 v30, v45, v39
	v_min_i32_e32 v39, v45, v39
	v_max_i32_e32 v45, v43, v31
	v_min_i32_e32 v31, v43, v31
	v_max_i32_e32 v43, v35, v27
	v_min_i32_e32 v27, v35, v27
	v_min_i32_e32 v57, v68, v57
	v_max_i32_e32 v68, v55, v54
	v_max_i32_e32 v71, v70, v36
	v_min_i32_e32 v36, v70, v36
	v_max_i32_e32 v70, v64, v58
	v_min_i32_e32 v58, v64, v58
	v_max_i32_e32 v35, v42, v46
	v_min_i32_e32 v42, v42, v46
	v_max_i32_e32 v46, v41, v30
	v_min_i32_e32 v30, v41, v30
	v_max_i32_e32 v41, v40, v45
	v_min_i32_e32 v40, v40, v45
	v_max_i32_e32 v45, v44, v43
	v_min_i32_e32 v43, v44, v43
	v_max_i32_e32 v44, v37, v29
	v_min_i32_e32 v29, v37, v29
	v_max_i32_e32 v37, v32, v39
	v_min_i32_e32 v32, v32, v39
	v_max_i32_e32 v39, v34, v31
	v_min_i32_e32 v31, v34, v31
	v_max_i32_e32 v34, v38, v27
	v_min_i32_e32 v27, v38, v27
	v_min_i32_e32 v54, v55, v54
	v_min_i32_e32 v55, v61, v33
	v_max_i32_e32 v64, v68, v57
	v_min_i32_e32 v57, v68, v57
	v_max_i32_e32 v68, v71, v60
	v_min_i32_e32 v60, v71, v60
	v_max_i32_e32 v71, v36, v63
	v_min_i32_e32 v36, v36, v63
	v_max_i32_e32 v63, v65, v70
	v_min_i32_e32 v65, v65, v70
	v_max_i32_e32 v70, v62, v58
	v_max_i32_e32 v38, v35, v41
	v_min_i32_e32 v35, v35, v41
	v_max_i32_e32 v41, v46, v45
	v_min_i32_e32 v45, v46, v45
	v_max_i32_e32 v46, v42, v40
	v_min_i32_e32 v40, v42, v40
	v_max_i32_e32 v42, v30, v43
	v_min_i32_e32 v30, v30, v43
	v_max_i32_e32 v43, v44, v39
	v_min_i32_e32 v39, v44, v39
	v_max_i32_e32 v44, v37, v34
	v_min_i32_e32 v34, v37, v34
	v_max_i32_e32 v37, v29, v31
	v_min_i32_e32 v29, v29, v31
	v_max_i32_e32 v31, v32, v27
	v_min_i32_e32 v27, v32, v27
	v_min_i32_e32 v58, v62, v58
	v_max_i32_e32 v62, v68, v55
	v_min_i32_e32 v55, v68, v55
	v_max_i32_e32 v68, v60, v71
	v_min_i32_e32 v60, v60, v71
	v_max_i32_e32 v71, v63, v36
	v_min_i32_e32 v36, v63, v36
	v_max_i32_e32 v63, v65, v70
	v_min_i32_e32 v32, v38, v41
	v_min_i32_e32 v47, v35, v45
	v_min_i32_e32 v48, v46, v42
	v_min_i32_e32 v49, v40, v30
	v_min_i32_e32 v50, v43, v44
	v_min_i32_e32 v51, v39, v34
	v_min_i32_e32 v52, v37, v31
	v_min_i32_e32 v53, v29, v27
	v_min_i32_e32 v65, v65, v70
	v_max_i32_e32 v70, v64, v58
	v_min_i32_e32 v58, v64, v58
	v_min_i32_e32 v64, v60, v71
	v_min_i32_e32 v72, v36, v63
	v_max3_i32 v28, v38, v41, v28
	v_max_i32_e32 v32, v32, v54
	v_max3_i32 v35, v35, v45, v57
	v_max_i32_e32 v38, v47, v58
	v_max3_i32 v41, v46, v42, v70
	v_max_i32_e32 v42, v48, v65
	v_max3_i32 v30, v40, v30, v72
	v_max3_i32 v36, v49, v36, v63
	v_max3_i32 v40, v43, v44, v64
	v_max3_i32 v43, v50, v60, v71
	v_max3_i32 v34, v39, v34, v68
	v_max_i32_e32 v39, v51, v55
	v_max3_i32 v31, v37, v31, v62
	v_max3_i32 v33, v52, v61, v33
	v_max3_i32 v27, v29, v27, v56
	v_max3_i32 v29, v53, v59, v69
	v_max_i32_e32 v37, v28, v40
	v_min_i32_e32 v28, v28, v40
	v_max_i32_e32 v40, v32, v43
	v_min_i32_e32 v32, v32, v43
	v_max_i32_e32 v43, v35, v34
	v_min_i32_e32 v34, v35, v34
	v_max_i32_e32 v35, v38, v39
	v_min_i32_e32 v38, v38, v39
	v_max_i32_e32 v39, v41, v31
	v_min_i32_e32 v31, v41, v31
	v_max_i32_e32 v41, v42, v33
	v_min_i32_e32 v33, v42, v33
	v_max_i32_e32 v42, v30, v27
	v_min_i32_e32 v27, v30, v27
	v_max_i32_e32 v30, v36, v29
	v_min_i32_e32 v29, v36, v29
	v_max_i32_e32 v36, v37, v39
	v_min_i32_e32 v37, v37, v39
	v_max_i32_e32 v39, v40, v41
	v_min_i32_e32 v40, v40, v41
	v_max_i32_e32 v41, v43, v42
	v_min_i32_e32 v42, v43, v42
	v_max_i32_e32 v43, v35, v30
	v_min_i32_e32 v30, v35, v30
	v_max_i32_e32 v35, v28, v31
	v_min_i32_e32 v28, v28, v31
	v_max_i32_e32 v31, v32, v33
	v_min_i32_e32 v32, v32, v33
	v_max_i32_e32 v33, v34, v27
	v_min_i32_e32 v27, v34, v27
	v_max_i32_e32 v34, v38, v29
	v_min_i32_e32 v29, v38, v29
	v_max_i32_e32 v38, v36, v41
	v_min_i32_e32 v36, v36, v41
	v_max_i32_e32 v41, v39, v43
	v_min_i32_e32 v39, v39, v43
	v_max_i32_e32 v43, v37, v42
	v_min_i32_e32 v37, v37, v42
	v_max_i32_e32 v42, v40, v30
	v_min_i32_e32 v30, v40, v30
	v_max_i32_e32 v40, v35, v33
	v_min_i32_e32 v33, v35, v33
	v_max_i32_e32 v35, v31, v34
	v_min_i32_e32 v31, v31, v34
	v_max_i32_e32 v34, v28, v27
	v_min_i32_e32 v27, v28, v27
	v_max_i32_e32 v28, v32, v29
	v_min_i32_e32 v29, v32, v29
	v_max_i32_e32 v32, v38, v41
	v_min_i32_e32 v38, v38, v41
	v_max_i32_e32 v41, v36, v39
	v_min_i32_e32 v36, v36, v39
	v_max_i32_e32 v39, v43, v42
	v_min_i32_e32 v42, v43, v42
	v_max_i32_e32 v43, v37, v30
	v_min_i32_e32 v30, v37, v30
	v_max_i32_e32 v37, v40, v35
	v_min_i32_e32 v35, v40, v35
	v_max_i32_e32 v40, v33, v31
	v_min_i32_e32 v31, v33, v31
	v_max_i32_e32 v33, v34, v28
	v_min_i32_e32 v28, v34, v28
	v_max_i32_e32 v34, v27, v29
	v_min_i32_e32 v27, v27, v29
	v_add_f32_e32 v29, v67, v26
	v_or_b32_e32 v29, 0xff, v29
	v_add_f32_e32 v26, v66, v26
	v_add_u32_e32 v29, 0xffffff20, v29
	v_or_b32_e32 v26, 0xff, v26
	v_add_u32_e32 v26, 0xffffff10, v26
	v_max_i32_e32 v44, v34, v29
	v_min_i32_e32 v29, v34, v29
	v_max3_i32 v26, v29, v27, v26
; __device__ __forceinline__ void route_task(int task, int tl0, const bf16* QP  , const LAS bf16* KHL, LAS unsigned short* EL, LAS float* GL, int lane) {
;     ...
;     int my[8];
; #pragma unroll
;     for (int i = 0; i < 8; ++i) { int lo_ = bk[i], hi_ = bk[8 + i]; asm volatile("" : "+v"(lo_), "+v"(hi_)); my[i] = hi ? hi_ : lo_; }
;     int bv[8];
; #pragma unroll
;     for (int i = 0; i < 8; ++i) {
;         const unsigned cd = 255u - ((unsigned)my[i] & 255u), ca = cd >> 4, cb = cd & 15u;
;         const unsigned wa = (ca >> 2) == 0u ? P1[0] : (ca >> 2) == 1u ? P1[1] : (ca >> 2) == 2u ? P1[2] : P1[3];
;         const unsigned wb = (cb >> 2) == 0u ? P2[0] : (cb >> 2) == 1u ? P2[1] : (cb >> 2) == 2u ? P2[2] : P2[3];
;         bv[i] = (int)((((wa >> (8u * (ca & 3u))) & 255u) << 7) | ((wb >> (8u * (cb & 3u))) & 255u));
;     }
;     float e[8], se = 0.f;
; #pragma unroll
;     for (int i = 0; i < 8; ++i) { e[i] = __expf(__int_as_float(my[i]) - __int_as_float(bk[0])); se += e[i]; }
	v_mov_b32_e32 v27, v32
	s_nop 0
	v_cndmask_b32_e64 v27, v37, v27, s[6:7]
	v_not_b32_e32 v29, v27
	v_bfe_u32 v45, v29, 6, 2
	v_cmp_eq_u32_e32 vcc, 2, v45
	v_cndmask_b32_e64 v30, v26, v30, s[6:7]
	v_bitop3_b32 v26, v27, s3, v27 bitop3:0xc
	v_cndmask_b32_e32 v46, v25, v23, vcc
	v_cmp_eq_u32_e32 vcc, 1, v45
	v_cndmask_b32_e64 v34, v35, v38, s[6:7]
	v_not_b32_e32 v35, v34
	v_cndmask_b32_e32 v45, v46, v21, vcc
	v_cmp_gt_u32_e32 vcc, 64, v26
	v_cndmask_b32_e64 v37, v40, v41, s[6:7]
	v_cndmask_b32_e64 v41, v44, v43, s[6:7]
	v_cndmask_b32_e32 v26, v45, v19, vcc
	v_bfe_u32 v45, v29, 2, 2
	v_cmp_eq_u32_e32 vcc, 2, v45
	v_bitop3_b32 v44, v27, 15, v27 bitop3:0xc
	v_bfe_u32 v47, v35, 6, 2
	v_cndmask_b32_e32 v46, v24, v22, vcc
	v_cmp_eq_u32_e32 vcc, 1, v45
	v_not_b32_e32 v38, v37
	v_bfe_u32 v49, v38, 6, 2
	v_cndmask_b32_e32 v45, v46, v20, vcc
	v_cmp_gt_u32_e32 vcc, 4, v44
	v_bitop3_b32 v46, v34, 15, v34 bitop3:0xc
	v_cndmask_b32_e64 v31, v31, v36, s[6:7]
	v_cndmask_b32_e32 v44, v45, v18, vcc
	v_cmp_eq_u32_e32 vcc, 2, v47
	v_bitop3_b32 v45, v34, s3, v34 bitop3:0xc
	v_not_b32_e32 v36, v31
	v_cndmask_b32_e32 v48, v25, v23, vcc
	v_cmp_eq_u32_e32 vcc, 1, v47
	v_bfe_u32 v51, v36, 6, 2
	v_cndmask_b32_e64 v33, v33, v39, s[6:7]
	v_cndmask_b32_e32 v47, v48, v21, vcc
	v_cmp_gt_u32_e32 vcc, 64, v45
	v_not_b32_e32 v39, v33
	v_bfe_u32 v53, v39, 6, 2
	v_cndmask_b32_e32 v45, v47, v19, vcc
	v_bfe_u32 v47, v35, 2, 2
	v_cmp_eq_u32_e32 vcc, 2, v47
	v_cndmask_b32_e64 v28, v28, v42, s[6:7]
	v_not_b32_e32 v40, v28
	v_cndmask_b32_e32 v48, v24, v22, vcc
	v_cmp_eq_u32_e32 vcc, 1, v47
	v_bfe_u32 v55, v40, 6, 2
	v_not_b32_e32 v42, v41
	v_cndmask_b32_e32 v47, v48, v20, vcc
	v_cmp_gt_u32_e32 vcc, 4, v46
	v_bitop3_b32 v48, v37, 15, v37 bitop3:0xc
	v_bfe_u32 v57, v42, 6, 2
	v_cndmask_b32_e32 v46, v47, v18, vcc
	v_cmp_eq_u32_e32 vcc, 2, v49
	v_bitop3_b32 v47, v37, s3, v37 bitop3:0xc
	v_not_b32_e32 v43, v30
	v_cndmask_b32_e32 v50, v25, v23, vcc
	v_cmp_eq_u32_e32 vcc, 1, v49
	v_bfe_u32 v59, v43, 6, 2
	s_nop 0
	v_cndmask_b32_e32 v49, v50, v21, vcc
	v_cmp_gt_u32_e32 vcc, 64, v47
	s_nop 1
	v_cndmask_b32_e32 v47, v49, v19, vcc
	v_bfe_u32 v49, v38, 2, 2
	v_cmp_eq_u32_e32 vcc, 2, v49
	s_nop 1
	v_cndmask_b32_e32 v50, v24, v22, vcc
	v_cmp_eq_u32_e32 vcc, 1, v49
	s_nop 1
	v_cndmask_b32_e32 v49, v50, v20, vcc
	v_cmp_gt_u32_e32 vcc, 4, v48
	v_bitop3_b32 v50, v31, 15, v31 bitop3:0xc
	s_nop 0
	v_cndmask_b32_e32 v48, v49, v18, vcc
	v_cmp_eq_u32_e32 vcc, 2, v51
	v_bitop3_b32 v49, v31, s3, v31 bitop3:0xc
	s_nop 0
	v_cndmask_b32_e32 v52, v25, v23, vcc
	v_cmp_eq_u32_e32 vcc, 1, v51
	s_nop 1
	v_cndmask_b32_e32 v51, v52, v21, vcc
	v_cmp_gt_u32_e32 vcc, 64, v49
	s_nop 1
	v_cndmask_b32_e32 v49, v51, v19, vcc
	v_bfe_u32 v51, v36, 2, 2
	v_cmp_eq_u32_e32 vcc, 2, v51
	s_nop 1
	v_cndmask_b32_e32 v52, v24, v22, vcc
	v_cmp_eq_u32_e32 vcc, 1, v51
	s_nop 1
	v_cndmask_b32_e32 v51, v52, v20, vcc
	v_cmp_gt_u32_e32 vcc, 4, v50
	v_bitop3_b32 v52, v33, 15, v33 bitop3:0xc
	s_nop 0
	v_cndmask_b32_e32 v50, v51, v18, vcc
	v_cmp_eq_u32_e32 vcc, 2, v53
	v_bitop3_b32 v51, v33, s3, v33 bitop3:0xc
	s_nop 0
	v_cndmask_b32_e32 v54, v25, v23, vcc
	v_cmp_eq_u32_e32 vcc, 1, v53
	s_nop 1
	v_cndmask_b32_e32 v53, v54, v21, vcc
	v_cmp_gt_u32_e32 vcc, 64, v51
	s_nop 1
	v_cndmask_b32_e32 v51, v53, v19, vcc
	v_bfe_u32 v53, v39, 2, 2
	v_cmp_eq_u32_e32 vcc, 2, v53
	s_nop 1
	v_cndmask_b32_e32 v54, v24, v22, vcc
	v_cmp_eq_u32_e32 vcc, 1, v53
	s_nop 1
	v_cndmask_b32_e32 v53, v54, v20, vcc
	v_cmp_gt_u32_e32 vcc, 4, v52
	v_bitop3_b32 v54, v28, 15, v28 bitop3:0xc
	s_nop 0
	v_cndmask_b32_e32 v52, v53, v18, vcc
	v_cmp_eq_u32_e32 vcc, 2, v55
	v_bitop3_b32 v53, v28, s3, v28 bitop3:0xc
	s_nop 0
	v_cndmask_b32_e32 v56, v25, v23, vcc
	v_cmp_eq_u32_e32 vcc, 1, v55
	s_nop 1
	v_cndmask_b32_e32 v55, v56, v21, vcc
	v_cmp_gt_u32_e32 vcc, 64, v53
	s_nop 1
	v_cndmask_b32_e32 v53, v55, v19, vcc
	v_bfe_u32 v55, v40, 2, 2
	v_cmp_eq_u32_e32 vcc, 2, v55
	s_nop 1
	v_cndmask_b32_e32 v56, v24, v22, vcc
	v_cmp_eq_u32_e32 vcc, 1, v55
	s_nop 1
	v_cndmask_b32_e32 v55, v56, v20, vcc
	v_cmp_gt_u32_e32 vcc, 4, v54
	v_bitop3_b32 v56, v41, 15, v41 bitop3:0xc
	s_nop 0
	v_cndmask_b32_e32 v54, v55, v18, vcc
	v_cmp_eq_u32_e32 vcc, 2, v57
	v_bitop3_b32 v55, v41, s3, v41 bitop3:0xc
	s_nop 0
	v_cndmask_b32_e32 v58, v25, v23, vcc
	v_cmp_eq_u32_e32 vcc, 1, v57
	s_nop 1
	v_cndmask_b32_e32 v57, v58, v21, vcc
	v_cmp_gt_u32_e32 vcc, 64, v55
	s_nop 1
	v_cndmask_b32_e32 v55, v57, v19, vcc
	v_bfe_u32 v57, v42, 2, 2
	v_cmp_eq_u32_e32 vcc, 2, v57
	s_nop 1
	v_cndmask_b32_e32 v58, v24, v22, vcc
	v_cmp_eq_u32_e32 vcc, 1, v57
	s_nop 1
	v_cndmask_b32_e32 v57, v58, v20, vcc
	v_cmp_gt_u32_e32 vcc, 4, v56
	v_bitop3_b32 v58, v30, 15, v30 bitop3:0xc
	s_nop 0
	v_cndmask_b32_e32 v56, v57, v18, vcc
	v_cmp_eq_u32_e32 vcc, 2, v59
	v_bitop3_b32 v57, v30, s3, v30 bitop3:0xc
	s_nop 0
	v_cndmask_b32_e32 v23, v25, v23, vcc
	v_cmp_eq_u32_e32 vcc, 1, v59
	v_sub_f32_e32 v25, v31, v32
	v_mul_f32_e32 v25, 0x3fb8aa3b, v25
	v_cndmask_b32_e32 v21, v23, v21, vcc
	v_cmp_gt_u32_e32 vcc, 64, v57
	v_lshrrev_b32_e32 v23, 1, v39
	v_and_b32_e32 v23, 24, v23
	v_cndmask_b32_e32 v19, v21, v19, vcc
	v_bfe_u32 v21, v43, 2, 2
	v_cmp_eq_u32_e32 vcc, 2, v21
	v_lshrrev_b32_e32 v23, v23, v51
	v_lshlrev_b32_e32 v23, 7, v23
	v_cndmask_b32_e32 v22, v24, v22, vcc
	v_cmp_eq_u32_e32 vcc, 1, v21
	v_lshrrev_b32_e32 v21, 1, v42
	v_and_b32_e32 v21, 24, v21
	v_cndmask_b32_e32 v20, v22, v20, vcc
	v_cmp_gt_u32_e32 vcc, 4, v58
	v_lshrrev_b32_e32 v21, v21, v55
	v_lshrrev_b32_e32 v22, 1, v40
	v_cndmask_b32_e32 v18, v20, v18, vcc
	v_lshlrev_b32_e32 v20, 3, v42
	v_lshlrev_b32_e32 v21, 7, v21
	v_and_b32_e32 v22, 24, v22
	v_lshrrev_b32_e32 v20, v20, v56
; #define LAS __attribute__((address_space(3)))
; __device__ __forceinline__ void peer_u_item(int p, int j, const LAS unsigned short* EL  , const unsigned char* __restrict__ XQ, const unsigned char* __restrict__ U8, LAS int* ACC  , int lane, int wave) {
;     asm volatile("" : "+v"(lane));
;     const int gidx = lane >> 3; const unsigned coff = (unsigned)(p * 128 + (lane & 7) * 16), toff = (unsigned)(p * (16384 * 128) + (lane & 7) * 16);
; #pragma unroll 1
;     for (int it = 0; it < 8; ++it) {
;         const int t = j * 64 + it * 8 + wave;
;         unsigned E[8];
;         { const LAS v4u* ep = (const LAS v4u*)(EL + (it * 8 + wave) * 128 + 16 * gidx); const v4u e0 = ep[0], e1 = ep[1];
;           E[0] = e0.x; E[1] = e0.y; E[2] = e0.z; E[3] = e0.w; E[4] = e1.x; E[5] = e1.y; E[6] = e1.z; E[7] = e1.w; }
;         uint4 uu[16];
; #pragma unroll
;         for (int i = 0; i < 16; ++i) uu[i] = *(const uint4*)(U8 + (size_t)(PE_ID(E, i) * 128u + toff));
;         const uint4 xh = *(const uint4*)(XQ + (size_t)t * 512 + coff), xl = *(const uint4*)(XQ + 8 * MiB + (size_t)t * 512 + coff);
; __device__ __forceinline__ void route_task(int task, int tl0, const bf16* QP  , const LAS bf16* KHL, LAS unsigned short* EL, LAS float* GL, int lane) {
;     ...
;     float e[8], se = 0.f;
; #pragma unroll
;     for (int i = 0; i < 8; ++i) { e[i] = __expf(__int_as_float(my[i]) - __int_as_float(bk[0])); se += e[i]; }
;     se += __shfl_xor(se, 32);
;     const float inv = 1.f / se;
;     {
;         int l2 = lane; asm volatile("" : "+v"(l2));
;         const int o2 = (tl0 + ((l2 & 31) >> 3)) * 128 + (l2 & 7) * 16 + 8 * (l2 >> 5);
;         LAS v4u* ip = (LAS v4u*)(EL + o2); typedef float f4v __attribute__((ext_vector_type(4))); LAS f4v* gp = (LAS f4v*)(GL + o2);
;         ip[0] = (v4u){(unsigned)bv[0] | ((unsigned)bv[1] << 16), (unsigned)bv[2] | ((unsigned)bv[3] << 16), (unsigned)bv[4] | ((unsigned)bv[5] << 16), (unsigned)bv[6] | ((unsigned)bv[7] << 16)};
;         gp[0] = (f4v){e[0] * inv, e[1] * inv, e[2] * inv, e[3] * inv}; gp[1] = (f4v){e[4] * inv, e[5] * inv, e[6] * inv, e[7] * inv};
;     }
	v_and_b32_e32 v21, 0x7f80, v21
	v_lshrrev_b32_e32 v22, v22, v53
	v_and_or_b32 v21, v20, s3, v21
	v_lshlrev_b32_e32 v20, 3, v40
	v_lshlrev_b32_e32 v22, 7, v22
	v_lshrrev_b32_e32 v20, v20, v54
	v_and_b32_e32 v22, 0x7f80, v22
	v_and_or_b32 v20, v20, s3, v22
	v_lshlrev_b32_e32 v22, 3, v39
	v_lshrrev_b32_e32 v22, v22, v52
	v_and_b32_e32 v23, 0x7f80, v23
	v_and_or_b32 v39, v22, s3, v23
	v_lshrrev_b32_e32 v23, 1, v36
	v_and_b32_e32 v23, 24, v23
	v_lshrrev_b32_e32 v23, v23, v49
	v_lshlrev_b32_e32 v22, 3, v36
	v_lshlrev_b32_e32 v23, 7, v23
	v_lshrrev_b32_e32 v22, v22, v50
	v_and_b32_e32 v23, 0x7f80, v23
	v_and_or_b32 v36, v22, s3, v23
	v_lshrrev_b32_e32 v23, 1, v38
	v_and_b32_e32 v23, 24, v23
	v_lshrrev_b32_e32 v23, v23, v47
	v_lshlrev_b32_e32 v22, 3, v38
	v_lshlrev_b32_e32 v23, 7, v23
	v_lshrrev_b32_e32 v22, v22, v48
	v_and_b32_e32 v23, 0x7f80, v23
	v_and_or_b32 v38, v22, s3, v23
	v_lshrrev_b32_e32 v23, 1, v35
	v_and_b32_e32 v23, 24, v23
	v_lshrrev_b32_e32 v23, v23, v45
	v_lshlrev_b32_e32 v22, 3, v35
	v_lshlrev_b32_e32 v23, 7, v23
	v_lshrrev_b32_e32 v22, v22, v46
	v_and_b32_e32 v23, 0x7f80, v23
	v_and_or_b32 v35, v22, s3, v23
	v_lshrrev_b32_e32 v23, 1, v29
	v_and_b32_e32 v23, 24, v23
	v_lshrrev_b32_e32 v23, v23, v26
	v_lshlrev_b32_e32 v22, 3, v29
	v_lshlrev_b32_e32 v23, 7, v23
	v_lshrrev_b32_e32 v22, v22, v44
	v_and_b32_e32 v23, 0x7f80, v23
	v_and_or_b32 v40, v22, s3, v23
	v_sub_f32_e32 v22, v27, v32
	v_mul_f32_e32 v22, 0x3fb8aa3b, v22
	v_sub_f32_e32 v23, v34, v32
	v_exp_f32_e32 v22, v22
	v_mul_f32_e32 v23, 0x3fb8aa3b, v23
	v_sub_f32_e32 v24, v37, v32
	v_exp_f32_e32 v23, v23
	v_mul_f32_e32 v24, 0x3fb8aa3b, v24
	v_exp_f32_e32 v24, v24
	v_exp_f32_e32 v25, v25
	v_add_f32_e32 v26, 0, v22
	v_add_f32_e32 v26, v23, v26
	v_add_f32_e32 v26, v24, v26
	v_add_f32_e32 v31, v25, v26
	v_sub_f32_e32 v26, v33, v32
	v_mul_f32_e32 v26, 0x3fb8aa3b, v26
	v_sub_f32_e32 v27, v28, v32
	v_exp_f32_e32 v26, v26
	v_mul_f32_e32 v27, 0x3fb8aa3b, v27
	v_sub_f32_e32 v28, v41, v32
	v_exp_f32_e32 v27, v27
	v_mul_f32_e32 v28, 0x3fb8aa3b, v28
	v_sub_f32_e32 v29, v30, v32
	v_exp_f32_e32 v28, v28
	v_mul_f32_e32 v29, 0x3fb8aa3b, v29
	v_exp_f32_e32 v29, v29
	v_add_f32_e32 v30, v26, v31
	v_add_f32_e32 v30, v27, v30
	v_add_f32_e32 v30, v28, v30
	v_add_f32_e32 v30, v29, v30
	ds_bpermute_b32 v31, v123, v30
	v_lshrrev_b32_e32 v42, 1, v43
	v_and_b32_e32 v32, 24, v42
	v_lshrrev_b32_e32 v19, v32, v19
	v_lshlrev_b32_e32 v19, 7, v19
	s_waitcnt lgkmcnt(0)
	v_add_f32_e32 v30, v30, v31
	v_div_scale_f32 v31, s[12:13], v30, v30, 1.0
	v_rcp_f32_e32 v32, v31
	v_lshlrev_b32_e32 v33, 3, v43
	v_and_b32_e32 v19, 0x7f80, v19
	v_lshrrev_b32_e32 v18, v33, v18
	v_and_or_b32 v33, v18, s3, v19
	v_fma_f32 v18, -v31, v32, 1.0
	v_fmac_f32_e32 v32, v18, v32
	v_div_scale_f32 v18, vcc, 1.0, v30, 1.0
	v_mul_f32_e32 v19, v18, v32
	v_fma_f32 v34, -v31, v19, v18
	v_fmac_f32_e32 v19, v34, v32
	v_fma_f32 v18, -v31, v19, v18
	v_div_fmas_f32 v18, v18, v32, v19
	v_div_fixup_f32 v30, v18, v30, 1.0
	v_mov_b32_e32 v18, v1
	v_lshl_or_b32 v20, v20, 16, v39
	v_lshrrev_b32_e32 v19, 3, v18
	v_and_or_b32 v19, v19, 3, s57
	v_lshlrev_b32_e32 v31, 4, v18
	v_ashrrev_i32_e32 v18, 2, v18
	v_lshlrev_b32_e32 v19, 7, v19
	v_and_b32_e32 v31, 0x70, v31
	v_and_b32_e32 v18, -8, v18
	v_add3_u32 v18, v18, v31, v19
	v_lshl_add_u32 v31, v18, 1, s11
	v_lshl_add_u32 v32, v18, 2, s69
	v_lshl_or_b32 v18, v35, 16, v40
	v_lshl_or_b32 v19, v36, 16, v38
	v_lshl_or_b32 v21, v33, 16, v21
	ds_write_b128 v31, v[18:21]
	v_pk_mul_f32 v[20:21], v[24:25], v[30:31] op_sel_hi:[1,0]
	v_pk_mul_f32 v[18:19], v[22:23], v[30:31] op_sel_hi:[1,0]
	ds_write_b128 v32, v[18:21]
	v_pk_mul_f32 v[20:21], v[28:29], v[30:31] op_sel_hi:[1,0]
	v_pk_mul_f32 v[18:19], v[26:27], v[30:31] op_sel_hi:[1,0]
	ds_write_b128 v32, v[18:21] offset:16
	v_xor_b32_e32 v18, 4, v112
	v_cmp_lt_i32_e32 vcc, v18, v122
	s_waitcnt lgkmcnt(0)
	s_barrier
	v_cndmask_b32_e32 v18, v112, v18, vcc
	v_lshlrev_b32_e32 v30, 2, v18
	v_xor_b32_e32 v18, 2, v112
	v_cmp_lt_i32_e32 vcc, v18, v122
	s_nop 1
	v_cndmask_b32_e32 v18, v112, v18, vcc
	v_lshlrev_b32_e32 v31, 2, v18
	v_xor_b32_e32 v18, 1, v112
	v_cmp_lt_i32_e32 vcc, v18, v122
	s_nop 1
	v_cndmask_b32_e32 v18, v112, v18, vcc
	v_lshlrev_b32_e32 v32, 2, v18
	v_lshlrev_b32_e32 v56, 4, v1
	v_and_b32_e32 v56, 0x70, v56
	v_lshrrev_b32_e32 v59, 3, v1
	v_lshlrev_b32_e32 v59, 5, v59
	v_add_u32_e32 v59, s66, v59
	v_add_u32_e32 v59, -16, v59
	v_lshl_add_u32 v60, v1, 3, s64
	v_and_b32_e32 v38, 4, v1
	v_cmp_ne_u32_e64 s[10:11], 0, v38
	v_and_b32_e32 v38, 2, v1
	v_cmp_ne_u32_e64 s[12:13], 0, v38
	v_and_b32_e32 v38, 1, v1
	v_cmp_ne_u32_e64 s[14:15], 0, v38
	s_movk_i32 s94, 0x80
	s_mov_b32 s42, 0
	s_mov_b32 s43, 0
	s_mov_b32 s44, 1
	s_mov_b32 s45, 0
	s_lshl_b32 s32, s42, 11
	v_add_u32_e32 v39, s32, v59
	ds_read_b128 v[202:205], v39
	ds_read_b128 v[206:209], v39 offset:16
	s_lshl_b32 s46, s42, 3
	s_add_i32 s46, s46, s40
	s_lshl_b32 s46, s46, 9
	s_lshl_b32 s32, s43, 7
	s_add_i32 s46, s46, s32
	v_add_u32_e32 v57, s46, v56
	global_load_dwordx4 v[186:189], v57, s[34:35]
	global_load_dwordx4 v[190:193], v57, s[36:37]
	v_mov_b32_e32 v58, v56
	s_waitcnt lgkmcnt(0)
	v_and_b32_e32 v38, 0xffff, v202
	v_lshl_add_u32 v38, v38, 7, v58
	global_load_dwordx4 v[122:125], v38, s[96:97]
	v_lshrrev_b32_e32 v38, 16, v202
	v_lshl_add_u32 v38, v38, 7, v58
	global_load_dwordx4 v[126:129], v38, s[96:97]
	v_and_b32_e32 v38, 0xffff, v203
	v_lshl_add_u32 v38, v38, 7, v58
	global_load_dwordx4 v[130:133], v38, s[96:97]
	v_lshrrev_b32_e32 v38, 16, v203
	v_lshl_add_u32 v38, v38, 7, v58
	global_load_dwordx4 v[134:137], v38, s[96:97]
	v_and_b32_e32 v38, 0xffff, v204
	v_lshl_add_u32 v38, v38, 7, v58
	global_load_dwordx4 v[138:141], v38, s[96:97]
	v_lshrrev_b32_e32 v38, 16, v204
	v_lshl_add_u32 v38, v38, 7, v58
	global_load_dwordx4 v[142:145], v38, s[96:97]
	v_and_b32_e32 v38, 0xffff, v205
	v_lshl_add_u32 v38, v38, 7, v58
	global_load_dwordx4 v[146:149], v38, s[96:97]
	v_lshrrev_b32_e32 v38, 16, v205
	v_lshl_add_u32 v38, v38, 7, v58
	global_load_dwordx4 v[150:153], v38, s[96:97]
	v_and_b32_e32 v38, 0xffff, v206
	v_lshl_add_u32 v38, v38, 7, v58
	global_load_dwordx4 v[154:157], v38, s[96:97]
	v_lshrrev_b32_e32 v38, 16, v206
	v_lshl_add_u32 v38, v38, 7, v58
	global_load_dwordx4 v[158:161], v38, s[96:97]
	v_and_b32_e32 v38, 0xffff, v207
	v_lshl_add_u32 v38, v38, 7, v58
	global_load_dwordx4 v[162:165], v38, s[96:97]
	v_lshrrev_b32_e32 v38, 16, v207
	v_lshl_add_u32 v38, v38, 7, v58
	global_load_dwordx4 v[166:169], v38, s[96:97]
	v_and_b32_e32 v38, 0xffff, v208
	v_lshl_add_u32 v38, v38, 7, v58
	global_load_dwordx4 v[170:173], v38, s[96:97]
	v_lshrrev_b32_e32 v38, 16, v208
	v_lshl_add_u32 v38, v38, 7, v58
	global_load_dwordx4 v[174:177], v38, s[96:97]
	v_and_b32_e32 v38, 0xffff, v209
	v_lshl_add_u32 v38, v38, 7, v58
	global_load_dwordx4 v[178:181], v38, s[96:97]
	v_lshrrev_b32_e32 v38, 16, v209
	v_lshl_add_u32 v38, v38, 7, v58
	global_load_dwordx4 v[182:185], v38, s[96:97]
	s_mov_b32 s47, 15
; #define LAS __attribute__((address_space(3)))
; __device__ __forceinline__ void peer_u_item(int p, int j, const LAS unsigned short* EL  , const unsigned char* __restrict__ XQ, const unsigned char* __restrict__ U8, LAS int* ACC  , int lane, int wave) {
;     ...
; #pragma unroll 1
;     for (int it = 0; it < 8; ++it) {
;         const int t = j * 64 + it * 8 + wave;
;         unsigned E[8];
;         { const LAS v4u* ep = (const LAS v4u*)(EL + (it * 8 + wave) * 128 + 16 * gidx); const v4u e0 = ep[0], e1 = ep[1];
;           E[0] = e0.x; E[1] = e0.y; E[2] = e0.z; E[3] = e0.w; E[4] = e1.x; E[5] = e1.y; E[6] = e1.z; E[7] = e1.w; }
;         uint4 uu[16];
; #pragma unroll
;         for (int i = 0; i < 16; ++i) uu[i] = *(const uint4*)(U8 + (size_t)(PE_ID(E, i) * 128u + toff));
;         const uint4 xh = *(const uint4*)(XQ + (size_t)t * 512 + coff), xl = *(const uint4*)(XQ + 8 * MiB + (size_t)t * 512 + coff);
;         int d[16];
; #pragma unroll
;         for (int i = 0; i < 16; ++i) {
;             int sh = __builtin_amdgcn_sdot8((int)uu[i].x, (int)xh.x, 0, false); sh = __builtin_amdgcn_sdot8((int)uu[i].y, (int)xh.y, sh, false);
;             sh = __builtin_amdgcn_sdot8((int)uu[i].z, (int)xh.z, sh, false); sh = __builtin_amdgcn_sdot8((int)uu[i].w, (int)xh.w, sh, false);
;             int sl = __builtin_amdgcn_sdot8((int)uu[i].x, (int)xl.x, 0, false); sl = __builtin_amdgcn_sdot8((int)uu[i].y, (int)xl.y, sl, false);
;             sl = __builtin_amdgcn_sdot8((int)uu[i].z, (int)xl.z, sl, false); sl = __builtin_amdgcn_sdot8((int)uu[i].w, (int)xl.w, sl, false);
;             d[i] = (sh << 4) + sl;
;         }
;         int r0, r1; treduce16i<4, 2, 1>(d, lane, r0, r1);
.Lpu_trip:
	s_lshl_b32 s32, s44, 11
	v_add_u32_e32 v39, s32, v59
	ds_read_b128 v[210:213], v39
	ds_read_b128 v[214:217], v39 offset:16
	s_lshl_b32 s32, s42, 12
	v_add_u32_e32 v61, s32, v60
	ds_read_b64 v[62:63], v61
	s_lshl_b32 s46, s44, 3
	s_add_i32 s46, s46, s40
	s_lshl_b32 s46, s46, 9
	s_lshl_b32 s32, s45, 7
	s_add_i32 s46, s46, s32
	v_add_u32_e32 v57, s46, v56
	global_load_dwordx4 v[194:197], v57, s[34:35]
	global_load_dwordx4 v[198:201], v57, s[36:37]
	s_lshl_b32 s32, s45, 21
	v_add_u32_e32 v58, s32, v56
	s_waitcnt lgkmcnt(0)
	s_waitcnt vmcnt(17)
	v_dot8_i32_i4 v34, v122, v186, 0
	v_dot8_i32_i4 v35, v122, v190, 0
	v_dot8_i32_i4 v34, v123, v187, v34
	v_dot8_i32_i4 v35, v123, v191, v35
	v_dot8_i32_i4 v34, v124, v188, v34
	v_dot8_i32_i4 v35, v124, v192, v35
	v_dot8_i32_i4 v34, v125, v189, v34
	v_dot8_i32_i4 v35, v125, v193, v35
	v_and_b32_e32 v38, 0xffff, v210
	v_lshl_add_u32 v38, v38, 7, v58
	global_load_dwordx4 v[122:125], v38, s[96:97]
	s_nop 0
	v_lshl_add_u32 v18, v34, 4, v35
	s_waitcnt vmcnt(17)
	v_dot8_i32_i4 v36, v126, v186, 0
	v_dot8_i32_i4 v37, v126, v190, 0
	v_dot8_i32_i4 v36, v127, v187, v36
	v_dot8_i32_i4 v37, v127, v191, v37
	v_dot8_i32_i4 v36, v128, v188, v36
	v_dot8_i32_i4 v37, v128, v192, v37
	v_dot8_i32_i4 v36, v129, v189, v36
	v_dot8_i32_i4 v37, v129, v193, v37
	v_lshrrev_b32_e32 v38, 16, v210
	v_lshl_add_u32 v38, v38, 7, v58
	global_load_dwordx4 v[126:129], v38, s[96:97]
	s_nop 0
	v_lshl_add_u32 v19, v36, 4, v37
	s_waitcnt vmcnt(17)
	v_dot8_i32_i4 v34, v130, v186, 0
	v_dot8_i32_i4 v35, v130, v190, 0
	v_dot8_i32_i4 v34, v131, v187, v34
	v_dot8_i32_i4 v35, v131, v191, v35
	v_dot8_i32_i4 v34, v132, v188, v34
	v_dot8_i32_i4 v35, v132, v192, v35
	v_dot8_i32_i4 v34, v133, v189, v34
	v_dot8_i32_i4 v35, v133, v193, v35
	v_and_b32_e32 v38, 0xffff, v211
	v_lshl_add_u32 v38, v38, 7, v58
	global_load_dwordx4 v[130:133], v38, s[96:97]
	s_nop 0
	v_lshl_add_u32 v20, v34, 4, v35
	s_waitcnt vmcnt(17)
	v_dot8_i32_i4 v36, v134, v186, 0
	v_dot8_i32_i4 v37, v134, v190, 0
	v_dot8_i32_i4 v36, v135, v187, v36
	v_dot8_i32_i4 v37, v135, v191, v37
	v_dot8_i32_i4 v36, v136, v188, v36
	v_dot8_i32_i4 v37, v136, v192, v37
	v_dot8_i32_i4 v36, v137, v189, v36
	v_dot8_i32_i4 v37, v137, v193, v37
	v_lshrrev_b32_e32 v38, 16, v211
	v_lshl_add_u32 v38, v38, 7, v58
	global_load_dwordx4 v[134:137], v38, s[96:97]
	s_nop 0
	v_lshl_add_u32 v21, v36, 4, v37
	s_waitcnt vmcnt(17)
	v_dot8_i32_i4 v34, v138, v186, 0
	v_dot8_i32_i4 v35, v138, v190, 0
	v_dot8_i32_i4 v34, v139, v187, v34
	v_dot8_i32_i4 v35, v139, v191, v35
	v_dot8_i32_i4 v34, v140, v188, v34
	v_dot8_i32_i4 v35, v140, v192, v35
	v_dot8_i32_i4 v34, v141, v189, v34
	v_dot8_i32_i4 v35, v141, v193, v35
	v_and_b32_e32 v38, 0xffff, v212
	v_lshl_add_u32 v38, v38, 7, v58
	global_load_dwordx4 v[138:141], v38, s[96:97]
	s_nop 0
	v_lshl_add_u32 v22, v34, 4, v35
	s_waitcnt vmcnt(17)
	v_dot8_i32_i4 v36, v142, v186, 0
	v_dot8_i32_i4 v37, v142, v190, 0
	v_dot8_i32_i4 v36, v143, v187, v36
	v_dot8_i32_i4 v37, v143, v191, v37
	v_dot8_i32_i4 v36, v144, v188, v36
	v_dot8_i32_i4 v37, v144, v192, v37
	v_dot8_i32_i4 v36, v145, v189, v36
	v_dot8_i32_i4 v37, v145, v193, v37
	v_lshrrev_b32_e32 v38, 16, v212
	v_lshl_add_u32 v38, v38, 7, v58
	global_load_dwordx4 v[142:145], v38, s[96:97]
	s_nop 0
	v_lshl_add_u32 v23, v36, 4, v37
	s_waitcnt vmcnt(17)
	v_dot8_i32_i4 v34, v146, v186, 0
	v_dot8_i32_i4 v35, v146, v190, 0
	v_dot8_i32_i4 v34, v147, v187, v34
	v_dot8_i32_i4 v35, v147, v191, v35
	v_dot8_i32_i4 v34, v148, v188, v34
	v_dot8_i32_i4 v35, v148, v192, v35
	v_dot8_i32_i4 v34, v149, v189, v34
	v_dot8_i32_i4 v35, v149, v193, v35
	v_and_b32_e32 v38, 0xffff, v213
	v_lshl_add_u32 v38, v38, 7, v58
	global_load_dwordx4 v[146:149], v38, s[96:97]
	s_nop 0
	v_lshl_add_u32 v24, v34, 4, v35
	s_waitcnt vmcnt(17)
	v_dot8_i32_i4 v36, v150, v186, 0
	v_dot8_i32_i4 v37, v150, v190, 0
	v_dot8_i32_i4 v36, v151, v187, v36
	v_dot8_i32_i4 v37, v151, v191, v37
	v_dot8_i32_i4 v36, v152, v188, v36
	v_dot8_i32_i4 v37, v152, v192, v37
	v_dot8_i32_i4 v36, v153, v189, v36
	v_dot8_i32_i4 v37, v153, v193, v37
	v_lshrrev_b32_e32 v38, 16, v213
	v_lshl_add_u32 v38, v38, 7, v58
	global_load_dwordx4 v[150:153], v38, s[96:97]
	s_nop 0
	v_lshl_add_u32 v25, v36, 4, v37
	s_waitcnt vmcnt(17)
	v_dot8_i32_i4 v34, v154, v186, 0
	v_dot8_i32_i4 v35, v154, v190, 0
	v_dot8_i32_i4 v34, v155, v187, v34
	v_dot8_i32_i4 v35, v155, v191, v35
	v_dot8_i32_i4 v34, v156, v188, v34
	v_dot8_i32_i4 v35, v156, v192, v35
	v_dot8_i32_i4 v34, v157, v189, v34
	v_dot8_i32_i4 v35, v157, v193, v35
	v_and_b32_e32 v38, 0xffff, v214
	v_lshl_add_u32 v38, v38, 7, v58
	global_load_dwordx4 v[154:157], v38, s[96:97]
	s_nop 0
	v_lshl_add_u32 v26, v34, 4, v35
	s_waitcnt vmcnt(17)
	v_dot8_i32_i4 v36, v158, v186, 0
	v_dot8_i32_i4 v37, v158, v190, 0
	v_dot8_i32_i4 v36, v159, v187, v36
	v_dot8_i32_i4 v37, v159, v191, v37
	v_dot8_i32_i4 v36, v160, v188, v36
	v_dot8_i32_i4 v37, v160, v192, v37
	v_dot8_i32_i4 v36, v161, v189, v36
	v_dot8_i32_i4 v37, v161, v193, v37
	v_lshrrev_b32_e32 v38, 16, v214
	v_lshl_add_u32 v38, v38, 7, v58
	global_load_dwordx4 v[158:161], v38, s[96:97]
	s_nop 0
	v_lshl_add_u32 v27, v36, 4, v37
	s_waitcnt vmcnt(17)
	v_dot8_i32_i4 v34, v162, v186, 0
	v_dot8_i32_i4 v35, v162, v190, 0
	v_dot8_i32_i4 v34, v163, v187, v34
	v_dot8_i32_i4 v35, v163, v191, v35
	v_dot8_i32_i4 v34, v164, v188, v34
	v_dot8_i32_i4 v35, v164, v192, v35
	v_dot8_i32_i4 v34, v165, v189, v34
	v_dot8_i32_i4 v35, v165, v193, v35
	v_and_b32_e32 v38, 0xffff, v215
	v_lshl_add_u32 v38, v38, 7, v58
	global_load_dwordx4 v[162:165], v38, s[96:97]
	s_nop 0
	v_lshl_add_u32 v28, v34, 4, v35
	s_waitcnt vmcnt(17)
; #define LAS __attribute__((address_space(3)))
; template <int M4, int M2, int M1> __device__ __forceinline__ void treduce16i(const int (&a)[16], int lane, int& r0, int& r1) {
;     int b[8], c[4];
;     { const bool hi = (lane & M4) != 0;
; #pragma unroll
;       for (int i = 0; i < 8; ++i) { const int send = hi ? a[i] : a[i + 8]; const int recv = __shfl_xor(send, M4); b[i] = (hi ? a[i + 8] : a[i]) + recv; } }
;     { const bool hi = (lane & M2) != 0;
; #pragma unroll
;       for (int i = 0; i < 4; ++i) { const int send = hi ? b[i] : b[i + 4]; const int recv = __shfl_xor(send, M2); c[i] = (hi ? b[i + 4] : b[i]) + recv; } }
;     { const bool hi = (lane & M1) != 0;
;       { const int send = hi ? c[0] : c[2]; const int recv = __shfl_xor(send, M1); r0 = (hi ? c[2] : c[0]) + recv; }
;       { const int send = hi ? c[1] : c[3]; const int recv = __shfl_xor(send, M1); r1 = (hi ? c[3] : c[1]) + recv; } }
; }
; __device__ __forceinline__ void peer_u_item(int p, int j, const LAS unsigned short* EL  , const unsigned char* __restrict__ XQ, const unsigned char* __restrict__ U8, LAS int* ACC  , int lane, int wave) {
;     ...
;         for (int i = 0; i < 16; ++i) {
;             int sh = __builtin_amdgcn_sdot8((int)uu[i].x, (int)xh.x, 0, false); sh = __builtin_amdgcn_sdot8((int)uu[i].y, (int)xh.y, sh, false);
;             sh = __builtin_amdgcn_sdot8((int)uu[i].z, (int)xh.z, sh, false); sh = __builtin_amdgcn_sdot8((int)uu[i].w, (int)xh.w, sh, false);
;             int sl = __builtin_amdgcn_sdot8((int)uu[i].x, (int)xl.x, 0, false); sl = __builtin_amdgcn_sdot8((int)uu[i].y, (int)xl.y, sl, false);
;             sl = __builtin_amdgcn_sdot8((int)uu[i].z, (int)xl.z, sl, false); sl = __builtin_amdgcn_sdot8((int)uu[i].w, (int)xl.w, sl, false);
;             d[i] = (sh << 4) + sl;
;         }
;         int r0, r1; treduce16i<4, 2, 1>(d, lane, r0, r1);
;         { typedef int i2v __attribute__((ext_vector_type(2))); LAS i2v* ap = (LAS i2v*)(ACC + (it * 8 + wave) * 128 + 2 * lane);
;           i2v a2; if (p == 0) { a2.x = r0; a2.y = r1; } else { a2 = *ap; a2.x += r0; a2.y += r1; } *ap = a2; }
;     }
; }
	v_dot8_i32_i4 v36, v166, v186, 0
	v_dot8_i32_i4 v37, v166, v190, 0
	v_dot8_i32_i4 v36, v167, v187, v36
	v_dot8_i32_i4 v37, v167, v191, v37
	v_dot8_i32_i4 v36, v168, v188, v36
	v_dot8_i32_i4 v37, v168, v192, v37
	v_dot8_i32_i4 v36, v169, v189, v36
	v_dot8_i32_i4 v37, v169, v193, v37
	v_lshrrev_b32_e32 v38, 16, v215
	v_lshl_add_u32 v38, v38, 7, v58
	global_load_dwordx4 v[166:169], v38, s[96:97]
	s_nop 0
	v_lshl_add_u32 v29, v36, 4, v37
	s_waitcnt vmcnt(17)
	v_dot8_i32_i4 v34, v170, v186, 0
	v_dot8_i32_i4 v35, v170, v190, 0
	v_dot8_i32_i4 v34, v171, v187, v34
	v_dot8_i32_i4 v35, v171, v191, v35
	v_dot8_i32_i4 v34, v172, v188, v34
	v_dot8_i32_i4 v35, v172, v192, v35
	v_dot8_i32_i4 v34, v173, v189, v34
	v_dot8_i32_i4 v35, v173, v193, v35
	v_and_b32_e32 v38, 0xffff, v216
	v_lshl_add_u32 v38, v38, 7, v58
	global_load_dwordx4 v[170:173], v38, s[96:97]
	s_nop 0
	v_lshl_add_u32 v30, v34, 4, v35
	s_waitcnt vmcnt(17)
	v_dot8_i32_i4 v36, v174, v186, 0
	v_dot8_i32_i4 v37, v174, v190, 0
	v_dot8_i32_i4 v36, v175, v187, v36
	v_dot8_i32_i4 v37, v175, v191, v37
	v_dot8_i32_i4 v36, v176, v188, v36
	v_dot8_i32_i4 v37, v176, v192, v37
	v_dot8_i32_i4 v36, v177, v189, v36
	v_dot8_i32_i4 v37, v177, v193, v37
	v_lshrrev_b32_e32 v38, 16, v216
	v_lshl_add_u32 v38, v38, 7, v58
	global_load_dwordx4 v[174:177], v38, s[96:97]
	s_nop 0
	v_lshl_add_u32 v31, v36, 4, v37
	s_waitcnt vmcnt(17)
	v_dot8_i32_i4 v34, v178, v186, 0
	v_dot8_i32_i4 v35, v178, v190, 0
	v_dot8_i32_i4 v34, v179, v187, v34
	v_dot8_i32_i4 v35, v179, v191, v35
	v_dot8_i32_i4 v34, v180, v188, v34
	v_dot8_i32_i4 v35, v180, v192, v35
	v_dot8_i32_i4 v34, v181, v189, v34
	v_dot8_i32_i4 v35, v181, v193, v35
	v_and_b32_e32 v38, 0xffff, v217
	v_lshl_add_u32 v38, v38, 7, v58
	global_load_dwordx4 v[178:181], v38, s[96:97]
	s_nop 0
	v_lshl_add_u32 v32, v34, 4, v35
	s_waitcnt vmcnt(17)
	v_dot8_i32_i4 v36, v182, v186, 0
	v_dot8_i32_i4 v37, v182, v190, 0
	v_dot8_i32_i4 v36, v183, v187, v36
	v_dot8_i32_i4 v37, v183, v191, v37
	v_dot8_i32_i4 v36, v184, v188, v36
	v_dot8_i32_i4 v37, v184, v192, v37
	v_dot8_i32_i4 v36, v185, v189, v36
	v_dot8_i32_i4 v37, v185, v193, v37
	v_lshrrev_b32_e32 v38, 16, v217
	v_lshl_add_u32 v38, v38, 7, v58
	global_load_dwordx4 v[182:185], v38, s[96:97]
	s_nop 0
	v_lshl_add_u32 v33, v36, 4, v37
	v_cndmask_b32_e64 v40, v26, v18, s[10:11]
	v_cndmask_b32_e64 v48, v18, v26, s[10:11]
	v_cndmask_b32_e64 v41, v27, v19, s[10:11]
	v_cndmask_b32_e64 v49, v19, v27, s[10:11]
	v_cndmask_b32_e64 v42, v28, v20, s[10:11]
	v_cndmask_b32_e64 v50, v20, v28, s[10:11]
	v_cndmask_b32_e64 v43, v29, v21, s[10:11]
	v_cndmask_b32_e64 v51, v21, v29, s[10:11]
	v_cndmask_b32_e64 v44, v30, v22, s[10:11]
	v_cndmask_b32_e64 v52, v22, v30, s[10:11]
	v_cndmask_b32_e64 v45, v31, v23, s[10:11]
	v_cndmask_b32_e64 v53, v23, v31, s[10:11]
	v_cndmask_b32_e64 v46, v32, v24, s[10:11]
	v_cndmask_b32_e64 v54, v24, v32, s[10:11]
	v_cndmask_b32_e64 v47, v33, v25, s[10:11]
	v_cndmask_b32_e64 v55, v25, v33, s[10:11]
	v_add_u32_dpp v18, v40, v48 row_shr:4 row_mask:0xf bank_mask:0xa
	v_add_u32_dpp v18, v40, v48 row_shl:4 row_mask:0xf bank_mask:0x5
	v_add_u32_dpp v19, v41, v49 row_shr:4 row_mask:0xf bank_mask:0xa
	v_add_u32_dpp v19, v41, v49 row_shl:4 row_mask:0xf bank_mask:0x5
	v_add_u32_dpp v20, v42, v50 row_shr:4 row_mask:0xf bank_mask:0xa
	v_add_u32_dpp v20, v42, v50 row_shl:4 row_mask:0xf bank_mask:0x5
	v_add_u32_dpp v21, v43, v51 row_shr:4 row_mask:0xf bank_mask:0xa
	v_add_u32_dpp v21, v43, v51 row_shl:4 row_mask:0xf bank_mask:0x5
	v_add_u32_dpp v22, v44, v52 row_shr:4 row_mask:0xf bank_mask:0xa
	v_add_u32_dpp v22, v44, v52 row_shl:4 row_mask:0xf bank_mask:0x5
	v_add_u32_dpp v23, v45, v53 row_shr:4 row_mask:0xf bank_mask:0xa
	v_add_u32_dpp v23, v45, v53 row_shl:4 row_mask:0xf bank_mask:0x5
	v_add_u32_dpp v24, v46, v54 row_shr:4 row_mask:0xf bank_mask:0xa
	v_add_u32_dpp v24, v46, v54 row_shl:4 row_mask:0xf bank_mask:0x5
	v_add_u32_dpp v25, v47, v55 row_shr:4 row_mask:0xf bank_mask:0xa
	v_add_u32_dpp v25, v47, v55 row_shl:4 row_mask:0xf bank_mask:0x5
	v_cndmask_b32_e64 v40, v22, v18, s[12:13]
	v_cndmask_b32_e64 v48, v18, v22, s[12:13]
	v_cndmask_b32_e64 v41, v23, v19, s[12:13]
	v_cndmask_b32_e64 v49, v19, v23, s[12:13]
	v_cndmask_b32_e64 v42, v24, v20, s[12:13]
	v_cndmask_b32_e64 v50, v20, v24, s[12:13]
	v_cndmask_b32_e64 v43, v25, v21, s[12:13]
	v_cndmask_b32_e64 v51, v21, v25, s[12:13]
	s_nop 0
	v_add_u32_dpp v26, v40, v48 quad_perm:[2,3,0,1] row_mask:0xf bank_mask:0xf
	v_add_u32_dpp v27, v41, v49 quad_perm:[2,3,0,1] row_mask:0xf bank_mask:0xf
	v_add_u32_dpp v28, v42, v50 quad_perm:[2,3,0,1] row_mask:0xf bank_mask:0xf
	v_add_u32_dpp v29, v43, v51 quad_perm:[2,3,0,1] row_mask:0xf bank_mask:0xf
	v_cndmask_b32_e64 v40, v28, v26, s[14:15]
	v_cndmask_b32_e64 v48, v26, v28, s[14:15]
	v_cndmask_b32_e64 v41, v29, v27, s[14:15]
	v_cndmask_b32_e64 v49, v27, v29, s[14:15]
	s_nop 1
	v_add_u32_dpp v44, v40, v48 quad_perm:[1,0,3,2] row_mask:0xf bank_mask:0xf
	v_add_u32_dpp v45, v41, v49 quad_perm:[1,0,3,2] row_mask:0xf bank_mask:0xf
	s_cmp_eq_u32 s43, 0
	s_cselect_b32 s32, 0, -1
	v_and_b32_e32 v62, s32, v62
	v_and_b32_e32 v63, s32, v63
	v_add_u32_e32 v44, v44, v62
	v_add_u32_e32 v45, v45, v63
	ds_write_b64 v61, v[44:45]
	s_mov_b32 s42, s44
	s_mov_b32 s43, s45
	s_add_i32 s44, s44, 1
	s_and_b32 s44, s44, 7
	s_cmp_eq_u32 s44, 0
	s_cselect_b32 s32, 1, 0
	s_add_i32 s45, s45, s32
	s_and_b32 s45, s45, 3
	s_lshl_b32 s32, s44, 11
	v_add_u32_e32 v39, s32, v59
	ds_read_b128 v[202:205], v39
	ds_read_b128 v[206:209], v39 offset:16
	s_lshl_b32 s32, s42, 12
	v_add_u32_e32 v61, s32, v60
	ds_read_b64 v[62:63], v61
	s_lshl_b32 s46, s44, 3
	s_add_i32 s46, s46, s40
	s_lshl_b32 s46, s46, 9
	s_lshl_b32 s32, s45, 7
	s_add_i32 s46, s46, s32
	v_add_u32_e32 v57, s46, v56
	global_load_dwordx4 v[186:189], v57, s[34:35]
	global_load_dwordx4 v[190:193], v57, s[36:37]
	s_lshl_b32 s32, s45, 21
	v_add_u32_e32 v58, s32, v56
	s_waitcnt lgkmcnt(0)
; __device__ __forceinline__ void peer_u_item(int p, int j, const LAS unsigned short* EL  , const unsigned char* __restrict__ XQ, const unsigned char* __restrict__ U8, LAS int* ACC  , int lane, int wave) {
;     ...
;         for (int i = 0; i < 16; ++i) {
;             int sh = __builtin_amdgcn_sdot8((int)uu[i].x, (int)xh.x, 0, false); sh = __builtin_amdgcn_sdot8((int)uu[i].y, (int)xh.y, sh, false);
;             sh = __builtin_amdgcn_sdot8((int)uu[i].z, (int)xh.z, sh, false); sh = __builtin_amdgcn_sdot8((int)uu[i].w, (int)xh.w, sh, false);
;             int sl = __builtin_amdgcn_sdot8((int)uu[i].x, (int)xl.x, 0, false); sl = __builtin_amdgcn_sdot8((int)uu[i].y, (int)xl.y, sl, false);
;             sl = __builtin_amdgcn_sdot8((int)uu[i].z, (int)xl.z, sl, false); sl = __builtin_amdgcn_sdot8((int)uu[i].w, (int)xl.w, sl, false);
;             d[i] = (sh << 4) + sl;
;         }
	s_waitcnt vmcnt(17)
	v_dot8_i32_i4 v34, v122, v194, 0
	v_dot8_i32_i4 v35, v122, v198, 0
	v_dot8_i32_i4 v34, v123, v195, v34
	v_dot8_i32_i4 v35, v123, v199, v35
	v_dot8_i32_i4 v34, v124, v196, v34
	v_dot8_i32_i4 v35, v124, v200, v35
	v_dot8_i32_i4 v34, v125, v197, v34
	v_dot8_i32_i4 v35, v125, v201, v35
	v_and_b32_e32 v38, 0xffff, v202
	v_lshl_add_u32 v38, v38, 7, v58
	global_load_dwordx4 v[122:125], v38, s[96:97]
	s_nop 0
	v_lshl_add_u32 v18, v34, 4, v35
	s_waitcnt vmcnt(17)
	v_dot8_i32_i4 v36, v126, v194, 0
	v_dot8_i32_i4 v37, v126, v198, 0
	v_dot8_i32_i4 v36, v127, v195, v36
	v_dot8_i32_i4 v37, v127, v199, v37
	v_dot8_i32_i4 v36, v128, v196, v36
	v_dot8_i32_i4 v37, v128, v200, v37
	v_dot8_i32_i4 v36, v129, v197, v36
	v_dot8_i32_i4 v37, v129, v201, v37
	v_lshrrev_b32_e32 v38, 16, v202
	v_lshl_add_u32 v38, v38, 7, v58
	global_load_dwordx4 v[126:129], v38, s[96:97]
	s_nop 0
	v_lshl_add_u32 v19, v36, 4, v37
	s_waitcnt vmcnt(17)
	v_dot8_i32_i4 v34, v130, v194, 0
	v_dot8_i32_i4 v35, v130, v198, 0
	v_dot8_i32_i4 v34, v131, v195, v34
	v_dot8_i32_i4 v35, v131, v199, v35
	v_dot8_i32_i4 v34, v132, v196, v34
	v_dot8_i32_i4 v35, v132, v200, v35
	v_dot8_i32_i4 v34, v133, v197, v34
	v_dot8_i32_i4 v35, v133, v201, v35
	v_and_b32_e32 v38, 0xffff, v203
	v_lshl_add_u32 v38, v38, 7, v58
	global_load_dwordx4 v[130:133], v38, s[96:97]
	s_nop 0
	v_lshl_add_u32 v20, v34, 4, v35
	s_waitcnt vmcnt(17)
	v_dot8_i32_i4 v36, v134, v194, 0
	v_dot8_i32_i4 v37, v134, v198, 0
	v_dot8_i32_i4 v36, v135, v195, v36
	v_dot8_i32_i4 v37, v135, v199, v37
	v_dot8_i32_i4 v36, v136, v196, v36
	v_dot8_i32_i4 v37, v136, v200, v37
	v_dot8_i32_i4 v36, v137, v197, v36
	v_dot8_i32_i4 v37, v137, v201, v37
	v_lshrrev_b32_e32 v38, 16, v203
	v_lshl_add_u32 v38, v38, 7, v58
	global_load_dwordx4 v[134:137], v38, s[96:97]
	s_nop 0
	v_lshl_add_u32 v21, v36, 4, v37
	s_waitcnt vmcnt(17)
	v_dot8_i32_i4 v34, v138, v194, 0
	v_dot8_i32_i4 v35, v138, v198, 0
	v_dot8_i32_i4 v34, v139, v195, v34
	v_dot8_i32_i4 v35, v139, v199, v35
	v_dot8_i32_i4 v34, v140, v196, v34
	v_dot8_i32_i4 v35, v140, v200, v35
	v_dot8_i32_i4 v34, v141, v197, v34
	v_dot8_i32_i4 v35, v141, v201, v35
	v_and_b32_e32 v38, 0xffff, v204
	v_lshl_add_u32 v38, v38, 7, v58
	global_load_dwordx4 v[138:141], v38, s[96:97]
	s_nop 0
	v_lshl_add_u32 v22, v34, 4, v35
	s_waitcnt vmcnt(17)
	v_dot8_i32_i4 v36, v142, v194, 0
	v_dot8_i32_i4 v37, v142, v198, 0
	v_dot8_i32_i4 v36, v143, v195, v36
	v_dot8_i32_i4 v37, v143, v199, v37
	v_dot8_i32_i4 v36, v144, v196, v36
	v_dot8_i32_i4 v37, v144, v200, v37
	v_dot8_i32_i4 v36, v145, v197, v36
	v_dot8_i32_i4 v37, v145, v201, v37
	v_lshrrev_b32_e32 v38, 16, v204
	v_lshl_add_u32 v38, v38, 7, v58
	global_load_dwordx4 v[142:145], v38, s[96:97]
	s_nop 0
	v_lshl_add_u32 v23, v36, 4, v37
	s_waitcnt vmcnt(17)
	v_dot8_i32_i4 v34, v146, v194, 0
	v_dot8_i32_i4 v35, v146, v198, 0
	v_dot8_i32_i4 v34, v147, v195, v34
	v_dot8_i32_i4 v35, v147, v199, v35
	v_dot8_i32_i4 v34, v148, v196, v34
	v_dot8_i32_i4 v35, v148, v200, v35
	v_dot8_i32_i4 v34, v149, v197, v34
	v_dot8_i32_i4 v35, v149, v201, v35
	v_and_b32_e32 v38, 0xffff, v205
	v_lshl_add_u32 v38, v38, 7, v58
	global_load_dwordx4 v[146:149], v38, s[96:97]
	s_nop 0
	v_lshl_add_u32 v24, v34, 4, v35
	s_waitcnt vmcnt(17)
	v_dot8_i32_i4 v36, v150, v194, 0
	v_dot8_i32_i4 v37, v150, v198, 0
	v_dot8_i32_i4 v36, v151, v195, v36
	v_dot8_i32_i4 v37, v151, v199, v37
	v_dot8_i32_i4 v36, v152, v196, v36
	v_dot8_i32_i4 v37, v152, v200, v37
	v_dot8_i32_i4 v36, v153, v197, v36
	v_dot8_i32_i4 v37, v153, v201, v37
	v_lshrrev_b32_e32 v38, 16, v205
	v_lshl_add_u32 v38, v38, 7, v58
	global_load_dwordx4 v[150:153], v38, s[96:97]
	s_nop 0
	v_lshl_add_u32 v25, v36, 4, v37
	s_waitcnt vmcnt(17)
	v_dot8_i32_i4 v34, v154, v194, 0
	v_dot8_i32_i4 v35, v154, v198, 0
	v_dot8_i32_i4 v34, v155, v195, v34
	v_dot8_i32_i4 v35, v155, v199, v35
	v_dot8_i32_i4 v34, v156, v196, v34
	v_dot8_i32_i4 v35, v156, v200, v35
	v_dot8_i32_i4 v34, v157, v197, v34
	v_dot8_i32_i4 v35, v157, v201, v35
	v_and_b32_e32 v38, 0xffff, v206
	v_lshl_add_u32 v38, v38, 7, v58
	global_load_dwordx4 v[154:157], v38, s[96:97]
	s_nop 0
	v_lshl_add_u32 v26, v34, 4, v35
	s_waitcnt vmcnt(17)
	v_dot8_i32_i4 v36, v158, v194, 0
	v_dot8_i32_i4 v37, v158, v198, 0
	v_dot8_i32_i4 v36, v159, v195, v36
	v_dot8_i32_i4 v37, v159, v199, v37
	v_dot8_i32_i4 v36, v160, v196, v36
	v_dot8_i32_i4 v37, v160, v200, v37
	v_dot8_i32_i4 v36, v161, v197, v36
	v_dot8_i32_i4 v37, v161, v201, v37
	v_lshrrev_b32_e32 v38, 16, v206
	v_lshl_add_u32 v38, v38, 7, v58
	global_load_dwordx4 v[158:161], v38, s[96:97]
	s_nop 0
	v_lshl_add_u32 v27, v36, 4, v37
	s_waitcnt vmcnt(17)
	v_dot8_i32_i4 v34, v162, v194, 0
	v_dot8_i32_i4 v35, v162, v198, 0
	v_dot8_i32_i4 v34, v163, v195, v34
	v_dot8_i32_i4 v35, v163, v199, v35
	v_dot8_i32_i4 v34, v164, v196, v34
	v_dot8_i32_i4 v35, v164, v200, v35
	v_dot8_i32_i4 v34, v165, v197, v34
	v_dot8_i32_i4 v35, v165, v201, v35
	v_and_b32_e32 v38, 0xffff, v207
	v_lshl_add_u32 v38, v38, 7, v58
	global_load_dwordx4 v[162:165], v38, s[96:97]
	s_nop 0
	v_lshl_add_u32 v28, v34, 4, v35
	s_waitcnt vmcnt(17)
	v_dot8_i32_i4 v36, v166, v194, 0
	v_dot8_i32_i4 v37, v166, v198, 0
	v_dot8_i32_i4 v36, v167, v195, v36
	v_dot8_i32_i4 v37, v167, v199, v37
	v_dot8_i32_i4 v36, v168, v196, v36
	v_dot8_i32_i4 v37, v168, v200, v37
	v_dot8_i32_i4 v36, v169, v197, v36
	v_dot8_i32_i4 v37, v169, v201, v37
	v_lshrrev_b32_e32 v38, 16, v207
	v_lshl_add_u32 v38, v38, 7, v58
	global_load_dwordx4 v[166:169], v38, s[96:97]
	s_nop 0
	v_lshl_add_u32 v29, v36, 4, v37
	s_waitcnt vmcnt(17)
; #define LAS __attribute__((address_space(3)))
; template <int M4, int M2, int M1> __device__ __forceinline__ void treduce16i(const int (&a)[16], int lane, int& r0, int& r1) {
;     int b[8], c[4];
;     { const bool hi = (lane & M4) != 0;
; #pragma unroll
;       for (int i = 0; i < 8; ++i) { const int send = hi ? a[i] : a[i + 8]; const int recv = __shfl_xor(send, M4); b[i] = (hi ? a[i + 8] : a[i]) + recv; } }
;     { const bool hi = (lane & M2) != 0;
; #pragma unroll
;       for (int i = 0; i < 4; ++i) { const int send = hi ? b[i] : b[i + 4]; const int recv = __shfl_xor(send, M2); c[i] = (hi ? b[i + 4] : b[i]) + recv; } }
;     { const bool hi = (lane & M1) != 0;
;       { const int send = hi ? c[0] : c[2]; const int recv = __shfl_xor(send, M1); r0 = (hi ? c[2] : c[0]) + recv; }
;       { const int send = hi ? c[1] : c[3]; const int recv = __shfl_xor(send, M1); r1 = (hi ? c[3] : c[1]) + recv; } }
; }
; __device__ __forceinline__ void peer_u_item(int p, int j, const LAS unsigned short* EL  , const unsigned char* __restrict__ XQ, const unsigned char* __restrict__ U8, LAS int* ACC  , int lane, int wave) {
;     ...
;         for (int i = 0; i < 16; ++i) {
;             int sh = __builtin_amdgcn_sdot8((int)uu[i].x, (int)xh.x, 0, false); sh = __builtin_amdgcn_sdot8((int)uu[i].y, (int)xh.y, sh, false);
;             sh = __builtin_amdgcn_sdot8((int)uu[i].z, (int)xh.z, sh, false); sh = __builtin_amdgcn_sdot8((int)uu[i].w, (int)xh.w, sh, false);
;             int sl = __builtin_amdgcn_sdot8((int)uu[i].x, (int)xl.x, 0, false); sl = __builtin_amdgcn_sdot8((int)uu[i].y, (int)xl.y, sl, false);
;             sl = __builtin_amdgcn_sdot8((int)uu[i].z, (int)xl.z, sl, false); sl = __builtin_amdgcn_sdot8((int)uu[i].w, (int)xl.w, sl, false);
;             d[i] = (sh << 4) + sl;
;         }
;         int r0, r1; treduce16i<4, 2, 1>(d, lane, r0, r1);
;         { typedef int i2v __attribute__((ext_vector_type(2))); LAS i2v* ap = (LAS i2v*)(ACC + (it * 8 + wave) * 128 + 2 * lane);
;           i2v a2; if (p == 0) { a2.x = r0; a2.y = r1; } else { a2 = *ap; a2.x += r0; a2.y += r1; } *ap = a2; }
;     }
; }
	v_dot8_i32_i4 v34, v170, v194, 0
	v_dot8_i32_i4 v35, v170, v198, 0
	v_dot8_i32_i4 v34, v171, v195, v34
	v_dot8_i32_i4 v35, v171, v199, v35
	v_dot8_i32_i4 v34, v172, v196, v34
	v_dot8_i32_i4 v35, v172, v200, v35
	v_dot8_i32_i4 v34, v173, v197, v34
	v_dot8_i32_i4 v35, v173, v201, v35
	v_and_b32_e32 v38, 0xffff, v208
	v_lshl_add_u32 v38, v38, 7, v58
	global_load_dwordx4 v[170:173], v38, s[96:97]
	s_nop 0
	v_lshl_add_u32 v30, v34, 4, v35
	s_waitcnt vmcnt(17)
	v_dot8_i32_i4 v36, v174, v194, 0
	v_dot8_i32_i4 v37, v174, v198, 0
	v_dot8_i32_i4 v36, v175, v195, v36
	v_dot8_i32_i4 v37, v175, v199, v37
	v_dot8_i32_i4 v36, v176, v196, v36
	v_dot8_i32_i4 v37, v176, v200, v37
	v_dot8_i32_i4 v36, v177, v197, v36
	v_dot8_i32_i4 v37, v177, v201, v37
	v_lshrrev_b32_e32 v38, 16, v208
	v_lshl_add_u32 v38, v38, 7, v58
	global_load_dwordx4 v[174:177], v38, s[96:97]
	s_nop 0
	v_lshl_add_u32 v31, v36, 4, v37
	s_waitcnt vmcnt(17)
	v_dot8_i32_i4 v34, v178, v194, 0
	v_dot8_i32_i4 v35, v178, v198, 0
	v_dot8_i32_i4 v34, v179, v195, v34
	v_dot8_i32_i4 v35, v179, v199, v35
	v_dot8_i32_i4 v34, v180, v196, v34
	v_dot8_i32_i4 v35, v180, v200, v35
	v_dot8_i32_i4 v34, v181, v197, v34
	v_dot8_i32_i4 v35, v181, v201, v35
	v_and_b32_e32 v38, 0xffff, v209
	v_lshl_add_u32 v38, v38, 7, v58
	global_load_dwordx4 v[178:181], v38, s[96:97]
	s_nop 0
	v_lshl_add_u32 v32, v34, 4, v35
	s_waitcnt vmcnt(17)
	v_dot8_i32_i4 v36, v182, v194, 0
	v_dot8_i32_i4 v37, v182, v198, 0
	v_dot8_i32_i4 v36, v183, v195, v36
	v_dot8_i32_i4 v37, v183, v199, v37
	v_dot8_i32_i4 v36, v184, v196, v36
	v_dot8_i32_i4 v37, v184, v200, v37
	v_dot8_i32_i4 v36, v185, v197, v36
	v_dot8_i32_i4 v37, v185, v201, v37
	v_lshrrev_b32_e32 v38, 16, v209
	v_lshl_add_u32 v38, v38, 7, v58
	global_load_dwordx4 v[182:185], v38, s[96:97]
	s_nop 0
	v_lshl_add_u32 v33, v36, 4, v37
	v_cndmask_b32_e64 v40, v26, v18, s[10:11]
	v_cndmask_b32_e64 v48, v18, v26, s[10:11]
	v_cndmask_b32_e64 v41, v27, v19, s[10:11]
	v_cndmask_b32_e64 v49, v19, v27, s[10:11]
	v_cndmask_b32_e64 v42, v28, v20, s[10:11]
	v_cndmask_b32_e64 v50, v20, v28, s[10:11]
	v_cndmask_b32_e64 v43, v29, v21, s[10:11]
	v_cndmask_b32_e64 v51, v21, v29, s[10:11]
	v_cndmask_b32_e64 v44, v30, v22, s[10:11]
	v_cndmask_b32_e64 v52, v22, v30, s[10:11]
	v_cndmask_b32_e64 v45, v31, v23, s[10:11]
	v_cndmask_b32_e64 v53, v23, v31, s[10:11]
	v_cndmask_b32_e64 v46, v32, v24, s[10:11]
	v_cndmask_b32_e64 v54, v24, v32, s[10:11]
	v_cndmask_b32_e64 v47, v33, v25, s[10:11]
	v_cndmask_b32_e64 v55, v25, v33, s[10:11]
	v_add_u32_dpp v18, v40, v48 row_shr:4 row_mask:0xf bank_mask:0xa
	v_add_u32_dpp v18, v40, v48 row_shl:4 row_mask:0xf bank_mask:0x5
	v_add_u32_dpp v19, v41, v49 row_shr:4 row_mask:0xf bank_mask:0xa
	v_add_u32_dpp v19, v41, v49 row_shl:4 row_mask:0xf bank_mask:0x5
	v_add_u32_dpp v20, v42, v50 row_shr:4 row_mask:0xf bank_mask:0xa
	v_add_u32_dpp v20, v42, v50 row_shl:4 row_mask:0xf bank_mask:0x5
	v_add_u32_dpp v21, v43, v51 row_shr:4 row_mask:0xf bank_mask:0xa
	v_add_u32_dpp v21, v43, v51 row_shl:4 row_mask:0xf bank_mask:0x5
	v_add_u32_dpp v22, v44, v52 row_shr:4 row_mask:0xf bank_mask:0xa
	v_add_u32_dpp v22, v44, v52 row_shl:4 row_mask:0xf bank_mask:0x5
	v_add_u32_dpp v23, v45, v53 row_shr:4 row_mask:0xf bank_mask:0xa
	v_add_u32_dpp v23, v45, v53 row_shl:4 row_mask:0xf bank_mask:0x5
	v_add_u32_dpp v24, v46, v54 row_shr:4 row_mask:0xf bank_mask:0xa
	v_add_u32_dpp v24, v46, v54 row_shl:4 row_mask:0xf bank_mask:0x5
	v_add_u32_dpp v25, v47, v55 row_shr:4 row_mask:0xf bank_mask:0xa
	v_add_u32_dpp v25, v47, v55 row_shl:4 row_mask:0xf bank_mask:0x5
	v_cndmask_b32_e64 v40, v22, v18, s[12:13]
	v_cndmask_b32_e64 v48, v18, v22, s[12:13]
	v_cndmask_b32_e64 v41, v23, v19, s[12:13]
	v_cndmask_b32_e64 v49, v19, v23, s[12:13]
	v_cndmask_b32_e64 v42, v24, v20, s[12:13]
	v_cndmask_b32_e64 v50, v20, v24, s[12:13]
	v_cndmask_b32_e64 v43, v25, v21, s[12:13]
	v_cndmask_b32_e64 v51, v21, v25, s[12:13]
	s_nop 0
	v_add_u32_dpp v26, v40, v48 quad_perm:[2,3,0,1] row_mask:0xf bank_mask:0xf
	v_add_u32_dpp v27, v41, v49 quad_perm:[2,3,0,1] row_mask:0xf bank_mask:0xf
	v_add_u32_dpp v28, v42, v50 quad_perm:[2,3,0,1] row_mask:0xf bank_mask:0xf
	v_add_u32_dpp v29, v43, v51 quad_perm:[2,3,0,1] row_mask:0xf bank_mask:0xf
	v_cndmask_b32_e64 v40, v28, v26, s[14:15]
	v_cndmask_b32_e64 v48, v26, v28, s[14:15]
	v_cndmask_b32_e64 v41, v29, v27, s[14:15]
	v_cndmask_b32_e64 v49, v27, v29, s[14:15]
	s_nop 1
	v_add_u32_dpp v44, v40, v48 quad_perm:[1,0,3,2] row_mask:0xf bank_mask:0xf
	v_add_u32_dpp v45, v41, v49 quad_perm:[1,0,3,2] row_mask:0xf bank_mask:0xf
	s_cmp_eq_u32 s43, 0
	s_cselect_b32 s32, 0, -1
	v_and_b32_e32 v62, s32, v62
	v_and_b32_e32 v63, s32, v63
	v_add_u32_e32 v44, v44, v62
	v_add_u32_e32 v45, v45, v63
	ds_write_b64 v61, v[44:45]
	s_mov_b32 s42, s44
	s_mov_b32 s43, s45
	s_add_i32 s44, s44, 1
	s_and_b32 s44, s44, 7
	s_cmp_eq_u32 s44, 0
	s_cselect_b32 s32, 1, 0
	s_add_i32 s45, s45, s32
	s_and_b32 s45, s45, 3
	s_add_i32 s47, s47, -1
	s_cmp_lg_u32 s47, 0
	s_cbranch_scc1 .Lpu_trip
; #define LAS __attribute__((address_space(3)))
; __device__ __forceinline__ void peer_u_item(int p, int j, const LAS unsigned short* EL  , const unsigned char* __restrict__ XQ, const unsigned char* __restrict__ U8, LAS int* ACC  , int lane, int wave) {
;     ...
; #pragma unroll 1
;     for (int it = 0; it < 8; ++it) {
;         const int t = j * 64 + it * 8 + wave;
;         unsigned E[8];
;         { const LAS v4u* ep = (const LAS v4u*)(EL + (it * 8 + wave) * 128 + 16 * gidx); const v4u e0 = ep[0], e1 = ep[1];
;           E[0] = e0.x; E[1] = e0.y; E[2] = e0.z; E[3] = e0.w; E[4] = e1.x; E[5] = e1.y; E[6] = e1.z; E[7] = e1.w; }
;         uint4 uu[16];
; #pragma unroll
;         for (int i = 0; i < 16; ++i) uu[i] = *(const uint4*)(U8 + (size_t)(PE_ID(E, i) * 128u + toff));
;         const uint4 xh = *(const uint4*)(XQ + (size_t)t * 512 + coff), xl = *(const uint4*)(XQ + 8 * MiB + (size_t)t * 512 + coff);
;         int d[16];
; #pragma unroll
;         for (int i = 0; i < 16; ++i) {
;             int sh = __builtin_amdgcn_sdot8((int)uu[i].x, (int)xh.x, 0, false); sh = __builtin_amdgcn_sdot8((int)uu[i].y, (int)xh.y, sh, false);
;             sh = __builtin_amdgcn_sdot8((int)uu[i].z, (int)xh.z, sh, false); sh = __builtin_amdgcn_sdot8((int)uu[i].w, (int)xh.w, sh, false);
;             int sl = __builtin_amdgcn_sdot8((int)uu[i].x, (int)xl.x, 0, false); sl = __builtin_amdgcn_sdot8((int)uu[i].y, (int)xl.y, sl, false);
;             sl = __builtin_amdgcn_sdot8((int)uu[i].z, (int)xl.z, sl, false); sl = __builtin_amdgcn_sdot8((int)uu[i].w, (int)xl.w, sl, false);
;             d[i] = (sh << 4) + sl;
;         }
	s_lshl_b32 s32, s44, 11
	v_add_u32_e32 v39, s32, v59
	ds_read_b128 v[210:213], v39
	ds_read_b128 v[214:217], v39 offset:16
	s_lshl_b32 s32, s42, 12
	v_add_u32_e32 v61, s32, v60
	ds_read_b64 v[62:63], v61
	s_lshl_b32 s46, s44, 3
	s_add_i32 s46, s46, s40
	s_lshl_b32 s46, s46, 9
	s_lshl_b32 s32, s45, 7
	s_add_i32 s46, s46, s32
	v_add_u32_e32 v57, s46, v56
	global_load_dwordx4 v[194:197], v57, s[34:35]
	global_load_dwordx4 v[198:201], v57, s[36:37]
	s_lshl_b32 s32, s45, 21
	v_add_u32_e32 v58, s32, v56
	s_waitcnt lgkmcnt(0)
	s_waitcnt vmcnt(17)
	v_dot8_i32_i4 v34, v122, v186, 0
	v_dot8_i32_i4 v35, v122, v190, 0
	v_dot8_i32_i4 v34, v123, v187, v34
	v_dot8_i32_i4 v35, v123, v191, v35
	v_dot8_i32_i4 v34, v124, v188, v34
	v_dot8_i32_i4 v35, v124, v192, v35
	v_dot8_i32_i4 v34, v125, v189, v34
	v_dot8_i32_i4 v35, v125, v193, v35
	v_and_b32_e32 v38, 0xffff, v210
	v_lshl_add_u32 v38, v38, 7, v58
	global_load_dwordx4 v[122:125], v38, s[96:97]
	s_nop 0
	v_lshl_add_u32 v18, v34, 4, v35
	s_waitcnt vmcnt(17)
	v_dot8_i32_i4 v36, v126, v186, 0
	v_dot8_i32_i4 v37, v126, v190, 0
	v_dot8_i32_i4 v36, v127, v187, v36
	v_dot8_i32_i4 v37, v127, v191, v37
	v_dot8_i32_i4 v36, v128, v188, v36
	v_dot8_i32_i4 v37, v128, v192, v37
	v_dot8_i32_i4 v36, v129, v189, v36
	v_dot8_i32_i4 v37, v129, v193, v37
	v_lshrrev_b32_e32 v38, 16, v210
	v_lshl_add_u32 v38, v38, 7, v58
	global_load_dwordx4 v[126:129], v38, s[96:97]
	s_nop 0
	v_lshl_add_u32 v19, v36, 4, v37
	s_waitcnt vmcnt(17)
	v_dot8_i32_i4 v34, v130, v186, 0
	v_dot8_i32_i4 v35, v130, v190, 0
	v_dot8_i32_i4 v34, v131, v187, v34
	v_dot8_i32_i4 v35, v131, v191, v35
	v_dot8_i32_i4 v34, v132, v188, v34
	v_dot8_i32_i4 v35, v132, v192, v35
	v_dot8_i32_i4 v34, v133, v189, v34
	v_dot8_i32_i4 v35, v133, v193, v35
	v_and_b32_e32 v38, 0xffff, v211
	v_lshl_add_u32 v38, v38, 7, v58
	global_load_dwordx4 v[130:133], v38, s[96:97]
	s_nop 0
	v_lshl_add_u32 v20, v34, 4, v35
	s_waitcnt vmcnt(17)
	v_dot8_i32_i4 v36, v134, v186, 0
	v_dot8_i32_i4 v37, v134, v190, 0
	v_dot8_i32_i4 v36, v135, v187, v36
	v_dot8_i32_i4 v37, v135, v191, v37
	v_dot8_i32_i4 v36, v136, v188, v36
	v_dot8_i32_i4 v37, v136, v192, v37
	v_dot8_i32_i4 v36, v137, v189, v36
	v_dot8_i32_i4 v37, v137, v193, v37
	v_lshrrev_b32_e32 v38, 16, v211
	v_lshl_add_u32 v38, v38, 7, v58
	global_load_dwordx4 v[134:137], v38, s[96:97]
	s_nop 0
	v_lshl_add_u32 v21, v36, 4, v37
	s_waitcnt vmcnt(17)
	v_dot8_i32_i4 v34, v138, v186, 0
	v_dot8_i32_i4 v35, v138, v190, 0
	v_dot8_i32_i4 v34, v139, v187, v34
	v_dot8_i32_i4 v35, v139, v191, v35
	v_dot8_i32_i4 v34, v140, v188, v34
	v_dot8_i32_i4 v35, v140, v192, v35
	v_dot8_i32_i4 v34, v141, v189, v34
	v_dot8_i32_i4 v35, v141, v193, v35
	v_and_b32_e32 v38, 0xffff, v212
	v_lshl_add_u32 v38, v38, 7, v58
	global_load_dwordx4 v[138:141], v38, s[96:97]
	s_nop 0
	v_lshl_add_u32 v22, v34, 4, v35
	s_waitcnt vmcnt(17)
	v_dot8_i32_i4 v36, v142, v186, 0
	v_dot8_i32_i4 v37, v142, v190, 0
	v_dot8_i32_i4 v36, v143, v187, v36
	v_dot8_i32_i4 v37, v143, v191, v37
	v_dot8_i32_i4 v36, v144, v188, v36
	v_dot8_i32_i4 v37, v144, v192, v37
	v_dot8_i32_i4 v36, v145, v189, v36
	v_dot8_i32_i4 v37, v145, v193, v37
	v_lshrrev_b32_e32 v38, 16, v212
	v_lshl_add_u32 v38, v38, 7, v58
	global_load_dwordx4 v[142:145], v38, s[96:97]
	s_nop 0
	v_lshl_add_u32 v23, v36, 4, v37
	s_waitcnt vmcnt(17)
	v_dot8_i32_i4 v34, v146, v186, 0
	v_dot8_i32_i4 v35, v146, v190, 0
	v_dot8_i32_i4 v34, v147, v187, v34
	v_dot8_i32_i4 v35, v147, v191, v35
	v_dot8_i32_i4 v34, v148, v188, v34
	v_dot8_i32_i4 v35, v148, v192, v35
	v_dot8_i32_i4 v34, v149, v189, v34
	v_dot8_i32_i4 v35, v149, v193, v35
	v_and_b32_e32 v38, 0xffff, v213
	v_lshl_add_u32 v38, v38, 7, v58
	global_load_dwordx4 v[146:149], v38, s[96:97]
	s_nop 0
	v_lshl_add_u32 v24, v34, 4, v35
	s_waitcnt vmcnt(17)
	v_dot8_i32_i4 v36, v150, v186, 0
	v_dot8_i32_i4 v37, v150, v190, 0
	v_dot8_i32_i4 v36, v151, v187, v36
	v_dot8_i32_i4 v37, v151, v191, v37
	v_dot8_i32_i4 v36, v152, v188, v36
	v_dot8_i32_i4 v37, v152, v192, v37
	v_dot8_i32_i4 v36, v153, v189, v36
	v_dot8_i32_i4 v37, v153, v193, v37
	v_lshrrev_b32_e32 v38, 16, v213
	v_lshl_add_u32 v38, v38, 7, v58
	global_load_dwordx4 v[150:153], v38, s[96:97]
	s_nop 0
	v_lshl_add_u32 v25, v36, 4, v37
	s_waitcnt vmcnt(17)
	v_dot8_i32_i4 v34, v154, v186, 0
	v_dot8_i32_i4 v35, v154, v190, 0
	v_dot8_i32_i4 v34, v155, v187, v34
	v_dot8_i32_i4 v35, v155, v191, v35
	v_dot8_i32_i4 v34, v156, v188, v34
	v_dot8_i32_i4 v35, v156, v192, v35
	v_dot8_i32_i4 v34, v157, v189, v34
	v_dot8_i32_i4 v35, v157, v193, v35
	v_and_b32_e32 v38, 0xffff, v214
	v_lshl_add_u32 v38, v38, 7, v58
	global_load_dwordx4 v[154:157], v38, s[96:97]
	s_nop 0
	v_lshl_add_u32 v26, v34, 4, v35
	s_waitcnt vmcnt(17)
	v_dot8_i32_i4 v36, v158, v186, 0
	v_dot8_i32_i4 v37, v158, v190, 0
	v_dot8_i32_i4 v36, v159, v187, v36
	v_dot8_i32_i4 v37, v159, v191, v37
	v_dot8_i32_i4 v36, v160, v188, v36
	v_dot8_i32_i4 v37, v160, v192, v37
	v_dot8_i32_i4 v36, v161, v189, v36
	v_dot8_i32_i4 v37, v161, v193, v37
	v_lshrrev_b32_e32 v38, 16, v214
	v_lshl_add_u32 v38, v38, 7, v58
	global_load_dwordx4 v[158:161], v38, s[96:97]
	s_nop 0
	v_lshl_add_u32 v27, v36, 4, v37
	s_waitcnt vmcnt(17)
	v_dot8_i32_i4 v34, v162, v186, 0
	v_dot8_i32_i4 v35, v162, v190, 0
	v_dot8_i32_i4 v34, v163, v187, v34
	v_dot8_i32_i4 v35, v163, v191, v35
	v_dot8_i32_i4 v34, v164, v188, v34
	v_dot8_i32_i4 v35, v164, v192, v35
	v_dot8_i32_i4 v34, v165, v189, v34
	v_dot8_i32_i4 v35, v165, v193, v35
	v_and_b32_e32 v38, 0xffff, v215
	v_lshl_add_u32 v38, v38, 7, v58
	global_load_dwordx4 v[162:165], v38, s[96:97]
	s_nop 0
	v_lshl_add_u32 v28, v34, 4, v35
	s_waitcnt vmcnt(17)
; #define LAS __attribute__((address_space(3)))
; template <int M4, int M2, int M1> __device__ __forceinline__ void treduce16i(const int (&a)[16], int lane, int& r0, int& r1) {
;     int b[8], c[4];
;     { const bool hi = (lane & M4) != 0;
; #pragma unroll
;       for (int i = 0; i < 8; ++i) { const int send = hi ? a[i] : a[i + 8]; const int recv = __shfl_xor(send, M4); b[i] = (hi ? a[i + 8] : a[i]) + recv; } }
;     { const bool hi = (lane & M2) != 0;
; #pragma unroll
;       for (int i = 0; i < 4; ++i) { const int send = hi ? b[i] : b[i + 4]; const int recv = __shfl_xor(send, M2); c[i] = (hi ? b[i + 4] : b[i]) + recv; } }
;     { const bool hi = (lane & M1) != 0;
;       { const int send = hi ? c[0] : c[2]; const int recv = __shfl_xor(send, M1); r0 = (hi ? c[2] : c[0]) + recv; }
;       { const int send = hi ? c[1] : c[3]; const int recv = __shfl_xor(send, M1); r1 = (hi ? c[3] : c[1]) + recv; } }
; }
; __device__ __forceinline__ void peer_u_item(int p, int j, const LAS unsigned short* EL  , const unsigned char* __restrict__ XQ, const unsigned char* __restrict__ U8, LAS int* ACC  , int lane, int wave) {
;     ...
;         for (int i = 0; i < 16; ++i) uu[i] = *(const uint4*)(U8 + (size_t)(PE_ID(E, i) * 128u + toff));
;         const uint4 xh = *(const uint4*)(XQ + (size_t)t * 512 + coff), xl = *(const uint4*)(XQ + 8 * MiB + (size_t)t * 512 + coff);
;         int d[16];
; #pragma unroll
;         for (int i = 0; i < 16; ++i) {
;             int sh = __builtin_amdgcn_sdot8((int)uu[i].x, (int)xh.x, 0, false); sh = __builtin_amdgcn_sdot8((int)uu[i].y, (int)xh.y, sh, false);
;             sh = __builtin_amdgcn_sdot8((int)uu[i].z, (int)xh.z, sh, false); sh = __builtin_amdgcn_sdot8((int)uu[i].w, (int)xh.w, sh, false);
;             int sl = __builtin_amdgcn_sdot8((int)uu[i].x, (int)xl.x, 0, false); sl = __builtin_amdgcn_sdot8((int)uu[i].y, (int)xl.y, sl, false);
;             sl = __builtin_amdgcn_sdot8((int)uu[i].z, (int)xl.z, sl, false); sl = __builtin_amdgcn_sdot8((int)uu[i].w, (int)xl.w, sl, false);
;             d[i] = (sh << 4) + sl;
;         }
;         int r0, r1; treduce16i<4, 2, 1>(d, lane, r0, r1);
;         { typedef int i2v __attribute__((ext_vector_type(2))); LAS i2v* ap = (LAS i2v*)(ACC + (it * 8 + wave) * 128 + 2 * lane);
;           i2v a2; if (p == 0) { a2.x = r0; a2.y = r1; } else { a2 = *ap; a2.x += r0; a2.y += r1; } *ap = a2; }
	v_dot8_i32_i4 v36, v166, v186, 0
	v_dot8_i32_i4 v37, v166, v190, 0
	v_dot8_i32_i4 v36, v167, v187, v36
	v_dot8_i32_i4 v37, v167, v191, v37
	v_dot8_i32_i4 v36, v168, v188, v36
	v_dot8_i32_i4 v37, v168, v192, v37
	v_dot8_i32_i4 v36, v169, v189, v36
	v_dot8_i32_i4 v37, v169, v193, v37
	v_lshrrev_b32_e32 v38, 16, v215
	v_lshl_add_u32 v38, v38, 7, v58
	global_load_dwordx4 v[166:169], v38, s[96:97]
	s_nop 0
	v_lshl_add_u32 v29, v36, 4, v37
	s_waitcnt vmcnt(17)
	v_dot8_i32_i4 v34, v170, v186, 0
	v_dot8_i32_i4 v35, v170, v190, 0
	v_dot8_i32_i4 v34, v171, v187, v34
	v_dot8_i32_i4 v35, v171, v191, v35
	v_dot8_i32_i4 v34, v172, v188, v34
	v_dot8_i32_i4 v35, v172, v192, v35
	v_dot8_i32_i4 v34, v173, v189, v34
	v_dot8_i32_i4 v35, v173, v193, v35
	v_and_b32_e32 v38, 0xffff, v216
	v_lshl_add_u32 v38, v38, 7, v58
	global_load_dwordx4 v[170:173], v38, s[96:97]
	s_nop 0
	v_lshl_add_u32 v30, v34, 4, v35
	s_waitcnt vmcnt(17)
	v_dot8_i32_i4 v36, v174, v186, 0
	v_dot8_i32_i4 v37, v174, v190, 0
	v_dot8_i32_i4 v36, v175, v187, v36
	v_dot8_i32_i4 v37, v175, v191, v37
	v_dot8_i32_i4 v36, v176, v188, v36
	v_dot8_i32_i4 v37, v176, v192, v37
	v_dot8_i32_i4 v36, v177, v189, v36
	v_dot8_i32_i4 v37, v177, v193, v37
	v_lshrrev_b32_e32 v38, 16, v216
	v_lshl_add_u32 v38, v38, 7, v58
	global_load_dwordx4 v[174:177], v38, s[96:97]
	s_nop 0
	v_lshl_add_u32 v31, v36, 4, v37
	s_waitcnt vmcnt(17)
	v_dot8_i32_i4 v34, v178, v186, 0
	v_dot8_i32_i4 v35, v178, v190, 0
	v_dot8_i32_i4 v34, v179, v187, v34
	v_dot8_i32_i4 v35, v179, v191, v35
	v_dot8_i32_i4 v34, v180, v188, v34
	v_dot8_i32_i4 v35, v180, v192, v35
	v_dot8_i32_i4 v34, v181, v189, v34
	v_dot8_i32_i4 v35, v181, v193, v35
	v_and_b32_e32 v38, 0xffff, v217
	v_lshl_add_u32 v38, v38, 7, v58
	global_load_dwordx4 v[178:181], v38, s[96:97]
	s_nop 0
	v_lshl_add_u32 v32, v34, 4, v35
	s_waitcnt vmcnt(17)
	v_dot8_i32_i4 v36, v182, v186, 0
	v_dot8_i32_i4 v37, v182, v190, 0
	v_dot8_i32_i4 v36, v183, v187, v36
	v_dot8_i32_i4 v37, v183, v191, v37
	v_dot8_i32_i4 v36, v184, v188, v36
	v_dot8_i32_i4 v37, v184, v192, v37
	v_dot8_i32_i4 v36, v185, v189, v36
	v_dot8_i32_i4 v37, v185, v193, v37
	v_lshrrev_b32_e32 v38, 16, v217
	v_lshl_add_u32 v38, v38, 7, v58
	global_load_dwordx4 v[182:185], v38, s[96:97]
	s_nop 0
	v_lshl_add_u32 v33, v36, 4, v37
	v_cndmask_b32_e64 v40, v26, v18, s[10:11]
	v_cndmask_b32_e64 v48, v18, v26, s[10:11]
	v_cndmask_b32_e64 v41, v27, v19, s[10:11]
	v_cndmask_b32_e64 v49, v19, v27, s[10:11]
	v_cndmask_b32_e64 v42, v28, v20, s[10:11]
	v_cndmask_b32_e64 v50, v20, v28, s[10:11]
	v_cndmask_b32_e64 v43, v29, v21, s[10:11]
	v_cndmask_b32_e64 v51, v21, v29, s[10:11]
	v_cndmask_b32_e64 v44, v30, v22, s[10:11]
	v_cndmask_b32_e64 v52, v22, v30, s[10:11]
	v_cndmask_b32_e64 v45, v31, v23, s[10:11]
	v_cndmask_b32_e64 v53, v23, v31, s[10:11]
	v_cndmask_b32_e64 v46, v32, v24, s[10:11]
	v_cndmask_b32_e64 v54, v24, v32, s[10:11]
	v_cndmask_b32_e64 v47, v33, v25, s[10:11]
	v_cndmask_b32_e64 v55, v25, v33, s[10:11]
	v_add_u32_dpp v18, v40, v48 row_shr:4 row_mask:0xf bank_mask:0xa
	v_add_u32_dpp v18, v40, v48 row_shl:4 row_mask:0xf bank_mask:0x5
	v_add_u32_dpp v19, v41, v49 row_shr:4 row_mask:0xf bank_mask:0xa
	v_add_u32_dpp v19, v41, v49 row_shl:4 row_mask:0xf bank_mask:0x5
	v_add_u32_dpp v20, v42, v50 row_shr:4 row_mask:0xf bank_mask:0xa
	v_add_u32_dpp v20, v42, v50 row_shl:4 row_mask:0xf bank_mask:0x5
	v_add_u32_dpp v21, v43, v51 row_shr:4 row_mask:0xf bank_mask:0xa
	v_add_u32_dpp v21, v43, v51 row_shl:4 row_mask:0xf bank_mask:0x5
	v_add_u32_dpp v22, v44, v52 row_shr:4 row_mask:0xf bank_mask:0xa
	v_add_u32_dpp v22, v44, v52 row_shl:4 row_mask:0xf bank_mask:0x5
	v_add_u32_dpp v23, v45, v53 row_shr:4 row_mask:0xf bank_mask:0xa
	v_add_u32_dpp v23, v45, v53 row_shl:4 row_mask:0xf bank_mask:0x5
	v_add_u32_dpp v24, v46, v54 row_shr:4 row_mask:0xf bank_mask:0xa
	v_add_u32_dpp v24, v46, v54 row_shl:4 row_mask:0xf bank_mask:0x5
	v_add_u32_dpp v25, v47, v55 row_shr:4 row_mask:0xf bank_mask:0xa
	v_add_u32_dpp v25, v47, v55 row_shl:4 row_mask:0xf bank_mask:0x5
	v_cndmask_b32_e64 v40, v22, v18, s[12:13]
	v_cndmask_b32_e64 v48, v18, v22, s[12:13]
	v_cndmask_b32_e64 v41, v23, v19, s[12:13]
	v_cndmask_b32_e64 v49, v19, v23, s[12:13]
	v_cndmask_b32_e64 v42, v24, v20, s[12:13]
	v_cndmask_b32_e64 v50, v20, v24, s[12:13]
	v_cndmask_b32_e64 v43, v25, v21, s[12:13]
	v_cndmask_b32_e64 v51, v21, v25, s[12:13]
	s_nop 0
	v_add_u32_dpp v26, v40, v48 quad_perm:[2,3,0,1] row_mask:0xf bank_mask:0xf
	v_add_u32_dpp v27, v41, v49 quad_perm:[2,3,0,1] row_mask:0xf bank_mask:0xf
	v_add_u32_dpp v28, v42, v50 quad_perm:[2,3,0,1] row_mask:0xf bank_mask:0xf
	v_add_u32_dpp v29, v43, v51 quad_perm:[2,3,0,1] row_mask:0xf bank_mask:0xf
	v_cndmask_b32_e64 v40, v28, v26, s[14:15]
	v_cndmask_b32_e64 v48, v26, v28, s[14:15]
	v_cndmask_b32_e64 v41, v29, v27, s[14:15]
	v_cndmask_b32_e64 v49, v27, v29, s[14:15]
	s_nop 1
	v_add_u32_dpp v44, v40, v48 quad_perm:[1,0,3,2] row_mask:0xf bank_mask:0xf
	v_add_u32_dpp v45, v41, v49 quad_perm:[1,0,3,2] row_mask:0xf bank_mask:0xf
	s_cmp_eq_u32 s43, 0
	s_cselect_b32 s32, 0, -1
	v_and_b32_e32 v62, s32, v62
	v_and_b32_e32 v63, s32, v63
	v_add_u32_e32 v44, v44, v62
	v_add_u32_e32 v45, v45, v63
	ds_write_b64 v61, v[44:45]
	s_mov_b32 s42, s44
	s_mov_b32 s43, s45
	s_add_i32 s44, s44, 1
	s_and_b32 s44, s44, 7
	s_cmp_eq_u32 s44, 0
	s_cselect_b32 s32, 1, 0
	s_add_i32 s45, s45, s32
	s_and_b32 s45, s45, 3
	s_lshl_b32 s32, s42, 12
	v_add_u32_e32 v61, s32, v60
	ds_read_b64 v[62:63], v61
	s_waitcnt lgkmcnt(0)
	s_waitcnt vmcnt(15)
; __device__ __forceinline__ void peer_u_item(int p, int j, const LAS unsigned short* EL  , const unsigned char* __restrict__ XQ, const unsigned char* __restrict__ U8, LAS int* ACC  , int lane, int wave) {
;     ...
;         for (int i = 0; i < 16; ++i) {
;             int sh = __builtin_amdgcn_sdot8((int)uu[i].x, (int)xh.x, 0, false); sh = __builtin_amdgcn_sdot8((int)uu[i].y, (int)xh.y, sh, false);
;             sh = __builtin_amdgcn_sdot8((int)uu[i].z, (int)xh.z, sh, false); sh = __builtin_amdgcn_sdot8((int)uu[i].w, (int)xh.w, sh, false);
;             int sl = __builtin_amdgcn_sdot8((int)uu[i].x, (int)xl.x, 0, false); sl = __builtin_amdgcn_sdot8((int)uu[i].y, (int)xl.y, sl, false);
;             sl = __builtin_amdgcn_sdot8((int)uu[i].z, (int)xl.z, sl, false); sl = __builtin_amdgcn_sdot8((int)uu[i].w, (int)xl.w, sl, false);
;             d[i] = (sh << 4) + sl;
;         }
	v_dot8_i32_i4 v34, v122, v194, 0
	v_dot8_i32_i4 v35, v122, v198, 0
	v_dot8_i32_i4 v34, v123, v195, v34
	v_dot8_i32_i4 v35, v123, v199, v35
	v_dot8_i32_i4 v34, v124, v196, v34
	v_dot8_i32_i4 v35, v124, v200, v35
	v_dot8_i32_i4 v34, v125, v197, v34
	v_dot8_i32_i4 v35, v125, v201, v35
	s_nop 2
	s_nop 0
	v_lshl_add_u32 v18, v34, 4, v35
	s_waitcnt vmcnt(14)
	v_dot8_i32_i4 v36, v126, v194, 0
	v_dot8_i32_i4 v37, v126, v198, 0
	v_dot8_i32_i4 v36, v127, v195, v36
	v_dot8_i32_i4 v37, v127, v199, v37
	v_dot8_i32_i4 v36, v128, v196, v36
	v_dot8_i32_i4 v37, v128, v200, v37
	v_dot8_i32_i4 v36, v129, v197, v36
	v_dot8_i32_i4 v37, v129, v201, v37
	s_nop 2
	s_nop 0
	v_lshl_add_u32 v19, v36, 4, v37
	s_waitcnt vmcnt(13)
	v_dot8_i32_i4 v34, v130, v194, 0
	v_dot8_i32_i4 v35, v130, v198, 0
	v_dot8_i32_i4 v34, v131, v195, v34
	v_dot8_i32_i4 v35, v131, v199, v35
	v_dot8_i32_i4 v34, v132, v196, v34
	v_dot8_i32_i4 v35, v132, v200, v35
	v_dot8_i32_i4 v34, v133, v197, v34
	v_dot8_i32_i4 v35, v133, v201, v35
	s_nop 2
	s_nop 0
	v_lshl_add_u32 v20, v34, 4, v35
	s_waitcnt vmcnt(12)
	v_dot8_i32_i4 v36, v134, v194, 0
	v_dot8_i32_i4 v37, v134, v198, 0
	v_dot8_i32_i4 v36, v135, v195, v36
	v_dot8_i32_i4 v37, v135, v199, v37
	v_dot8_i32_i4 v36, v136, v196, v36
	v_dot8_i32_i4 v37, v136, v200, v37
	v_dot8_i32_i4 v36, v137, v197, v36
	v_dot8_i32_i4 v37, v137, v201, v37
	s_nop 2
	s_nop 0
	v_lshl_add_u32 v21, v36, 4, v37
	s_waitcnt vmcnt(11)
	v_dot8_i32_i4 v34, v138, v194, 0
	v_dot8_i32_i4 v35, v138, v198, 0
	v_dot8_i32_i4 v34, v139, v195, v34
	v_dot8_i32_i4 v35, v139, v199, v35
	v_dot8_i32_i4 v34, v140, v196, v34
	v_dot8_i32_i4 v35, v140, v200, v35
	v_dot8_i32_i4 v34, v141, v197, v34
	v_dot8_i32_i4 v35, v141, v201, v35
	s_nop 2
	s_nop 0
	v_lshl_add_u32 v22, v34, 4, v35
	s_waitcnt vmcnt(10)
	v_dot8_i32_i4 v36, v142, v194, 0
	v_dot8_i32_i4 v37, v142, v198, 0
	v_dot8_i32_i4 v36, v143, v195, v36
	v_dot8_i32_i4 v37, v143, v199, v37
	v_dot8_i32_i4 v36, v144, v196, v36
	v_dot8_i32_i4 v37, v144, v200, v37
	v_dot8_i32_i4 v36, v145, v197, v36
	v_dot8_i32_i4 v37, v145, v201, v37
	s_nop 2
	s_nop 0
	v_lshl_add_u32 v23, v36, 4, v37
	s_waitcnt vmcnt(9)
	v_dot8_i32_i4 v34, v146, v194, 0
	v_dot8_i32_i4 v35, v146, v198, 0
	v_dot8_i32_i4 v34, v147, v195, v34
	v_dot8_i32_i4 v35, v147, v199, v35
	v_dot8_i32_i4 v34, v148, v196, v34
	v_dot8_i32_i4 v35, v148, v200, v35
	v_dot8_i32_i4 v34, v149, v197, v34
	v_dot8_i32_i4 v35, v149, v201, v35
	s_nop 2
	s_nop 0
	v_lshl_add_u32 v24, v34, 4, v35
	s_waitcnt vmcnt(8)
	v_dot8_i32_i4 v36, v150, v194, 0
	v_dot8_i32_i4 v37, v150, v198, 0
	v_dot8_i32_i4 v36, v151, v195, v36
	v_dot8_i32_i4 v37, v151, v199, v37
	v_dot8_i32_i4 v36, v152, v196, v36
	v_dot8_i32_i4 v37, v152, v200, v37
	v_dot8_i32_i4 v36, v153, v197, v36
	v_dot8_i32_i4 v37, v153, v201, v37
	s_nop 2
	s_nop 0
	v_lshl_add_u32 v25, v36, 4, v37
	s_waitcnt vmcnt(7)
	v_dot8_i32_i4 v34, v154, v194, 0
	v_dot8_i32_i4 v35, v154, v198, 0
	v_dot8_i32_i4 v34, v155, v195, v34
	v_dot8_i32_i4 v35, v155, v199, v35
	v_dot8_i32_i4 v34, v156, v196, v34
	v_dot8_i32_i4 v35, v156, v200, v35
	v_dot8_i32_i4 v34, v157, v197, v34
	v_dot8_i32_i4 v35, v157, v201, v35
	s_nop 2
	s_nop 0
	v_lshl_add_u32 v26, v34, 4, v35
	s_waitcnt vmcnt(6)
	v_dot8_i32_i4 v36, v158, v194, 0
	v_dot8_i32_i4 v37, v158, v198, 0
	v_dot8_i32_i4 v36, v159, v195, v36
	v_dot8_i32_i4 v37, v159, v199, v37
	v_dot8_i32_i4 v36, v160, v196, v36
	v_dot8_i32_i4 v37, v160, v200, v37
	v_dot8_i32_i4 v36, v161, v197, v36
	v_dot8_i32_i4 v37, v161, v201, v37
	s_nop 2
	s_nop 0
	v_lshl_add_u32 v27, v36, 4, v37
	s_waitcnt vmcnt(5)
	v_dot8_i32_i4 v34, v162, v194, 0
	v_dot8_i32_i4 v35, v162, v198, 0
	v_dot8_i32_i4 v34, v163, v195, v34
	v_dot8_i32_i4 v35, v163, v199, v35
	v_dot8_i32_i4 v34, v164, v196, v34
	v_dot8_i32_i4 v35, v164, v200, v35
	v_dot8_i32_i4 v34, v165, v197, v34
	v_dot8_i32_i4 v35, v165, v201, v35
	s_nop 2
	s_nop 0
	v_lshl_add_u32 v28, v34, 4, v35
	s_waitcnt vmcnt(4)
	v_dot8_i32_i4 v36, v166, v194, 0
	v_dot8_i32_i4 v37, v166, v198, 0
	v_dot8_i32_i4 v36, v167, v195, v36
	v_dot8_i32_i4 v37, v167, v199, v37
	v_dot8_i32_i4 v36, v168, v196, v36
	v_dot8_i32_i4 v37, v168, v200, v37
	v_dot8_i32_i4 v36, v169, v197, v36
	v_dot8_i32_i4 v37, v169, v201, v37
	s_nop 2
	s_nop 0
	v_lshl_add_u32 v29, v36, 4, v37
	s_waitcnt vmcnt(3)
; #define LAS __attribute__((address_space(3)))
; template <int M4, int M2, int M1> __device__ __forceinline__ void treduce16i(const int (&a)[16], int lane, int& r0, int& r1) {
;     int b[8], c[4];
;     { const bool hi = (lane & M4) != 0;
; #pragma unroll
;       for (int i = 0; i < 8; ++i) { const int send = hi ? a[i] : a[i + 8]; const int recv = __shfl_xor(send, M4); b[i] = (hi ? a[i + 8] : a[i]) + recv; } }
;     { const bool hi = (lane & M2) != 0;
; #pragma unroll
;       for (int i = 0; i < 4; ++i) { const int send = hi ? b[i] : b[i + 4]; const int recv = __shfl_xor(send, M2); c[i] = (hi ? b[i + 4] : b[i]) + recv; } }
;     { const bool hi = (lane & M1) != 0;
;       { const int send = hi ? c[0] : c[2]; const int recv = __shfl_xor(send, M1); r0 = (hi ? c[2] : c[0]) + recv; }
;       { const int send = hi ? c[1] : c[3]; const int recv = __shfl_xor(send, M1); r1 = (hi ? c[3] : c[1]) + recv; } }
; }
; __device__ __forceinline__ void peer_u_item(int p, int j, const LAS unsigned short* EL  , const unsigned char* __restrict__ XQ, const unsigned char* __restrict__ U8, LAS int* ACC  , int lane, int wave) {
;     ...
;         for (int i = 0; i < 16; ++i) {
;             int sh = __builtin_amdgcn_sdot8((int)uu[i].x, (int)xh.x, 0, false); sh = __builtin_amdgcn_sdot8((int)uu[i].y, (int)xh.y, sh, false);
;             sh = __builtin_amdgcn_sdot8((int)uu[i].z, (int)xh.z, sh, false); sh = __builtin_amdgcn_sdot8((int)uu[i].w, (int)xh.w, sh, false);
;             int sl = __builtin_amdgcn_sdot8((int)uu[i].x, (int)xl.x, 0, false); sl = __builtin_amdgcn_sdot8((int)uu[i].y, (int)xl.y, sl, false);
;             sl = __builtin_amdgcn_sdot8((int)uu[i].z, (int)xl.z, sl, false); sl = __builtin_amdgcn_sdot8((int)uu[i].w, (int)xl.w, sl, false);
;             d[i] = (sh << 4) + sl;
;         }
;         int r0, r1; treduce16i<4, 2, 1>(d, lane, r0, r1);
;         { typedef int i2v __attribute__((ext_vector_type(2))); LAS i2v* ap = (LAS i2v*)(ACC + (it * 8 + wave) * 128 + 2 * lane);
;           i2v a2; if (p == 0) { a2.x = r0; a2.y = r1; } else { a2 = *ap; a2.x += r0; a2.y += r1; } *ap = a2; }
	v_dot8_i32_i4 v34, v170, v194, 0
	v_dot8_i32_i4 v35, v170, v198, 0
	v_dot8_i32_i4 v34, v171, v195, v34
	v_dot8_i32_i4 v35, v171, v199, v35
	v_dot8_i32_i4 v34, v172, v196, v34
	v_dot8_i32_i4 v35, v172, v200, v35
	v_dot8_i32_i4 v34, v173, v197, v34
	v_dot8_i32_i4 v35, v173, v201, v35
	s_nop 2
	s_nop 0
	v_lshl_add_u32 v30, v34, 4, v35
	s_waitcnt vmcnt(2)
	v_dot8_i32_i4 v36, v174, v194, 0
	v_dot8_i32_i4 v37, v174, v198, 0
	v_dot8_i32_i4 v36, v175, v195, v36
	v_dot8_i32_i4 v37, v175, v199, v37
	v_dot8_i32_i4 v36, v176, v196, v36
	v_dot8_i32_i4 v37, v176, v200, v37
	v_dot8_i32_i4 v36, v177, v197, v36
	v_dot8_i32_i4 v37, v177, v201, v37
	s_nop 2
	s_nop 0
	v_lshl_add_u32 v31, v36, 4, v37
	s_waitcnt vmcnt(1)
	v_dot8_i32_i4 v34, v178, v194, 0
	v_dot8_i32_i4 v35, v178, v198, 0
	v_dot8_i32_i4 v34, v179, v195, v34
	v_dot8_i32_i4 v35, v179, v199, v35
	v_dot8_i32_i4 v34, v180, v196, v34
	v_dot8_i32_i4 v35, v180, v200, v35
	v_dot8_i32_i4 v34, v181, v197, v34
	v_dot8_i32_i4 v35, v181, v201, v35
	s_nop 2
	s_nop 0
	v_lshl_add_u32 v32, v34, 4, v35
	s_waitcnt vmcnt(0)
	v_dot8_i32_i4 v36, v182, v194, 0
	v_dot8_i32_i4 v37, v182, v198, 0
	v_dot8_i32_i4 v36, v183, v195, v36
	v_dot8_i32_i4 v37, v183, v199, v37
	v_dot8_i32_i4 v36, v184, v196, v36
	v_dot8_i32_i4 v37, v184, v200, v37
	v_dot8_i32_i4 v36, v185, v197, v36
	v_dot8_i32_i4 v37, v185, v201, v37
	s_nop 2
	s_nop 0
	v_lshl_add_u32 v33, v36, 4, v37
	v_cndmask_b32_e64 v40, v26, v18, s[10:11]
	v_cndmask_b32_e64 v48, v18, v26, s[10:11]
	v_cndmask_b32_e64 v41, v27, v19, s[10:11]
	v_cndmask_b32_e64 v49, v19, v27, s[10:11]
	v_cndmask_b32_e64 v42, v28, v20, s[10:11]
	v_cndmask_b32_e64 v50, v20, v28, s[10:11]
	v_cndmask_b32_e64 v43, v29, v21, s[10:11]
	v_cndmask_b32_e64 v51, v21, v29, s[10:11]
	v_cndmask_b32_e64 v44, v30, v22, s[10:11]
	v_cndmask_b32_e64 v52, v22, v30, s[10:11]
	v_cndmask_b32_e64 v45, v31, v23, s[10:11]
	v_cndmask_b32_e64 v53, v23, v31, s[10:11]
	v_cndmask_b32_e64 v46, v32, v24, s[10:11]
	v_cndmask_b32_e64 v54, v24, v32, s[10:11]
	v_cndmask_b32_e64 v47, v33, v25, s[10:11]
	v_cndmask_b32_e64 v55, v25, v33, s[10:11]
	v_add_u32_dpp v18, v40, v48 row_shr:4 row_mask:0xf bank_mask:0xa
	v_add_u32_dpp v18, v40, v48 row_shl:4 row_mask:0xf bank_mask:0x5
	v_add_u32_dpp v19, v41, v49 row_shr:4 row_mask:0xf bank_mask:0xa
	v_add_u32_dpp v19, v41, v49 row_shl:4 row_mask:0xf bank_mask:0x5
	v_add_u32_dpp v20, v42, v50 row_shr:4 row_mask:0xf bank_mask:0xa
	v_add_u32_dpp v20, v42, v50 row_shl:4 row_mask:0xf bank_mask:0x5
	v_add_u32_dpp v21, v43, v51 row_shr:4 row_mask:0xf bank_mask:0xa
	v_add_u32_dpp v21, v43, v51 row_shl:4 row_mask:0xf bank_mask:0x5
	v_add_u32_dpp v22, v44, v52 row_shr:4 row_mask:0xf bank_mask:0xa
	v_add_u32_dpp v22, v44, v52 row_shl:4 row_mask:0xf bank_mask:0x5
	v_add_u32_dpp v23, v45, v53 row_shr:4 row_mask:0xf bank_mask:0xa
	v_add_u32_dpp v23, v45, v53 row_shl:4 row_mask:0xf bank_mask:0x5
	v_add_u32_dpp v24, v46, v54 row_shr:4 row_mask:0xf bank_mask:0xa
	v_add_u32_dpp v24, v46, v54 row_shl:4 row_mask:0xf bank_mask:0x5
	v_add_u32_dpp v25, v47, v55 row_shr:4 row_mask:0xf bank_mask:0xa
	v_add_u32_dpp v25, v47, v55 row_shl:4 row_mask:0xf bank_mask:0x5
	v_cndmask_b32_e64 v40, v22, v18, s[12:13]
	v_cndmask_b32_e64 v48, v18, v22, s[12:13]
	v_cndmask_b32_e64 v41, v23, v19, s[12:13]
	v_cndmask_b32_e64 v49, v19, v23, s[12:13]
	v_cndmask_b32_e64 v42, v24, v20, s[12:13]
	v_cndmask_b32_e64 v50, v20, v24, s[12:13]
	v_cndmask_b32_e64 v43, v25, v21, s[12:13]
	v_cndmask_b32_e64 v51, v21, v25, s[12:13]
	s_nop 0
	v_add_u32_dpp v26, v40, v48 quad_perm:[2,3,0,1] row_mask:0xf bank_mask:0xf
	v_add_u32_dpp v27, v41, v49 quad_perm:[2,3,0,1] row_mask:0xf bank_mask:0xf
	v_add_u32_dpp v28, v42, v50 quad_perm:[2,3,0,1] row_mask:0xf bank_mask:0xf
	v_add_u32_dpp v29, v43, v51 quad_perm:[2,3,0,1] row_mask:0xf bank_mask:0xf
	v_cndmask_b32_e64 v40, v28, v26, s[14:15]
	v_cndmask_b32_e64 v48, v26, v28, s[14:15]
	v_cndmask_b32_e64 v41, v29, v27, s[14:15]
	v_cndmask_b32_e64 v49, v27, v29, s[14:15]
	s_nop 1
	v_add_u32_dpp v44, v40, v48 quad_perm:[1,0,3,2] row_mask:0xf bank_mask:0xf
	v_add_u32_dpp v45, v41, v49 quad_perm:[1,0,3,2] row_mask:0xf bank_mask:0xf
	s_cmp_eq_u32 s43, 0
	s_cselect_b32 s32, 0, -1
	v_and_b32_e32 v62, s32, v62
	v_and_b32_e32 v63, s32, v63
	v_add_u32_e32 v44, v44, v62
	v_add_u32_e32 v45, v45, v63
	ds_write_b64 v61, v[44:45]
	s_mov_b32 s42, s44
	s_mov_b32 s43, s45
	s_add_i32 s44, s44, 1
	s_and_b32 s44, s44, 7
	s_cmp_eq_u32 s44, 0
	s_cselect_b32 s32, 1, 0
	s_add_i32 s45, s45, s32
	s_and_b32 s45, s45, 3
	s_waitcnt lgkmcnt(0)
